# GEMM loops: post-MMA barrier sunk 2 MFMAs with prio-2 tail, setprio 1 hoisted above pre-MMA barrier, k=1 A-fragment LDS reads moved into own MFMA shadow; final RMSNorm prefetch
# speedup vs baseline: 1.0222x; 1.0063x over previous
; #define PG8_STAGE(bufoff, gbase, voff) do { _Pragma("unroll") for (int _i = 0; _i < 2; ++_i) \
;         __builtin_amdgcn_global_load_lds((const unsigned*)((const char*)(gbase) + (voff)[_i]), (LAS unsigned*)(lds + (bufoff) + ldsw + _i * 8192), 16, 0, 0); } while (0)
; #define PG8_LDA(dst, b, h) do { _Pragma("unroll") for (int m = 0; m < 4; ++m) _Pragma("unroll") for (int k = 0; k < 2; ++k) dst[m][k] = *(const LAS bf16x8*)(lds + PG8_SA(b, h) + aoff + m * 2048 + k * 1024); } while (0)
; #define PG8_LDB(dst, b, h) do { _Pragma("unroll") for (int n = 0; n < 2; ++n) _Pragma("unroll") for (int k = 0; k < 2; ++k) dst[n][k] = *(const LAS bf16x8*)(lds + PG8_SB(b, h) + boff + n * 2048 + k * 1024); } while (0)
; #define PG8_MMA(ai, bj, At, Bt) do { __builtin_amdgcn_s_setprio(1); _Pragma("unroll") for (int m = 0; m < 4; ++m) _Pragma("unroll") for (int n = 0; n < 2; ++n) _Pragma("unroll") for (int k = 0; k < 2; ++k) \
;         acc[ai][bj][m][n] = __builtin_amdgcn_mfma_f32_16x16x32_bf16(Bt[n][k], At[m][k], acc[ai][bj][m][n], 0, 0, 0); __builtin_amdgcn_s_setprio(0); } while (0)
; #define PG8_WAIT_V(n) asm volatile("s_waitcnt vmcnt(" #n ")" ::: "memory")
; #define PG8_WAIT_L(n) asm volatile("s_waitcnt lgkmcnt(" #n ")" ::: "memory")
; #define PG8_BAR __builtin_amdgcn_s_barrier()
; #define PG8_SCHED __builtin_amdgcn_sched_barrier(0)
; #define PG8_STAGE(bufoff, gbase, voff) do { _Pragma("unroll") for (int _i = 0; _i < 2; ++_i) \
;         __builtin_amdgcn_global_load_lds((const unsigned*)((const char*)(gbase) + (voff)[_i]), (LAS unsigned*)(lds + (bufoff) + ldsw + _i * 8192), 16, 0, 0); } while (0)
; template <class Epi0, class Epi1>
; DI void gemm_phase_dual(LAS unsigned char* lds, const Gemm g, const Gemm g1, const StaticOrder S, const Epi0 E0, const Epi1 E1) {
;     ...
;             PG8_LDB(B0, 0, 0); PG8_SCHED; PG8_LDA(At, 0, 0); PG8_STAGE(PG8_SA(1, 1), a1 + hstep, voffA);
;             PG8_WAIT_L(8); PG8_BAR; PG8_WAIT_L(0); PG8_MMA(0, 0, At, B0); PG8_BAR; PG8_SCHED;
;             PG8_LDB(B1, 0, 1); PG8_STAGE(PG8_SB(0, 0), b2, voffB);
;             PG8_BAR; PG8_WAIT_L(0); PG8_MMA(0, 1, At, B1); PG8_BAR;
;             PG8_LDA(At, 0, 1); PG8_STAGE(PG8_SA(0, 0), a2, voffA);
;             PG8_BAR; PG8_WAIT_L(0); PG8_MMA(1, 0, At, B0); PG8_BAR; PG8_SCHED;
;             PG8_STAGE(PG8_SB(0, 1), b2 + hstep, voffB);
;             PG8_WAIT_V(6); PG8_BAR; PG8_MMA(1, 1, At, B1); PG8_BAR;
.LBB0_107:
	ds_read_b128 v[152:155], v149
	ds_read_b128 v[156:159], v149 offset:1024
	ds_read_b128 v[160:163], v149 offset:2048
	ds_read_b128 v[164:167], v149 offset:3072
	s_add_u32 s14, s76, 0xfffc0080
	s_addc_u32 s15, s77, -1
	s_cmp_eq_u32 s97, 12
	s_cselect_b32 s81, s11, s15
	s_cselect_b32 s80, s93, s14
	s_cselect_b32 s79, s9, s96
	s_cselect_b32 s78, s94, s95
	v_lshl_add_u64 v[144:145], s[76:77], 0, v[136:137]
	s_add_i32 m0, s29, 0xc000
	ds_read_b128 v[168:171], v150
	ds_read_b128 v[176:179], v150 offset:2048
	ds_read_b128 v[184:187], v150 offset:4096
	ds_read_b128 v[192:195], v150 offset:6144
	global_load_lds_dwordx4 v[144:145], off
	v_lshl_add_u64 v[144:145], s[76:77], 0, v[138:139]
	s_add_i32 m0, s29, 0xe000
	s_nop 0
	global_load_lds_dwordx4 v[144:145], off
	s_waitcnt lgkmcnt(4)
	s_setprio 1
	s_barrier
	s_waitcnt lgkmcnt(0)
	v_mfma_f32_16x16x32_bf16 v[124:127], v[152:155], v[168:171], v[124:127]
	ds_read_b128 v[172:175], v150 offset:1024
	v_mfma_f32_16x16x32_bf16 v[116:119], v[160:163], v[168:171], v[116:119]
	ds_read_b128 v[180:183], v150 offset:3072
	v_mfma_f32_16x16x32_bf16 v[108:111], v[152:155], v[176:179], v[108:111]
	ds_read_b128 v[188:191], v150 offset:5120
	v_mfma_f32_16x16x32_bf16 v[100:103], v[160:163], v[176:179], v[100:103]
	ds_read_b128 v[196:199], v150 offset:7168
	v_mfma_f32_16x16x32_bf16 v[92:95], v[152:155], v[184:187], v[92:95]
	v_mfma_f32_16x16x32_bf16 v[84:87], v[160:163], v[184:187], v[84:87]
	v_mfma_f32_16x16x32_bf16 v[76:79], v[152:155], v[192:195], v[76:79]
	v_mfma_f32_16x16x32_bf16 v[68:71], v[160:163], v[192:195], v[68:71]
	s_waitcnt lgkmcnt(3)
	v_mfma_f32_16x16x32_bf16 v[124:127], v[156:159], v[172:175], v[124:127]
	v_mfma_f32_16x16x32_bf16 v[116:119], v[164:167], v[172:175], v[116:119]
	s_waitcnt lgkmcnt(2)
	v_mfma_f32_16x16x32_bf16 v[108:111], v[156:159], v[180:183], v[108:111]
	v_mfma_f32_16x16x32_bf16 v[100:103], v[164:167], v[180:183], v[100:103]
	s_waitcnt lgkmcnt(1)
	v_mfma_f32_16x16x32_bf16 v[92:95], v[156:159], v[188:191], v[92:95]
	v_mfma_f32_16x16x32_bf16 v[84:87], v[164:167], v[188:191], v[84:87]
	s_waitcnt lgkmcnt(0)
	s_setprio 2
	s_barrier
	v_mfma_f32_16x16x32_bf16 v[76:79], v[156:159], v[196:199], v[76:79]
	v_mfma_f32_16x16x32_bf16 v[68:71], v[164:167], v[196:199], v[68:71]
	s_setprio 0
	s_add_i32 s14, s89, s7
	v_lshl_add_u64 v[144:145], s[78:79], 0, v[132:133]
	s_mov_b32 m0, s14
	ds_read_b128 v[200:203], v151
	ds_read_b128 v[204:207], v151 offset:1024
	ds_read_b128 v[208:211], v151 offset:2048
	ds_read_b128 v[212:215], v151 offset:3072
	global_load_lds_dwordx4 v[144:145], off
	v_lshl_add_u64 v[216:217], s[78:79], 0, v[128:129]
	s_add_i32 m0, s14, 0x2000
	s_nop 0
	global_load_lds_dwordx4 v[216:217], off
	s_setprio 1
	s_barrier
	s_waitcnt lgkmcnt(0)
	v_mfma_f32_16x16x32_bf16 v[120:123], v[200:203], v[168:171], v[120:123]
	v_mfma_f32_16x16x32_bf16 v[112:115], v[208:211], v[168:171], v[112:115]
	v_mfma_f32_16x16x32_bf16 v[104:107], v[200:203], v[176:179], v[104:107]
	v_mfma_f32_16x16x32_bf16 v[96:99], v[208:211], v[176:179], v[96:99]
	v_mfma_f32_16x16x32_bf16 v[88:91], v[200:203], v[184:187], v[88:91]
	v_mfma_f32_16x16x32_bf16 v[80:83], v[208:211], v[184:187], v[80:83]
	v_mfma_f32_16x16x32_bf16 v[72:75], v[200:203], v[192:195], v[72:75]
	v_mfma_f32_16x16x32_bf16 v[64:67], v[208:211], v[192:195], v[64:67]
	v_mfma_f32_16x16x32_bf16 v[120:123], v[204:207], v[172:175], v[120:123]
	v_mfma_f32_16x16x32_bf16 v[112:115], v[212:215], v[172:175], v[112:115]
	v_mfma_f32_16x16x32_bf16 v[104:107], v[204:207], v[180:183], v[104:107]
	v_mfma_f32_16x16x32_bf16 v[96:99], v[212:215], v[180:183], v[96:99]
	v_mfma_f32_16x16x32_bf16 v[88:91], v[204:207], v[188:191], v[88:91]
	v_mfma_f32_16x16x32_bf16 v[80:83], v[212:215], v[188:191], v[80:83]
	s_setprio 2
	s_barrier
	v_mfma_f32_16x16x32_bf16 v[72:75], v[204:207], v[196:199], v[72:75]
	v_mfma_f32_16x16x32_bf16 v[64:67], v[212:215], v[196:199], v[64:67]
	s_setprio 0
	s_mov_b32 m0, s29
	v_lshl_add_u64 v[218:219], s[80:81], 0, v[134:135]
	ds_read_b128 v[168:171], v150 offset:16384
	ds_read_b128 v[176:179], v150 offset:18432
	ds_read_b128 v[184:187], v150 offset:20480
	ds_read_b128 v[192:195], v150 offset:22528
	global_load_lds_dwordx4 v[218:219], off
	v_lshl_add_u64 v[220:221], s[80:81], 0, v[130:131]
	s_mov_b32 m0, s59
	s_nop 0
	global_load_lds_dwordx4 v[220:221], off
	s_setprio 1
	s_barrier
	s_waitcnt lgkmcnt(0)
	v_mfma_f32_16x16x32_bf16 v[60:63], v[152:155], v[168:171], v[60:63]
	ds_read_b128 v[172:175], v150 offset:17408
	v_mfma_f32_16x16x32_bf16 v[52:55], v[160:163], v[168:171], v[52:55]
	ds_read_b128 v[180:183], v150 offset:19456
	v_mfma_f32_16x16x32_bf16 v[44:47], v[152:155], v[176:179], v[44:47]
	ds_read_b128 v[188:191], v150 offset:21504
	v_mfma_f32_16x16x32_bf16 v[36:39], v[160:163], v[176:179], v[36:39]
	ds_read_b128 v[196:199], v150 offset:23552
	v_mfma_f32_16x16x32_bf16 v[28:31], v[152:155], v[184:187], v[28:31]
	v_mfma_f32_16x16x32_bf16 v[20:23], v[160:163], v[184:187], v[20:23]
	v_mfma_f32_16x16x32_bf16 v[12:15], v[152:155], v[192:195], v[12:15]
	v_mfma_f32_16x16x32_bf16 v[4:7], v[160:163], v[192:195], v[4:7]
	s_waitcnt lgkmcnt(3)
	v_mfma_f32_16x16x32_bf16 v[60:63], v[156:159], v[172:175], v[60:63]
	v_mfma_f32_16x16x32_bf16 v[52:55], v[164:167], v[172:175], v[52:55]
	s_waitcnt lgkmcnt(2)
	v_mfma_f32_16x16x32_bf16 v[44:47], v[156:159], v[180:183], v[44:47]
	v_mfma_f32_16x16x32_bf16 v[36:39], v[164:167], v[180:183], v[36:39]
	s_waitcnt lgkmcnt(1)
	v_mfma_f32_16x16x32_bf16 v[28:31], v[156:159], v[188:191], v[28:31]
	v_mfma_f32_16x16x32_bf16 v[20:23], v[164:167], v[188:191], v[20:23]
	s_waitcnt lgkmcnt(0)
	s_setprio 2
	s_barrier
; #define PG8_STAGE(bufoff, gbase, voff) do { _Pragma("unroll") for (int _i = 0; _i < 2; ++_i) \
;         __builtin_amdgcn_global_load_lds((const unsigned*)((const char*)(gbase) + (voff)[_i]), (LAS unsigned*)(lds + (bufoff) + ldsw + _i * 8192), 16, 0, 0); } while (0)
; #define PG8_LDA(dst, b, h) do { _Pragma("unroll") for (int m = 0; m < 4; ++m) _Pragma("unroll") for (int k = 0; k < 2; ++k) dst[m][k] = *(const LAS bf16x8*)(lds + PG8_SA(b, h) + aoff + m * 2048 + k * 1024); } while (0)
; #define PG8_LDB(dst, b, h) do { _Pragma("unroll") for (int n = 0; n < 2; ++n) _Pragma("unroll") for (int k = 0; k < 2; ++k) dst[n][k] = *(const LAS bf16x8*)(lds + PG8_SB(b, h) + boff + n * 2048 + k * 1024); } while (0)
; #define PG8_MMA(ai, bj, At, Bt) do { __builtin_amdgcn_s_setprio(1); _Pragma("unroll") for (int m = 0; m < 4; ++m) _Pragma("unroll") for (int n = 0; n < 2; ++n) _Pragma("unroll") for (int k = 0; k < 2; ++k) \
;         acc[ai][bj][m][n] = __builtin_amdgcn_mfma_f32_16x16x32_bf16(Bt[n][k], At[m][k], acc[ai][bj][m][n], 0, 0, 0); __builtin_amdgcn_s_setprio(0); } while (0)
; #define PG8_WAIT_V(n) asm volatile("s_waitcnt vmcnt(" #n ")" ::: "memory")
; #define PG8_WAIT_L(n) asm volatile("s_waitcnt lgkmcnt(" #n ")" ::: "memory")
; #define PG8_BAR __builtin_amdgcn_s_barrier()
; #define PG8_SCHED __builtin_amdgcn_sched_barrier(0)
; #define PG8_STAGE(bufoff, gbase, voff) do { _Pragma("unroll") for (int _i = 0; _i < 2; ++_i) \
;         __builtin_amdgcn_global_load_lds((const unsigned*)((const char*)(gbase) + (voff)[_i]), (LAS unsigned*)(lds + (bufoff) + ldsw + _i * 8192), 16, 0, 0); } while (0)
; #define PG8_BAR __builtin_amdgcn_s_barrier()
; template <class Epi0, class Epi1>
; DI void gemm_phase_dual(LAS unsigned char* lds, const Gemm g, const Gemm g1, const StaticOrder S, const Epi0 E0, const Epi1 E1) {
;     ...
;             PG8_BAR; PG8_WAIT_L(0); PG8_MMA(1, 0, At, B0); PG8_BAR; PG8_SCHED;
;             PG8_STAGE(PG8_SB(0, 1), b2 + hstep, voffB);
;             PG8_WAIT_V(6); PG8_BAR; PG8_MMA(1, 1, At, B1); PG8_BAR;
;             PG8_LDB(B0, 1, 0); PG8_SCHED; PG8_LDA(At, 1, 0); PG8_STAGE(PG8_SA(0, 1), a2 + hstep, voffA);
;             PG8_WAIT_L(8); PG8_BAR; PG8_WAIT_L(0); PG8_MMA(0, 0, At, B0); PG8_BAR; PG8_SCHED;
;             PG8_LDB(B1, 1, 1); PG8_STAGE(PG8_SB(1, 0), b3, voffB);
;             PG8_BAR; PG8_WAIT_L(0); PG8_MMA(0, 1, At, B1); PG8_BAR;
	v_mfma_f32_16x16x32_bf16 v[12:15], v[156:159], v[196:199], v[12:15]
	v_mfma_f32_16x16x32_bf16 v[4:7], v[164:167], v[196:199], v[4:7]
	s_setprio 0
	s_add_u32 s14, s78, 0x40000
	s_addc_u32 s15, s79, 0
	s_add_i32 s35, s90, s7
	v_lshl_add_u64 v[152:153], s[14:15], 0, v[132:133]
	s_mov_b32 m0, s35
	s_nop 0
	global_load_lds_dwordx4 v[152:153], off
	v_lshl_add_u64 v[152:153], s[14:15], 0, v[128:129]
	s_add_i32 m0, s35, 0x2000
	s_nop 0
	global_load_lds_dwordx4 v[152:153], off
	s_waitcnt vmcnt(6)
	s_setprio 1
	s_barrier
	v_mfma_f32_16x16x32_bf16 v[56:59], v[200:203], v[168:171], v[56:59]
	v_mfma_f32_16x16x32_bf16 v[48:51], v[208:211], v[168:171], v[48:51]
	v_mfma_f32_16x16x32_bf16 v[40:43], v[200:203], v[176:179], v[40:43]
	v_mfma_f32_16x16x32_bf16 v[32:35], v[208:211], v[176:179], v[32:35]
	v_mfma_f32_16x16x32_bf16 v[24:27], v[200:203], v[184:187], v[24:27]
	v_mfma_f32_16x16x32_bf16 v[16:19], v[208:211], v[184:187], v[16:19]
	v_mfma_f32_16x16x32_bf16 v[8:11], v[200:203], v[192:195], v[8:11]
	v_mfma_f32_16x16x32_bf16 v[0:3], v[208:211], v[192:195], v[0:3]
	v_mfma_f32_16x16x32_bf16 v[56:59], v[204:207], v[172:175], v[56:59]
	v_mfma_f32_16x16x32_bf16 v[48:51], v[212:215], v[172:175], v[48:51]
	v_mfma_f32_16x16x32_bf16 v[40:43], v[204:207], v[180:183], v[40:43]
	v_mfma_f32_16x16x32_bf16 v[32:35], v[212:215], v[180:183], v[32:35]
	v_mfma_f32_16x16x32_bf16 v[24:27], v[204:207], v[188:191], v[24:27]
	v_mfma_f32_16x16x32_bf16 v[16:19], v[212:215], v[188:191], v[16:19]
	s_setprio 2
	s_barrier
	v_mfma_f32_16x16x32_bf16 v[8:11], v[204:207], v[196:199], v[8:11]
	v_mfma_f32_16x16x32_bf16 v[0:3], v[212:215], v[196:199], v[0:3]
	s_setprio 0
	s_add_i32 s35, 0, 0x18000
	v_add_u32_e32 v164, s35, v147
	ds_read_b128 v[152:155], v164
	ds_read_b128 v[156:159], v164 offset:1024
	ds_read_b128 v[160:163], v164 offset:2048
	ds_read_b128 v[164:167], v164 offset:3072
	s_add_u32 s14, s80, 0x40000
	s_addc_u32 s15, s81, 0
	s_mov_b32 m0, s82
	v_lshl_add_u64 v[200:201], s[14:15], 0, v[134:135]
	ds_read_b128 v[168:171], v150 offset:32768
	ds_read_b128 v[176:179], v150 offset:34816
	ds_read_b128 v[184:187], v150 offset:36864
	ds_read_b128 v[192:195], v150 offset:38912
	global_load_lds_dwordx4 v[200:201], off
	v_lshl_add_u64 v[200:201], s[14:15], 0, v[130:131]
	s_mov_b32 m0, s83
	s_nop 0
	global_load_lds_dwordx4 v[200:201], off
	s_waitcnt lgkmcnt(4)
	s_setprio 1
	s_barrier
	s_waitcnt lgkmcnt(0)
	v_mfma_f32_16x16x32_bf16 v[124:127], v[152:155], v[168:171], v[124:127]
	ds_read_b128 v[172:175], v150 offset:33792
	v_mfma_f32_16x16x32_bf16 v[116:119], v[160:163], v[168:171], v[116:119]
	ds_read_b128 v[180:183], v150 offset:35840
	v_mfma_f32_16x16x32_bf16 v[108:111], v[152:155], v[176:179], v[108:111]
	ds_read_b128 v[188:191], v150 offset:37888
	v_mfma_f32_16x16x32_bf16 v[100:103], v[160:163], v[176:179], v[100:103]
	ds_read_b128 v[196:199], v150 offset:39936
	v_mfma_f32_16x16x32_bf16 v[92:95], v[152:155], v[184:187], v[92:95]
	v_mfma_f32_16x16x32_bf16 v[84:87], v[160:163], v[184:187], v[84:87]
	v_mfma_f32_16x16x32_bf16 v[76:79], v[152:155], v[192:195], v[76:79]
	v_mfma_f32_16x16x32_bf16 v[68:71], v[160:163], v[192:195], v[68:71]
	s_waitcnt lgkmcnt(3)
	v_mfma_f32_16x16x32_bf16 v[124:127], v[156:159], v[172:175], v[124:127]
	v_mfma_f32_16x16x32_bf16 v[116:119], v[164:167], v[172:175], v[116:119]
	s_waitcnt lgkmcnt(2)
	v_mfma_f32_16x16x32_bf16 v[108:111], v[156:159], v[180:183], v[108:111]
	v_mfma_f32_16x16x32_bf16 v[100:103], v[164:167], v[180:183], v[100:103]
	s_waitcnt lgkmcnt(1)
	v_mfma_f32_16x16x32_bf16 v[92:95], v[156:159], v[188:191], v[92:95]
	v_mfma_f32_16x16x32_bf16 v[84:87], v[164:167], v[188:191], v[84:87]
	s_waitcnt lgkmcnt(0)
	s_setprio 2
	s_barrier
	v_mfma_f32_16x16x32_bf16 v[76:79], v[156:159], v[196:199], v[76:79]
	v_mfma_f32_16x16x32_bf16 v[68:71], v[164:167], v[196:199], v[68:71]
	s_setprio 0
	s_add_i32 s80, 0, 0x1c000
	s_add_i32 s14, s35, s7
	v_add_u32_e32 v212, s80, v147
	v_lshl_add_u64 v[144:145], v[144:145], 0, s[4:5]
	s_mov_b32 m0, s14
	ds_read_b128 v[200:203], v212
	ds_read_b128 v[204:207], v212 offset:1024
	ds_read_b128 v[208:211], v212 offset:2048
	ds_read_b128 v[212:215], v212 offset:3072
	global_load_lds_dwordx4 v[144:145], off
	v_lshl_add_u64 v[144:145], v[216:217], 0, s[4:5]
	s_add_i32 m0, s14, 0x2000
	s_nop 0
	global_load_lds_dwordx4 v[144:145], off
	s_setprio 1
	s_barrier
	s_waitcnt lgkmcnt(0)
	v_mfma_f32_16x16x32_bf16 v[120:123], v[200:203], v[168:171], v[120:123]
	v_mfma_f32_16x16x32_bf16 v[112:115], v[208:211], v[168:171], v[112:115]
	v_mfma_f32_16x16x32_bf16 v[104:107], v[200:203], v[176:179], v[104:107]
	v_mfma_f32_16x16x32_bf16 v[96:99], v[208:211], v[176:179], v[96:99]
	v_mfma_f32_16x16x32_bf16 v[88:91], v[200:203], v[184:187], v[88:91]
	v_mfma_f32_16x16x32_bf16 v[80:83], v[208:211], v[184:187], v[80:83]
	v_mfma_f32_16x16x32_bf16 v[72:75], v[200:203], v[192:195], v[72:75]
	v_mfma_f32_16x16x32_bf16 v[64:67], v[208:211], v[192:195], v[64:67]
	v_mfma_f32_16x16x32_bf16 v[120:123], v[204:207], v[172:175], v[120:123]
	v_mfma_f32_16x16x32_bf16 v[112:115], v[212:215], v[172:175], v[112:115]
	v_mfma_f32_16x16x32_bf16 v[104:107], v[204:207], v[180:183], v[104:107]
	v_mfma_f32_16x16x32_bf16 v[96:99], v[212:215], v[180:183], v[96:99]
	v_mfma_f32_16x16x32_bf16 v[88:91], v[204:207], v[188:191], v[88:91]
	v_mfma_f32_16x16x32_bf16 v[80:83], v[212:215], v[188:191], v[80:83]
	s_setprio 2
	s_barrier
; DI unsigned pk_bf16(float lo, float hi) { f32x2 v = {lo, hi}; return __builtin_bit_cast(unsigned, __builtin_convertvector(v, bf16v2)); }
; DI float fast_silu(float x) { return x * fast_sigmoid(x); }
; #define PG8_STAGE(bufoff, gbase, voff) do { _Pragma("unroll") for (int _i = 0; _i < 2; ++_i) \
;         __builtin_amdgcn_global_load_lds((const unsigned*)((const char*)(gbase) + (voff)[_i]), (LAS unsigned*)(lds + (bufoff) + ldsw + _i * 8192), 16, 0, 0); } while (0)
; #define PG8_LDA(dst, b, h) do { _Pragma("unroll") for (int m = 0; m < 4; ++m) _Pragma("unroll") for (int k = 0; k < 2; ++k) dst[m][k] = *(const LAS bf16x8*)(lds + PG8_SA(b, h) + aoff + m * 2048 + k * 1024); } while (0)
; #define PG8_MMA(ai, bj, At, Bt) do { __builtin_amdgcn_s_setprio(1); _Pragma("unroll") for (int m = 0; m < 4; ++m) _Pragma("unroll") for (int n = 0; n < 2; ++n) _Pragma("unroll") for (int k = 0; k < 2; ++k) \
;         acc[ai][bj][m][n] = __builtin_amdgcn_mfma_f32_16x16x32_bf16(Bt[n][k], At[m][k], acc[ai][bj][m][n], 0, 0, 0); __builtin_amdgcn_s_setprio(0); } while (0)
; template <class Epi0, class Epi1>
; DI void gemm_phase_dual(LAS unsigned char* lds, const Gemm g, const Gemm g1, const StaticOrder S, const Epi0 E0, const Epi1 E1) {
;     ...
;             PG8_LDA(At, 1, 1); PG8_STAGE(PG8_SA(1, 0), a3, voffA);
;             PG8_BAR; PG8_WAIT_L(0); PG8_MMA(1, 0, At, B0); PG8_BAR; PG8_SCHED;
;             PG8_STAGE(PG8_SB(1, 1), b3 + hstep, voffB);
;             PG8_WAIT_V(6); PG8_BAR; PG8_MMA(1, 1, At, B1); PG8_BAR;
;         }
;         if (ui & 1) E1(acc, cur, wr, wc, fr, fq); else E0(acc, cur, wr, wc, fr, fq);
;         if (!has_next) break;
; #pragma unroll
;     DI void operator()(AccRef acc, const Unit& u, int wr, int wc, int fr, int fq) const {
;     ...
;                 const int row = row0 + ai * 128 + m * 16;
;                 const float r = RS ? rsc.r[ai][m] : 1.0f;
;                 const f32x4 a0 = acc[ai][0][m][0] * r, a1 = acc[ai][0][m][1] * r, b0 = acc[ai][1][m][0] * r, b1 = acc[ai][1][m][1] * r;
;                 u32x4 w;
;                 w.x = pk_bf16(fast_silu(a0[0]) * b0[0], fast_silu(a0[1]) * b0[1]); w.y = pk_bf16(fast_silu(a0[2]) * b0[2], fast_silu(a0[3]) * b0[3]);
;                 w.z = pk_bf16(fast_silu(a1[0]) * b1[0], fast_silu(a1[1]) * b1[1]); w.w = pk_bf16(fast_silu(a1[2]) * b1[2], fast_silu(a1[3]) * b1[3]);
;                 *(u32x4*)(G + (size_t)row * DFF + col) = w;
	v_mfma_f32_16x16x32_bf16 v[72:75], v[204:207], v[196:199], v[72:75]
	v_mfma_f32_16x16x32_bf16 v[64:67], v[212:215], v[196:199], v[64:67]
	s_setprio 0
	s_mov_b32 m0, s85
	v_lshl_add_u64 v[144:145], v[218:219], 0, s[4:5]
	ds_read_b128 v[168:171], v150 offset:49152
	ds_read_b128 v[176:179], v150 offset:51200
	ds_read_b128 v[184:187], v150 offset:53248
	ds_read_b128 v[192:195], v150 offset:55296
	global_load_lds_dwordx4 v[144:145], off
	v_lshl_add_u64 v[144:145], v[220:221], 0, s[4:5]
	s_mov_b32 m0, s86
	s_nop 0
	global_load_lds_dwordx4 v[144:145], off
	s_setprio 1
	s_barrier
	s_waitcnt lgkmcnt(0)
	v_mfma_f32_16x16x32_bf16 v[60:63], v[152:155], v[168:171], v[60:63]
	ds_read_b128 v[172:175], v150 offset:50176
	v_mfma_f32_16x16x32_bf16 v[52:55], v[160:163], v[168:171], v[52:55]
	ds_read_b128 v[180:183], v150 offset:52224
	v_mfma_f32_16x16x32_bf16 v[44:47], v[152:155], v[176:179], v[44:47]
	ds_read_b128 v[188:191], v150 offset:54272
	v_mfma_f32_16x16x32_bf16 v[36:39], v[160:163], v[176:179], v[36:39]
	ds_read_b128 v[196:199], v150 offset:56320
	v_mfma_f32_16x16x32_bf16 v[28:31], v[152:155], v[184:187], v[28:31]
	v_mfma_f32_16x16x32_bf16 v[20:23], v[160:163], v[184:187], v[20:23]
	v_mfma_f32_16x16x32_bf16 v[12:15], v[152:155], v[192:195], v[12:15]
	v_mfma_f32_16x16x32_bf16 v[4:7], v[160:163], v[192:195], v[4:7]
	s_waitcnt lgkmcnt(3)
	v_mfma_f32_16x16x32_bf16 v[60:63], v[156:159], v[172:175], v[60:63]
	v_mfma_f32_16x16x32_bf16 v[52:55], v[164:167], v[172:175], v[52:55]
	s_waitcnt lgkmcnt(2)
	v_mfma_f32_16x16x32_bf16 v[44:47], v[156:159], v[180:183], v[44:47]
	v_mfma_f32_16x16x32_bf16 v[36:39], v[164:167], v[180:183], v[36:39]
	s_waitcnt lgkmcnt(1)
	v_mfma_f32_16x16x32_bf16 v[28:31], v[156:159], v[188:191], v[28:31]
	v_mfma_f32_16x16x32_bf16 v[20:23], v[164:167], v[188:191], v[20:23]
	s_waitcnt lgkmcnt(0)
	s_setprio 2
	s_barrier
	v_mfma_f32_16x16x32_bf16 v[12:15], v[156:159], v[196:199], v[12:15]
	v_mfma_f32_16x16x32_bf16 v[4:7], v[164:167], v[196:199], v[4:7]
	s_setprio 0
	s_add_u32 s14, s78, 0x40080
	s_addc_u32 s15, s79, 0
	s_add_i32 s35, s80, s7
	v_lshl_add_u64 v[144:145], s[14:15], 0, v[132:133]
	s_mov_b32 m0, s35
	s_nop 0
	global_load_lds_dwordx4 v[144:145], off
	v_lshl_add_u64 v[144:145], s[14:15], 0, v[128:129]
	s_add_i32 m0, s35, 0x2000
	s_nop 0
	global_load_lds_dwordx4 v[144:145], off
	s_waitcnt vmcnt(6)
	s_setprio 1
	s_barrier
	v_mfma_f32_16x16x32_bf16 v[56:59], v[200:203], v[168:171], v[56:59]
	v_mfma_f32_16x16x32_bf16 v[48:51], v[208:211], v[168:171], v[48:51]
	v_mfma_f32_16x16x32_bf16 v[40:43], v[200:203], v[176:179], v[40:43]
	v_mfma_f32_16x16x32_bf16 v[32:35], v[208:211], v[176:179], v[32:35]
	v_mfma_f32_16x16x32_bf16 v[24:27], v[200:203], v[184:187], v[24:27]
	v_mfma_f32_16x16x32_bf16 v[16:19], v[208:211], v[184:187], v[16:19]
	v_mfma_f32_16x16x32_bf16 v[8:11], v[200:203], v[192:195], v[8:11]
	v_mfma_f32_16x16x32_bf16 v[0:3], v[208:211], v[192:195], v[0:3]
	v_mfma_f32_16x16x32_bf16 v[56:59], v[204:207], v[172:175], v[56:59]
	v_mfma_f32_16x16x32_bf16 v[48:51], v[212:215], v[172:175], v[48:51]
	v_mfma_f32_16x16x32_bf16 v[40:43], v[204:207], v[180:183], v[40:43]
	v_mfma_f32_16x16x32_bf16 v[32:35], v[212:215], v[180:183], v[32:35]
	v_mfma_f32_16x16x32_bf16 v[24:27], v[204:207], v[188:191], v[24:27]
	v_mfma_f32_16x16x32_bf16 v[16:19], v[212:215], v[188:191], v[16:19]
	s_setprio 2
	s_barrier
	v_mfma_f32_16x16x32_bf16 v[8:11], v[204:207], v[196:199], v[8:11]
	v_mfma_f32_16x16x32_bf16 v[0:3], v[212:215], v[196:199], v[0:3]
	s_setprio 0
	s_add_i32 s97, s97, 2
	s_add_u32 s76, s76, 0x100
	s_addc_u32 s77, s77, 0
	s_add_u32 s95, s95, 0x100
	s_addc_u32 s96, s96, 0
	s_cmp_gt_u32 s97, 13
	s_cbranch_scc0 .LBB0_107
	v_mul_f32_e32 v153, 0xbfb8aa3b, v124
	v_exp_f32_e32 v153, v153
	v_mul_f32_e32 v154, 0xbfb8aa3b, v125
	v_exp_f32_e32 v155, v154
	v_lshl_or_b32 v144, s92, 7, v148
	v_add_f32_e32 v153, 1.0, v153
	v_rcp_f32_e32 v154, v153
	v_add_f32_e32 v153, 1.0, v155
	v_mul_f32_e32 v155, 0xbfb8aa3b, v126
	v_exp_f32_e32 v156, v155
	v_mul_f32_e32 v155, 0xbfb8aa3b, v127
	v_exp_f32_e32 v157, v155
	v_rcp_f32_e32 v155, v153
	v_add_f32_e32 v153, 1.0, v156
	v_rcp_f32_e32 v156, v153
	v_add_f32_e32 v153, 1.0, v157
	v_rcp_f32_e32 v157, v153
	v_pk_mul_f32 v[124:125], v[124:125], v[154:155]
	v_ashrrev_i32_e32 v145, 31, v144
	v_pk_mul_f32 v[120:121], v[124:125], v[120:121]
	v_pk_mul_f32 v[124:125], v[126:127], v[156:157]
	v_cvt_pk_bf16_f32 v120, v120, v121
	v_mul_f32_e32 v121, 0xbfb8aa3b, v116
	v_pk_mul_f32 v[122:123], v[124:125], v[122:123]
	v_exp_f32_e32 v124, v121
	v_mul_f32_e32 v121, 0xbfb8aa3b, v117
	v_exp_f32_e32 v125, v121
	v_cvt_pk_bf16_f32 v121, v122, v123
	v_add_f32_e32 v122, 1.0, v124
	v_mul_f32_e32 v124, 0xbfb8aa3b, v118
	v_add_f32_e32 v123, 1.0, v125
	v_mul_f32_e32 v125, 0xbfb8aa3b, v119
	v_exp_f32_e32 v124, v124
	v_exp_f32_e32 v125, v125
	v_rcp_f32_e32 v122, v122
	v_rcp_f32_e32 v123, v123
	v_add_f32_e32 v124, 1.0, v124
	v_add_f32_e32 v125, 1.0, v125
	v_rcp_f32_e32 v124, v124
	v_rcp_f32_e32 v125, v125
	v_pk_mul_f32 v[116:117], v[116:117], v[122:123]
	v_lshl_add_u32 v152, s28, 8, v146
	v_pk_mul_f32 v[112:113], v[116:117], v[112:113]
	v_lshl_add_u64 v[144:145], v[144:145], 1, s[54:55]
	v_cvt_pk_bf16_f32 v122, v112, v113
	v_pk_mul_f32 v[112:113], v[118:119], v[124:125]
	v_or_b32_e32 v116, 16, v152
	v_pk_mul_f32 v[112:113], v[112:113], v[114:115]
	v_mul_f32_e32 v114, 0xbfb8aa3b, v110
	v_cvt_pk_bf16_f32 v123, v112, v113
	v_mad_i64_i32 v[112:113], s[14:15], v152, s91, v[144:145]
	global_store_dwordx4 v[112:113], v[120:123], off
	v_mul_f32_e32 v112, 0xbfb8aa3b, v108
	v_mul_f32_e32 v113, 0xbfb8aa3b, v109
	v_exp_f32_e32 v112, v112
	v_exp_f32_e32 v113, v113
; DI unsigned pk_bf16(float lo, float hi) { f32x2 v = {lo, hi}; return __builtin_bit_cast(unsigned, __builtin_convertvector(v, bf16v2)); }
; DI float fast_silu(float x) { return x * fast_sigmoid(x); }
;     DI void operator()(AccRef acc, const Unit& u, int wr, int wc, int fr, int fq) const {
;     ...
;                 const int row = row0 + ai * 128 + m * 16;
;                 const float r = RS ? rsc.r[ai][m] : 1.0f;
;                 const f32x4 a0 = acc[ai][0][m][0] * r, a1 = acc[ai][0][m][1] * r, b0 = acc[ai][1][m][0] * r, b1 = acc[ai][1][m][1] * r;
;                 u32x4 w;
;                 w.x = pk_bf16(fast_silu(a0[0]) * b0[0], fast_silu(a0[1]) * b0[1]); w.y = pk_bf16(fast_silu(a0[2]) * b0[2], fast_silu(a0[3]) * b0[3]);
;                 w.z = pk_bf16(fast_silu(a1[0]) * b1[0], fast_silu(a1[1]) * b1[1]); w.w = pk_bf16(fast_silu(a1[2]) * b1[2], fast_silu(a1[3]) * b1[3]);
;                 *(u32x4*)(G + (size_t)row * DFF + col) = w;
	v_mul_f32_e32 v115, 0xbfb8aa3b, v111
	v_exp_f32_e32 v114, v114
	v_exp_f32_e32 v115, v115
	v_add_f32_e32 v112, 1.0, v112
	v_add_f32_e32 v113, 1.0, v113
	v_rcp_f32_e32 v112, v112
	v_rcp_f32_e32 v113, v113
	v_add_f32_e32 v114, 1.0, v114
	v_add_f32_e32 v115, 1.0, v115
	v_rcp_f32_e32 v114, v114
	v_rcp_f32_e32 v115, v115
	v_pk_mul_f32 v[108:109], v[108:109], v[112:113]
	s_and_b64 vcc, exec, s[0:1]
	v_pk_mul_f32 v[104:105], v[108:109], v[104:105]
	v_pk_mul_f32 v[108:109], v[110:111], v[114:115]
	v_cvt_pk_bf16_f32 v104, v104, v105
	v_mul_f32_e32 v105, 0xbfb8aa3b, v100
	v_pk_mul_f32 v[106:107], v[108:109], v[106:107]
	v_exp_f32_e32 v108, v105
	v_mul_f32_e32 v105, 0xbfb8aa3b, v101
	v_exp_f32_e32 v109, v105
	v_cvt_pk_bf16_f32 v105, v106, v107
	v_add_f32_e32 v106, 1.0, v108
	v_mul_f32_e32 v108, 0xbfb8aa3b, v102
	v_add_f32_e32 v107, 1.0, v109
	v_mul_f32_e32 v109, 0xbfb8aa3b, v103
	v_exp_f32_e32 v108, v108
	v_exp_f32_e32 v109, v109
	v_rcp_f32_e32 v106, v106
	v_rcp_f32_e32 v107, v107
	v_add_f32_e32 v108, 1.0, v108
	v_add_f32_e32 v109, 1.0, v109
	v_rcp_f32_e32 v108, v108
	v_rcp_f32_e32 v109, v109
	v_pk_mul_f32 v[100:101], v[100:101], v[106:107]
	s_mov_b32 s92, s8
	v_pk_mul_f32 v[96:97], v[100:101], v[96:97]
	v_or_b32_e32 v100, 32, v152
	v_cvt_pk_bf16_f32 v106, v96, v97
	v_pk_mul_f32 v[96:97], v[102:103], v[108:109]
	s_mov_b32 s28, s10
	v_pk_mul_f32 v[96:97], v[96:97], v[98:99]
	v_mul_f32_e32 v98, 0xbfb8aa3b, v94
	v_cvt_pk_bf16_f32 v107, v96, v97
	v_mad_i64_i32 v[96:97], s[14:15], v116, s91, v[144:145]
	global_store_dwordx4 v[96:97], v[104:107], off
	v_mul_f32_e32 v96, 0xbfb8aa3b, v92
	v_mul_f32_e32 v97, 0xbfb8aa3b, v93
	v_exp_f32_e32 v96, v96
	v_exp_f32_e32 v97, v97
	v_mul_f32_e32 v99, 0xbfb8aa3b, v95
	v_exp_f32_e32 v98, v98
	v_exp_f32_e32 v99, v99
	v_add_f32_e32 v96, 1.0, v96
	v_add_f32_e32 v97, 1.0, v97
	v_rcp_f32_e32 v96, v96
	v_rcp_f32_e32 v97, v97
	v_add_f32_e32 v98, 1.0, v98
	v_add_f32_e32 v99, 1.0, v99
	v_rcp_f32_e32 v98, v98
	v_rcp_f32_e32 v99, v99
	v_pk_mul_f32 v[92:93], v[92:93], v[96:97]
	s_mov_b64 s[78:79], s[26:27]
	v_pk_mul_f32 v[88:89], v[92:93], v[88:89]
	v_pk_mul_f32 v[92:93], v[94:95], v[98:99]
	v_cvt_pk_bf16_f32 v88, v88, v89
	v_mul_f32_e32 v89, 0xbfb8aa3b, v84
	v_pk_mul_f32 v[90:91], v[92:93], v[90:91]
	v_exp_f32_e32 v92, v89
	v_mul_f32_e32 v89, 0xbfb8aa3b, v85
	v_exp_f32_e32 v93, v89
	v_cvt_pk_bf16_f32 v89, v90, v91
	v_add_f32_e32 v90, 1.0, v92
	v_mul_f32_e32 v92, 0xbfb8aa3b, v86
	v_add_f32_e32 v91, 1.0, v93
	v_mul_f32_e32 v93, 0xbfb8aa3b, v87
	v_exp_f32_e32 v92, v92
	v_exp_f32_e32 v93, v93
	v_rcp_f32_e32 v90, v90
	v_rcp_f32_e32 v91, v91
	v_add_f32_e32 v92, 1.0, v92
	v_add_f32_e32 v93, 1.0, v93
	v_rcp_f32_e32 v92, v92
	v_rcp_f32_e32 v93, v93
	v_pk_mul_f32 v[84:85], v[84:85], v[90:91]
	s_mov_b64 s[76:77], s[24:25]
	v_pk_mul_f32 v[80:81], v[84:85], v[80:81]
	v_or_b32_e32 v84, 48, v152
	v_cvt_pk_bf16_f32 v90, v80, v81
	v_pk_mul_f32 v[80:81], v[86:87], v[92:93]
	s_nop 0
	v_pk_mul_f32 v[80:81], v[80:81], v[82:83]
	v_mul_f32_e32 v82, 0xbfb8aa3b, v78
	v_cvt_pk_bf16_f32 v91, v80, v81
	v_mad_i64_i32 v[80:81], s[14:15], v100, s91, v[144:145]
	global_store_dwordx4 v[80:81], v[88:91], off
	v_mul_f32_e32 v80, 0xbfb8aa3b, v76
	v_mul_f32_e32 v81, 0xbfb8aa3b, v77
	v_exp_f32_e32 v80, v80
	v_exp_f32_e32 v81, v81
	v_mul_f32_e32 v83, 0xbfb8aa3b, v79
	v_exp_f32_e32 v82, v82
	v_exp_f32_e32 v83, v83
	v_add_f32_e32 v80, 1.0, v80
	v_add_f32_e32 v81, 1.0, v81
	v_rcp_f32_e32 v80, v80
	v_rcp_f32_e32 v81, v81
	v_add_f32_e32 v82, 1.0, v82
	v_add_f32_e32 v83, 1.0, v83
	v_rcp_f32_e32 v82, v82
	v_rcp_f32_e32 v83, v83
	v_pk_mul_f32 v[76:77], v[76:77], v[80:81]
	s_nop 0
	v_pk_mul_f32 v[72:73], v[76:77], v[72:73]
	v_pk_mul_f32 v[76:77], v[78:79], v[82:83]
	v_cvt_pk_bf16_f32 v72, v72, v73
	v_mul_f32_e32 v73, 0xbfb8aa3b, v68
	v_pk_mul_f32 v[74:75], v[76:77], v[74:75]
	v_exp_f32_e32 v76, v73
	v_mul_f32_e32 v73, 0xbfb8aa3b, v69
	v_exp_f32_e32 v77, v73
	v_cvt_pk_bf16_f32 v73, v74, v75
	v_add_f32_e32 v74, 1.0, v76
	v_mul_f32_e32 v76, 0xbfb8aa3b, v70
	v_add_f32_e32 v75, 1.0, v77
	v_mul_f32_e32 v77, 0xbfb8aa3b, v71
	v_exp_f32_e32 v76, v76
	v_exp_f32_e32 v77, v77
	v_rcp_f32_e32 v74, v74
	v_rcp_f32_e32 v75, v75
	v_add_f32_e32 v76, 1.0, v76
	v_add_f32_e32 v77, 1.0, v77
	v_rcp_f32_e32 v76, v76
	v_rcp_f32_e32 v77, v77
	v_pk_mul_f32 v[68:69], v[68:69], v[74:75]
	s_nop 0
	v_pk_mul_f32 v[64:65], v[68:69], v[64:65]
	v_add_u32_e32 v68, 0x80, v152
	v_cvt_pk_bf16_f32 v74, v64, v65
	v_pk_mul_f32 v[64:65], v[70:71], v[76:77]
	s_nop 0
	v_pk_mul_f32 v[64:65], v[64:65], v[66:67]
	v_mul_f32_e32 v66, 0xbfb8aa3b, v62
	v_cvt_pk_bf16_f32 v75, v64, v65
	v_mad_i64_i32 v[64:65], s[14:15], v84, s91, v[144:145]
	global_store_dwordx4 v[64:65], v[72:75], off
	v_mul_f32_e32 v64, 0xbfb8aa3b, v60
	v_mul_f32_e32 v65, 0xbfb8aa3b, v61
	v_exp_f32_e32 v64, v64
	v_exp_f32_e32 v65, v65
	v_mul_f32_e32 v67, 0xbfb8aa3b, v63
	v_exp_f32_e32 v66, v66
	v_exp_f32_e32 v67, v67
	v_add_f32_e32 v64, 1.0, v64
	v_add_f32_e32 v65, 1.0, v65
	v_rcp_f32_e32 v64, v64
	v_rcp_f32_e32 v65, v65
	v_add_f32_e32 v66, 1.0, v66
	v_add_f32_e32 v67, 1.0, v67
	v_rcp_f32_e32 v66, v66
	v_rcp_f32_e32 v67, v67
	v_pk_mul_f32 v[60:61], v[60:61], v[64:65]
	s_nop 0
	v_pk_mul_f32 v[56:57], v[60:61], v[56:57]
	v_pk_mul_f32 v[60:61], v[62:63], v[66:67]
	v_cvt_pk_bf16_f32 v56, v56, v57
	v_mul_f32_e32 v57, 0xbfb8aa3b, v52
	v_pk_mul_f32 v[58:59], v[60:61], v[58:59]
	v_exp_f32_e32 v60, v57
	v_mul_f32_e32 v57, 0xbfb8aa3b, v53
	v_exp_f32_e32 v61, v57
	v_cvt_pk_bf16_f32 v57, v58, v59
; DI unsigned pk_bf16(float lo, float hi) { f32x2 v = {lo, hi}; return __builtin_bit_cast(unsigned, __builtin_convertvector(v, bf16v2)); }
; DI float fast_silu(float x) { return x * fast_sigmoid(x); }
; #define PG8_WAIT_V(n) asm volatile("s_waitcnt vmcnt(" #n ")" ::: "memory")
; #define PG8_BAR __builtin_amdgcn_s_barrier()
; #define PG8_WAIT_V(n) asm volatile("s_waitcnt vmcnt(" #n ")" ::: "memory")
; #define PG8_BAR __builtin_amdgcn_s_barrier()
; template <class Epi>
; DI void gemm_phase(LAS unsigned char* lds, const Gemm g, const StaticOrder S, const Epi E) {
;     ...
;         if (!has_next) break;
; #pragma unroll
;         for (int a = 0; a < 2; ++a)
; #pragma unroll
;             for (int b = 0; b < 2; ++b)
; #pragma unroll
;                 for (int m = 0; m < 4; ++m)
; #pragma unroll
;                     for (int n = 0; n < 2; ++n) acc[a][b][m][n] = (f32x4){0.f, 0.f, 0.f, 0.f};
;         cur = nxt; cA = nA; cB = nB; ++ui;
;     }
;     PG8_WAIT_V(0);
;     if (wr == 0) PG8_BAR;
;     PG8_BAR;
;     DI void operator()(AccRef acc, const Unit& u, int wr, int wc, int fr, int fq) const {
;     ...
;                 const int row = row0 + ai * 128 + m * 16;
;                 const float r = RS ? rsc.r[ai][m] : 1.0f;
;                 const f32x4 a0 = acc[ai][0][m][0] * r, a1 = acc[ai][0][m][1] * r, b0 = acc[ai][1][m][0] * r, b1 = acc[ai][1][m][1] * r;
;                 u32x4 w;
;                 w.x = pk_bf16(fast_silu(a0[0]) * b0[0], fast_silu(a0[1]) * b0[1]); w.y = pk_bf16(fast_silu(a0[2]) * b0[2], fast_silu(a0[3]) * b0[3]);
;                 w.z = pk_bf16(fast_silu(a1[0]) * b1[0], fast_silu(a1[1]) * b1[1]); w.w = pk_bf16(fast_silu(a1[2]) * b1[2], fast_silu(a1[3]) * b1[3]);
;                 *(u32x4*)(G + (size_t)row * DFF + col) = w;
	v_add_f32_e32 v58, 1.0, v60
	v_mul_f32_e32 v60, 0xbfb8aa3b, v54
	v_add_f32_e32 v59, 1.0, v61
	v_mul_f32_e32 v61, 0xbfb8aa3b, v55
	v_exp_f32_e32 v60, v60
	v_exp_f32_e32 v61, v61
	v_rcp_f32_e32 v58, v58
	v_rcp_f32_e32 v59, v59
	v_add_f32_e32 v60, 1.0, v60
	v_add_f32_e32 v61, 1.0, v61
	v_rcp_f32_e32 v60, v60
	v_rcp_f32_e32 v61, v61
	v_pk_mul_f32 v[52:53], v[52:53], v[58:59]
	s_nop 0
	v_pk_mul_f32 v[48:49], v[52:53], v[48:49]
	v_add_u32_e32 v52, 0x90, v152
	v_cvt_pk_bf16_f32 v58, v48, v49
	v_pk_mul_f32 v[48:49], v[54:55], v[60:61]
	s_nop 0
	v_pk_mul_f32 v[48:49], v[48:49], v[50:51]
	v_mul_f32_e32 v50, 0xbfb8aa3b, v46
	v_cvt_pk_bf16_f32 v59, v48, v49
	v_mad_i64_i32 v[48:49], s[14:15], v68, s91, v[144:145]
	global_store_dwordx4 v[48:49], v[56:59], off
	v_mul_f32_e32 v48, 0xbfb8aa3b, v44
	v_mul_f32_e32 v49, 0xbfb8aa3b, v45
	v_exp_f32_e32 v48, v48
	v_exp_f32_e32 v49, v49
	v_mul_f32_e32 v51, 0xbfb8aa3b, v47
	v_exp_f32_e32 v50, v50
	v_exp_f32_e32 v51, v51
	v_add_f32_e32 v48, 1.0, v48
	v_add_f32_e32 v49, 1.0, v49
	v_rcp_f32_e32 v48, v48
	v_rcp_f32_e32 v49, v49
	v_add_f32_e32 v50, 1.0, v50
	v_add_f32_e32 v51, 1.0, v51
	v_rcp_f32_e32 v50, v50
	v_rcp_f32_e32 v51, v51
	v_pk_mul_f32 v[44:45], v[44:45], v[48:49]
	s_nop 0
	v_pk_mul_f32 v[40:41], v[44:45], v[40:41]
	v_pk_mul_f32 v[44:45], v[46:47], v[50:51]
	v_cvt_pk_bf16_f32 v40, v40, v41
	v_mul_f32_e32 v41, 0xbfb8aa3b, v36
	v_pk_mul_f32 v[42:43], v[44:45], v[42:43]
	v_exp_f32_e32 v44, v41
	v_mul_f32_e32 v41, 0xbfb8aa3b, v37
	v_exp_f32_e32 v45, v41
	v_cvt_pk_bf16_f32 v41, v42, v43
	v_add_f32_e32 v42, 1.0, v44
	v_mul_f32_e32 v44, 0xbfb8aa3b, v38
	v_add_f32_e32 v43, 1.0, v45
	v_mul_f32_e32 v45, 0xbfb8aa3b, v39
	v_exp_f32_e32 v44, v44
	v_exp_f32_e32 v45, v45
	v_rcp_f32_e32 v42, v42
	v_rcp_f32_e32 v43, v43
	v_add_f32_e32 v44, 1.0, v44
	v_add_f32_e32 v45, 1.0, v45
	v_rcp_f32_e32 v44, v44
	v_rcp_f32_e32 v45, v45
	v_pk_mul_f32 v[36:37], v[36:37], v[42:43]
	s_nop 0
	v_pk_mul_f32 v[32:33], v[36:37], v[32:33]
	v_add_u32_e32 v36, 0xa0, v152
	v_cvt_pk_bf16_f32 v42, v32, v33
	v_pk_mul_f32 v[32:33], v[38:39], v[44:45]
	s_nop 0
	v_pk_mul_f32 v[32:33], v[32:33], v[34:35]
	v_mul_f32_e32 v34, 0xbfb8aa3b, v30
	v_cvt_pk_bf16_f32 v43, v32, v33
	v_mad_i64_i32 v[32:33], s[14:15], v52, s91, v[144:145]
	global_store_dwordx4 v[32:33], v[40:43], off
	v_mul_f32_e32 v32, 0xbfb8aa3b, v28
	v_mul_f32_e32 v33, 0xbfb8aa3b, v29
	v_exp_f32_e32 v32, v32
	v_exp_f32_e32 v33, v33
	v_mul_f32_e32 v35, 0xbfb8aa3b, v31
	v_exp_f32_e32 v34, v34
	v_exp_f32_e32 v35, v35
	v_add_f32_e32 v32, 1.0, v32
	v_add_f32_e32 v33, 1.0, v33
	v_rcp_f32_e32 v32, v32
	v_rcp_f32_e32 v33, v33
	v_add_f32_e32 v34, 1.0, v34
	v_add_f32_e32 v35, 1.0, v35
	v_rcp_f32_e32 v34, v34
	v_rcp_f32_e32 v35, v35
	v_pk_mul_f32 v[28:29], v[28:29], v[32:33]
	s_nop 0
	v_pk_mul_f32 v[24:25], v[28:29], v[24:25]
	v_pk_mul_f32 v[28:29], v[30:31], v[34:35]
	v_cvt_pk_bf16_f32 v24, v24, v25
	v_mul_f32_e32 v25, 0xbfb8aa3b, v20
	v_pk_mul_f32 v[26:27], v[28:29], v[26:27]
	v_exp_f32_e32 v28, v25
	v_mul_f32_e32 v25, 0xbfb8aa3b, v21
	v_exp_f32_e32 v29, v25
	v_cvt_pk_bf16_f32 v25, v26, v27
	v_add_f32_e32 v26, 1.0, v28
	v_mul_f32_e32 v28, 0xbfb8aa3b, v22
	v_add_f32_e32 v27, 1.0, v29
	v_mul_f32_e32 v29, 0xbfb8aa3b, v23
	v_exp_f32_e32 v28, v28
	v_exp_f32_e32 v29, v29
	v_rcp_f32_e32 v26, v26
	v_rcp_f32_e32 v27, v27
	v_add_f32_e32 v28, 1.0, v28
	v_add_f32_e32 v29, 1.0, v29
	v_rcp_f32_e32 v28, v28
	v_rcp_f32_e32 v29, v29
	v_pk_mul_f32 v[20:21], v[20:21], v[26:27]
	s_nop 0
	v_pk_mul_f32 v[16:17], v[20:21], v[16:17]
	v_add_u32_e32 v20, 0xb0, v152
	v_cvt_pk_bf16_f32 v26, v16, v17
	v_pk_mul_f32 v[16:17], v[22:23], v[28:29]
	s_nop 0
	v_pk_mul_f32 v[16:17], v[16:17], v[18:19]
	v_mul_f32_e32 v18, 0xbfb8aa3b, v14
	v_cvt_pk_bf16_f32 v27, v16, v17
	v_mad_i64_i32 v[16:17], s[14:15], v36, s91, v[144:145]
	global_store_dwordx4 v[16:17], v[24:27], off
	v_mul_f32_e32 v16, 0xbfb8aa3b, v12
	v_mul_f32_e32 v17, 0xbfb8aa3b, v13
	v_exp_f32_e32 v16, v16
	v_exp_f32_e32 v17, v17
	v_mul_f32_e32 v19, 0xbfb8aa3b, v15
	v_exp_f32_e32 v18, v18
	v_exp_f32_e32 v19, v19
	v_add_f32_e32 v16, 1.0, v16
	v_add_f32_e32 v17, 1.0, v17
	v_rcp_f32_e32 v16, v16
	v_rcp_f32_e32 v17, v17
	v_add_f32_e32 v18, 1.0, v18
	v_add_f32_e32 v19, 1.0, v19
	v_rcp_f32_e32 v18, v18
	v_rcp_f32_e32 v19, v19
	v_pk_mul_f32 v[12:13], v[12:13], v[16:17]
	s_nop 0
	v_pk_mul_f32 v[8:9], v[12:13], v[8:9]
	v_pk_mul_f32 v[12:13], v[14:15], v[18:19]
	v_cvt_pk_bf16_f32 v8, v8, v9
	v_mul_f32_e32 v9, 0xbfb8aa3b, v4
	v_pk_mul_f32 v[10:11], v[12:13], v[10:11]
	v_exp_f32_e32 v12, v9
	v_mul_f32_e32 v9, 0xbfb8aa3b, v5
	v_exp_f32_e32 v13, v9
	v_cvt_pk_bf16_f32 v9, v10, v11
	v_add_f32_e32 v10, 1.0, v12
	v_mul_f32_e32 v12, 0xbfb8aa3b, v6
	v_add_f32_e32 v11, 1.0, v13
	v_mul_f32_e32 v13, 0xbfb8aa3b, v7
	v_exp_f32_e32 v12, v12
	v_exp_f32_e32 v13, v13
	v_rcp_f32_e32 v10, v10
	v_rcp_f32_e32 v11, v11
	v_add_f32_e32 v12, 1.0, v12
	v_add_f32_e32 v13, 1.0, v13
	v_rcp_f32_e32 v12, v12
	v_rcp_f32_e32 v13, v13
	v_pk_mul_f32 v[4:5], v[4:5], v[10:11]
	s_nop 0
	v_pk_mul_f32 v[0:1], v[4:5], v[0:1]
	s_nop 0
	v_cvt_pk_bf16_f32 v10, v0, v1
	v_pk_mul_f32 v[0:1], v[6:7], v[12:13]
	s_nop 0
	v_pk_mul_f32 v[0:1], v[0:1], v[2:3]
	s_nop 0
	v_cvt_pk_bf16_f32 v11, v0, v1
	v_mad_i64_i32 v[0:1], s[14:15], v20, s91, v[144:145]
	global_store_dwordx4 v[0:1], v[8:11], off
	s_cbranch_vccz .LBB0_104
	s_waitcnt vmcnt(0)
	v_readlane_b32 s92, v243, 8
	s_cmpk_gt_u32 s6, 0xff
	v_readlane_b32 s93, v243, 9
	s_cbranch_scc1 .LBB0_111
	s_barrier

; #define PG8_STAGE(bufoff, gbase, voff) do { _Pragma("unroll") for (int _i = 0; _i < 2; ++_i) \
;         __builtin_amdgcn_global_load_lds((const unsigned*)((const char*)(gbase) + (voff)[_i]), (LAS unsigned*)(lds + (bufoff) + ldsw + _i * 8192), 16, 0, 0); } while (0)
; #define PG8_LDA(dst, b, h) do { _Pragma("unroll") for (int m = 0; m < 4; ++m) _Pragma("unroll") for (int k = 0; k < 2; ++k) dst[m][k] = *(const LAS bf16x8*)(lds + PG8_SA(b, h) + aoff + m * 2048 + k * 1024); } while (0)
; #define PG8_LDB(dst, b, h) do { _Pragma("unroll") for (int n = 0; n < 2; ++n) _Pragma("unroll") for (int k = 0; k < 2; ++k) dst[n][k] = *(const LAS bf16x8*)(lds + PG8_SB(b, h) + boff + n * 2048 + k * 1024); } while (0)
; #define PG8_MMA(ai, bj, At, Bt) do { __builtin_amdgcn_s_setprio(1); _Pragma("unroll") for (int m = 0; m < 4; ++m) _Pragma("unroll") for (int n = 0; n < 2; ++n) _Pragma("unroll") for (int k = 0; k < 2; ++k) \
;         acc[ai][bj][m][n] = __builtin_amdgcn_mfma_f32_16x16x32_bf16(Bt[n][k], At[m][k], acc[ai][bj][m][n], 0, 0, 0); __builtin_amdgcn_s_setprio(0); } while (0)
; #define PG8_WAIT_V(n) asm volatile("s_waitcnt vmcnt(" #n ")" ::: "memory")
; #define PG8_WAIT_L(n) asm volatile("s_waitcnt lgkmcnt(" #n ")" ::: "memory")
; #define PG8_BAR __builtin_amdgcn_s_barrier()
; #define PG8_SCHED __builtin_amdgcn_sched_barrier(0)
; #define PG8_STAGE(bufoff, gbase, voff) do { _Pragma("unroll") for (int _i = 0; _i < 2; ++_i) \
;         __builtin_amdgcn_global_load_lds((const unsigned*)((const char*)(gbase) + (voff)[_i]), (LAS unsigned*)(lds + (bufoff) + ldsw + _i * 8192), 16, 0, 0); } while (0)
; template <class Epi0, class Epi1>
; DI void gemm_phase_dual(LAS unsigned char* lds, const Gemm g, const Gemm g1, const StaticOrder S, const Epi0 E0, const Epi1 E1) {
;     ...
;             PG8_LDB(B0, 0, 0); PG8_SCHED; PG8_LDA(At, 0, 0); PG8_STAGE(PG8_SA(1, 1), a1 + hstep, voffA);
;             PG8_WAIT_L(8); PG8_BAR; PG8_WAIT_L(0); PG8_MMA(0, 0, At, B0); PG8_BAR; PG8_SCHED;
;             PG8_LDB(B1, 0, 1); PG8_STAGE(PG8_SB(0, 0), b2, voffB);
;             PG8_BAR; PG8_WAIT_L(0); PG8_MMA(0, 1, At, B1); PG8_BAR;
;             PG8_LDA(At, 0, 1); PG8_STAGE(PG8_SA(0, 0), a2, voffA);
;             PG8_BAR; PG8_WAIT_L(0); PG8_MMA(1, 0, At, B0); PG8_BAR; PG8_SCHED;
;             PG8_STAGE(PG8_SB(0, 1), b2 + hstep, voffB);
;             PG8_WAIT_V(6); PG8_BAR; PG8_MMA(1, 1, At, B1); PG8_BAR;
.LBB0_186:
	ds_read_b128 v[128:131], v207
	ds_read_b128 v[132:135], v207 offset:1024
	ds_read_b128 v[136:139], v207 offset:2048
	ds_read_b128 v[140:143], v207 offset:3072
	s_add_u32 s76, s28, 0x100
	s_addc_u32 s77, s29, 0
	s_cmp_eq_u32 s97, 40
	s_cselect_b32 s81, s9, s77
	s_cselect_b32 s80, s8, s76
	s_cselect_b32 s79, s11, s7
	s_cselect_b32 s78, s10, s6
	v_lshl_add_u64 v[192:193], s[28:29], 0, v[184:185]
	s_add_i32 m0, s82, 0xc000
	ds_read_b128 v[144:147], v208
	ds_read_b128 v[152:155], v208 offset:2048
	ds_read_b128 v[160:163], v208 offset:4096
	ds_read_b128 v[168:171], v208 offset:6144
	global_load_lds_dwordx4 v[192:193], off
	v_lshl_add_u64 v[192:193], s[28:29], 0, v[186:187]
	s_add_i32 m0, s82, 0xe000
	s_nop 0
	global_load_lds_dwordx4 v[192:193], off
	s_waitcnt lgkmcnt(4)
	s_setprio 1
	s_barrier
	s_waitcnt lgkmcnt(0)
	v_mfma_f32_16x16x32_bf16 v[124:127], v[128:131], v[144:147], v[124:127]
	ds_read_b128 v[148:151], v208 offset:1024
	v_mfma_f32_16x16x32_bf16 v[120:123], v[136:139], v[144:147], v[120:123]
	ds_read_b128 v[156:159], v208 offset:3072
	v_mfma_f32_16x16x32_bf16 v[108:111], v[128:131], v[152:155], v[108:111]
	ds_read_b128 v[164:167], v208 offset:5120
	v_mfma_f32_16x16x32_bf16 v[104:107], v[136:139], v[152:155], v[104:107]
	ds_read_b128 v[172:175], v208 offset:7168
	v_mfma_f32_16x16x32_bf16 v[92:95], v[128:131], v[160:163], v[92:95]
	v_mfma_f32_16x16x32_bf16 v[88:91], v[136:139], v[160:163], v[88:91]
	v_mfma_f32_16x16x32_bf16 v[76:79], v[128:131], v[168:171], v[76:79]
	v_mfma_f32_16x16x32_bf16 v[72:75], v[136:139], v[168:171], v[72:75]
	s_waitcnt lgkmcnt(3)
	v_mfma_f32_16x16x32_bf16 v[124:127], v[132:135], v[148:151], v[124:127]
	v_mfma_f32_16x16x32_bf16 v[120:123], v[140:143], v[148:151], v[120:123]
	s_waitcnt lgkmcnt(2)
	v_mfma_f32_16x16x32_bf16 v[108:111], v[132:135], v[156:159], v[108:111]
	v_mfma_f32_16x16x32_bf16 v[104:107], v[140:143], v[156:159], v[104:107]
	s_waitcnt lgkmcnt(1)
	v_mfma_f32_16x16x32_bf16 v[92:95], v[132:135], v[164:167], v[92:95]
	v_mfma_f32_16x16x32_bf16 v[88:91], v[140:143], v[164:167], v[88:91]
	s_waitcnt lgkmcnt(0)
	s_setprio 2
	s_barrier
	v_mfma_f32_16x16x32_bf16 v[76:79], v[132:135], v[172:175], v[76:79]
	v_mfma_f32_16x16x32_bf16 v[72:75], v[140:143], v[172:175], v[72:75]
	s_setprio 0
	s_add_i32 s14, s91, s59
	v_lshl_add_u64 v[216:217], s[78:79], 0, v[178:179]
	s_mov_b32 m0, s14
	ds_read_b128 v[192:195], v209
	ds_read_b128 v[196:199], v209 offset:1024
	ds_read_b128 v[200:203], v209 offset:2048
	ds_read_b128 v[212:215], v209 offset:3072
	global_load_lds_dwordx4 v[216:217], off
	v_lshl_add_u64 v[218:219], s[78:79], 0, v[182:183]
	s_add_i32 m0, s14, 0x2000
	s_nop 0
	global_load_lds_dwordx4 v[218:219], off
	s_setprio 1
	s_barrier
	s_waitcnt lgkmcnt(0)
	v_mfma_f32_16x16x32_bf16 v[116:119], v[192:195], v[144:147], v[116:119]
	v_mfma_f32_16x16x32_bf16 v[112:115], v[200:203], v[144:147], v[112:115]
	v_mfma_f32_16x16x32_bf16 v[100:103], v[192:195], v[152:155], v[100:103]
	v_mfma_f32_16x16x32_bf16 v[96:99], v[200:203], v[152:155], v[96:99]
	v_mfma_f32_16x16x32_bf16 v[84:87], v[192:195], v[160:163], v[84:87]
	v_mfma_f32_16x16x32_bf16 v[80:83], v[200:203], v[160:163], v[80:83]
	v_mfma_f32_16x16x32_bf16 v[68:71], v[192:195], v[168:171], v[68:71]
	v_mfma_f32_16x16x32_bf16 v[64:67], v[200:203], v[168:171], v[64:67]
	v_mfma_f32_16x16x32_bf16 v[116:119], v[196:199], v[148:151], v[116:119]
	v_mfma_f32_16x16x32_bf16 v[112:115], v[212:215], v[148:151], v[112:115]
	v_mfma_f32_16x16x32_bf16 v[100:103], v[196:199], v[156:159], v[100:103]
	v_mfma_f32_16x16x32_bf16 v[96:99], v[212:215], v[156:159], v[96:99]
	v_mfma_f32_16x16x32_bf16 v[84:87], v[196:199], v[164:167], v[84:87]
	v_mfma_f32_16x16x32_bf16 v[80:83], v[212:215], v[164:167], v[80:83]
	s_setprio 2
	s_barrier
	v_mfma_f32_16x16x32_bf16 v[68:71], v[196:199], v[172:175], v[68:71]
	v_mfma_f32_16x16x32_bf16 v[64:67], v[212:215], v[172:175], v[64:67]
	s_setprio 0
	s_mov_b32 m0, s82
	v_lshl_add_u64 v[220:221], s[80:81], 0, v[176:177]
	ds_read_b128 v[144:147], v208 offset:16384
	ds_read_b128 v[152:155], v208 offset:18432
	ds_read_b128 v[160:163], v208 offset:20480
	ds_read_b128 v[168:171], v208 offset:22528
	global_load_lds_dwordx4 v[220:221], off
	v_lshl_add_u64 v[224:225], s[80:81], 0, v[180:181]
	s_mov_b32 m0, s83
	s_nop 0
	global_load_lds_dwordx4 v[224:225], off
	s_setprio 1
	s_barrier
	s_waitcnt lgkmcnt(0)
	v_mfma_f32_16x16x32_bf16 v[60:63], v[128:131], v[144:147], v[60:63]
	ds_read_b128 v[148:151], v208 offset:17408
	v_mfma_f32_16x16x32_bf16 v[56:59], v[136:139], v[144:147], v[56:59]
	ds_read_b128 v[156:159], v208 offset:19456
	v_mfma_f32_16x16x32_bf16 v[44:47], v[128:131], v[152:155], v[44:47]
	ds_read_b128 v[164:167], v208 offset:21504
	v_mfma_f32_16x16x32_bf16 v[40:43], v[136:139], v[152:155], v[40:43]
	ds_read_b128 v[172:175], v208 offset:23552
	v_mfma_f32_16x16x32_bf16 v[28:31], v[128:131], v[160:163], v[28:31]
	v_mfma_f32_16x16x32_bf16 v[24:27], v[136:139], v[160:163], v[24:27]
	v_mfma_f32_16x16x32_bf16 v[12:15], v[128:131], v[168:171], v[12:15]
	v_mfma_f32_16x16x32_bf16 v[8:11], v[136:139], v[168:171], v[8:11]
	s_waitcnt lgkmcnt(3)
	v_mfma_f32_16x16x32_bf16 v[60:63], v[132:135], v[148:151], v[60:63]
	v_mfma_f32_16x16x32_bf16 v[56:59], v[140:143], v[148:151], v[56:59]
	s_waitcnt lgkmcnt(2)
	v_mfma_f32_16x16x32_bf16 v[44:47], v[132:135], v[156:159], v[44:47]
	v_mfma_f32_16x16x32_bf16 v[40:43], v[140:143], v[156:159], v[40:43]
	s_waitcnt lgkmcnt(1)
	v_mfma_f32_16x16x32_bf16 v[28:31], v[132:135], v[164:167], v[28:31]
	v_mfma_f32_16x16x32_bf16 v[24:27], v[140:143], v[164:167], v[24:27]
	s_waitcnt lgkmcnt(0)
	s_setprio 2
	s_barrier
; #define PG8_STAGE(bufoff, gbase, voff) do { _Pragma("unroll") for (int _i = 0; _i < 2; ++_i) \
;         __builtin_amdgcn_global_load_lds((const unsigned*)((const char*)(gbase) + (voff)[_i]), (LAS unsigned*)(lds + (bufoff) + ldsw + _i * 8192), 16, 0, 0); } while (0)
; #define PG8_LDA(dst, b, h) do { _Pragma("unroll") for (int m = 0; m < 4; ++m) _Pragma("unroll") for (int k = 0; k < 2; ++k) dst[m][k] = *(const LAS bf16x8*)(lds + PG8_SA(b, h) + aoff + m * 2048 + k * 1024); } while (0)
; #define PG8_LDB(dst, b, h) do { _Pragma("unroll") for (int n = 0; n < 2; ++n) _Pragma("unroll") for (int k = 0; k < 2; ++k) dst[n][k] = *(const LAS bf16x8*)(lds + PG8_SB(b, h) + boff + n * 2048 + k * 1024); } while (0)
; #define PG8_MMA(ai, bj, At, Bt) do { __builtin_amdgcn_s_setprio(1); _Pragma("unroll") for (int m = 0; m < 4; ++m) _Pragma("unroll") for (int n = 0; n < 2; ++n) _Pragma("unroll") for (int k = 0; k < 2; ++k) \
;         acc[ai][bj][m][n] = __builtin_amdgcn_mfma_f32_16x16x32_bf16(Bt[n][k], At[m][k], acc[ai][bj][m][n], 0, 0, 0); __builtin_amdgcn_s_setprio(0); } while (0)
; #define PG8_WAIT_V(n) asm volatile("s_waitcnt vmcnt(" #n ")" ::: "memory")
; #define PG8_WAIT_L(n) asm volatile("s_waitcnt lgkmcnt(" #n ")" ::: "memory")
; #define PG8_BAR __builtin_amdgcn_s_barrier()
; #define PG8_SCHED __builtin_amdgcn_sched_barrier(0)
; #define PG8_STAGE(bufoff, gbase, voff) do { _Pragma("unroll") for (int _i = 0; _i < 2; ++_i) \
;         __builtin_amdgcn_global_load_lds((const unsigned*)((const char*)(gbase) + (voff)[_i]), (LAS unsigned*)(lds + (bufoff) + ldsw + _i * 8192), 16, 0, 0); } while (0)
; #define PG8_BAR __builtin_amdgcn_s_barrier()
; template <class Epi0, class Epi1>
; DI void gemm_phase_dual(LAS unsigned char* lds, const Gemm g, const Gemm g1, const StaticOrder S, const Epi0 E0, const Epi1 E1) {
;     ...
;             PG8_WAIT_V(6); PG8_BAR; PG8_MMA(1, 1, At, B1); PG8_BAR;
;             PG8_LDB(B0, 1, 0); PG8_SCHED; PG8_LDA(At, 1, 0); PG8_STAGE(PG8_SA(0, 1), a2 + hstep, voffA);
;             PG8_WAIT_L(8); PG8_BAR; PG8_WAIT_L(0); PG8_MMA(0, 0, At, B0); PG8_BAR; PG8_SCHED;
;             PG8_LDB(B1, 1, 1); PG8_STAGE(PG8_SB(1, 0), b3, voffB);
;             PG8_BAR; PG8_WAIT_L(0); PG8_MMA(0, 1, At, B1); PG8_BAR;
;             PG8_LDA(At, 1, 1); PG8_STAGE(PG8_SA(1, 0), a3, voffA);
;             PG8_BAR; PG8_WAIT_L(0); PG8_MMA(1, 0, At, B0); PG8_BAR; PG8_SCHED;
	v_mfma_f32_16x16x32_bf16 v[12:15], v[132:135], v[172:175], v[12:15]
	v_mfma_f32_16x16x32_bf16 v[8:11], v[140:143], v[172:175], v[8:11]
	s_setprio 0
	s_add_u32 s14, s78, 0xb0000
	s_addc_u32 s15, s79, 0
	s_add_i32 s28, s92, s59
	v_lshl_add_u64 v[128:129], s[14:15], 0, v[178:179]
	s_mov_b32 m0, s28
	s_nop 0
	global_load_lds_dwordx4 v[128:129], off
	v_lshl_add_u64 v[128:129], s[14:15], 0, v[182:183]
	s_add_i32 m0, s28, 0x2000
	s_nop 0
	global_load_lds_dwordx4 v[128:129], off
	s_waitcnt vmcnt(6)
	s_setprio 1
	s_barrier
	v_mfma_f32_16x16x32_bf16 v[52:55], v[192:195], v[144:147], v[52:55]
	v_mfma_f32_16x16x32_bf16 v[48:51], v[200:203], v[144:147], v[48:51]
	v_mfma_f32_16x16x32_bf16 v[36:39], v[192:195], v[152:155], v[36:39]
	v_mfma_f32_16x16x32_bf16 v[32:35], v[200:203], v[152:155], v[32:35]
	v_mfma_f32_16x16x32_bf16 v[20:23], v[192:195], v[160:163], v[20:23]
	v_mfma_f32_16x16x32_bf16 v[16:19], v[200:203], v[160:163], v[16:19]
	v_mfma_f32_16x16x32_bf16 v[4:7], v[192:195], v[168:171], v[4:7]
	v_mfma_f32_16x16x32_bf16 v[0:3], v[200:203], v[168:171], v[0:3]
	v_mfma_f32_16x16x32_bf16 v[52:55], v[196:199], v[148:151], v[52:55]
	v_mfma_f32_16x16x32_bf16 v[48:51], v[212:215], v[148:151], v[48:51]
	v_mfma_f32_16x16x32_bf16 v[36:39], v[196:199], v[156:159], v[36:39]
	v_mfma_f32_16x16x32_bf16 v[32:35], v[212:215], v[156:159], v[32:35]
	v_mfma_f32_16x16x32_bf16 v[20:23], v[196:199], v[164:167], v[20:23]
	v_mfma_f32_16x16x32_bf16 v[16:19], v[212:215], v[164:167], v[16:19]
	s_setprio 2
	s_barrier
	v_mfma_f32_16x16x32_bf16 v[4:7], v[196:199], v[172:175], v[4:7]
	v_mfma_f32_16x16x32_bf16 v[0:3], v[212:215], v[172:175], v[0:3]
	s_setprio 0
	s_add_i32 s28, 0, 0x18000
	v_add_u32_e32 v140, s28, v205
	ds_read_b128 v[128:131], v140
	ds_read_b128 v[132:135], v140 offset:1024
	ds_read_b128 v[136:139], v140 offset:2048
	ds_read_b128 v[140:143], v140 offset:3072
	s_add_u32 s14, s80, 0xb0000
	s_addc_u32 s15, s81, 0
	s_mov_b32 m0, s84
	v_lshl_add_u64 v[192:193], s[14:15], 0, v[176:177]
	ds_read_b128 v[144:147], v208 offset:32768
	ds_read_b128 v[152:155], v208 offset:34816
	ds_read_b128 v[160:163], v208 offset:36864
	ds_read_b128 v[168:171], v208 offset:38912
	global_load_lds_dwordx4 v[192:193], off
	v_lshl_add_u64 v[192:193], s[14:15], 0, v[180:181]
	s_mov_b32 m0, s85
	s_nop 0
	global_load_lds_dwordx4 v[192:193], off
	s_waitcnt lgkmcnt(4)
	s_setprio 1
	s_barrier
	s_waitcnt lgkmcnt(0)
	v_mfma_f32_16x16x32_bf16 v[124:127], v[128:131], v[144:147], v[124:127]
	ds_read_b128 v[148:151], v208 offset:33792
	v_mfma_f32_16x16x32_bf16 v[120:123], v[136:139], v[144:147], v[120:123]
	ds_read_b128 v[156:159], v208 offset:35840
	v_mfma_f32_16x16x32_bf16 v[108:111], v[128:131], v[152:155], v[108:111]
	ds_read_b128 v[164:167], v208 offset:37888
	v_mfma_f32_16x16x32_bf16 v[104:107], v[136:139], v[152:155], v[104:107]
	ds_read_b128 v[172:175], v208 offset:39936
	v_mfma_f32_16x16x32_bf16 v[92:95], v[128:131], v[160:163], v[92:95]
	v_mfma_f32_16x16x32_bf16 v[88:91], v[136:139], v[160:163], v[88:91]
	v_mfma_f32_16x16x32_bf16 v[76:79], v[128:131], v[168:171], v[76:79]
	v_mfma_f32_16x16x32_bf16 v[72:75], v[136:139], v[168:171], v[72:75]
	s_waitcnt lgkmcnt(3)
	v_mfma_f32_16x16x32_bf16 v[124:127], v[132:135], v[148:151], v[124:127]
	v_mfma_f32_16x16x32_bf16 v[120:123], v[140:143], v[148:151], v[120:123]
	s_waitcnt lgkmcnt(2)
	v_mfma_f32_16x16x32_bf16 v[108:111], v[132:135], v[156:159], v[108:111]
	v_mfma_f32_16x16x32_bf16 v[104:107], v[140:143], v[156:159], v[104:107]
	s_waitcnt lgkmcnt(1)
	v_mfma_f32_16x16x32_bf16 v[92:95], v[132:135], v[164:167], v[92:95]
	v_mfma_f32_16x16x32_bf16 v[88:91], v[140:143], v[164:167], v[88:91]
	s_waitcnt lgkmcnt(0)
	s_setprio 2
	s_barrier
	v_mfma_f32_16x16x32_bf16 v[76:79], v[132:135], v[172:175], v[76:79]
	v_mfma_f32_16x16x32_bf16 v[72:75], v[140:143], v[172:175], v[72:75]
	s_setprio 0
	s_add_i32 s29, 0, 0x1c000
	s_add_i32 s14, s28, s59
	v_add_u32_e32 v211, s29, v205
	v_lshl_add_u64 v[216:217], v[216:217], 0, s[24:25]
	s_mov_b32 m0, s14
	ds_read_b128 v[192:195], v211
	ds_read_b128 v[196:199], v211 offset:1024
	ds_read_b128 v[200:203], v211 offset:2048
	ds_read_b128 v[212:215], v211 offset:3072
	global_load_lds_dwordx4 v[216:217], off
	v_lshl_add_u64 v[216:217], v[218:219], 0, s[24:25]
	s_add_i32 m0, s14, 0x2000
	s_nop 0
	global_load_lds_dwordx4 v[216:217], off
	s_setprio 1
	s_barrier
	s_waitcnt lgkmcnt(0)
	v_mfma_f32_16x16x32_bf16 v[116:119], v[192:195], v[144:147], v[116:119]
	v_mfma_f32_16x16x32_bf16 v[112:115], v[200:203], v[144:147], v[112:115]
	v_mfma_f32_16x16x32_bf16 v[100:103], v[192:195], v[152:155], v[100:103]
	v_mfma_f32_16x16x32_bf16 v[96:99], v[200:203], v[152:155], v[96:99]
	v_mfma_f32_16x16x32_bf16 v[84:87], v[192:195], v[160:163], v[84:87]
	v_mfma_f32_16x16x32_bf16 v[80:83], v[200:203], v[160:163], v[80:83]
	v_mfma_f32_16x16x32_bf16 v[68:71], v[192:195], v[168:171], v[68:71]
	v_mfma_f32_16x16x32_bf16 v[64:67], v[200:203], v[168:171], v[64:67]
	v_mfma_f32_16x16x32_bf16 v[116:119], v[196:199], v[148:151], v[116:119]
	v_mfma_f32_16x16x32_bf16 v[112:115], v[212:215], v[148:151], v[112:115]
	v_mfma_f32_16x16x32_bf16 v[100:103], v[196:199], v[156:159], v[100:103]
	v_mfma_f32_16x16x32_bf16 v[96:99], v[212:215], v[156:159], v[96:99]
	v_mfma_f32_16x16x32_bf16 v[84:87], v[196:199], v[164:167], v[84:87]
	v_mfma_f32_16x16x32_bf16 v[80:83], v[212:215], v[164:167], v[80:83]
	s_setprio 2
	s_barrier
; #define PG8_STAGE(bufoff, gbase, voff) do { _Pragma("unroll") for (int _i = 0; _i < 2; ++_i) \
;         __builtin_amdgcn_global_load_lds((const unsigned*)((const char*)(gbase) + (voff)[_i]), (LAS unsigned*)(lds + (bufoff) + ldsw + _i * 8192), 16, 0, 0); } while (0)
; #define PG8_LDA(dst, b, h) do { _Pragma("unroll") for (int m = 0; m < 4; ++m) _Pragma("unroll") for (int k = 0; k < 2; ++k) dst[m][k] = *(const LAS bf16x8*)(lds + PG8_SA(b, h) + aoff + m * 2048 + k * 1024); } while (0)
; #define PG8_MMA(ai, bj, At, Bt) do { __builtin_amdgcn_s_setprio(1); _Pragma("unroll") for (int m = 0; m < 4; ++m) _Pragma("unroll") for (int n = 0; n < 2; ++n) _Pragma("unroll") for (int k = 0; k < 2; ++k) \
;         acc[ai][bj][m][n] = __builtin_amdgcn_mfma_f32_16x16x32_bf16(Bt[n][k], At[m][k], acc[ai][bj][m][n], 0, 0, 0); __builtin_amdgcn_s_setprio(0); } while (0)
; #define PG8_WAIT_V(n) asm volatile("s_waitcnt vmcnt(" #n ")" ::: "memory")
; #define PG8_WAIT_L(n) asm volatile("s_waitcnt lgkmcnt(" #n ")" ::: "memory")
; #define PG8_BAR __builtin_amdgcn_s_barrier()
; #define PG8_SCHED __builtin_amdgcn_sched_barrier(0)
; #define PG8_STAGE(bufoff, gbase, voff) do { _Pragma("unroll") for (int _i = 0; _i < 2; ++_i) \
;         __builtin_amdgcn_global_load_lds((const unsigned*)((const char*)(gbase) + (voff)[_i]), (LAS unsigned*)(lds + (bufoff) + ldsw + _i * 8192), 16, 0, 0); } while (0)
; #define PG8_LDA(dst, b, h) do { _Pragma("unroll") for (int m = 0; m < 4; ++m) _Pragma("unroll") for (int k = 0; k < 2; ++k) dst[m][k] = *(const LAS bf16x8*)(lds + PG8_SA(b, h) + aoff + m * 2048 + k * 1024); } while (0)
; #define PG8_WAIT_V(n) asm volatile("s_waitcnt vmcnt(" #n ")" ::: "memory")
; #define PG8_WAIT_L(n) asm volatile("s_waitcnt lgkmcnt(" #n ")" ::: "memory")
; #define PG8_BAR __builtin_amdgcn_s_barrier()
; #define PG8_SCHED __builtin_amdgcn_sched_barrier(0)
; template <class Epi0, class Epi1>
; DI void gemm_phase_dual(LAS unsigned char* lds, const Gemm g, const Gemm g1, const StaticOrder S, const Epi0 E0, const Epi1 E1) {
;     ...
;             PG8_LDA(At, 1, 1); PG8_STAGE(PG8_SA(1, 0), a3, voffA);
;             PG8_BAR; PG8_WAIT_L(0); PG8_MMA(1, 0, At, B0); PG8_BAR; PG8_SCHED;
;             PG8_STAGE(PG8_SB(1, 1), b3 + hstep, voffB);
;             PG8_WAIT_V(6); PG8_BAR; PG8_MMA(1, 1, At, B1); PG8_BAR;
	v_mfma_f32_16x16x32_bf16 v[68:71], v[196:199], v[172:175], v[68:71]
	v_mfma_f32_16x16x32_bf16 v[64:67], v[212:215], v[172:175], v[64:67]
	s_setprio 0
	s_mov_b32 m0, s87
	v_lshl_add_u64 v[216:217], v[220:221], 0, s[24:25]
	ds_read_b128 v[144:147], v208 offset:49152
	ds_read_b128 v[152:155], v208 offset:51200
	ds_read_b128 v[160:163], v208 offset:53248
	ds_read_b128 v[168:171], v208 offset:55296
	global_load_lds_dwordx4 v[216:217], off
	v_lshl_add_u64 v[216:217], v[224:225], 0, s[24:25]
	s_mov_b32 m0, s88
	s_nop 0
	global_load_lds_dwordx4 v[216:217], off
	s_setprio 1
	s_barrier
	s_waitcnt lgkmcnt(0)
	v_mfma_f32_16x16x32_bf16 v[60:63], v[128:131], v[144:147], v[60:63]
	ds_read_b128 v[148:151], v208 offset:50176
	v_mfma_f32_16x16x32_bf16 v[56:59], v[136:139], v[144:147], v[56:59]
	ds_read_b128 v[156:159], v208 offset:52224
	v_mfma_f32_16x16x32_bf16 v[44:47], v[128:131], v[152:155], v[44:47]
	ds_read_b128 v[164:167], v208 offset:54272
	v_mfma_f32_16x16x32_bf16 v[40:43], v[136:139], v[152:155], v[40:43]
	ds_read_b128 v[172:175], v208 offset:56320
	v_mfma_f32_16x16x32_bf16 v[28:31], v[128:131], v[160:163], v[28:31]
	v_mfma_f32_16x16x32_bf16 v[24:27], v[136:139], v[160:163], v[24:27]
	v_mfma_f32_16x16x32_bf16 v[12:15], v[128:131], v[168:171], v[12:15]
	v_mfma_f32_16x16x32_bf16 v[8:11], v[136:139], v[168:171], v[8:11]
	s_waitcnt lgkmcnt(3)
	v_mfma_f32_16x16x32_bf16 v[60:63], v[132:135], v[148:151], v[60:63]
	v_mfma_f32_16x16x32_bf16 v[56:59], v[140:143], v[148:151], v[56:59]
	s_waitcnt lgkmcnt(2)
	v_mfma_f32_16x16x32_bf16 v[44:47], v[132:135], v[156:159], v[44:47]
	v_mfma_f32_16x16x32_bf16 v[40:43], v[140:143], v[156:159], v[40:43]
	s_waitcnt lgkmcnt(1)
	v_mfma_f32_16x16x32_bf16 v[28:31], v[132:135], v[164:167], v[28:31]
	v_mfma_f32_16x16x32_bf16 v[24:27], v[140:143], v[164:167], v[24:27]
	s_waitcnt lgkmcnt(0)
	s_setprio 2
	s_barrier
	v_mfma_f32_16x16x32_bf16 v[12:15], v[132:135], v[172:175], v[12:15]
	v_mfma_f32_16x16x32_bf16 v[8:11], v[140:143], v[172:175], v[8:11]
	s_setprio 0
	s_add_u32 s14, s78, 0xb0080
	s_addc_u32 s15, s79, 0
	s_add_i32 s28, s29, s59
	v_lshl_add_u64 v[128:129], s[14:15], 0, v[178:179]
	s_mov_b32 m0, s28
	s_nop 0
	global_load_lds_dwordx4 v[128:129], off
	v_lshl_add_u64 v[128:129], s[14:15], 0, v[182:183]
	s_add_i32 m0, s28, 0x2000
	s_nop 0
	global_load_lds_dwordx4 v[128:129], off
	s_waitcnt vmcnt(6)
	s_setprio 1
	s_barrier
	v_mfma_f32_16x16x32_bf16 v[52:55], v[192:195], v[144:147], v[52:55]
	v_mfma_f32_16x16x32_bf16 v[48:51], v[200:203], v[144:147], v[48:51]
	v_mfma_f32_16x16x32_bf16 v[36:39], v[192:195], v[152:155], v[36:39]
	v_mfma_f32_16x16x32_bf16 v[32:35], v[200:203], v[152:155], v[32:35]
	v_mfma_f32_16x16x32_bf16 v[20:23], v[192:195], v[160:163], v[20:23]
	v_mfma_f32_16x16x32_bf16 v[16:19], v[200:203], v[160:163], v[16:19]
	v_mfma_f32_16x16x32_bf16 v[4:7], v[192:195], v[168:171], v[4:7]
	v_mfma_f32_16x16x32_bf16 v[0:3], v[200:203], v[168:171], v[0:3]
	v_mfma_f32_16x16x32_bf16 v[52:55], v[196:199], v[148:151], v[52:55]
	v_mfma_f32_16x16x32_bf16 v[48:51], v[212:215], v[148:151], v[48:51]
	v_mfma_f32_16x16x32_bf16 v[36:39], v[196:199], v[156:159], v[36:39]
	v_mfma_f32_16x16x32_bf16 v[32:35], v[212:215], v[156:159], v[32:35]
	v_mfma_f32_16x16x32_bf16 v[20:23], v[196:199], v[164:167], v[20:23]
	v_mfma_f32_16x16x32_bf16 v[16:19], v[212:215], v[164:167], v[16:19]
	s_setprio 2
	s_barrier
	v_mfma_f32_16x16x32_bf16 v[4:7], v[196:199], v[172:175], v[4:7]
	v_mfma_f32_16x16x32_bf16 v[0:3], v[212:215], v[172:175], v[0:3]
	s_setprio 0
	s_add_i32 s97, s97, 2
	s_add_u32 s6, s6, 0x100
	s_addc_u32 s7, s7, 0
	s_cmp_gt_u32 s97, 41
	s_mov_b64 s[28:29], s[76:77]
	s_cbranch_scc0 .LBB0_186
; DI unsigned pk_bf16(float lo, float hi) { f32x2 v = {lo, hi}; return __builtin_bit_cast(unsigned, __builtin_convertvector(v, bf16v2)); }
; DI f32x4 bf_lo4(u32x4 w) { f32x4 r; r[0] = bf_lo(w.x); r[1] = bf_hi(w.x); r[2] = bf_lo(w.y); r[3] = bf_hi(w.y); return r; }
; DI f32x4 bf_hi4(u32x4 w) { f32x4 r; r[0] = bf_lo(w.z); r[1] = bf_hi(w.z); r[2] = bf_lo(w.w); r[3] = bf_hi(w.w); return r; }
;     DI void operator()(AccRef acc, const Unit& u, int wr, int wc, int fr, int fq) const {
;     ...
;         const int row0 = u.pm * 256 + wr * 64 + fr, col0 = u.pn * 256 + wc * 32 + 8 * fq;
; #pragma unroll
;         for (int ai = 0; ai < 2; ++ai) {
;             f32x4 bv[4][2][2];
; #pragma unroll
;             for (int m = 0; m < 4; ++m)
; #pragma unroll
;                 for (int bj = 0; bj < 2; ++bj) {
;                     const size_t o = (size_t)(row0 + ai * 128 + m * 16) * DM + col0 + bj * 128;
;                     if (BASEF32) { bv[m][bj][0] = *(const f32x4*)(basef + o); bv[m][bj][1] = *(const f32x4*)(basef + o + 4); }
;                     else { const u32x4 h = *(const u32x4*)(xnb + o); bv[m][bj][0] = bf_lo4(h); bv[m][bj][1] = bf_hi4(h); }
;                 }
; #pragma unroll
;             for (int m = 0; m < 4; ++m) {
;                 const int row = row0 + ai * 128 + m * 16;
;                 float q = 0.f;
; #pragma unroll
;                 for (int bj = 0; bj < 2; ++bj) {
;                     const size_t o = (size_t)row * DM + col0 + bj * 128;
;                     const f32x4 r0 = bv[m][bj][0] + scale * acc[ai][bj][m][0], r1 = bv[m][bj][1] + scale * acc[ai][bj][m][1];
;                     u32x4 w; w.x = pk_bf16(r0[0], r0[1]); w.y = pk_bf16(r0[2], r0[3]); w.z = pk_bf16(r1[0], r1[1]); w.w = pk_bf16(r1[2], r1[3]);
;                     *(u32x4*)(xnb + o) = w;
;                     if (STATS) q += r0[0] * r0[0] + r0[1] * r0[1] + r0[2] * r0[2] + r0[3] * r0[3] + r1[0] * r1[0] + r1[1] * r1[1] + r1[2] * r1[2] + r1[3] * r1[3];
;                 }
;                 if (STATS) { q += __shfl_xor(q, 16); q += __shfl_xor(q, 32); if (fq == 0) atomicAdd(ss + row, q); }
	v_lshl_add_u32 v194, s96, 8, v204
	v_lshl_or_b32 v192, s95, 8, v206
	v_ashrrev_i32_e32 v193, 31, v192
	v_ashrrev_i32_e32 v195, 31, v194
	v_lshl_add_u64 v[196:197], v[192:193], 2, s[52:53]
	v_lshlrev_b64 v[128:129], 12, v[194:195]
	v_lshl_add_u64 v[128:129], v[196:197], 0, v[128:129]
	global_load_dwordx4 v[214:217], v[128:129], off
	global_load_dwordx4 v[218:221], v[128:129], off offset:16
	global_load_dwordx4 v[224:227], v[128:129], off offset:512
	global_load_dwordx4 v[228:231], v[128:129], off offset:528
	v_or_b32_e32 v202, 16, v194
	v_or_b32_e32 v200, 32, v194
	v_or_b32_e32 v198, 48, v194
	v_ashrrev_i32_e32 v203, 31, v202
	v_ashrrev_i32_e32 v201, 31, v200
	v_ashrrev_i32_e32 v199, 31, v198
	v_lshlrev_b64 v[128:129], 12, v[202:203]
	v_lshlrev_b64 v[130:131], 12, v[200:201]
	v_lshlrev_b64 v[132:133], 12, v[198:199]
	v_lshl_add_u64 v[128:129], v[196:197], 0, v[128:129]
	v_lshl_add_u64 v[130:131], v[196:197], 0, v[130:131]
	v_lshl_add_u64 v[132:133], v[196:197], 0, v[132:133]
	global_load_dwordx4 v[168:171], v[128:129], off offset:16
	global_load_dwordx4 v[172:175], v[128:129], off
	global_load_dwordx4 v[160:163], v[128:129], off offset:528
	global_load_dwordx4 v[164:167], v[128:129], off offset:512
	global_load_dwordx4 v[152:155], v[130:131], off offset:16
	global_load_dwordx4 v[156:159], v[130:131], off
	global_load_dwordx4 v[144:147], v[130:131], off offset:528
	global_load_dwordx4 v[148:151], v[130:131], off offset:512
	global_load_dwordx4 v[136:139], v[132:133], off offset:16
	global_load_dwordx4 v[140:143], v[132:133], off
	s_nop 0
	global_load_dwordx4 v[128:131], v[132:133], off offset:528
	s_nop 0
	global_load_dwordx4 v[132:135], v[132:133], off offset:512
	v_and_b32_e32 v212, 64, v210
	v_xor_b32_e32 v211, 16, v210
	v_add_u32_e32 v212, 64, v212
	v_xor_b32_e32 v213, 32, v210
	v_cmp_lt_i32_e32 vcc, v211, v212
	v_lshlrev_b64 v[232:233], 11, v[194:195]
	s_waitcnt vmcnt(0)
	v_pk_fma_f32 v[124:125], v[124:125], 0.5, v[214:215] op_sel_hi:[1,0,1]
	v_cndmask_b32_e32 v211, v210, v211, vcc
	v_cmp_lt_i32_e32 vcc, v213, v212
	v_pk_fma_f32 v[116:117], v[116:117], 0.5, v[224:225] op_sel_hi:[1,0,1]
	v_lshlrev_b32_e32 v212, 2, v211
	v_cndmask_b32_e32 v213, v210, v213, vcc
	v_lshlrev_b32_e32 v211, 2, v213
	v_pk_fma_f32 v[126:127], v[126:127], 0.5, v[216:217] op_sel_hi:[1,0,1]
	v_pk_fma_f32 v[216:217], v[112:113], 0.5, v[228:229] op_sel_hi:[1,0,1]
	v_cvt_pk_bf16_f32 v112, v124, v125
	v_mul_f32_e32 v125, v125, v125
	v_mul_f32_e32 v213, v117, v117
	v_pk_fma_f32 v[118:119], v[118:119], 0.5, v[226:227] op_sel_hi:[1,0,1]
	v_fmac_f32_e32 v125, v124, v124
	v_fmac_f32_e32 v213, v116, v116
	v_fmac_f32_e32 v125, v126, v126
	v_fmac_f32_e32 v213, v118, v118
	v_pk_fma_f32 v[120:121], v[120:121], 0.5, v[218:219] op_sel_hi:[1,0,1]
	v_fmac_f32_e32 v125, v127, v127
	v_fmac_f32_e32 v213, v119, v119
	v_fmac_f32_e32 v125, v120, v120
	v_fmac_f32_e32 v213, v216, v216
	v_pk_fma_f32 v[122:123], v[122:123], 0.5, v[220:221] op_sel_hi:[1,0,1]
	v_pk_fma_f32 v[214:215], v[114:115], 0.5, v[230:231] op_sel_hi:[1,0,1]
	v_fmac_f32_e32 v125, v121, v121
	v_fmac_f32_e32 v213, v217, v217
	v_fmac_f32_e32 v125, v122, v122
	v_fmac_f32_e32 v213, v214, v214
	v_fmac_f32_e32 v125, v123, v123
	v_fmac_f32_e32 v213, v215, v215
	v_cvt_pk_bf16_f32 v115, v122, v123
	v_add_f32_e32 v122, v125, v213
	ds_bpermute_b32 v123, v212, v122
	v_cvt_pk_bf16_f32 v114, v120, v121
	v_lshl_add_u64 v[120:121], s[56:57], 0, v[232:233]
	v_cvt_pk_bf16_f32 v113, v126, v127
	v_lshl_add_u64 v[120:121], v[192:193], 1, v[120:121]
	global_store_dwordx4 v[120:121], v[112:115], off
	s_waitcnt lgkmcnt(0)
	s_nop 0
	v_add_f32_e32 v112, v122, v123
	ds_bpermute_b32 v113, v211, v112
	v_cvt_pk_bf16_f32 v114, v116, v117
	v_cvt_pk_bf16_f32 v115, v118, v119
	v_cvt_pk_bf16_f32 v116, v216, v217
	v_cvt_pk_bf16_f32 v117, v214, v215
	global_store_dwordx4 v[120:121], v[114:117], off offset:256
	s_and_saveexec_b64 s[6:7], s[0:1]
	s_cbranch_execz .LBB0_189
	v_lshl_add_u64 v[114:115], v[194:195], 2, s[60:61]
	s_waitcnt lgkmcnt(0)
	v_add_f32_e32 v112, v112, v113
	global_atomic_add_f32 v[114:115], v112, off

; #define PG8_STAGE(bufoff, gbase, voff) do { _Pragma("unroll") for (int _i = 0; _i < 2; ++_i) \
;         __builtin_amdgcn_global_load_lds((const unsigned*)((const char*)(gbase) + (voff)[_i]), (LAS unsigned*)(lds + (bufoff) + ldsw + _i * 8192), 16, 0, 0); } while (0)
; #define PG8_LDA(dst, b, h) do { _Pragma("unroll") for (int m = 0; m < 4; ++m) _Pragma("unroll") for (int k = 0; k < 2; ++k) dst[m][k] = *(const LAS bf16x8*)(lds + PG8_SA(b, h) + aoff + m * 2048 + k * 1024); } while (0)
; #define PG8_LDB(dst, b, h) do { _Pragma("unroll") for (int n = 0; n < 2; ++n) _Pragma("unroll") for (int k = 0; k < 2; ++k) dst[n][k] = *(const LAS bf16x8*)(lds + PG8_SB(b, h) + boff + n * 2048 + k * 1024); } while (0)
; #define PG8_MMA(ai, bj, At, Bt) do { __builtin_amdgcn_s_setprio(1); _Pragma("unroll") for (int m = 0; m < 4; ++m) _Pragma("unroll") for (int n = 0; n < 2; ++n) _Pragma("unroll") for (int k = 0; k < 2; ++k) \
;         acc[ai][bj][m][n] = __builtin_amdgcn_mfma_f32_16x16x32_bf16(Bt[n][k], At[m][k], acc[ai][bj][m][n], 0, 0, 0); __builtin_amdgcn_s_setprio(0); } while (0)
; #define PG8_WAIT_V(n) asm volatile("s_waitcnt vmcnt(" #n ")" ::: "memory")
; #define PG8_WAIT_L(n) asm volatile("s_waitcnt lgkmcnt(" #n ")" ::: "memory")
; #define PG8_BAR __builtin_amdgcn_s_barrier()
; #define PG8_SCHED __builtin_amdgcn_sched_barrier(0)
; #define PG8_STAGE(bufoff, gbase, voff) do { _Pragma("unroll") for (int _i = 0; _i < 2; ++_i) \
;         __builtin_amdgcn_global_load_lds((const unsigned*)((const char*)(gbase) + (voff)[_i]), (LAS unsigned*)(lds + (bufoff) + ldsw + _i * 8192), 16, 0, 0); } while (0)
; template <class Epi0, class Epi1>
; DI void gemm_phase_dual(LAS unsigned char* lds, const Gemm g, const Gemm g1, const StaticOrder S, const Epi0 E0, const Epi1 E1) {
;     ...
;             PG8_LDB(B0, 0, 0); PG8_SCHED; PG8_LDA(At, 0, 0); PG8_STAGE(PG8_SA(1, 1), a1 + hstep, voffA);
;             PG8_WAIT_L(8); PG8_BAR; PG8_WAIT_L(0); PG8_MMA(0, 0, At, B0); PG8_BAR; PG8_SCHED;
;             PG8_LDB(B1, 0, 1); PG8_STAGE(PG8_SB(0, 0), b2, voffB);
;             PG8_BAR; PG8_WAIT_L(0); PG8_MMA(0, 1, At, B1); PG8_BAR;
;             PG8_LDA(At, 0, 1); PG8_STAGE(PG8_SA(0, 0), a2, voffA);
;             PG8_BAR; PG8_WAIT_L(0); PG8_MMA(1, 0, At, B0); PG8_BAR; PG8_SCHED;
;             PG8_STAGE(PG8_SB(0, 1), b2 + hstep, voffB);
;             PG8_WAIT_V(6); PG8_BAR; PG8_MMA(1, 1, At, B1); PG8_BAR;
.LBB0_274:
	ds_read_b128 v[100:103], v227
	ds_read_b128 v[134:137], v227 offset:1024
	ds_read_b128 v[138:141], v227 offset:2048
	ds_read_b128 v[142:145], v227 offset:3072
	s_add_u32 s14, s8, 0xfffc0080
	s_addc_u32 s15, s9, -1
	s_cmp_eq_u32 s95, 12
	s_cselect_b32 s77, s1, s15
	s_cselect_b32 s76, s6, s14
	s_cselect_b32 s53, s7, s94
	s_cselect_b32 s52, s21, s23
	v_lshl_add_u64 v[104:105], s[8:9], 0, v[212:213]
	s_add_i32 m0, s78, 0xc000
	ds_read_b128 v[146:149], v228
	ds_read_b128 v[154:157], v228 offset:2048
	ds_read_b128 v[162:165], v228 offset:4096
	ds_read_b128 v[170:173], v228 offset:6144
	global_load_lds_dwordx4 v[104:105], off
	v_lshl_add_u64 v[104:105], s[8:9], 0, v[214:215]
	s_add_i32 m0, s78, 0xe000
	s_nop 0
	global_load_lds_dwordx4 v[104:105], off
	s_waitcnt lgkmcnt(4)
	s_setprio 1
	s_barrier
	s_waitcnt lgkmcnt(0)
	v_mfma_f32_16x16x32_bf16 v[130:133], v[100:103], v[146:149], v[130:133]
	ds_read_b128 v[150:153], v228 offset:1024
	v_mfma_f32_16x16x32_bf16 v[126:129], v[138:141], v[146:149], v[126:129]
	ds_read_b128 v[158:161], v228 offset:3072
	v_mfma_f32_16x16x32_bf16 v[114:117], v[100:103], v[154:157], v[114:117]
	ds_read_b128 v[166:169], v228 offset:5120
	v_mfma_f32_16x16x32_bf16 v[110:113], v[138:141], v[154:157], v[110:113]
	ds_read_b128 v[174:177], v228 offset:7168
	v_mfma_f32_16x16x32_bf16 v[92:95], v[100:103], v[162:165], v[92:95]
	v_mfma_f32_16x16x32_bf16 v[88:91], v[138:141], v[162:165], v[88:91]
	v_mfma_f32_16x16x32_bf16 v[76:79], v[100:103], v[170:173], v[76:79]
	v_mfma_f32_16x16x32_bf16 v[72:75], v[138:141], v[170:173], v[72:75]
	s_waitcnt lgkmcnt(3)
	v_mfma_f32_16x16x32_bf16 v[130:133], v[134:137], v[150:153], v[130:133]
	v_mfma_f32_16x16x32_bf16 v[126:129], v[142:145], v[150:153], v[126:129]
	s_waitcnt lgkmcnt(2)
	v_mfma_f32_16x16x32_bf16 v[114:117], v[134:137], v[158:161], v[114:117]
	v_mfma_f32_16x16x32_bf16 v[110:113], v[142:145], v[158:161], v[110:113]
	s_waitcnt lgkmcnt(1)
	v_mfma_f32_16x16x32_bf16 v[92:95], v[134:137], v[166:169], v[92:95]
	v_mfma_f32_16x16x32_bf16 v[88:91], v[142:145], v[166:169], v[88:91]
	s_waitcnt lgkmcnt(0)
	s_setprio 2
	s_barrier
	v_mfma_f32_16x16x32_bf16 v[76:79], v[134:137], v[174:177], v[76:79]
	v_mfma_f32_16x16x32_bf16 v[72:75], v[142:145], v[174:177], v[72:75]
	s_setprio 0
	s_add_i32 s14, s87, s59
	v_lshl_add_u64 v[194:195], s[52:53], 0, v[200:201]
	s_mov_b32 m0, s14
	ds_read_b128 v[178:181], v229
	ds_read_b128 v[182:185], v229 offset:1024
	ds_read_b128 v[186:189], v229 offset:2048
	ds_read_b128 v[190:193], v229 offset:3072
	global_load_lds_dwordx4 v[194:195], off
	v_lshl_add_u64 v[196:197], s[52:53], 0, v[204:205]
	s_add_i32 m0, s14, 0x2000
	s_nop 0
	global_load_lds_dwordx4 v[196:197], off
	s_setprio 1
	s_barrier
	s_waitcnt lgkmcnt(0)
	v_mfma_f32_16x16x32_bf16 v[122:125], v[178:181], v[146:149], v[122:125]
	v_mfma_f32_16x16x32_bf16 v[118:121], v[186:189], v[146:149], v[118:121]
	v_mfma_f32_16x16x32_bf16 v[104:107], v[178:181], v[154:157], v[106:109]
	v_mfma_f32_16x16x32_bf16 v[96:99], v[186:189], v[154:157], v[96:99]
	v_mfma_f32_16x16x32_bf16 v[84:87], v[178:181], v[162:165], v[84:87]
	v_mfma_f32_16x16x32_bf16 v[80:83], v[186:189], v[162:165], v[80:83]
	v_mfma_f32_16x16x32_bf16 v[68:71], v[178:181], v[170:173], v[68:71]
	v_mfma_f32_16x16x32_bf16 v[64:67], v[186:189], v[170:173], v[64:67]
	v_mfma_f32_16x16x32_bf16 v[122:125], v[182:185], v[150:153], v[122:125]
	v_mfma_f32_16x16x32_bf16 v[118:121], v[190:193], v[150:153], v[118:121]
	v_mfma_f32_16x16x32_bf16 v[104:107], v[182:185], v[158:161], v[104:107]
	v_mfma_f32_16x16x32_bf16 v[96:99], v[190:193], v[158:161], v[96:99]
	v_mfma_f32_16x16x32_bf16 v[84:87], v[182:185], v[166:169], v[84:87]
	v_mfma_f32_16x16x32_bf16 v[80:83], v[190:193], v[166:169], v[80:83]
	s_setprio 2
	s_barrier
	v_mfma_f32_16x16x32_bf16 v[68:71], v[182:185], v[174:177], v[68:71]
	v_mfma_f32_16x16x32_bf16 v[64:67], v[190:193], v[174:177], v[64:67]
	s_setprio 0
	s_mov_b32 m0, s78
	v_lshl_add_u64 v[220:221], s[76:77], 0, v[198:199]
	ds_read_b128 v[146:149], v228 offset:16384
	ds_read_b128 v[154:157], v228 offset:18432
	ds_read_b128 v[162:165], v228 offset:20480
	ds_read_b128 v[170:173], v228 offset:22528
	global_load_lds_dwordx4 v[220:221], off
	v_lshl_add_u64 v[232:233], s[76:77], 0, v[202:203]
	s_mov_b32 m0, s79
	s_nop 0
	global_load_lds_dwordx4 v[232:233], off
	s_setprio 1
	s_barrier
	s_waitcnt lgkmcnt(0)
	v_mfma_f32_16x16x32_bf16 v[60:63], v[100:103], v[146:149], v[60:63]
	ds_read_b128 v[150:153], v228 offset:17408
	v_mfma_f32_16x16x32_bf16 v[56:59], v[138:141], v[146:149], v[56:59]
	ds_read_b128 v[158:161], v228 offset:19456
	v_mfma_f32_16x16x32_bf16 v[44:47], v[100:103], v[154:157], v[44:47]
	ds_read_b128 v[166:169], v228 offset:21504
	v_mfma_f32_16x16x32_bf16 v[40:43], v[138:141], v[154:157], v[40:43]
	ds_read_b128 v[174:177], v228 offset:23552
	v_mfma_f32_16x16x32_bf16 v[28:31], v[100:103], v[162:165], v[28:31]
	v_mfma_f32_16x16x32_bf16 v[24:27], v[138:141], v[162:165], v[24:27]
	v_mfma_f32_16x16x32_bf16 v[12:15], v[100:103], v[170:173], v[12:15]
	v_mfma_f32_16x16x32_bf16 v[8:11], v[138:141], v[170:173], v[8:11]
	s_waitcnt lgkmcnt(3)
	v_mfma_f32_16x16x32_bf16 v[60:63], v[134:137], v[150:153], v[60:63]
	v_mfma_f32_16x16x32_bf16 v[56:59], v[142:145], v[150:153], v[56:59]
	s_waitcnt lgkmcnt(2)
	v_mfma_f32_16x16x32_bf16 v[44:47], v[134:137], v[158:161], v[44:47]
	v_mfma_f32_16x16x32_bf16 v[40:43], v[142:145], v[158:161], v[40:43]
	s_waitcnt lgkmcnt(1)
	v_mfma_f32_16x16x32_bf16 v[28:31], v[134:137], v[166:169], v[28:31]
	v_mfma_f32_16x16x32_bf16 v[24:27], v[142:145], v[166:169], v[24:27]
	s_waitcnt lgkmcnt(0)
	s_setprio 2
	s_barrier
; #define PG8_STAGE(bufoff, gbase, voff) do { _Pragma("unroll") for (int _i = 0; _i < 2; ++_i) \
;         __builtin_amdgcn_global_load_lds((const unsigned*)((const char*)(gbase) + (voff)[_i]), (LAS unsigned*)(lds + (bufoff) + ldsw + _i * 8192), 16, 0, 0); } while (0)
; #define PG8_LDA(dst, b, h) do { _Pragma("unroll") for (int m = 0; m < 4; ++m) _Pragma("unroll") for (int k = 0; k < 2; ++k) dst[m][k] = *(const LAS bf16x8*)(lds + PG8_SA(b, h) + aoff + m * 2048 + k * 1024); } while (0)
; #define PG8_LDB(dst, b, h) do { _Pragma("unroll") for (int n = 0; n < 2; ++n) _Pragma("unroll") for (int k = 0; k < 2; ++k) dst[n][k] = *(const LAS bf16x8*)(lds + PG8_SB(b, h) + boff + n * 2048 + k * 1024); } while (0)
; #define PG8_MMA(ai, bj, At, Bt) do { __builtin_amdgcn_s_setprio(1); _Pragma("unroll") for (int m = 0; m < 4; ++m) _Pragma("unroll") for (int n = 0; n < 2; ++n) _Pragma("unroll") for (int k = 0; k < 2; ++k) \
;         acc[ai][bj][m][n] = __builtin_amdgcn_mfma_f32_16x16x32_bf16(Bt[n][k], At[m][k], acc[ai][bj][m][n], 0, 0, 0); __builtin_amdgcn_s_setprio(0); } while (0)
; #define PG8_WAIT_V(n) asm volatile("s_waitcnt vmcnt(" #n ")" ::: "memory")
; #define PG8_WAIT_L(n) asm volatile("s_waitcnt lgkmcnt(" #n ")" ::: "memory")
; #define PG8_BAR __builtin_amdgcn_s_barrier()
; #define PG8_SCHED __builtin_amdgcn_sched_barrier(0)
; #define PG8_STAGE(bufoff, gbase, voff) do { _Pragma("unroll") for (int _i = 0; _i < 2; ++_i) \
;         __builtin_amdgcn_global_load_lds((const unsigned*)((const char*)(gbase) + (voff)[_i]), (LAS unsigned*)(lds + (bufoff) + ldsw + _i * 8192), 16, 0, 0); } while (0)
; #define PG8_BAR __builtin_amdgcn_s_barrier()
; template <class Epi0, class Epi1>
; DI void gemm_phase_dual(LAS unsigned char* lds, const Gemm g, const Gemm g1, const StaticOrder S, const Epi0 E0, const Epi1 E1) {
;     ...
;             PG8_WAIT_V(6); PG8_BAR; PG8_MMA(1, 1, At, B1); PG8_BAR;
;             PG8_LDB(B0, 1, 0); PG8_SCHED; PG8_LDA(At, 1, 0); PG8_STAGE(PG8_SA(0, 1), a2 + hstep, voffA);
;             PG8_WAIT_L(8); PG8_BAR; PG8_WAIT_L(0); PG8_MMA(0, 0, At, B0); PG8_BAR; PG8_SCHED;
;             PG8_LDB(B1, 1, 1); PG8_STAGE(PG8_SB(1, 0), b3, voffB);
;             PG8_BAR; PG8_WAIT_L(0); PG8_MMA(0, 1, At, B1); PG8_BAR;
;             PG8_LDA(At, 1, 1); PG8_STAGE(PG8_SA(1, 0), a3, voffA);
;             PG8_BAR; PG8_WAIT_L(0); PG8_MMA(1, 0, At, B0); PG8_BAR; PG8_SCHED;
	v_mfma_f32_16x16x32_bf16 v[12:15], v[134:137], v[174:177], v[12:15]
	v_mfma_f32_16x16x32_bf16 v[8:11], v[142:145], v[174:177], v[8:11]
	s_setprio 0
	s_add_u32 s14, s52, 0x40000
	s_addc_u32 s15, s53, 0
	s_add_i32 s35, s90, s59
	v_lshl_add_u64 v[100:101], s[14:15], 0, v[200:201]
	s_mov_b32 m0, s35
	s_nop 0
	global_load_lds_dwordx4 v[100:101], off
	v_lshl_add_u64 v[100:101], s[14:15], 0, v[204:205]
	s_add_i32 m0, s35, 0x2000
	s_nop 0
	global_load_lds_dwordx4 v[100:101], off
	s_waitcnt vmcnt(6)
	s_setprio 1
	s_barrier
	v_mfma_f32_16x16x32_bf16 v[52:55], v[178:181], v[146:149], v[52:55]
	v_mfma_f32_16x16x32_bf16 v[48:51], v[186:189], v[146:149], v[48:51]
	v_mfma_f32_16x16x32_bf16 v[36:39], v[178:181], v[154:157], v[36:39]
	v_mfma_f32_16x16x32_bf16 v[32:35], v[186:189], v[154:157], v[32:35]
	v_mfma_f32_16x16x32_bf16 v[20:23], v[178:181], v[162:165], v[20:23]
	v_mfma_f32_16x16x32_bf16 v[16:19], v[186:189], v[162:165], v[16:19]
	v_mfma_f32_16x16x32_bf16 v[4:7], v[178:181], v[170:173], v[4:7]
	v_mfma_f32_16x16x32_bf16 v[0:3], v[186:189], v[170:173], v[0:3]
	v_mfma_f32_16x16x32_bf16 v[52:55], v[182:185], v[150:153], v[52:55]
	v_mfma_f32_16x16x32_bf16 v[48:51], v[190:193], v[150:153], v[48:51]
	v_mfma_f32_16x16x32_bf16 v[36:39], v[182:185], v[158:161], v[36:39]
	v_mfma_f32_16x16x32_bf16 v[32:35], v[190:193], v[158:161], v[32:35]
	v_mfma_f32_16x16x32_bf16 v[20:23], v[182:185], v[166:169], v[20:23]
	v_mfma_f32_16x16x32_bf16 v[16:19], v[190:193], v[166:169], v[16:19]
	s_setprio 2
	s_barrier
	v_mfma_f32_16x16x32_bf16 v[4:7], v[182:185], v[174:177], v[4:7]
	v_mfma_f32_16x16x32_bf16 v[0:3], v[190:193], v[174:177], v[0:3]
	s_setprio 0
	s_add_i32 s35, 0, 0x18000
	v_add_u32_e32 v108, s35, v225
	ds_read_b128 v[100:103], v108
	ds_read_b128 v[134:137], v108 offset:1024
	ds_read_b128 v[138:141], v108 offset:2048
	ds_read_b128 v[142:145], v108 offset:3072
	s_add_u32 s14, s76, 0x40000
	s_addc_u32 s15, s77, 0
	s_mov_b32 m0, s80
	v_lshl_add_u64 v[108:109], s[14:15], 0, v[198:199]
	ds_read_b128 v[146:149], v228 offset:32768
	ds_read_b128 v[154:157], v228 offset:34816
	ds_read_b128 v[162:165], v228 offset:36864
	ds_read_b128 v[170:173], v228 offset:38912
	global_load_lds_dwordx4 v[108:109], off
	v_lshl_add_u64 v[108:109], s[14:15], 0, v[202:203]
	s_mov_b32 m0, s81
	s_nop 0
	global_load_lds_dwordx4 v[108:109], off
	s_waitcnt lgkmcnt(4)
	s_setprio 1
	s_barrier
	s_waitcnt lgkmcnt(0)
	v_mfma_f32_16x16x32_bf16 v[130:133], v[100:103], v[146:149], v[130:133]
	ds_read_b128 v[150:153], v228 offset:33792
	v_mfma_f32_16x16x32_bf16 v[126:129], v[138:141], v[146:149], v[126:129]
	ds_read_b128 v[158:161], v228 offset:35840
	v_mfma_f32_16x16x32_bf16 v[114:117], v[100:103], v[154:157], v[114:117]
	ds_read_b128 v[166:169], v228 offset:37888
	v_mfma_f32_16x16x32_bf16 v[108:111], v[138:141], v[154:157], v[110:113]
	ds_read_b128 v[174:177], v228 offset:39936
	v_mfma_f32_16x16x32_bf16 v[92:95], v[100:103], v[162:165], v[92:95]
	v_mfma_f32_16x16x32_bf16 v[88:91], v[138:141], v[162:165], v[88:91]
	v_mfma_f32_16x16x32_bf16 v[76:79], v[100:103], v[170:173], v[76:79]
	v_mfma_f32_16x16x32_bf16 v[72:75], v[138:141], v[170:173], v[72:75]
	s_waitcnt lgkmcnt(3)
	v_mfma_f32_16x16x32_bf16 v[130:133], v[134:137], v[150:153], v[130:133]
	v_mfma_f32_16x16x32_bf16 v[126:129], v[142:145], v[150:153], v[126:129]
	s_waitcnt lgkmcnt(2)
	v_mfma_f32_16x16x32_bf16 v[114:117], v[134:137], v[158:161], v[114:117]
	v_mfma_f32_16x16x32_bf16 v[110:113], v[142:145], v[158:161], v[108:111]
	s_waitcnt lgkmcnt(1)
	v_mfma_f32_16x16x32_bf16 v[92:95], v[134:137], v[166:169], v[92:95]
	v_mfma_f32_16x16x32_bf16 v[88:91], v[142:145], v[166:169], v[88:91]
	s_waitcnt lgkmcnt(0)
	s_setprio 2
	s_barrier
	v_mfma_f32_16x16x32_bf16 v[76:79], v[134:137], v[174:177], v[76:79]
	v_mfma_f32_16x16x32_bf16 v[72:75], v[142:145], v[174:177], v[72:75]
	s_setprio 0
	s_add_i32 s76, 0, 0x1c000
	v_add_u32_e32 v108, s76, v225
	s_add_i32 s14, s35, s59
	ds_read_b128 v[178:181], v108
	ds_read_b128 v[182:185], v108 offset:1024
	ds_read_b128 v[186:189], v108 offset:2048
	ds_read_b128 v[190:193], v108 offset:3072
	v_lshl_add_u64 v[108:109], v[194:195], 0, s[18:19]
	s_mov_b32 m0, s14
	s_nop 0
	global_load_lds_dwordx4 v[108:109], off
	v_lshl_add_u64 v[108:109], v[196:197], 0, s[18:19]
	s_add_i32 m0, s14, 0x2000
	s_nop 0
	global_load_lds_dwordx4 v[108:109], off
	s_setprio 1
	s_barrier
	s_waitcnt lgkmcnt(0)
	v_mfma_f32_16x16x32_bf16 v[122:125], v[178:181], v[146:149], v[122:125]
	v_mfma_f32_16x16x32_bf16 v[118:121], v[186:189], v[146:149], v[118:121]
	v_mfma_f32_16x16x32_bf16 v[104:107], v[178:181], v[154:157], v[104:107]
	v_mfma_f32_16x16x32_bf16 v[96:99], v[186:189], v[154:157], v[96:99]
	v_mfma_f32_16x16x32_bf16 v[84:87], v[178:181], v[162:165], v[84:87]
	v_mfma_f32_16x16x32_bf16 v[80:83], v[186:189], v[162:165], v[80:83]
	v_mfma_f32_16x16x32_bf16 v[68:71], v[178:181], v[170:173], v[68:71]
	v_mfma_f32_16x16x32_bf16 v[64:67], v[186:189], v[170:173], v[64:67]
	v_mfma_f32_16x16x32_bf16 v[122:125], v[182:185], v[150:153], v[122:125]
	v_mfma_f32_16x16x32_bf16 v[118:121], v[190:193], v[150:153], v[118:121]
	v_mfma_f32_16x16x32_bf16 v[106:109], v[182:185], v[158:161], v[104:107]
	v_mfma_f32_16x16x32_bf16 v[96:99], v[190:193], v[158:161], v[96:99]
	v_mfma_f32_16x16x32_bf16 v[84:87], v[182:185], v[166:169], v[84:87]
	v_mfma_f32_16x16x32_bf16 v[80:83], v[190:193], v[166:169], v[80:83]
	s_setprio 2
	s_barrier
; #define PG8_STAGE(bufoff, gbase, voff) do { _Pragma("unroll") for (int _i = 0; _i < 2; ++_i) \
;         __builtin_amdgcn_global_load_lds((const unsigned*)((const char*)(gbase) + (voff)[_i]), (LAS unsigned*)(lds + (bufoff) + ldsw + _i * 8192), 16, 0, 0); } while (0)
; #define PG8_LDA(dst, b, h) do { _Pragma("unroll") for (int m = 0; m < 4; ++m) _Pragma("unroll") for (int k = 0; k < 2; ++k) dst[m][k] = *(const LAS bf16x8*)(lds + PG8_SA(b, h) + aoff + m * 2048 + k * 1024); } while (0)
; #define PG8_MMA(ai, bj, At, Bt) do { __builtin_amdgcn_s_setprio(1); _Pragma("unroll") for (int m = 0; m < 4; ++m) _Pragma("unroll") for (int n = 0; n < 2; ++n) _Pragma("unroll") for (int k = 0; k < 2; ++k) \
;         acc[ai][bj][m][n] = __builtin_amdgcn_mfma_f32_16x16x32_bf16(Bt[n][k], At[m][k], acc[ai][bj][m][n], 0, 0, 0); __builtin_amdgcn_s_setprio(0); } while (0)
; #define PG8_WAIT_V(n) asm volatile("s_waitcnt vmcnt(" #n ")" ::: "memory")
; #define PG8_WAIT_L(n) asm volatile("s_waitcnt lgkmcnt(" #n ")" ::: "memory")
; #define PG8_BAR __builtin_amdgcn_s_barrier()
; #define PG8_SCHED __builtin_amdgcn_sched_barrier(0)
; #define PG8_STAGE(bufoff, gbase, voff) do { _Pragma("unroll") for (int _i = 0; _i < 2; ++_i) \
;         __builtin_amdgcn_global_load_lds((const unsigned*)((const char*)(gbase) + (voff)[_i]), (LAS unsigned*)(lds + (bufoff) + ldsw + _i * 8192), 16, 0, 0); } while (0)
; #define PG8_LDA(dst, b, h) do { _Pragma("unroll") for (int m = 0; m < 4; ++m) _Pragma("unroll") for (int k = 0; k < 2; ++k) dst[m][k] = *(const LAS bf16x8*)(lds + PG8_SA(b, h) + aoff + m * 2048 + k * 1024); } while (0)
; #define PG8_WAIT_V(n) asm volatile("s_waitcnt vmcnt(" #n ")" ::: "memory")
; #define PG8_WAIT_L(n) asm volatile("s_waitcnt lgkmcnt(" #n ")" ::: "memory")
; template <class Epi0, class Epi1>
; DI void gemm_phase_dual(LAS unsigned char* lds, const Gemm g, const Gemm g1, const StaticOrder S, const Epi0 E0, const Epi1 E1) {
;     ...
;             PG8_LDA(At, 1, 1); PG8_STAGE(PG8_SA(1, 0), a3, voffA);
;             PG8_BAR; PG8_WAIT_L(0); PG8_MMA(1, 0, At, B0); PG8_BAR; PG8_SCHED;
;             PG8_STAGE(PG8_SB(1, 1), b3 + hstep, voffB);
;             PG8_WAIT_V(6); PG8_BAR; PG8_MMA(1, 1, At, B1); PG8_BAR;
;         }
;         if (ui & 1) E1(acc, cur, wr, wc, fr, fq); else E0(acc, cur, wr, wc, fr, fq);
;         if (!has_next) break;
; #pragma unroll
	v_mfma_f32_16x16x32_bf16 v[68:71], v[182:185], v[174:177], v[68:71]
	v_mfma_f32_16x16x32_bf16 v[64:67], v[190:193], v[174:177], v[64:67]
	s_setprio 0
	s_mov_b32 m0, s83
	v_lshl_add_u64 v[104:105], v[220:221], 0, s[18:19]
	ds_read_b128 v[146:149], v228 offset:49152
	ds_read_b128 v[154:157], v228 offset:51200
	ds_read_b128 v[162:165], v228 offset:53248
	ds_read_b128 v[170:173], v228 offset:55296
	global_load_lds_dwordx4 v[104:105], off
	v_lshl_add_u64 v[104:105], v[232:233], 0, s[18:19]
	s_mov_b32 m0, s84
	s_nop 0
	global_load_lds_dwordx4 v[104:105], off
	s_setprio 1
	s_barrier
	s_waitcnt lgkmcnt(0)
	v_mfma_f32_16x16x32_bf16 v[60:63], v[100:103], v[146:149], v[60:63]
	ds_read_b128 v[150:153], v228 offset:50176
	v_mfma_f32_16x16x32_bf16 v[56:59], v[138:141], v[146:149], v[56:59]
	ds_read_b128 v[158:161], v228 offset:52224
	v_mfma_f32_16x16x32_bf16 v[44:47], v[100:103], v[154:157], v[44:47]
	ds_read_b128 v[166:169], v228 offset:54272
	v_mfma_f32_16x16x32_bf16 v[40:43], v[138:141], v[154:157], v[40:43]
	ds_read_b128 v[174:177], v228 offset:56320
	v_mfma_f32_16x16x32_bf16 v[28:31], v[100:103], v[162:165], v[28:31]
	v_mfma_f32_16x16x32_bf16 v[24:27], v[138:141], v[162:165], v[24:27]
	v_mfma_f32_16x16x32_bf16 v[12:15], v[100:103], v[170:173], v[12:15]
	v_mfma_f32_16x16x32_bf16 v[8:11], v[138:141], v[170:173], v[8:11]
	s_waitcnt lgkmcnt(3)
	v_mfma_f32_16x16x32_bf16 v[60:63], v[134:137], v[150:153], v[60:63]
	v_mfma_f32_16x16x32_bf16 v[56:59], v[142:145], v[150:153], v[56:59]
	s_waitcnt lgkmcnt(2)
	v_mfma_f32_16x16x32_bf16 v[44:47], v[134:137], v[158:161], v[44:47]
	v_mfma_f32_16x16x32_bf16 v[40:43], v[142:145], v[158:161], v[40:43]
	s_waitcnt lgkmcnt(1)
	v_mfma_f32_16x16x32_bf16 v[28:31], v[134:137], v[166:169], v[28:31]
	v_mfma_f32_16x16x32_bf16 v[24:27], v[142:145], v[166:169], v[24:27]
	s_waitcnt lgkmcnt(0)
	s_setprio 2
	s_barrier
	v_mfma_f32_16x16x32_bf16 v[12:15], v[134:137], v[174:177], v[12:15]
	v_mfma_f32_16x16x32_bf16 v[8:11], v[142:145], v[174:177], v[8:11]
	s_setprio 0
	s_add_u32 s14, s52, 0x40080
	s_addc_u32 s15, s53, 0
	s_add_i32 s35, s76, s59
	v_lshl_add_u64 v[100:101], s[14:15], 0, v[200:201]
	s_mov_b32 m0, s35
	s_nop 0
	global_load_lds_dwordx4 v[100:101], off
	v_lshl_add_u64 v[100:101], s[14:15], 0, v[204:205]
	s_add_i32 m0, s35, 0x2000
	s_nop 0
	global_load_lds_dwordx4 v[100:101], off
	s_waitcnt vmcnt(6)
	s_setprio 1
	s_barrier
	v_mfma_f32_16x16x32_bf16 v[52:55], v[178:181], v[146:149], v[52:55]
	v_mfma_f32_16x16x32_bf16 v[48:51], v[186:189], v[146:149], v[48:51]
	v_mfma_f32_16x16x32_bf16 v[36:39], v[178:181], v[154:157], v[36:39]
	v_mfma_f32_16x16x32_bf16 v[32:35], v[186:189], v[154:157], v[32:35]
	v_mfma_f32_16x16x32_bf16 v[20:23], v[178:181], v[162:165], v[20:23]
	v_mfma_f32_16x16x32_bf16 v[16:19], v[186:189], v[162:165], v[16:19]
	v_mfma_f32_16x16x32_bf16 v[4:7], v[178:181], v[170:173], v[4:7]
	v_mfma_f32_16x16x32_bf16 v[0:3], v[186:189], v[170:173], v[0:3]
	v_mfma_f32_16x16x32_bf16 v[52:55], v[182:185], v[150:153], v[52:55]
	v_mfma_f32_16x16x32_bf16 v[48:51], v[190:193], v[150:153], v[48:51]
	v_mfma_f32_16x16x32_bf16 v[36:39], v[182:185], v[158:161], v[36:39]
	v_mfma_f32_16x16x32_bf16 v[32:35], v[190:193], v[158:161], v[32:35]
	v_mfma_f32_16x16x32_bf16 v[20:23], v[182:185], v[166:169], v[20:23]
	v_mfma_f32_16x16x32_bf16 v[16:19], v[190:193], v[166:169], v[16:19]
	s_setprio 2
	s_barrier
	v_mfma_f32_16x16x32_bf16 v[4:7], v[182:185], v[174:177], v[4:7]
	v_mfma_f32_16x16x32_bf16 v[0:3], v[190:193], v[174:177], v[0:3]
	s_setprio 0
	s_add_i32 s95, s95, 2
	s_add_u32 s8, s8, 0x100
	s_addc_u32 s9, s9, 0
	s_add_u32 s23, s23, 0x100
	s_addc_u32 s94, s94, 0
	s_cmp_gt_u32 s95, 13
	s_cbranch_scc0 .LBB0_274
;     DI void operator()(AccRef acc, const Unit& u, int wr, int wc, int fr, int fq) const {
;         const int X = u.pn >> 2, h = u.pn & 3, isk = wc >> 1, i0 = (wc & 1) * 32 + 8 * fq;
;         bf16_t* dst = (X ? qkoB : qkoA) + h * 256 + isk * 128 + i0;
;         const float qs0 = isk ? 1.0f : 0.08838834764831845f;
;         const int row0 = u.pm * 256 + wr * 64 + fr;
;         const RowScales rsc = load_rowscales(ss, row0);
; #pragma unroll
;         for (int ai = 0; ai < 2; ++ai) {
;             f32x4 cs[4][2], sn[4][2];
;             if (X == 0) {
; #pragma unroll
;                 for (int m = 0; m < 4; ++m) {
;                     const int pos = (row0 + ai * 128 + m * 16) & (SEQ - 1);
;                     cs[m][0] = *(const f32x4*)(cosT + pos * 64 + i0); cs[m][1] = *(const f32x4*)(cosT + pos * 64 + i0 + 4);
;                     sn[m][0] = *(const f32x4*)(sinT + pos * 64 + i0); sn[m][1] = *(const f32x4*)(sinT + pos * 64 + i0 + 4);
;                 }
;             } else {
; #pragma unroll
;                 for (int m = 0; m < 4; ++m) { cs[m][0] = cs[m][1] = (f32x4){1.f, 1.f, 1.f, 1.f}; sn[m][0] = sn[m][1] = (f32x4){0.f, 0.f, 0.f, 0.f}; }
;             }
	v_lshl_add_u32 v102, s0, 8, v224
	v_ashrrev_i32_e32 v103, 31, v102
	v_lshl_add_u64 v[134:135], v[102:103], 2, s[60:61]
	global_load_dword v237, v[134:135], off
	global_load_dword v236, v[134:135], off offset:64
	global_load_dword v105, v[134:135], off offset:128
	global_load_dword v101, v[134:135], off offset:192
	global_load_dword v231, v[134:135], off offset:512
	global_load_dword v232, v[134:135], off offset:576
	global_load_dword v233, v[134:135], off offset:640
	global_load_dword v234, v[134:135], off offset:704
	s_cmp_lt_u32 s93, 4
	s_cselect_b64 s[0:1], -1, 0
	s_cmp_gt_u32 s93, 3
	v_lshlrev_b32_e32 v235, 6, v102
	v_mov_b32_e32 v100, 1.0
	v_mov_b32_e32 v104, 0
	v_mov_b32_e32 v134, 0
	v_mov_b32_e32 v135, 0
	v_mov_b32_e32 v136, 0
	v_mov_b32_e32 v137, 0
	v_mov_b32_e32 v142, 0
	v_mov_b32_e32 v143, 0
	v_mov_b32_e32 v144, 0
	v_mov_b32_e32 v145, 0
	v_mov_b32_e32 v146, 0
	v_mov_b32_e32 v147, 0
	v_mov_b32_e32 v148, 0
	v_mov_b32_e32 v149, 0
	v_mov_b32_e32 v154, 0
	v_mov_b32_e32 v155, 0
	v_mov_b32_e32 v156, 0
	v_mov_b32_e32 v157, 0
	v_mov_b32_e32 v162, 0
	v_mov_b32_e32 v163, 0
	v_mov_b32_e32 v164, 0
	v_mov_b32_e32 v165, 0
	v_mov_b32_e32 v174, 0
	v_mov_b32_e32 v175, 0
	v_mov_b32_e32 v176, 0
	v_mov_b32_e32 v177, 0
	v_mov_b32_e32 v182, 0
	v_mov_b32_e32 v183, 0
	v_mov_b32_e32 v184, 0
	v_mov_b32_e32 v185, 0
	v_mov_b32_e32 v194, 0
	v_mov_b32_e32 v195, 0
	v_mov_b32_e32 v196, 0
	v_mov_b32_e32 v197, 0
	v_mov_b32_e32 v138, 1.0
	v_mov_b32_e32 v139, 1.0
	v_mov_b32_e32 v140, 1.0
	v_mov_b32_e32 v141, 1.0
	v_mov_b32_e32 v190, 1.0
	v_mov_b32_e32 v191, 1.0
	v_mov_b32_e32 v192, 1.0
	v_mov_b32_e32 v193, 1.0
	v_mov_b32_e32 v186, 1.0
	v_mov_b32_e32 v187, 1.0
	v_mov_b32_e32 v188, 1.0
	v_mov_b32_e32 v189, 1.0
	v_mov_b32_e32 v178, 1.0
	v_mov_b32_e32 v179, 1.0
	v_mov_b32_e32 v180, 1.0
	v_mov_b32_e32 v181, 1.0
	v_mov_b32_e32 v170, 1.0
	v_mov_b32_e32 v171, 1.0
	v_mov_b32_e32 v172, 1.0
	v_mov_b32_e32 v173, 1.0
	v_mov_b32_e32 v166, 1.0
	v_mov_b32_e32 v167, 1.0
	v_mov_b32_e32 v168, 1.0
	v_mov_b32_e32 v169, 1.0
	v_mov_b32_e32 v158, 1.0
	v_mov_b32_e32 v159, 1.0
	v_mov_b32_e32 v160, 1.0
	v_mov_b32_e32 v161, 1.0
	v_mov_b32_e32 v150, 1.0
	v_mov_b32_e32 v151, 1.0
	v_mov_b32_e32 v152, 1.0
	v_mov_b32_e32 v153, 1.0
	s_cbranch_scc1 .LBB0_277
	v_lshlrev_b32_e32 v134, 2, v235
	v_and_b32_e32 v134, 0x1fcf00, v134
	v_mov_b32_e32 v135, v207
	v_lshl_add_u64 v[136:137], v[208:209], 0, v[134:135]
	global_load_dwordx4 v[190:193], v[136:137], off
	global_load_dwordx4 v[186:189], v[136:137], off offset:16
	v_lshl_add_u64 v[136:137], v[210:211], 0, v[134:135]
	global_load_dwordx4 v[182:185], v[136:137], off offset:16
	global_load_dwordx4 v[194:197], v[136:137], off
	v_or_b32_e32 v136, 0x1000, v134
	v_mov_b32_e32 v137, v207
	v_lshl_add_u64 v[138:139], v[208:209], 0, v[136:137]
	v_lshl_add_u64 v[136:137], v[210:211], 0, v[136:137]
	global_load_dwordx4 v[178:181], v[138:139], off
	global_load_dwordx4 v[170:173], v[138:139], off offset:16
	global_load_dwordx4 v[162:165], v[136:137], off offset:16
	global_load_dwordx4 v[174:177], v[136:137], off
	v_or_b32_e32 v136, 0x2000, v134
	v_mov_b32_e32 v137, v207
	v_lshl_add_u64 v[138:139], v[208:209], 0, v[136:137]
	v_lshl_add_u64 v[136:137], v[210:211], 0, v[136:137]
	v_or_b32_e32 v134, 0x3000, v134
	global_load_dwordx4 v[166:169], v[138:139], off
	global_load_dwordx4 v[158:161], v[138:139], off offset:16
	global_load_dwordx4 v[146:149], v[136:137], off offset:16
	global_load_dwordx4 v[154:157], v[136:137], off
	v_lshl_add_u64 v[136:137], v[208:209], 0, v[134:135]
	v_lshl_add_u64 v[142:143], v[210:211], 0, v[134:135]
	global_load_dwordx4 v[138:141], v[136:137], off offset:16
	global_load_dwordx4 v[150:153], v[136:137], off
	s_nop 0
	global_load_dwordx4 v[134:137], v[142:143], off offset:16
	s_nop 0
	global_load_dwordx4 v[142:145], v[142:143], off

; #define PG8_STAGE(bufoff, gbase, voff) do { _Pragma("unroll") for (int _i = 0; _i < 2; ++_i) \
;         __builtin_amdgcn_global_load_lds((const unsigned*)((const char*)(gbase) + (voff)[_i]), (LAS unsigned*)(lds + (bufoff) + ldsw + _i * 8192), 16, 0, 0); } while (0)
; #define PG8_LDA(dst, b, h) do { _Pragma("unroll") for (int m = 0; m < 4; ++m) _Pragma("unroll") for (int k = 0; k < 2; ++k) dst[m][k] = *(const LAS bf16x8*)(lds + PG8_SA(b, h) + aoff + m * 2048 + k * 1024); } while (0)
; #define PG8_LDB(dst, b, h) do { _Pragma("unroll") for (int n = 0; n < 2; ++n) _Pragma("unroll") for (int k = 0; k < 2; ++k) dst[n][k] = *(const LAS bf16x8*)(lds + PG8_SB(b, h) + boff + n * 2048 + k * 1024); } while (0)
; #define PG8_MMA(ai, bj, At, Bt) do { __builtin_amdgcn_s_setprio(1); _Pragma("unroll") for (int m = 0; m < 4; ++m) _Pragma("unroll") for (int n = 0; n < 2; ++n) _Pragma("unroll") for (int k = 0; k < 2; ++k) \
;         acc[ai][bj][m][n] = __builtin_amdgcn_mfma_f32_16x16x32_bf16(Bt[n][k], At[m][k], acc[ai][bj][m][n], 0, 0, 0); __builtin_amdgcn_s_setprio(0); } while (0)
; #define PG8_WAIT_V(n) asm volatile("s_waitcnt vmcnt(" #n ")" ::: "memory")
; #define PG8_WAIT_L(n) asm volatile("s_waitcnt lgkmcnt(" #n ")" ::: "memory")
; #define PG8_BAR __builtin_amdgcn_s_barrier()
; #define PG8_SCHED __builtin_amdgcn_sched_barrier(0)
; #define PG8_STAGE(bufoff, gbase, voff) do { _Pragma("unroll") for (int _i = 0; _i < 2; ++_i) \
;         __builtin_amdgcn_global_load_lds((const unsigned*)((const char*)(gbase) + (voff)[_i]), (LAS unsigned*)(lds + (bufoff) + ldsw + _i * 8192), 16, 0, 0); } while (0)
; template <class Epi0, class Epi1>
; DI void gemm_phase_dual(LAS unsigned char* lds, const Gemm g, const Gemm g1, const StaticOrder S, const Epi0 E0, const Epi1 E1) {
;     ...
;             PG8_LDB(B0, 0, 0); PG8_SCHED; PG8_LDA(At, 0, 0); PG8_STAGE(PG8_SA(1, 1), a1 + hstep, voffA);
;             PG8_WAIT_L(8); PG8_BAR; PG8_WAIT_L(0); PG8_MMA(0, 0, At, B0); PG8_BAR; PG8_SCHED;
;             PG8_LDB(B1, 0, 1); PG8_STAGE(PG8_SB(0, 0), b2, voffB);
;             PG8_BAR; PG8_WAIT_L(0); PG8_MMA(0, 1, At, B1); PG8_BAR;
;             PG8_LDA(At, 0, 1); PG8_STAGE(PG8_SA(0, 0), a2, voffA);
;             PG8_BAR; PG8_WAIT_L(0); PG8_MMA(1, 0, At, B0); PG8_BAR; PG8_SCHED;
;             PG8_STAGE(PG8_SB(0, 1), b2 + hstep, voffB);
;             PG8_WAIT_V(6); PG8_BAR; PG8_MMA(1, 1, At, B1); PG8_BAR;
.LBB0_298:
	ds_read_b128 v[128:131], v168
	ds_read_b128 v[132:135], v168 offset:1024
	ds_read_b128 v[154:157], v168 offset:2048
	ds_read_b128 v[158:161], v168 offset:3072
	s_add_u32 s5, s8, 0xfffc0080
	s_addc_u32 s14, s9, -1
	s_cmp_eq_u32 s4, 12
	s_cselect_b32 s81, s6, s14
	s_cselect_b32 s80, s7, s5
	s_cselect_b32 s79, s21, vcc_hi
	s_cselect_b32 s78, s23, vcc_lo
	v_lshl_add_u64 v[162:163], s[8:9], 0, v[146:147]
	s_add_i32 m0, s58, 0xc000
	ds_read_b128 v[172:175], v169
	ds_read_b128 v[180:183], v169 offset:2048
	ds_read_b128 v[188:191], v169 offset:4096
	ds_read_b128 v[196:199], v169 offset:6144
	global_load_lds_dwordx4 v[162:163], off
	v_lshl_add_u64 v[162:163], s[8:9], 0, v[148:149]
	s_add_i32 m0, s58, 0xe000
	s_nop 0
	global_load_lds_dwordx4 v[162:163], off
	s_waitcnt lgkmcnt(4)
	s_setprio 1
	s_barrier
	s_waitcnt lgkmcnt(0)
	v_mfma_f32_16x16x32_bf16 v[124:127], v[128:131], v[172:175], v[124:127]
	ds_read_b128 v[176:179], v169 offset:1024
	v_mfma_f32_16x16x32_bf16 v[120:123], v[154:157], v[172:175], v[120:123]
	ds_read_b128 v[184:187], v169 offset:3072
	v_mfma_f32_16x16x32_bf16 v[112:115], v[128:131], v[180:183], v[112:115]
	ds_read_b128 v[192:195], v169 offset:5120
	v_mfma_f32_16x16x32_bf16 v[104:107], v[154:157], v[180:183], v[104:107]
	ds_read_b128 v[200:203], v169 offset:7168
	v_mfma_f32_16x16x32_bf16 v[96:99], v[128:131], v[188:191], v[96:99]
	v_mfma_f32_16x16x32_bf16 v[88:91], v[154:157], v[188:191], v[88:91]
	v_mfma_f32_16x16x32_bf16 v[80:83], v[128:131], v[196:199], v[80:83]
	v_mfma_f32_16x16x32_bf16 v[72:75], v[154:157], v[196:199], v[72:75]
	s_waitcnt lgkmcnt(3)
	v_mfma_f32_16x16x32_bf16 v[124:127], v[132:135], v[176:179], v[124:127]
	v_mfma_f32_16x16x32_bf16 v[120:123], v[158:161], v[176:179], v[120:123]
	s_waitcnt lgkmcnt(2)
	v_mfma_f32_16x16x32_bf16 v[112:115], v[132:135], v[184:187], v[112:115]
	v_mfma_f32_16x16x32_bf16 v[104:107], v[158:161], v[184:187], v[104:107]
	s_waitcnt lgkmcnt(1)
	v_mfma_f32_16x16x32_bf16 v[96:99], v[132:135], v[192:195], v[96:99]
	v_mfma_f32_16x16x32_bf16 v[88:91], v[158:161], v[192:195], v[88:91]
	s_waitcnt lgkmcnt(0)
	s_setprio 2
	s_barrier
	v_mfma_f32_16x16x32_bf16 v[80:83], v[132:135], v[200:203], v[80:83]
	v_mfma_f32_16x16x32_bf16 v[72:75], v[158:161], v[200:203], v[72:75]
	s_setprio 0
	s_add_i32 s5, s94, s19
	v_lshl_add_u64 v[162:163], s[78:79], 0, v[138:139]
	s_mov_b32 m0, s5
	ds_read_b128 v[204:207], v170
	ds_read_b128 v[208:211], v170 offset:1024
	ds_read_b128 v[212:215], v170 offset:2048
	ds_read_b128 v[216:219], v170 offset:3072
	global_load_lds_dwordx4 v[162:163], off
	v_lshl_add_u64 v[220:221], s[78:79], 0, v[142:143]
	s_add_i32 m0, s5, 0x2000
	s_nop 0
	global_load_lds_dwordx4 v[220:221], off
	s_setprio 1
	s_barrier
	s_waitcnt lgkmcnt(0)
	v_mfma_f32_16x16x32_bf16 v[116:119], v[204:207], v[172:175], v[116:119]
	v_mfma_f32_16x16x32_bf16 v[108:111], v[212:215], v[172:175], v[108:111]
	v_mfma_f32_16x16x32_bf16 v[100:103], v[204:207], v[180:183], v[100:103]
	v_mfma_f32_16x16x32_bf16 v[92:95], v[212:215], v[180:183], v[92:95]
	v_mfma_f32_16x16x32_bf16 v[84:87], v[204:207], v[188:191], v[84:87]
	v_mfma_f32_16x16x32_bf16 v[76:79], v[212:215], v[188:191], v[76:79]
	v_mfma_f32_16x16x32_bf16 v[68:71], v[204:207], v[196:199], v[68:71]
	v_mfma_f32_16x16x32_bf16 v[64:67], v[212:215], v[196:199], v[64:67]
	v_mfma_f32_16x16x32_bf16 v[116:119], v[208:211], v[176:179], v[116:119]
	v_mfma_f32_16x16x32_bf16 v[108:111], v[216:219], v[176:179], v[108:111]
	v_mfma_f32_16x16x32_bf16 v[100:103], v[208:211], v[184:187], v[100:103]
	v_mfma_f32_16x16x32_bf16 v[92:95], v[216:219], v[184:187], v[92:95]
	v_mfma_f32_16x16x32_bf16 v[84:87], v[208:211], v[192:195], v[84:87]
	v_mfma_f32_16x16x32_bf16 v[76:79], v[216:219], v[192:195], v[76:79]
	s_setprio 2
	s_barrier
	v_mfma_f32_16x16x32_bf16 v[68:71], v[208:211], v[200:203], v[68:71]
	v_mfma_f32_16x16x32_bf16 v[64:67], v[216:219], v[200:203], v[64:67]
	s_setprio 0
	s_mov_b32 m0, s58
	v_lshl_add_u64 v[224:225], s[80:81], 0, v[136:137]
	ds_read_b128 v[172:175], v169 offset:16384
	ds_read_b128 v[180:183], v169 offset:18432
	ds_read_b128 v[188:191], v169 offset:20480
	ds_read_b128 v[196:199], v169 offset:22528
	global_load_lds_dwordx4 v[224:225], off
	v_lshl_add_u64 v[226:227], s[80:81], 0, v[140:141]
	s_mov_b32 m0, s59
	s_nop 0
	global_load_lds_dwordx4 v[226:227], off
	s_setprio 1
	s_barrier
	s_waitcnt lgkmcnt(0)
	v_mfma_f32_16x16x32_bf16 v[60:63], v[128:131], v[172:175], v[60:63]
	ds_read_b128 v[176:179], v169 offset:17408
	v_mfma_f32_16x16x32_bf16 v[56:59], v[154:157], v[172:175], v[56:59]
	ds_read_b128 v[184:187], v169 offset:19456
	v_mfma_f32_16x16x32_bf16 v[48:51], v[128:131], v[180:183], v[48:51]
	ds_read_b128 v[192:195], v169 offset:21504
	v_mfma_f32_16x16x32_bf16 v[40:43], v[154:157], v[180:183], v[40:43]
	ds_read_b128 v[200:203], v169 offset:23552
	v_mfma_f32_16x16x32_bf16 v[32:35], v[128:131], v[188:191], v[32:35]
	v_mfma_f32_16x16x32_bf16 v[24:27], v[154:157], v[188:191], v[24:27]
	v_mfma_f32_16x16x32_bf16 v[16:19], v[128:131], v[196:199], v[16:19]
	v_mfma_f32_16x16x32_bf16 v[8:11], v[154:157], v[196:199], v[8:11]
	s_waitcnt lgkmcnt(3)
	v_mfma_f32_16x16x32_bf16 v[60:63], v[132:135], v[176:179], v[60:63]
	v_mfma_f32_16x16x32_bf16 v[56:59], v[158:161], v[176:179], v[56:59]
	s_waitcnt lgkmcnt(2)
	v_mfma_f32_16x16x32_bf16 v[48:51], v[132:135], v[184:187], v[48:51]
	v_mfma_f32_16x16x32_bf16 v[40:43], v[158:161], v[184:187], v[40:43]
	s_waitcnt lgkmcnt(1)
	v_mfma_f32_16x16x32_bf16 v[32:35], v[132:135], v[192:195], v[32:35]
	v_mfma_f32_16x16x32_bf16 v[24:27], v[158:161], v[192:195], v[24:27]
	s_waitcnt lgkmcnt(0)
	s_setprio 2
	s_barrier
; #define PG8_STAGE(bufoff, gbase, voff) do { _Pragma("unroll") for (int _i = 0; _i < 2; ++_i) \
;         __builtin_amdgcn_global_load_lds((const unsigned*)((const char*)(gbase) + (voff)[_i]), (LAS unsigned*)(lds + (bufoff) + ldsw + _i * 8192), 16, 0, 0); } while (0)
; #define PG8_LDA(dst, b, h) do { _Pragma("unroll") for (int m = 0; m < 4; ++m) _Pragma("unroll") for (int k = 0; k < 2; ++k) dst[m][k] = *(const LAS bf16x8*)(lds + PG8_SA(b, h) + aoff + m * 2048 + k * 1024); } while (0)
; #define PG8_LDB(dst, b, h) do { _Pragma("unroll") for (int n = 0; n < 2; ++n) _Pragma("unroll") for (int k = 0; k < 2; ++k) dst[n][k] = *(const LAS bf16x8*)(lds + PG8_SB(b, h) + boff + n * 2048 + k * 1024); } while (0)
; #define PG8_MMA(ai, bj, At, Bt) do { __builtin_amdgcn_s_setprio(1); _Pragma("unroll") for (int m = 0; m < 4; ++m) _Pragma("unroll") for (int n = 0; n < 2; ++n) _Pragma("unroll") for (int k = 0; k < 2; ++k) \
;         acc[ai][bj][m][n] = __builtin_amdgcn_mfma_f32_16x16x32_bf16(Bt[n][k], At[m][k], acc[ai][bj][m][n], 0, 0, 0); __builtin_amdgcn_s_setprio(0); } while (0)
; #define PG8_WAIT_V(n) asm volatile("s_waitcnt vmcnt(" #n ")" ::: "memory")
; #define PG8_WAIT_L(n) asm volatile("s_waitcnt lgkmcnt(" #n ")" ::: "memory")
; #define PG8_BAR __builtin_amdgcn_s_barrier()
; #define PG8_SCHED __builtin_amdgcn_sched_barrier(0)
; #define PG8_STAGE(bufoff, gbase, voff) do { _Pragma("unroll") for (int _i = 0; _i < 2; ++_i) \
;         __builtin_amdgcn_global_load_lds((const unsigned*)((const char*)(gbase) + (voff)[_i]), (LAS unsigned*)(lds + (bufoff) + ldsw + _i * 8192), 16, 0, 0); } while (0)
; #define PG8_WAIT_V(n) asm volatile("s_waitcnt vmcnt(" #n ")" ::: "memory")
; template <class Epi>
; DI void gemm_phase(LAS unsigned char* lds, const Gemm g, const StaticOrder S, const Epi E) {
;     ...
;             PG8_BAR; PG8_WAIT_L(0); PG8_MMA(1, 0, At, B0); PG8_BAR; PG8_SCHED;
;             PG8_STAGE(PG8_SB(0, 1), b2 + hstep, voffB);
;             PG8_WAIT_V(6); PG8_BAR; PG8_MMA(1, 1, At, B1); PG8_BAR;
;             PG8_LDB(B0, 1, 0); PG8_SCHED; PG8_LDA(At, 1, 0); PG8_STAGE(PG8_SA(0, 1), a2 + hstep, voffA);
;             PG8_WAIT_L(8); PG8_BAR; PG8_WAIT_L(0); PG8_MMA(0, 0, At, B0); PG8_BAR; PG8_SCHED;
;             PG8_LDB(B1, 1, 1); PG8_STAGE(PG8_SB(1, 0), b3, voffB);
;             PG8_BAR; PG8_WAIT_L(0); PG8_MMA(0, 1, At, B1); PG8_BAR;
	v_mfma_f32_16x16x32_bf16 v[16:19], v[132:135], v[200:203], v[16:19]
	v_mfma_f32_16x16x32_bf16 v[8:11], v[158:161], v[200:203], v[8:11]
	s_setprio 0
	s_add_u32 s14, s78, 0x40000
	s_addc_u32 s15, s79, 0
	s_add_i32 s5, s95, s19
	v_lshl_add_u64 v[128:129], s[14:15], 0, v[138:139]
	s_mov_b32 m0, s5
	s_nop 0
	global_load_lds_dwordx4 v[128:129], off
	v_lshl_add_u64 v[128:129], s[14:15], 0, v[142:143]
	s_add_i32 m0, s5, 0x2000
	s_nop 0
	global_load_lds_dwordx4 v[128:129], off
	s_waitcnt vmcnt(6)
	s_setprio 1
	s_barrier
	v_mfma_f32_16x16x32_bf16 v[52:55], v[204:207], v[172:175], v[52:55]
	v_mfma_f32_16x16x32_bf16 v[44:47], v[212:215], v[172:175], v[44:47]
	v_mfma_f32_16x16x32_bf16 v[36:39], v[204:207], v[180:183], v[36:39]
	v_mfma_f32_16x16x32_bf16 v[28:31], v[212:215], v[180:183], v[28:31]
	v_mfma_f32_16x16x32_bf16 v[20:23], v[204:207], v[188:191], v[20:23]
	v_mfma_f32_16x16x32_bf16 v[12:15], v[212:215], v[188:191], v[12:15]
	v_mfma_f32_16x16x32_bf16 v[4:7], v[204:207], v[196:199], v[4:7]
	v_mfma_f32_16x16x32_bf16 v[0:3], v[212:215], v[196:199], v[0:3]
	v_mfma_f32_16x16x32_bf16 v[52:55], v[208:211], v[176:179], v[52:55]
	v_mfma_f32_16x16x32_bf16 v[44:47], v[216:219], v[176:179], v[44:47]
	v_mfma_f32_16x16x32_bf16 v[36:39], v[208:211], v[184:187], v[36:39]
	v_mfma_f32_16x16x32_bf16 v[28:31], v[216:219], v[184:187], v[28:31]
	v_mfma_f32_16x16x32_bf16 v[20:23], v[208:211], v[192:195], v[20:23]
	v_mfma_f32_16x16x32_bf16 v[12:15], v[216:219], v[192:195], v[12:15]
	s_setprio 2
	s_barrier
	v_mfma_f32_16x16x32_bf16 v[4:7], v[208:211], v[200:203], v[4:7]
	v_mfma_f32_16x16x32_bf16 v[0:3], v[216:219], v[200:203], v[0:3]
	s_setprio 0
	s_add_i32 s5, 0, 0x18000
	v_add_u32_e32 v158, s5, v165
	ds_read_b128 v[128:131], v158
	ds_read_b128 v[132:135], v158 offset:1024
	ds_read_b128 v[154:157], v158 offset:2048
	ds_read_b128 v[158:161], v158 offset:3072
	s_add_u32 s14, s80, 0x40000
	s_addc_u32 s15, s81, 0
	s_mov_b32 m0, s77
	v_lshl_add_u64 v[204:205], s[14:15], 0, v[136:137]
	ds_read_b128 v[172:175], v169 offset:32768
	ds_read_b128 v[180:183], v169 offset:34816
	ds_read_b128 v[188:191], v169 offset:36864
	ds_read_b128 v[196:199], v169 offset:38912
	global_load_lds_dwordx4 v[204:205], off
	v_lshl_add_u64 v[204:205], s[14:15], 0, v[140:141]
	s_mov_b32 m0, s82
	s_nop 0
	global_load_lds_dwordx4 v[204:205], off
	s_waitcnt lgkmcnt(4)
	s_setprio 1
	s_barrier
	s_waitcnt lgkmcnt(0)
	v_mfma_f32_16x16x32_bf16 v[124:127], v[128:131], v[172:175], v[124:127]
	ds_read_b128 v[176:179], v169 offset:33792
	v_mfma_f32_16x16x32_bf16 v[120:123], v[154:157], v[172:175], v[120:123]
	ds_read_b128 v[184:187], v169 offset:35840
	v_mfma_f32_16x16x32_bf16 v[112:115], v[128:131], v[180:183], v[112:115]
	ds_read_b128 v[192:195], v169 offset:37888
	v_mfma_f32_16x16x32_bf16 v[104:107], v[154:157], v[180:183], v[104:107]
	ds_read_b128 v[200:203], v169 offset:39936
	v_mfma_f32_16x16x32_bf16 v[96:99], v[128:131], v[188:191], v[96:99]
	v_mfma_f32_16x16x32_bf16 v[88:91], v[154:157], v[188:191], v[88:91]
	v_mfma_f32_16x16x32_bf16 v[80:83], v[128:131], v[196:199], v[80:83]
	v_mfma_f32_16x16x32_bf16 v[72:75], v[154:157], v[196:199], v[72:75]
	s_waitcnt lgkmcnt(3)
	v_mfma_f32_16x16x32_bf16 v[124:127], v[132:135], v[176:179], v[124:127]
	v_mfma_f32_16x16x32_bf16 v[120:123], v[158:161], v[176:179], v[120:123]
	s_waitcnt lgkmcnt(2)
	v_mfma_f32_16x16x32_bf16 v[112:115], v[132:135], v[184:187], v[112:115]
	v_mfma_f32_16x16x32_bf16 v[104:107], v[158:161], v[184:187], v[104:107]
	s_waitcnt lgkmcnt(1)
	v_mfma_f32_16x16x32_bf16 v[96:99], v[132:135], v[192:195], v[96:99]
	v_mfma_f32_16x16x32_bf16 v[88:91], v[158:161], v[192:195], v[88:91]
	s_waitcnt lgkmcnt(0)
	s_setprio 2
	s_barrier
	v_mfma_f32_16x16x32_bf16 v[80:83], v[132:135], v[200:203], v[80:83]
	v_mfma_f32_16x16x32_bf16 v[72:75], v[158:161], v[200:203], v[72:75]
	s_setprio 0
	s_add_i32 s35, 0, 0x1c000
	s_add_i32 s5, s5, s19
	v_add_u32_e32 v171, s35, v165
	v_lshl_add_u64 v[162:163], v[162:163], 0, s[10:11]
	s_mov_b32 m0, s5
	ds_read_b128 v[204:207], v171
	ds_read_b128 v[208:211], v171 offset:1024
	ds_read_b128 v[212:215], v171 offset:2048
	ds_read_b128 v[216:219], v171 offset:3072
	global_load_lds_dwordx4 v[162:163], off
	v_lshl_add_u64 v[162:163], v[220:221], 0, s[10:11]
	s_add_i32 m0, s5, 0x2000
	s_nop 0
	global_load_lds_dwordx4 v[162:163], off
	s_setprio 1
	s_barrier
	s_waitcnt lgkmcnt(0)
	v_mfma_f32_16x16x32_bf16 v[116:119], v[204:207], v[172:175], v[116:119]
	v_mfma_f32_16x16x32_bf16 v[108:111], v[212:215], v[172:175], v[108:111]
	v_mfma_f32_16x16x32_bf16 v[100:103], v[204:207], v[180:183], v[100:103]
	v_mfma_f32_16x16x32_bf16 v[92:95], v[212:215], v[180:183], v[92:95]
	v_mfma_f32_16x16x32_bf16 v[84:87], v[204:207], v[188:191], v[84:87]
	v_mfma_f32_16x16x32_bf16 v[76:79], v[212:215], v[188:191], v[76:79]
	v_mfma_f32_16x16x32_bf16 v[68:71], v[204:207], v[196:199], v[68:71]
	v_mfma_f32_16x16x32_bf16 v[64:67], v[212:215], v[196:199], v[64:67]
	v_mfma_f32_16x16x32_bf16 v[116:119], v[208:211], v[176:179], v[116:119]
	v_mfma_f32_16x16x32_bf16 v[108:111], v[216:219], v[176:179], v[108:111]
	v_mfma_f32_16x16x32_bf16 v[100:103], v[208:211], v[184:187], v[100:103]
	v_mfma_f32_16x16x32_bf16 v[92:95], v[216:219], v[184:187], v[92:95]
	v_mfma_f32_16x16x32_bf16 v[84:87], v[208:211], v[192:195], v[84:87]
	v_mfma_f32_16x16x32_bf16 v[76:79], v[216:219], v[192:195], v[76:79]
	s_setprio 2
	s_barrier
; #define PG8_STAGE(bufoff, gbase, voff) do { _Pragma("unroll") for (int _i = 0; _i < 2; ++_i) \
;         __builtin_amdgcn_global_load_lds((const unsigned*)((const char*)(gbase) + (voff)[_i]), (LAS unsigned*)(lds + (bufoff) + ldsw + _i * 8192), 16, 0, 0); } while (0)
; #define PG8_LDA(dst, b, h) do { _Pragma("unroll") for (int m = 0; m < 4; ++m) _Pragma("unroll") for (int k = 0; k < 2; ++k) dst[m][k] = *(const LAS bf16x8*)(lds + PG8_SA(b, h) + aoff + m * 2048 + k * 1024); } while (0)
; #define PG8_MMA(ai, bj, At, Bt) do { __builtin_amdgcn_s_setprio(1); _Pragma("unroll") for (int m = 0; m < 4; ++m) _Pragma("unroll") for (int n = 0; n < 2; ++n) _Pragma("unroll") for (int k = 0; k < 2; ++k) \
;         acc[ai][bj][m][n] = __builtin_amdgcn_mfma_f32_16x16x32_bf16(Bt[n][k], At[m][k], acc[ai][bj][m][n], 0, 0, 0); __builtin_amdgcn_s_setprio(0); } while (0)
; #define PG8_WAIT_V(n) asm volatile("s_waitcnt vmcnt(" #n ")" ::: "memory")
; #define PG8_WAIT_L(n) asm volatile("s_waitcnt lgkmcnt(" #n ")" ::: "memory")
; #define PG8_BAR __builtin_amdgcn_s_barrier()
; #define PG8_SCHED __builtin_amdgcn_sched_barrier(0)
; #define PG8_STAGE(bufoff, gbase, voff) do { _Pragma("unroll") for (int _i = 0; _i < 2; ++_i) \
;         __builtin_amdgcn_global_load_lds((const unsigned*)((const char*)(gbase) + (voff)[_i]), (LAS unsigned*)(lds + (bufoff) + ldsw + _i * 8192), 16, 0, 0); } while (0)
; #define PG8_WAIT_V(n) asm volatile("s_waitcnt vmcnt(" #n ")" ::: "memory")
; #define PG8_WAIT_L(n) asm volatile("s_waitcnt lgkmcnt(" #n ")" ::: "memory")
; template <class Epi>
; DI void gemm_phase(LAS unsigned char* lds, const Gemm g, const StaticOrder S, const Epi E) {
;     ...
;             PG8_BAR; PG8_WAIT_L(0); PG8_MMA(0, 1, At, B1); PG8_BAR;
;             PG8_LDA(At, 1, 1); PG8_STAGE(PG8_SA(1, 0), a3, voffA);
;             PG8_BAR; PG8_WAIT_L(0); PG8_MMA(1, 0, At, B0); PG8_BAR; PG8_SCHED;
;             PG8_STAGE(PG8_SB(1, 1), b3 + hstep, voffB);
;             PG8_WAIT_V(6); PG8_BAR; PG8_MMA(1, 1, At, B1); PG8_BAR;
;         }
;         E(acc, cur, wr, wc, fr, fq);
;     DI void operator()(AccRef acc, const Unit& u, int wr, int wc, int fr, int fq) const {
;         f32x4 ts[2][2];
; #pragma unroll
;         for (int bj = 0; bj < 2; ++bj) { const int tok = u.pn * 256 + bj * 128 + wc * 32 + 8 * fq; ts[bj][0] = *(const f32x4*)(ss + tok); ts[bj][1] = *(const f32x4*)(ss + tok + 4); }
	v_mfma_f32_16x16x32_bf16 v[68:71], v[208:211], v[200:203], v[68:71]
	v_mfma_f32_16x16x32_bf16 v[64:67], v[216:219], v[200:203], v[64:67]
	s_setprio 0
	s_mov_b32 m0, s86
	v_lshl_add_u64 v[162:163], v[224:225], 0, s[10:11]
	ds_read_b128 v[172:175], v169 offset:49152
	ds_read_b128 v[180:183], v169 offset:51200
	ds_read_b128 v[188:191], v169 offset:53248
	ds_read_b128 v[196:199], v169 offset:55296
	global_load_lds_dwordx4 v[162:163], off
	v_lshl_add_u64 v[162:163], v[226:227], 0, s[10:11]
	s_mov_b32 m0, s87
	s_nop 0
	global_load_lds_dwordx4 v[162:163], off
	s_setprio 1
	s_barrier
	s_waitcnt lgkmcnt(0)
	v_mfma_f32_16x16x32_bf16 v[60:63], v[128:131], v[172:175], v[60:63]
	ds_read_b128 v[176:179], v169 offset:50176
	v_mfma_f32_16x16x32_bf16 v[56:59], v[154:157], v[172:175], v[56:59]
	ds_read_b128 v[184:187], v169 offset:52224
	v_mfma_f32_16x16x32_bf16 v[48:51], v[128:131], v[180:183], v[48:51]
	ds_read_b128 v[192:195], v169 offset:54272
	v_mfma_f32_16x16x32_bf16 v[40:43], v[154:157], v[180:183], v[40:43]
	ds_read_b128 v[200:203], v169 offset:56320
	v_mfma_f32_16x16x32_bf16 v[32:35], v[128:131], v[188:191], v[32:35]
	v_mfma_f32_16x16x32_bf16 v[24:27], v[154:157], v[188:191], v[24:27]
	v_mfma_f32_16x16x32_bf16 v[16:19], v[128:131], v[196:199], v[16:19]
	v_mfma_f32_16x16x32_bf16 v[8:11], v[154:157], v[196:199], v[8:11]
	s_waitcnt lgkmcnt(3)
	v_mfma_f32_16x16x32_bf16 v[60:63], v[132:135], v[176:179], v[60:63]
	v_mfma_f32_16x16x32_bf16 v[56:59], v[158:161], v[176:179], v[56:59]
	s_waitcnt lgkmcnt(2)
	v_mfma_f32_16x16x32_bf16 v[48:51], v[132:135], v[184:187], v[48:51]
	v_mfma_f32_16x16x32_bf16 v[40:43], v[158:161], v[184:187], v[40:43]
	s_waitcnt lgkmcnt(1)
	v_mfma_f32_16x16x32_bf16 v[32:35], v[132:135], v[192:195], v[32:35]
	v_mfma_f32_16x16x32_bf16 v[24:27], v[158:161], v[192:195], v[24:27]
	s_waitcnt lgkmcnt(0)
	s_setprio 2
	s_barrier
	v_mfma_f32_16x16x32_bf16 v[16:19], v[132:135], v[200:203], v[16:19]
	v_mfma_f32_16x16x32_bf16 v[8:11], v[158:161], v[200:203], v[8:11]
	s_setprio 0
	s_add_u32 s14, s78, 0x40080
	s_addc_u32 s15, s79, 0
	s_add_i32 s5, s35, s19
	v_lshl_add_u64 v[128:129], s[14:15], 0, v[138:139]
	s_mov_b32 m0, s5
	s_nop 0
	global_load_lds_dwordx4 v[128:129], off
	v_lshl_add_u64 v[128:129], s[14:15], 0, v[142:143]
	s_add_i32 m0, s5, 0x2000
	s_nop 0
	global_load_lds_dwordx4 v[128:129], off
	s_waitcnt vmcnt(6)
	s_setprio 1
	s_barrier
	v_mfma_f32_16x16x32_bf16 v[52:55], v[204:207], v[172:175], v[52:55]
	v_mfma_f32_16x16x32_bf16 v[44:47], v[212:215], v[172:175], v[44:47]
	v_mfma_f32_16x16x32_bf16 v[36:39], v[204:207], v[180:183], v[36:39]
	v_mfma_f32_16x16x32_bf16 v[28:31], v[212:215], v[180:183], v[28:31]
	v_mfma_f32_16x16x32_bf16 v[20:23], v[204:207], v[188:191], v[20:23]
	v_mfma_f32_16x16x32_bf16 v[12:15], v[212:215], v[188:191], v[12:15]
	v_mfma_f32_16x16x32_bf16 v[4:7], v[204:207], v[196:199], v[4:7]
	v_mfma_f32_16x16x32_bf16 v[0:3], v[212:215], v[196:199], v[0:3]
	v_mfma_f32_16x16x32_bf16 v[52:55], v[208:211], v[176:179], v[52:55]
	v_mfma_f32_16x16x32_bf16 v[44:47], v[216:219], v[176:179], v[44:47]
	v_mfma_f32_16x16x32_bf16 v[36:39], v[208:211], v[184:187], v[36:39]
	v_mfma_f32_16x16x32_bf16 v[28:31], v[216:219], v[184:187], v[28:31]
	v_mfma_f32_16x16x32_bf16 v[20:23], v[208:211], v[192:195], v[20:23]
	v_mfma_f32_16x16x32_bf16 v[12:15], v[216:219], v[192:195], v[12:15]
	s_setprio 2
	s_barrier
	v_mfma_f32_16x16x32_bf16 v[4:7], v[208:211], v[200:203], v[4:7]
	v_mfma_f32_16x16x32_bf16 v[0:3], v[216:219], v[200:203], v[0:3]
	s_setprio 0
	s_add_i32 s4, s4, 2
	s_add_u32 s8, s8, 0x100
	s_addc_u32 s9, s9, 0
	s_add_u32 vcc_lo, vcc_lo, 0x100
	s_addc_u32 vcc_hi, vcc_hi, 0
	s_cmp_gt_u32 s4, 13
	s_cbranch_scc0 .LBB0_298
	s_lshl_b32 s4, s97, 8
	v_or_b32_e32 v128, s4, v166
	v_ashrrev_i32_e32 v129, 31, v128
	v_lshl_add_u64 v[132:133], v[128:129], 2, s[60:61]
	global_load_dwordx4 v[158:161], v[132:133], off offset:16
	global_load_dwordx4 v[154:157], v[132:133], off
	global_load_dwordx4 v[128:131], v[132:133], off offset:528
	s_nop 0
	global_load_dwordx4 v[132:135], v[132:133], off offset:512
	s_mov_b32 s6, 0x358637bd
	v_mov_b64_e32 v[162:163], s[6:7]
	s_lshl_b32 s6, s76, 8
	s_add_i32 s6, s6, s84
	s_lshr_b32 s5, s97, 3
	s_and_b32 s7, s5, 0x1fffc
	s_bfe_u32 s5, s6, 0x20008
	s_or_b32 s4, s4, s85
	s_or_b32 s5, s5, s7
	s_cmpk_lt_u32 s6, 0x400
	s_mov_b32 s97, s20
	s_mov_b32 s76, s22
	s_mov_b64 s[78:79], s[28:29]
	s_waitcnt vmcnt(0)
; DI unsigned pk_bf16(float lo, float hi) { f32x2 v = {lo, hi}; return __builtin_bit_cast(unsigned, __builtin_convertvector(v, bf16v2)); }
;     DI void operator()(AccRef acc, const Unit& u, int wr, int wc, int fr, int fq) const {
;         f32x4 ts[2][2];
; #pragma unroll
;         for (int bj = 0; bj < 2; ++bj) { const int tok = u.pn * 256 + bj * 128 + wc * 32 + 8 * fq; ts[bj][0] = *(const f32x4*)(ss + tok); ts[bj][1] = *(const f32x4*)(ss + tok + 4); }
; #pragma unroll
;         for (int bj = 0; bj < 2; ++bj)
; #pragma unroll
;             for (int n = 0; n < 2; ++n)
; #pragma unroll
;                 for (int e = 0; e < 4; ++e) ts[bj][n][e] = rsqrtf(ts[bj][n][e] * (1.0f / 1024.0f) + 1e-6f);
; #pragma unroll
;         for (int ai = 0; ai < 2; ++ai)
; #pragma unroll
;             for (int m = 0; m < 4; ++m) {
;                 const int R = u.pm * 256 + ai * 128 + wr * 64 + m * 16 + fr, X = R >> 10, hv = R & 1023;
; #pragma unroll
;                 for (int bj = 0; bj < 2; ++bj) {
;                     const int tok = u.pn * 256 + bj * 128 + wc * 32 + 8 * fq, b = tok >> 13, s = tok & (SEQ - 1);
;                     bf16_t* dst = (X ? vtB : vtA) + ((size_t)(((b * 4 + (hv >> 8)) * 128 + (s >> 6)) * 256 + (hv & 255))) * 64 + (s & 63);
;                     const f32x4 v0 = acc[ai][bj][m][0] * ts[bj][0], v1 = acc[ai][bj][m][1] * ts[bj][1];
;                     u32x4 w; w.x = pk_bf16(v0[0], v0[1]); w.y = pk_bf16(v0[2], v0[3]); w.z = pk_bf16(v1[0], v1[1]); w.w = pk_bf16(v1[2], v1[3]);
;                     *(u32x4*)dst = w;
	v_pk_fma_f32 v[158:159], v[158:159], s[16:17], v[162:163] op_sel_hi:[1,0,0]
	v_pk_fma_f32 v[154:155], v[154:155], s[16:17], v[162:163] op_sel_hi:[1,0,0]
	v_pk_fma_f32 v[156:157], v[156:157], s[16:17], v[162:163] op_sel_hi:[1,0,0]
	v_mul_f32_e32 v171, 0x4b800000, v154
	v_cmp_gt_f32_e64 s[8:9], s96, v154
	v_cmp_gt_f32_e32 vcc, s96, v155
	v_pk_fma_f32 v[160:161], v[160:161], s[16:17], v[162:163] op_sel_hi:[1,0,0]
	v_cndmask_b32_e64 v154, v154, v171, s[8:9]
	v_mul_f32_e32 v171, 0x4b800000, v155
	v_cndmask_b32_e32 v155, v155, v171, vcc
	v_rsq_f32_e32 v154, v154
	v_rsq_f32_e32 v155, v155
	v_mul_f32_e32 v171, 0x4b800000, v156
	v_pk_fma_f32 v[132:133], v[132:133], s[16:17], v[162:163] op_sel_hi:[1,0,0]
	v_pk_fma_f32 v[134:135], v[134:135], s[16:17], v[162:163] op_sel_hi:[1,0,0]
	v_pk_mul_f32 v[172:173], v[154:155], s[18:19] op_sel_hi:[1,0]
	v_pk_fma_f32 v[128:129], v[128:129], s[16:17], v[162:163] op_sel_hi:[1,0,0]
	v_cndmask_b32_e64 v154, v154, v172, s[8:9]
	v_cmp_gt_f32_e64 s[8:9], s96, v156
	v_cndmask_b32_e32 v155, v155, v173, vcc
	v_cmp_gt_f32_e32 vcc, s96, v157
	v_cndmask_b32_e64 v156, v156, v171, s[8:9]
	v_mul_f32_e32 v171, 0x4b800000, v157
	v_cndmask_b32_e32 v157, v157, v171, vcc
	v_rsq_f32_e32 v156, v156
	v_rsq_f32_e32 v157, v157
	v_mul_f32_e32 v171, 0x4b800000, v158
	v_pk_fma_f32 v[130:131], v[130:131], s[16:17], v[162:163] op_sel_hi:[1,0,0]
	v_pk_mul_f32 v[124:125], v[124:125], v[154:155]
	v_pk_mul_f32 v[172:173], v[156:157], s[18:19] op_sel_hi:[1,0]
	v_mul_f32_e32 v162, 0x4b800000, v130
	v_cndmask_b32_e64 v156, v156, v172, s[8:9]
	v_cmp_gt_f32_e64 s[8:9], s96, v158
	v_cndmask_b32_e32 v157, v157, v173, vcc
	v_cmp_gt_f32_e32 vcc, s96, v159
	v_cndmask_b32_e64 v158, v158, v171, s[8:9]
	v_mul_f32_e32 v171, 0x4b800000, v159
	v_cndmask_b32_e32 v159, v159, v171, vcc
	v_rsq_f32_e32 v158, v158
	v_rsq_f32_e32 v159, v159
	v_mul_f32_e32 v171, 0x4b800000, v160
	v_pk_mul_f32 v[126:127], v[126:127], v[156:157]
	v_pk_mul_f32 v[112:113], v[112:113], v[154:155]
	v_pk_mul_f32 v[172:173], v[158:159], s[18:19] op_sel_hi:[1,0]
	v_pk_mul_f32 v[96:97], v[96:97], v[154:155]
	v_cndmask_b32_e64 v158, v158, v172, s[8:9]
	v_cmp_gt_f32_e64 s[8:9], s96, v160
	v_cndmask_b32_e32 v159, v159, v173, vcc
	v_cmp_gt_f32_e32 vcc, s96, v161
	v_cndmask_b32_e64 v160, v160, v171, s[8:9]
	v_mul_f32_e32 v171, 0x4b800000, v161
	v_cndmask_b32_e32 v161, v161, v171, vcc
	v_rsq_f32_e32 v160, v160
	v_rsq_f32_e32 v161, v161
	v_mul_f32_e32 v171, 0x4b800000, v132
	v_pk_mul_f32 v[80:81], v[80:81], v[154:155]
	v_pk_mul_f32 v[62:63], v[62:63], v[156:157]
	v_pk_mul_f32 v[172:173], v[160:161], s[18:19] op_sel_hi:[1,0]
	v_pk_mul_f32 v[60:61], v[60:61], v[154:155]
	v_cndmask_b32_e64 v160, v160, v172, s[8:9]
	v_cmp_gt_f32_e64 s[8:9], s96, v132
	v_cndmask_b32_e32 v161, v161, v173, vcc
	v_cmp_gt_f32_e32 vcc, s96, v133
	v_cndmask_b32_e64 v132, v132, v171, s[8:9]
	v_mul_f32_e32 v171, 0x4b800000, v133
	v_cndmask_b32_e32 v133, v133, v171, vcc
	v_rsq_f32_e32 v132, v132
	v_rsq_f32_e32 v133, v133
	v_mul_f32_e32 v171, 0x4b800000, v134
	v_pk_mul_f32 v[48:49], v[48:49], v[154:155]
	v_pk_mul_f32 v[32:33], v[32:33], v[154:155]
	v_pk_mul_f32 v[172:173], v[132:133], s[18:19] op_sel_hi:[1,0]
	v_pk_mul_f32 v[16:17], v[16:17], v[154:155]
	v_cndmask_b32_e64 v132, v132, v172, s[8:9]
	v_cmp_gt_f32_e64 s[8:9], s96, v134
	v_cndmask_b32_e32 v133, v133, v173, vcc
	v_cmp_gt_f32_e32 vcc, s96, v135
	v_cndmask_b32_e64 v134, v134, v171, s[8:9]
	v_mul_f32_e32 v171, 0x4b800000, v135
	v_cndmask_b32_e32 v135, v135, v171, vcc
	v_rsq_f32_e32 v134, v134
	v_rsq_f32_e32 v135, v135
	v_mul_f32_e32 v171, 0x4b800000, v128
	v_pk_mul_f32 v[116:117], v[116:117], v[132:133]
	v_pk_mul_f32 v[100:101], v[100:101], v[132:133]
	v_pk_mul_f32 v[172:173], v[134:135], s[18:19] op_sel_hi:[1,0]
	v_pk_mul_f32 v[84:85], v[84:85], v[132:133]
	v_cndmask_b32_e64 v134, v134, v172, s[8:9]
	v_cmp_gt_f32_e64 s[8:9], s96, v128
	v_cndmask_b32_e32 v135, v135, v173, vcc
	v_cmp_gt_f32_e32 vcc, s96, v129
	v_cndmask_b32_e64 v128, v128, v171, s[8:9]
	v_mul_f32_e32 v171, 0x4b800000, v129
	v_cndmask_b32_e32 v129, v129, v171, vcc
	v_rsq_f32_e32 v128, v128
	v_rsq_f32_e32 v129, v129
	v_lshl_or_b32 v171, s5, 15, v167
	v_pk_mul_f32 v[118:119], v[118:119], v[134:135]
	v_pk_mul_f32 v[102:103], v[102:103], v[134:135]
	v_pk_mul_f32 v[172:173], v[128:129], s[18:19] op_sel_hi:[1,0]
	v_pk_mul_f32 v[86:87], v[86:87], v[134:135]
	v_cndmask_b32_e64 v128, v128, v172, s[8:9]
	v_cmp_gt_f32_e64 s[8:9], s96, v130
	v_cndmask_b32_e32 v129, v129, v173, vcc
	v_cmp_gt_f32_e32 vcc, s96, v131
	v_cndmask_b32_e64 v130, v130, v162, s[8:9]
	v_mul_f32_e32 v162, 0x4b800000, v131
	v_cndmask_b32_e32 v131, v131, v162, vcc
	v_rsq_f32_e32 v130, v130
	v_rsq_f32_e32 v131, v131
	v_pk_mul_f32 v[172:173], v[122:123], v[160:161]
	v_pk_mul_f32 v[122:123], v[120:121], v[158:159]
	v_cvt_pk_bf16_f32 v120, v124, v125
	v_pk_mul_f32 v[162:163], v[130:131], s[18:19] op_sel_hi:[1,0]
	v_cvt_pk_bf16_f32 v121, v126, v127
	v_cndmask_b32_e64 v130, v130, v162, s[8:9]
	s_cselect_b32 s9, s53, s91
	s_cselect_b32 s8, s52, s90
	s_lshl_b32 s4, s4, 2
	s_and_b32 s4, s4, 0x7d00
	v_or_b32_e32 v162, s4, v171
	v_cndmask_b32_e32 v131, v131, v163, vcc
	v_ashrrev_i32_e32 v163, 31, v162
	v_lshlrev_b64 v[162:163], 7, v[162:163]
	v_lshl_add_u64 v[162:163], s[8:9], 0, v[162:163]
	v_lshl_add_u64 v[162:163], v[162:163], 0, v[144:145]
	v_cvt_pk_bf16_f32 v122, v122, v123
	v_cvt_pk_bf16_f32 v123, v172, v173
	s_or_b32 s5, s4, 0x200
	global_store_dwordx4 v[162:163], v[120:123], off
	s_addk_i32 s6, 0x80
	v_pk_mul_f32 v[70:71], v[70:71], v[134:135]
	v_or_b32_e32 v120, s5, v171
	v_ashrrev_i32_e32 v121, 31, v120
	v_lshlrev_b64 v[120:121], 7, v[120:121]
; DI unsigned pk_bf16(float lo, float hi) { f32x2 v = {lo, hi}; return __builtin_bit_cast(unsigned, __builtin_convertvector(v, bf16v2)); }
;     DI void operator()(AccRef acc, const Unit& u, int wr, int wc, int fr, int fq) const {
;     ...
;             for (int m = 0; m < 4; ++m) {
;                 const int R = u.pm * 256 + ai * 128 + wr * 64 + m * 16 + fr, X = R >> 10, hv = R & 1023;
; #pragma unroll
;                 for (int bj = 0; bj < 2; ++bj) {
;                     const int tok = u.pn * 256 + bj * 128 + wc * 32 + 8 * fq, b = tok >> 13, s = tok & (SEQ - 1);
;                     bf16_t* dst = (X ? vtB : vtA) + ((size_t)(((b * 4 + (hv >> 8)) * 128 + (s >> 6)) * 256 + (hv & 255))) * 64 + (s & 63);
;                     const f32x4 v0 = acc[ai][bj][m][0] * ts[bj][0], v1 = acc[ai][bj][m][1] * ts[bj][1];
;                     u32x4 w; w.x = pk_bf16(v0[0], v0[1]); w.y = pk_bf16(v0[2], v0[3]); w.z = pk_bf16(v1[0], v1[1]); w.w = pk_bf16(v1[2], v1[3]);
;                     *(u32x4*)dst = w;
	v_lshl_add_u64 v[120:121], s[8:9], 0, v[120:121]
	v_pk_mul_f32 v[122:123], v[110:111], v[130:131]
	v_pk_mul_f32 v[110:111], v[108:109], v[128:129]
	v_lshl_add_u64 v[120:121], v[120:121], 0, v[144:145]
	v_cvt_pk_bf16_f32 v108, v116, v117
	v_cvt_pk_bf16_f32 v109, v118, v119
	v_cvt_pk_bf16_f32 v110, v110, v111
	v_cvt_pk_bf16_f32 v111, v122, v123
	v_or_b32_e32 v116, 16, v171
	global_store_dwordx4 v[120:121], v[108:111], off
	v_pk_mul_f32 v[68:69], v[68:69], v[132:133]
	v_pk_mul_f32 v[54:55], v[54:55], v[134:135]
	v_or_b32_e32 v108, s4, v116
	v_ashrrev_i32_e32 v109, 31, v108
	v_lshlrev_b64 v[108:109], 7, v[108:109]
	v_lshl_add_u64 v[108:109], s[8:9], 0, v[108:109]
	v_pk_mul_f32 v[110:111], v[114:115], v[156:157]
	v_pk_mul_f32 v[114:115], v[106:107], v[160:161]
	v_pk_mul_f32 v[106:107], v[104:105], v[158:159]
	v_lshl_add_u64 v[108:109], v[108:109], 0, v[144:145]
	v_cvt_pk_bf16_f32 v104, v112, v113
	v_cvt_pk_bf16_f32 v105, v110, v111
	v_cvt_pk_bf16_f32 v106, v106, v107
	v_cvt_pk_bf16_f32 v107, v114, v115
	global_store_dwordx4 v[108:109], v[104:107], off
	v_pk_mul_f32 v[52:53], v[52:53], v[132:133]
	v_pk_mul_f32 v[38:39], v[38:39], v[134:135]
	v_or_b32_e32 v104, s5, v116
	v_ashrrev_i32_e32 v105, 31, v104
	v_lshlrev_b64 v[104:105], 7, v[104:105]
	v_lshl_add_u64 v[104:105], s[8:9], 0, v[104:105]
	v_pk_mul_f32 v[106:107], v[94:95], v[130:131]
	v_pk_mul_f32 v[94:95], v[92:93], v[128:129]
	v_lshl_add_u64 v[104:105], v[104:105], 0, v[144:145]
	v_cvt_pk_bf16_f32 v92, v100, v101
	v_cvt_pk_bf16_f32 v93, v102, v103
	v_cvt_pk_bf16_f32 v94, v94, v95
	v_cvt_pk_bf16_f32 v95, v106, v107
	v_or_b32_e32 v100, 32, v171
	global_store_dwordx4 v[104:105], v[92:95], off
	v_pk_mul_f32 v[36:37], v[36:37], v[132:133]
	v_pk_mul_f32 v[22:23], v[22:23], v[134:135]
	v_or_b32_e32 v92, s4, v100
	v_ashrrev_i32_e32 v93, 31, v92
	v_lshlrev_b64 v[92:93], 7, v[92:93]
	v_lshl_add_u64 v[92:93], s[8:9], 0, v[92:93]
	v_pk_mul_f32 v[94:95], v[98:99], v[156:157]
	v_pk_mul_f32 v[98:99], v[90:91], v[160:161]
	v_pk_mul_f32 v[90:91], v[88:89], v[158:159]
	v_lshl_add_u64 v[92:93], v[92:93], 0, v[144:145]
	v_cvt_pk_bf16_f32 v88, v96, v97
	v_cvt_pk_bf16_f32 v89, v94, v95
	v_cvt_pk_bf16_f32 v90, v90, v91
	v_cvt_pk_bf16_f32 v91, v98, v99
	global_store_dwordx4 v[92:93], v[88:91], off
	v_pk_mul_f32 v[20:21], v[20:21], v[132:133]
	v_pk_mul_f32 v[6:7], v[6:7], v[134:135]
	v_or_b32_e32 v88, s5, v100
	v_ashrrev_i32_e32 v89, 31, v88
	v_lshlrev_b64 v[88:89], 7, v[88:89]
	v_lshl_add_u64 v[88:89], s[8:9], 0, v[88:89]
	v_pk_mul_f32 v[90:91], v[78:79], v[130:131]
	v_pk_mul_f32 v[78:79], v[76:77], v[128:129]
	v_lshl_add_u64 v[88:89], v[88:89], 0, v[144:145]
	v_cvt_pk_bf16_f32 v76, v84, v85
	v_cvt_pk_bf16_f32 v77, v86, v87
	v_cvt_pk_bf16_f32 v78, v78, v79
	v_cvt_pk_bf16_f32 v79, v90, v91
	v_or_b32_e32 v84, 48, v171
	global_store_dwordx4 v[88:89], v[76:79], off
	v_pk_mul_f32 v[4:5], v[4:5], v[132:133]
	s_nop 0
	v_or_b32_e32 v76, s4, v84
	v_ashrrev_i32_e32 v77, 31, v76
	v_lshlrev_b64 v[76:77], 7, v[76:77]
	v_lshl_add_u64 v[76:77], s[8:9], 0, v[76:77]
	v_pk_mul_f32 v[78:79], v[82:83], v[156:157]
	v_pk_mul_f32 v[82:83], v[74:75], v[160:161]
	v_pk_mul_f32 v[74:75], v[72:73], v[158:159]
	v_lshl_add_u64 v[76:77], v[76:77], 0, v[144:145]
	v_cvt_pk_bf16_f32 v72, v80, v81
	v_cvt_pk_bf16_f32 v73, v78, v79
	v_cvt_pk_bf16_f32 v74, v74, v75
	v_cvt_pk_bf16_f32 v75, v82, v83
	global_store_dwordx4 v[76:77], v[72:75], off
	s_nop 1
	v_or_b32_e32 v72, s5, v84
	v_ashrrev_i32_e32 v73, 31, v72
	v_lshlrev_b64 v[72:73], 7, v[72:73]
	v_lshl_add_u64 v[72:73], s[8:9], 0, v[72:73]
	s_bfe_u32 s8, s6, 0x20008
	s_or_b32 s7, s8, s7
	s_lshl_b32 s7, s7, 15
	s_and_b32 s8, s6, 0xc0
	v_pk_mul_f32 v[74:75], v[66:67], v[130:131]
	v_pk_mul_f32 v[66:67], v[64:65], v[128:129]
	s_or_b32 s7, s7, s8
	v_lshl_add_u64 v[72:73], v[72:73], 0, v[144:145]
	v_cvt_pk_bf16_f32 v64, v68, v69
	v_cvt_pk_bf16_f32 v65, v70, v71
	v_cvt_pk_bf16_f32 v66, v66, v67
	v_cvt_pk_bf16_f32 v67, v74, v75
	v_or_b32_e32 v68, s7, v164
	global_store_dwordx4 v[72:73], v[64:67], off
	s_cmpk_lt_u32 s6, 0x400
	s_cselect_b32 s9, s53, s91
	v_or_b32_e32 v64, s4, v68
; DI unsigned pk_bf16(float lo, float hi) { f32x2 v = {lo, hi}; return __builtin_bit_cast(unsigned, __builtin_convertvector(v, bf16v2)); }
; #define PG8_WAIT_V(n) asm volatile("s_waitcnt vmcnt(" #n ")" ::: "memory")
; #define PG8_BAR __builtin_amdgcn_s_barrier()
; #define PG8_WAIT_V(n) asm volatile("s_waitcnt vmcnt(" #n ")" ::: "memory")
; #define PG8_BAR __builtin_amdgcn_s_barrier()
; template <class Epi>
; DI void gemm_phase(LAS unsigned char* lds, const Gemm g, const StaticOrder S, const Epi E) {
;     ...
;         if (!has_next) break;
; #pragma unroll
;         for (int a = 0; a < 2; ++a)
; #pragma unroll
;             for (int b = 0; b < 2; ++b)
; #pragma unroll
;                 for (int m = 0; m < 4; ++m)
; #pragma unroll
;                     for (int n = 0; n < 2; ++n) acc[a][b][m][n] = (f32x4){0.f, 0.f, 0.f, 0.f};
;         cur = nxt; cA = nA; cB = nB; ++ui;
;     }
;     PG8_WAIT_V(0);
;     if (wr == 0) PG8_BAR;
;     DI void operator()(AccRef acc, const Unit& u, int wr, int wc, int fr, int fq) const {
;     ...
;             for (int m = 0; m < 4; ++m) {
;                 const int R = u.pm * 256 + ai * 128 + wr * 64 + m * 16 + fr, X = R >> 10, hv = R & 1023;
; #pragma unroll
;                 for (int bj = 0; bj < 2; ++bj) {
;                     const int tok = u.pn * 256 + bj * 128 + wc * 32 + 8 * fq, b = tok >> 13, s = tok & (SEQ - 1);
;                     bf16_t* dst = (X ? vtB : vtA) + ((size_t)(((b * 4 + (hv >> 8)) * 128 + (s >> 6)) * 256 + (hv & 255))) * 64 + (s & 63);
;                     const f32x4 v0 = acc[ai][bj][m][0] * ts[bj][0], v1 = acc[ai][bj][m][1] * ts[bj][1];
;                     u32x4 w; w.x = pk_bf16(v0[0], v0[1]); w.y = pk_bf16(v0[2], v0[3]); w.z = pk_bf16(v1[0], v1[1]); w.w = pk_bf16(v1[2], v1[3]);
;                     *(u32x4*)dst = w;
	v_ashrrev_i32_e32 v65, 31, v64
	s_cselect_b32 s8, s52, s90
	v_lshlrev_b64 v[64:65], 7, v[64:65]
	v_lshl_add_u64 v[64:65], s[8:9], 0, v[64:65]
	v_pk_mul_f32 v[66:67], v[58:59], v[160:161]
	v_pk_mul_f32 v[58:59], v[56:57], v[158:159]
	v_lshl_add_u64 v[64:65], v[64:65], 0, v[144:145]
	v_cvt_pk_bf16_f32 v56, v60, v61
	v_cvt_pk_bf16_f32 v57, v62, v63
	v_cvt_pk_bf16_f32 v58, v58, v59
	v_cvt_pk_bf16_f32 v59, v66, v67
	global_store_dwordx4 v[64:65], v[56:59], off
	s_and_b64 vcc, exec, s[0:1]
	s_nop 0
	v_or_b32_e32 v56, s5, v68
	v_ashrrev_i32_e32 v57, 31, v56
	v_lshlrev_b64 v[56:57], 7, v[56:57]
	v_lshl_add_u64 v[56:57], s[8:9], 0, v[56:57]
	v_pk_mul_f32 v[58:59], v[46:47], v[130:131]
	v_pk_mul_f32 v[46:47], v[44:45], v[128:129]
	v_lshl_add_u64 v[56:57], v[56:57], 0, v[144:145]
	v_cvt_pk_bf16_f32 v44, v52, v53
	v_cvt_pk_bf16_f32 v45, v54, v55
	v_cvt_pk_bf16_f32 v46, v46, v47
	v_cvt_pk_bf16_f32 v47, v58, v59
	v_or_b32_e32 v52, 16, v68
	global_store_dwordx4 v[56:57], v[44:47], off
	s_nop 1
	v_or_b32_e32 v44, s4, v52
	v_ashrrev_i32_e32 v45, 31, v44
	v_lshlrev_b64 v[44:45], 7, v[44:45]
	v_lshl_add_u64 v[44:45], s[8:9], 0, v[44:45]
	v_pk_mul_f32 v[46:47], v[50:51], v[156:157]
	v_pk_mul_f32 v[50:51], v[42:43], v[160:161]
	v_pk_mul_f32 v[42:43], v[40:41], v[158:159]
	v_lshl_add_u64 v[44:45], v[44:45], 0, v[144:145]
	v_cvt_pk_bf16_f32 v40, v48, v49
	v_cvt_pk_bf16_f32 v41, v46, v47
	v_cvt_pk_bf16_f32 v42, v42, v43
	v_cvt_pk_bf16_f32 v43, v50, v51
	global_store_dwordx4 v[44:45], v[40:43], off
	s_nop 1
	v_or_b32_e32 v40, s5, v52
	v_ashrrev_i32_e32 v41, 31, v40
	v_lshlrev_b64 v[40:41], 7, v[40:41]
	v_lshl_add_u64 v[40:41], s[8:9], 0, v[40:41]
	v_pk_mul_f32 v[42:43], v[30:31], v[130:131]
	v_pk_mul_f32 v[30:31], v[28:29], v[128:129]
	v_lshl_add_u64 v[40:41], v[40:41], 0, v[144:145]
	v_cvt_pk_bf16_f32 v28, v36, v37
	v_cvt_pk_bf16_f32 v29, v38, v39
	v_cvt_pk_bf16_f32 v30, v30, v31
	v_cvt_pk_bf16_f32 v31, v42, v43
	v_or_b32_e32 v36, 32, v68
	global_store_dwordx4 v[40:41], v[28:31], off
	s_nop 1
	v_or_b32_e32 v28, s4, v36
	v_ashrrev_i32_e32 v29, 31, v28
	v_lshlrev_b64 v[28:29], 7, v[28:29]
	v_lshl_add_u64 v[28:29], s[8:9], 0, v[28:29]
	v_pk_mul_f32 v[30:31], v[34:35], v[156:157]
	v_pk_mul_f32 v[34:35], v[26:27], v[160:161]
	v_pk_mul_f32 v[26:27], v[24:25], v[158:159]
	v_lshl_add_u64 v[28:29], v[28:29], 0, v[144:145]
	v_cvt_pk_bf16_f32 v24, v32, v33
	v_cvt_pk_bf16_f32 v25, v30, v31
	v_cvt_pk_bf16_f32 v26, v26, v27
	v_cvt_pk_bf16_f32 v27, v34, v35
	global_store_dwordx4 v[28:29], v[24:27], off
	s_nop 1
	v_or_b32_e32 v24, s5, v36
	v_ashrrev_i32_e32 v25, 31, v24
	v_lshlrev_b64 v[24:25], 7, v[24:25]
	v_lshl_add_u64 v[24:25], s[8:9], 0, v[24:25]
	v_pk_mul_f32 v[26:27], v[14:15], v[130:131]
	v_pk_mul_f32 v[14:15], v[12:13], v[128:129]
	v_lshl_add_u64 v[24:25], v[24:25], 0, v[144:145]
	v_cvt_pk_bf16_f32 v12, v20, v21
	v_cvt_pk_bf16_f32 v13, v22, v23
	v_cvt_pk_bf16_f32 v14, v14, v15
	v_cvt_pk_bf16_f32 v15, v26, v27
	v_or_b32_e32 v20, 48, v68
	global_store_dwordx4 v[24:25], v[12:15], off
	s_nop 1
	v_or_b32_e32 v12, s4, v20
	v_ashrrev_i32_e32 v13, 31, v12
	v_lshlrev_b64 v[12:13], 7, v[12:13]
	v_lshl_add_u64 v[12:13], s[8:9], 0, v[12:13]
	v_pk_mul_f32 v[14:15], v[18:19], v[156:157]
	v_pk_mul_f32 v[18:19], v[10:11], v[160:161]
	v_pk_mul_f32 v[10:11], v[8:9], v[158:159]
	v_lshl_add_u64 v[12:13], v[12:13], 0, v[144:145]
	v_cvt_pk_bf16_f32 v8, v16, v17
	v_cvt_pk_bf16_f32 v9, v14, v15
	v_cvt_pk_bf16_f32 v10, v10, v11
	v_cvt_pk_bf16_f32 v11, v18, v19
	global_store_dwordx4 v[12:13], v[8:11], off
	s_nop 1
	v_or_b32_e32 v8, s5, v20
	v_ashrrev_i32_e32 v9, 31, v8
	v_lshlrev_b64 v[8:9], 7, v[8:9]
	v_lshl_add_u64 v[8:9], s[8:9], 0, v[8:9]
	v_pk_mul_f32 v[10:11], v[2:3], v[130:131]
	v_pk_mul_f32 v[2:3], v[0:1], v[128:129]
	v_lshl_add_u64 v[8:9], v[8:9], 0, v[144:145]
	v_cvt_pk_bf16_f32 v0, v4, v5
	v_cvt_pk_bf16_f32 v1, v6, v7
	v_cvt_pk_bf16_f32 v2, v2, v3
	v_cvt_pk_bf16_f32 v3, v10, v11
	s_mov_b64 s[8:9], s[24:25]
	global_store_dwordx4 v[8:9], v[0:3], off
	s_cbranch_vccz .LBB0_291
	s_waitcnt vmcnt(0)
	s_cmpk_gt_u32 s17, 0xff
	s_cbranch_scc1 .LBB0_302
	s_barrier

; #define PG8_STAGE(bufoff, gbase, voff) do { _Pragma("unroll") for (int _i = 0; _i < 2; ++_i) \
;         __builtin_amdgcn_global_load_lds((const unsigned*)((const char*)(gbase) + (voff)[_i]), (LAS unsigned*)(lds + (bufoff) + ldsw + _i * 8192), 16, 0, 0); } while (0)
; #define PG8_LDA(dst, b, h) do { _Pragma("unroll") for (int m = 0; m < 4; ++m) _Pragma("unroll") for (int k = 0; k < 2; ++k) dst[m][k] = *(const LAS bf16x8*)(lds + PG8_SA(b, h) + aoff + m * 2048 + k * 1024); } while (0)
; #define PG8_LDB(dst, b, h) do { _Pragma("unroll") for (int n = 0; n < 2; ++n) _Pragma("unroll") for (int k = 0; k < 2; ++k) dst[n][k] = *(const LAS bf16x8*)(lds + PG8_SB(b, h) + boff + n * 2048 + k * 1024); } while (0)
; #define PG8_MMA(ai, bj, At, Bt) do { __builtin_amdgcn_s_setprio(1); _Pragma("unroll") for (int m = 0; m < 4; ++m) _Pragma("unroll") for (int n = 0; n < 2; ++n) _Pragma("unroll") for (int k = 0; k < 2; ++k) \
;         acc[ai][bj][m][n] = __builtin_amdgcn_mfma_f32_16x16x32_bf16(Bt[n][k], At[m][k], acc[ai][bj][m][n], 0, 0, 0); __builtin_amdgcn_s_setprio(0); } while (0)
; #define PG8_WAIT_L(n) asm volatile("s_waitcnt lgkmcnt(" #n ")" ::: "memory")
; #define PG8_BAR __builtin_amdgcn_s_barrier()
; #define PG8_SCHED __builtin_amdgcn_sched_barrier(0)
; #define PG8_STAGE(bufoff, gbase, voff) do { _Pragma("unroll") for (int _i = 0; _i < 2; ++_i) \
;         __builtin_amdgcn_global_load_lds((const unsigned*)((const char*)(gbase) + (voff)[_i]), (LAS unsigned*)(lds + (bufoff) + ldsw + _i * 8192), 16, 0, 0); } while (0)
; #define PG8_WAIT_L(n) asm volatile("s_waitcnt lgkmcnt(" #n ")" ::: "memory")
; #define PG8_BAR __builtin_amdgcn_s_barrier()
; #define PG8_SCHED __builtin_amdgcn_sched_barrier(0)
; template <class Epi0, class Epi1>
; DI void gemm_phase_dual(LAS unsigned char* lds, const Gemm g, const Gemm g1, const StaticOrder S, const Epi0 E0, const Epi1 E1) {
;     ...
;             PG8_LDB(B0, 0, 0); PG8_SCHED; PG8_LDA(At, 0, 0); PG8_STAGE(PG8_SA(1, 1), a1 + hstep, voffA);
;             PG8_WAIT_L(8); PG8_BAR; PG8_WAIT_L(0); PG8_MMA(0, 0, At, B0); PG8_BAR; PG8_SCHED;
;             PG8_LDB(B1, 0, 1); PG8_STAGE(PG8_SB(0, 0), b2, voffB);
;             PG8_BAR; PG8_WAIT_L(0); PG8_MMA(0, 1, At, B1); PG8_BAR;
;             PG8_LDA(At, 0, 1); PG8_STAGE(PG8_SA(0, 0), a2, voffA);
;             PG8_BAR; PG8_WAIT_L(0); PG8_MMA(1, 0, At, B0); PG8_BAR; PG8_SCHED;
.LBB0_632:
	ds_read_b128 v[128:131], v181
	ds_read_b128 v[132:135], v181 offset:1024
	ds_read_b128 v[136:139], v181 offset:2048
	ds_read_b128 v[140:143], v181 offset:3072
	s_add_u32 s12, s10, 0xfffc0080
	s_addc_u32 s13, s11, -1
	s_cmp_eq_u32 s19, 12
	s_cselect_b32 s15, s1, s13
	s_cselect_b32 s14, s6, s12
	s_cselect_b32 s13, s7, s18
	s_cselect_b32 s12, s16, s17
	v_lshl_add_u64 v[190:191], s[10:11], 0, v[168:169]
	s_add_i32 m0, s49, 0xc000
	ds_read_b128 v[144:147], v183
	ds_read_b128 v[152:155], v183 offset:2048
	ds_read_b128 v[194:197], v183 offset:4096
	ds_read_b128 v[202:205], v183 offset:6144
	global_load_lds_dwordx4 v[190:191], off
	v_lshl_add_u64 v[190:191], s[10:11], 0, v[170:171]
	s_add_i32 m0, s49, 0xe000
	s_nop 0
	global_load_lds_dwordx4 v[190:191], off
	s_waitcnt lgkmcnt(4)
	s_setprio 1
	s_barrier
	s_waitcnt lgkmcnt(0)
	v_mfma_f32_16x16x32_bf16 v[124:127], v[128:131], v[144:147], v[124:127]
	ds_read_b128 v[148:151], v183 offset:1024
	v_mfma_f32_16x16x32_bf16 v[120:123], v[136:139], v[144:147], v[120:123]
	ds_read_b128 v[184:187], v183 offset:3072
	v_mfma_f32_16x16x32_bf16 v[108:111], v[128:131], v[152:155], v[108:111]
	ds_read_b128 v[198:201], v183 offset:5120
	v_mfma_f32_16x16x32_bf16 v[104:107], v[136:139], v[152:155], v[104:107]
	ds_read_b128 v[206:209], v183 offset:7168
	v_mfma_f32_16x16x32_bf16 v[92:95], v[128:131], v[194:197], v[92:95]
	v_mfma_f32_16x16x32_bf16 v[88:91], v[136:139], v[194:197], v[88:91]
	v_mfma_f32_16x16x32_bf16 v[76:79], v[128:131], v[202:205], v[76:79]
	v_mfma_f32_16x16x32_bf16 v[72:75], v[136:139], v[202:205], v[72:75]
	s_waitcnt lgkmcnt(3)
	v_mfma_f32_16x16x32_bf16 v[124:127], v[132:135], v[148:151], v[124:127]
	v_mfma_f32_16x16x32_bf16 v[120:123], v[140:143], v[148:151], v[120:123]
	s_waitcnt lgkmcnt(2)
	v_mfma_f32_16x16x32_bf16 v[108:111], v[132:135], v[184:187], v[108:111]
	v_mfma_f32_16x16x32_bf16 v[104:107], v[140:143], v[184:187], v[104:107]
	s_waitcnt lgkmcnt(1)
	v_mfma_f32_16x16x32_bf16 v[92:95], v[132:135], v[198:201], v[92:95]
	v_mfma_f32_16x16x32_bf16 v[88:91], v[140:143], v[198:201], v[88:91]
	s_waitcnt lgkmcnt(0)
	s_setprio 2
	s_barrier
	v_mfma_f32_16x16x32_bf16 v[76:79], v[132:135], v[206:209], v[76:79]
	v_mfma_f32_16x16x32_bf16 v[72:75], v[140:143], v[206:209], v[72:75]
	s_setprio 0
	s_add_i32 s41, s78, s48
	v_lshl_add_u64 v[190:191], s[12:13], 0, v[158:159]
	s_mov_b32 m0, s41
	ds_read_b128 v[210:213], v189
	ds_read_b128 v[214:217], v189 offset:1024
	ds_read_b128 v[218:221], v189 offset:2048
	ds_read_b128 v[224:227], v189 offset:3072
	global_load_lds_dwordx4 v[190:191], off
	v_lshl_add_u64 v[228:229], s[12:13], 0, v[162:163]
	s_add_i32 m0, s41, 0x2000
	s_nop 0
	global_load_lds_dwordx4 v[228:229], off
	s_setprio 1
	s_barrier
	s_waitcnt lgkmcnt(0)
	v_mfma_f32_16x16x32_bf16 v[116:119], v[210:213], v[144:147], v[116:119]
	v_mfma_f32_16x16x32_bf16 v[112:115], v[218:221], v[144:147], v[112:115]
	v_mfma_f32_16x16x32_bf16 v[100:103], v[210:213], v[152:155], v[100:103]
	v_mfma_f32_16x16x32_bf16 v[96:99], v[218:221], v[152:155], v[96:99]
	v_mfma_f32_16x16x32_bf16 v[84:87], v[210:213], v[194:197], v[84:87]
	v_mfma_f32_16x16x32_bf16 v[80:83], v[218:221], v[194:197], v[80:83]
	v_mfma_f32_16x16x32_bf16 v[68:71], v[210:213], v[202:205], v[68:71]
	v_mfma_f32_16x16x32_bf16 v[64:67], v[218:221], v[202:205], v[64:67]
	v_mfma_f32_16x16x32_bf16 v[116:119], v[214:217], v[148:151], v[116:119]
	v_mfma_f32_16x16x32_bf16 v[112:115], v[224:227], v[148:151], v[112:115]
	v_mfma_f32_16x16x32_bf16 v[100:103], v[214:217], v[184:187], v[100:103]
	v_mfma_f32_16x16x32_bf16 v[96:99], v[224:227], v[184:187], v[96:99]
	v_mfma_f32_16x16x32_bf16 v[84:87], v[214:217], v[198:201], v[84:87]
	v_mfma_f32_16x16x32_bf16 v[80:83], v[224:227], v[198:201], v[80:83]
	s_setprio 2
	s_barrier
	v_mfma_f32_16x16x32_bf16 v[68:71], v[214:217], v[206:209], v[68:71]
	v_mfma_f32_16x16x32_bf16 v[64:67], v[224:227], v[206:209], v[64:67]
	s_setprio 0
	s_mov_b32 m0, s49
	v_lshl_add_u64 v[230:231], s[14:15], 0, v[156:157]
	ds_read_b128 v[144:147], v183 offset:16384
	ds_read_b128 v[152:155], v183 offset:18432
	ds_read_b128 v[194:197], v183 offset:20480
	ds_read_b128 v[202:205], v183 offset:22528
	global_load_lds_dwordx4 v[230:231], off
	v_lshl_add_u64 v[232:233], s[14:15], 0, v[160:161]
	s_mov_b32 m0, s50
	s_nop 0
	global_load_lds_dwordx4 v[232:233], off
	s_setprio 1
	s_barrier
	s_waitcnt lgkmcnt(0)
	v_mfma_f32_16x16x32_bf16 v[60:63], v[128:131], v[144:147], v[60:63]
	ds_read_b128 v[148:151], v183 offset:17408
	v_mfma_f32_16x16x32_bf16 v[56:59], v[136:139], v[144:147], v[56:59]
	ds_read_b128 v[184:187], v183 offset:19456
	v_mfma_f32_16x16x32_bf16 v[44:47], v[128:131], v[152:155], v[44:47]
	ds_read_b128 v[198:201], v183 offset:21504
	v_mfma_f32_16x16x32_bf16 v[40:43], v[136:139], v[152:155], v[40:43]
	ds_read_b128 v[206:209], v183 offset:23552
	v_mfma_f32_16x16x32_bf16 v[28:31], v[128:131], v[194:197], v[28:31]
	v_mfma_f32_16x16x32_bf16 v[24:27], v[136:139], v[194:197], v[24:27]
	v_mfma_f32_16x16x32_bf16 v[12:15], v[128:131], v[202:205], v[12:15]
	v_mfma_f32_16x16x32_bf16 v[8:11], v[136:139], v[202:205], v[8:11]
	s_waitcnt lgkmcnt(3)
	v_mfma_f32_16x16x32_bf16 v[60:63], v[132:135], v[148:151], v[60:63]
	v_mfma_f32_16x16x32_bf16 v[56:59], v[140:143], v[148:151], v[56:59]
	s_waitcnt lgkmcnt(2)
	v_mfma_f32_16x16x32_bf16 v[44:47], v[132:135], v[184:187], v[44:47]
	v_mfma_f32_16x16x32_bf16 v[40:43], v[140:143], v[184:187], v[40:43]
	s_waitcnt lgkmcnt(1)
	v_mfma_f32_16x16x32_bf16 v[28:31], v[132:135], v[198:201], v[28:31]
	v_mfma_f32_16x16x32_bf16 v[24:27], v[140:143], v[198:201], v[24:27]
	s_waitcnt lgkmcnt(0)
	s_setprio 2
	s_barrier
; #define PG8_STAGE(bufoff, gbase, voff) do { _Pragma("unroll") for (int _i = 0; _i < 2; ++_i) \
;         __builtin_amdgcn_global_load_lds((const unsigned*)((const char*)(gbase) + (voff)[_i]), (LAS unsigned*)(lds + (bufoff) + ldsw + _i * 8192), 16, 0, 0); } while (0)
; #define PG8_LDA(dst, b, h) do { _Pragma("unroll") for (int m = 0; m < 4; ++m) _Pragma("unroll") for (int k = 0; k < 2; ++k) dst[m][k] = *(const LAS bf16x8*)(lds + PG8_SA(b, h) + aoff + m * 2048 + k * 1024); } while (0)
; #define PG8_LDB(dst, b, h) do { _Pragma("unroll") for (int n = 0; n < 2; ++n) _Pragma("unroll") for (int k = 0; k < 2; ++k) dst[n][k] = *(const LAS bf16x8*)(lds + PG8_SB(b, h) + boff + n * 2048 + k * 1024); } while (0)
; #define PG8_MMA(ai, bj, At, Bt) do { __builtin_amdgcn_s_setprio(1); _Pragma("unroll") for (int m = 0; m < 4; ++m) _Pragma("unroll") for (int n = 0; n < 2; ++n) _Pragma("unroll") for (int k = 0; k < 2; ++k) \
;         acc[ai][bj][m][n] = __builtin_amdgcn_mfma_f32_16x16x32_bf16(Bt[n][k], At[m][k], acc[ai][bj][m][n], 0, 0, 0); __builtin_amdgcn_s_setprio(0); } while (0)
; #define PG8_WAIT_V(n) asm volatile("s_waitcnt vmcnt(" #n ")" ::: "memory")
; #define PG8_WAIT_L(n) asm volatile("s_waitcnt lgkmcnt(" #n ")" ::: "memory")
; #define PG8_BAR __builtin_amdgcn_s_barrier()
; #define PG8_SCHED __builtin_amdgcn_sched_barrier(0)
; #define PG8_STAGE(bufoff, gbase, voff) do { _Pragma("unroll") for (int _i = 0; _i < 2; ++_i) \
;         __builtin_amdgcn_global_load_lds((const unsigned*)((const char*)(gbase) + (voff)[_i]), (LAS unsigned*)(lds + (bufoff) + ldsw + _i * 8192), 16, 0, 0); } while (0)
; #define PG8_BAR __builtin_amdgcn_s_barrier()
; template <class Epi0, class Epi1>
; DI void gemm_phase_dual(LAS unsigned char* lds, const Gemm g, const Gemm g1, const StaticOrder S, const Epi0 E0, const Epi1 E1) {
;     ...
;             PG8_BAR; PG8_WAIT_L(0); PG8_MMA(1, 0, At, B0); PG8_BAR; PG8_SCHED;
;             PG8_STAGE(PG8_SB(0, 1), b2 + hstep, voffB);
;             PG8_WAIT_V(6); PG8_BAR; PG8_MMA(1, 1, At, B1); PG8_BAR;
;             PG8_LDB(B0, 1, 0); PG8_SCHED; PG8_LDA(At, 1, 0); PG8_STAGE(PG8_SA(0, 1), a2 + hstep, voffA);
;             PG8_WAIT_L(8); PG8_BAR; PG8_WAIT_L(0); PG8_MMA(0, 0, At, B0); PG8_BAR; PG8_SCHED;
;             PG8_LDB(B1, 1, 1); PG8_STAGE(PG8_SB(1, 0), b3, voffB);
;             PG8_BAR; PG8_WAIT_L(0); PG8_MMA(0, 1, At, B1); PG8_BAR;
	v_mfma_f32_16x16x32_bf16 v[12:15], v[132:135], v[206:209], v[12:15]
	v_mfma_f32_16x16x32_bf16 v[8:11], v[140:143], v[206:209], v[8:11]
	s_setprio 0
	s_add_u32 s90, s12, 0x40000
	s_addc_u32 s91, s13, 0
	s_add_i32 s41, s79, s48
	v_lshl_add_u64 v[128:129], s[90:91], 0, v[158:159]
	s_mov_b32 m0, s41
	s_nop 0
	global_load_lds_dwordx4 v[128:129], off
	v_lshl_add_u64 v[128:129], s[90:91], 0, v[162:163]
	s_add_i32 m0, s41, 0x2000
	s_nop 0
	global_load_lds_dwordx4 v[128:129], off
	s_waitcnt vmcnt(6)
	s_setprio 1
	s_barrier
	v_mfma_f32_16x16x32_bf16 v[52:55], v[210:213], v[144:147], v[52:55]
	v_mfma_f32_16x16x32_bf16 v[48:51], v[218:221], v[144:147], v[48:51]
	v_mfma_f32_16x16x32_bf16 v[36:39], v[210:213], v[152:155], v[36:39]
	v_mfma_f32_16x16x32_bf16 v[32:35], v[218:221], v[152:155], v[32:35]
	v_mfma_f32_16x16x32_bf16 v[20:23], v[210:213], v[194:197], v[20:23]
	v_mfma_f32_16x16x32_bf16 v[16:19], v[218:221], v[194:197], v[16:19]
	v_mfma_f32_16x16x32_bf16 v[4:7], v[210:213], v[202:205], v[4:7]
	v_mfma_f32_16x16x32_bf16 v[0:3], v[218:221], v[202:205], v[0:3]
	v_mfma_f32_16x16x32_bf16 v[52:55], v[214:217], v[148:151], v[52:55]
	v_mfma_f32_16x16x32_bf16 v[48:51], v[224:227], v[148:151], v[48:51]
	v_mfma_f32_16x16x32_bf16 v[36:39], v[214:217], v[184:187], v[36:39]
	v_mfma_f32_16x16x32_bf16 v[32:35], v[224:227], v[184:187], v[32:35]
	v_mfma_f32_16x16x32_bf16 v[20:23], v[214:217], v[198:201], v[20:23]
	v_mfma_f32_16x16x32_bf16 v[16:19], v[224:227], v[198:201], v[16:19]
	s_setprio 2
	s_barrier
	v_mfma_f32_16x16x32_bf16 v[4:7], v[214:217], v[206:209], v[4:7]
	v_mfma_f32_16x16x32_bf16 v[0:3], v[224:227], v[206:209], v[0:3]
	s_setprio 0
	s_add_i32 s41, 0, 0x18000
	v_add_u32_e32 v140, s41, v179
	ds_read_b128 v[128:131], v140
	ds_read_b128 v[132:135], v140 offset:1024
	ds_read_b128 v[136:139], v140 offset:2048
	ds_read_b128 v[140:143], v140 offset:3072
	s_add_u32 s14, s14, 0x40000
	s_addc_u32 s15, s15, 0
	s_mov_b32 m0, s51
	v_lshl_add_u64 v[210:211], s[14:15], 0, v[156:157]
	ds_read_b128 v[144:147], v183 offset:32768
	ds_read_b128 v[152:155], v183 offset:34816
	ds_read_b128 v[194:197], v183 offset:36864
	ds_read_b128 v[202:205], v183 offset:38912
	global_load_lds_dwordx4 v[210:211], off
	v_lshl_add_u64 v[210:211], s[14:15], 0, v[160:161]
	s_mov_b32 m0, s58
	s_nop 0
	global_load_lds_dwordx4 v[210:211], off
	s_waitcnt lgkmcnt(4)
	s_setprio 1
	s_barrier
	s_waitcnt lgkmcnt(0)
	v_mfma_f32_16x16x32_bf16 v[124:127], v[128:131], v[144:147], v[124:127]
	ds_read_b128 v[148:151], v183 offset:33792
	v_mfma_f32_16x16x32_bf16 v[120:123], v[136:139], v[144:147], v[120:123]
	ds_read_b128 v[184:187], v183 offset:35840
	v_mfma_f32_16x16x32_bf16 v[108:111], v[128:131], v[152:155], v[108:111]
	ds_read_b128 v[198:201], v183 offset:37888
	v_mfma_f32_16x16x32_bf16 v[104:107], v[136:139], v[152:155], v[104:107]
	ds_read_b128 v[206:209], v183 offset:39936
	v_mfma_f32_16x16x32_bf16 v[92:95], v[128:131], v[194:197], v[92:95]
	v_mfma_f32_16x16x32_bf16 v[88:91], v[136:139], v[194:197], v[88:91]
	v_mfma_f32_16x16x32_bf16 v[76:79], v[128:131], v[202:205], v[76:79]
	v_mfma_f32_16x16x32_bf16 v[72:75], v[136:139], v[202:205], v[72:75]
	s_waitcnt lgkmcnt(3)
	v_mfma_f32_16x16x32_bf16 v[124:127], v[132:135], v[148:151], v[124:127]
	v_mfma_f32_16x16x32_bf16 v[120:123], v[140:143], v[148:151], v[120:123]
	s_waitcnt lgkmcnt(2)
	v_mfma_f32_16x16x32_bf16 v[108:111], v[132:135], v[184:187], v[108:111]
	v_mfma_f32_16x16x32_bf16 v[104:107], v[140:143], v[184:187], v[104:107]
	s_waitcnt lgkmcnt(1)
	v_mfma_f32_16x16x32_bf16 v[92:95], v[132:135], v[198:201], v[92:95]
	v_mfma_f32_16x16x32_bf16 v[88:91], v[140:143], v[198:201], v[88:91]
	s_waitcnt lgkmcnt(0)
	s_setprio 2
	s_barrier
	v_mfma_f32_16x16x32_bf16 v[76:79], v[132:135], v[206:209], v[76:79]
	v_mfma_f32_16x16x32_bf16 v[72:75], v[140:143], v[206:209], v[72:75]
	s_setprio 0
	s_add_i32 s14, 0, 0x1c000
	s_add_i32 s15, s41, s48
	v_add_u32_e32 v176, s14, v179
	v_lshl_add_u64 v[190:191], v[190:191], 0, s[22:23]
	s_mov_b32 m0, s15
	ds_read_b128 v[210:213], v176
	ds_read_b128 v[214:217], v176 offset:1024
	ds_read_b128 v[218:221], v176 offset:2048
	ds_read_b128 v[224:227], v176 offset:3072
	global_load_lds_dwordx4 v[190:191], off
	v_lshl_add_u64 v[190:191], v[228:229], 0, s[22:23]
	s_add_i32 m0, s15, 0x2000
	s_nop 0
	global_load_lds_dwordx4 v[190:191], off
	s_setprio 1
	s_barrier
	s_waitcnt lgkmcnt(0)
	v_mfma_f32_16x16x32_bf16 v[116:119], v[210:213], v[144:147], v[116:119]
	v_mfma_f32_16x16x32_bf16 v[112:115], v[218:221], v[144:147], v[112:115]
	v_mfma_f32_16x16x32_bf16 v[100:103], v[210:213], v[152:155], v[100:103]
	v_mfma_f32_16x16x32_bf16 v[96:99], v[218:221], v[152:155], v[96:99]
	v_mfma_f32_16x16x32_bf16 v[84:87], v[210:213], v[194:197], v[84:87]
	v_mfma_f32_16x16x32_bf16 v[80:83], v[218:221], v[194:197], v[80:83]
	v_mfma_f32_16x16x32_bf16 v[68:71], v[210:213], v[202:205], v[68:71]
	v_mfma_f32_16x16x32_bf16 v[64:67], v[218:221], v[202:205], v[64:67]
	v_mfma_f32_16x16x32_bf16 v[116:119], v[214:217], v[148:151], v[116:119]
	v_mfma_f32_16x16x32_bf16 v[112:115], v[224:227], v[148:151], v[112:115]
	v_mfma_f32_16x16x32_bf16 v[100:103], v[214:217], v[184:187], v[100:103]
	v_mfma_f32_16x16x32_bf16 v[96:99], v[224:227], v[184:187], v[96:99]
	v_mfma_f32_16x16x32_bf16 v[84:87], v[214:217], v[198:201], v[84:87]
	v_mfma_f32_16x16x32_bf16 v[80:83], v[224:227], v[198:201], v[80:83]
	s_setprio 2
	s_barrier
; #define PG8_STAGE(bufoff, gbase, voff) do { _Pragma("unroll") for (int _i = 0; _i < 2; ++_i) \
;         __builtin_amdgcn_global_load_lds((const unsigned*)((const char*)(gbase) + (voff)[_i]), (LAS unsigned*)(lds + (bufoff) + ldsw + _i * 8192), 16, 0, 0); } while (0)
; #define PG8_LDA(dst, b, h) do { _Pragma("unroll") for (int m = 0; m < 4; ++m) _Pragma("unroll") for (int k = 0; k < 2; ++k) dst[m][k] = *(const LAS bf16x8*)(lds + PG8_SA(b, h) + aoff + m * 2048 + k * 1024); } while (0)
; #define PG8_MMA(ai, bj, At, Bt) do { __builtin_amdgcn_s_setprio(1); _Pragma("unroll") for (int m = 0; m < 4; ++m) _Pragma("unroll") for (int n = 0; n < 2; ++n) _Pragma("unroll") for (int k = 0; k < 2; ++k) \
;         acc[ai][bj][m][n] = __builtin_amdgcn_mfma_f32_16x16x32_bf16(Bt[n][k], At[m][k], acc[ai][bj][m][n], 0, 0, 0); __builtin_amdgcn_s_setprio(0); } while (0)
; #define PG8_WAIT_V(n) asm volatile("s_waitcnt vmcnt(" #n ")" ::: "memory")
; #define PG8_WAIT_L(n) asm volatile("s_waitcnt lgkmcnt(" #n ")" ::: "memory")
; #define PG8_BAR __builtin_amdgcn_s_barrier()
; #define PG8_SCHED __builtin_amdgcn_sched_barrier(0)
; #define PG8_STAGE(bufoff, gbase, voff) do { _Pragma("unroll") for (int _i = 0; _i < 2; ++_i) \
;         __builtin_amdgcn_global_load_lds((const unsigned*)((const char*)(gbase) + (voff)[_i]), (LAS unsigned*)(lds + (bufoff) + ldsw + _i * 8192), 16, 0, 0); } while (0)
; #define PG8_WAIT_V(n) asm volatile("s_waitcnt vmcnt(" #n ")" ::: "memory")
; template <class Epi0, class Epi1>
; DI void gemm_phase_dual(LAS unsigned char* lds, const Gemm g, const Gemm g1, const StaticOrder S, const Epi0 E0, const Epi1 E1) {
;     ...
;             PG8_BAR; PG8_WAIT_L(0); PG8_MMA(0, 1, At, B1); PG8_BAR;
;             PG8_LDA(At, 1, 1); PG8_STAGE(PG8_SA(1, 0), a3, voffA);
;             PG8_BAR; PG8_WAIT_L(0); PG8_MMA(1, 0, At, B0); PG8_BAR; PG8_SCHED;
;             PG8_STAGE(PG8_SB(1, 1), b3 + hstep, voffB);
;             PG8_WAIT_V(6); PG8_BAR; PG8_MMA(1, 1, At, B1); PG8_BAR;
;         }
;         if (ui & 1) E1(acc, cur, wr, wc, fr, fq); else E0(acc, cur, wr, wc, fr, fq);
;     DI void operator()(AccRef acc, const Unit& u, int wr, int wc, int fr, int fq) const {
;         const int row0 = u.pm * 256 + wr * 64 + fr;
;         bf16_t* Gp = gab + (size_t)(u.pm * 8 + u.pn) * 65536 + (wr * 64 + fr) * 256 + wc * 32 + 8 * fq;
;         const RowScales rsc = load_rowscales(ss, row0);
	v_mfma_f32_16x16x32_bf16 v[68:71], v[214:217], v[206:209], v[68:71]
	v_mfma_f32_16x16x32_bf16 v[64:67], v[224:227], v[206:209], v[64:67]
	s_setprio 0
	s_mov_b32 m0, s76
	v_lshl_add_u64 v[190:191], v[230:231], 0, s[22:23]
	ds_read_b128 v[144:147], v183 offset:49152
	ds_read_b128 v[152:155], v183 offset:51200
	ds_read_b128 v[194:197], v183 offset:53248
	ds_read_b128 v[202:205], v183 offset:55296
	global_load_lds_dwordx4 v[190:191], off
	v_lshl_add_u64 v[190:191], v[232:233], 0, s[22:23]
	s_mov_b32 m0, s77
	s_nop 0
	global_load_lds_dwordx4 v[190:191], off
	s_setprio 1
	s_barrier
	s_waitcnt lgkmcnt(0)
	v_mfma_f32_16x16x32_bf16 v[60:63], v[128:131], v[144:147], v[60:63]
	ds_read_b128 v[148:151], v183 offset:50176
	v_mfma_f32_16x16x32_bf16 v[56:59], v[136:139], v[144:147], v[56:59]
	ds_read_b128 v[184:187], v183 offset:52224
	v_mfma_f32_16x16x32_bf16 v[44:47], v[128:131], v[152:155], v[44:47]
	ds_read_b128 v[198:201], v183 offset:54272
	v_mfma_f32_16x16x32_bf16 v[40:43], v[136:139], v[152:155], v[40:43]
	ds_read_b128 v[206:209], v183 offset:56320
	v_mfma_f32_16x16x32_bf16 v[28:31], v[128:131], v[194:197], v[28:31]
	v_mfma_f32_16x16x32_bf16 v[24:27], v[136:139], v[194:197], v[24:27]
	v_mfma_f32_16x16x32_bf16 v[12:15], v[128:131], v[202:205], v[12:15]
	v_mfma_f32_16x16x32_bf16 v[8:11], v[136:139], v[202:205], v[8:11]
	s_waitcnt lgkmcnt(3)
	v_mfma_f32_16x16x32_bf16 v[60:63], v[132:135], v[148:151], v[60:63]
	v_mfma_f32_16x16x32_bf16 v[56:59], v[140:143], v[148:151], v[56:59]
	s_waitcnt lgkmcnt(2)
	v_mfma_f32_16x16x32_bf16 v[44:47], v[132:135], v[184:187], v[44:47]
	v_mfma_f32_16x16x32_bf16 v[40:43], v[140:143], v[184:187], v[40:43]
	s_waitcnt lgkmcnt(1)
	v_mfma_f32_16x16x32_bf16 v[28:31], v[132:135], v[198:201], v[28:31]
	v_mfma_f32_16x16x32_bf16 v[24:27], v[140:143], v[198:201], v[24:27]
	s_waitcnt lgkmcnt(0)
	s_setprio 2
	s_barrier
	v_mfma_f32_16x16x32_bf16 v[12:15], v[132:135], v[206:209], v[12:15]
	v_mfma_f32_16x16x32_bf16 v[8:11], v[140:143], v[206:209], v[8:11]
	s_setprio 0
	s_add_u32 s12, s12, 0x40080
	s_addc_u32 s13, s13, 0
	s_add_i32 s14, s14, s48
	v_lshl_add_u64 v[128:129], s[12:13], 0, v[158:159]
	s_mov_b32 m0, s14
	s_nop 0
	global_load_lds_dwordx4 v[128:129], off
	v_lshl_add_u64 v[128:129], s[12:13], 0, v[162:163]
	s_add_i32 m0, s14, 0x2000
	s_nop 0
	global_load_lds_dwordx4 v[128:129], off
	s_waitcnt vmcnt(6)
	s_setprio 1
	s_barrier
	v_mfma_f32_16x16x32_bf16 v[52:55], v[210:213], v[144:147], v[52:55]
	v_mfma_f32_16x16x32_bf16 v[48:51], v[218:221], v[144:147], v[48:51]
	v_mfma_f32_16x16x32_bf16 v[36:39], v[210:213], v[152:155], v[36:39]
	v_mfma_f32_16x16x32_bf16 v[32:35], v[218:221], v[152:155], v[32:35]
	v_mfma_f32_16x16x32_bf16 v[20:23], v[210:213], v[194:197], v[20:23]
	v_mfma_f32_16x16x32_bf16 v[16:19], v[218:221], v[194:197], v[16:19]
	v_mfma_f32_16x16x32_bf16 v[4:7], v[210:213], v[202:205], v[4:7]
	v_mfma_f32_16x16x32_bf16 v[0:3], v[218:221], v[202:205], v[0:3]
	v_mfma_f32_16x16x32_bf16 v[52:55], v[214:217], v[148:151], v[52:55]
	v_mfma_f32_16x16x32_bf16 v[48:51], v[224:227], v[148:151], v[48:51]
	v_mfma_f32_16x16x32_bf16 v[36:39], v[214:217], v[184:187], v[36:39]
	v_mfma_f32_16x16x32_bf16 v[32:35], v[224:227], v[184:187], v[32:35]
	v_mfma_f32_16x16x32_bf16 v[20:23], v[214:217], v[198:201], v[20:23]
	v_mfma_f32_16x16x32_bf16 v[16:19], v[224:227], v[198:201], v[16:19]
	s_setprio 2
	s_barrier
	v_mfma_f32_16x16x32_bf16 v[4:7], v[214:217], v[206:209], v[4:7]
	v_mfma_f32_16x16x32_bf16 v[0:3], v[224:227], v[206:209], v[0:3]
	s_setprio 0
	s_add_i32 s19, s19, 2
	s_add_u32 s10, s10, 0x100
	s_addc_u32 s11, s11, 0
	s_add_u32 s17, s17, 0x100
	s_addc_u32 s18, s18, 0
	s_cmp_gt_u32 s19, 13
	s_cbranch_scc0 .LBB0_632
	v_lshl_add_u32 v128, s0, 8, v177
	s_mov_b64 s[6:7], -1
	s_and_b64 vcc, exec, s[8:9]
	v_ashrrev_i32_e32 v129, 31, v128
	s_cbranch_vccz .LBB0_635
	v_lshl_add_u64 v[130:131], v[128:129], 2, s[60:61]
	global_load_dword v132, v[130:131], off
	global_load_dword v133, v[130:131], off offset:64
	global_load_dword v134, v[130:131], off offset:128
	global_load_dword v135, v[130:131], off offset:192
	global_load_dword v136, v[130:131], off offset:512
	global_load_dword v137, v[130:131], off offset:576
	global_load_dword v138, v[130:131], off offset:640
	global_load_dword v139, v[130:131], off offset:704
	s_lshl_b32 s0, s0, 3
	s_add_i32 s0, s0, s87
	s_ashr_i32 s1, s0, 31
	s_lshl_b64 s[0:1], s[0:1], 17
	v_lshl_add_u64 v[130:131], v[166:167], 0, s[0:1]
	s_mov_b64 s[6:7], 0
	s_waitcnt vmcnt(0)
; DI unsigned pk_bf16(float lo, float hi) { f32x2 v = {lo, hi}; return __builtin_bit_cast(unsigned, __builtin_convertvector(v, bf16v2)); }
; DI float fast_sigmoid(float x) { return __builtin_amdgcn_rcpf(1.0f + __expf(-x)); }
; DI RowScales load_rowscales(const float* ss, int row0) {
;     ...
;     for (int ai = 0; ai < 2; ++ai)
; #pragma unroll
;         for (int m = 0; m < 4; ++m) t.r[ai][m] = rsqrtf(t.r[ai][m] * (1.0f / 1024.0f) + 1e-6f);
;     DI void operator()(AccRef acc, const Unit& u, int wr, int wc, int fr, int fq) const {
;     ...
; #pragma unroll
;         for (int ai = 0; ai < 2; ++ai)
; #pragma unroll
;             for (int m = 0; m < 4; ++m)
; #pragma unroll
;                 for (int bj = 0; bj < 2; ++bj) {
;                     const float rs = rsc.r[ai][m];
;                     const f32x4 r0 = acc[ai][bj][m][0] * rs, r1 = acc[ai][bj][m][1] * rs;
;                     u32x4 w;
;                     w.x = pk_bf16(fast_sigmoid(r0[0]), fast_sigmoid(r0[1])); w.y = pk_bf16(fast_sigmoid(r0[2]), fast_sigmoid(r0[3]));
;                     w.z = pk_bf16(fast_sigmoid(r1[0]), fast_sigmoid(r1[1])); w.w = pk_bf16(fast_sigmoid(r1[2]), fast_sigmoid(r1[3]));
;                     *(u32x4*)(Gp + (ai * 128 + m * 16) * 256 + bj * 128) = w;
;                 }
	v_fmamk_f32 v132, v132, 0x3a800000, v193
	v_mul_f32_e32 v140, 0x4b800000, v132
	v_cmp_gt_f32_e32 vcc, s80, v132
	v_fmamk_f32 v134, v134, 0x3a800000, v193
	v_fmamk_f32 v136, v136, 0x3a800000, v193
	v_fmamk_f32 v137, v137, 0x3a800000, v193
	v_fmamk_f32 v138, v138, 0x3a800000, v193
	v_fmamk_f32 v139, v139, 0x3a800000, v193
	v_mul_f32_e32 v144, 0x4b800000, v136
	v_mul_f32_e32 v145, 0x4b800000, v137
	v_cndmask_b32_e32 v132, v132, v140, vcc
	v_cmp_gt_f32_e64 s[12:13], s80, v136
	v_cmp_gt_f32_e64 s[14:15], s80, v137
	v_fmamk_f32 v133, v133, 0x3a800000, v193
	v_fmamk_f32 v135, v135, 0x3a800000, v193
	v_mul_f32_e32 v142, 0x4b800000, v134
	v_mul_f32_e32 v146, 0x4b800000, v138
	v_mul_f32_e32 v147, 0x4b800000, v139
	v_cmp_gt_f32_e64 s[8:9], s80, v134
	v_cndmask_b32_e64 v136, v136, v144, s[12:13]
	v_cndmask_b32_e64 v137, v137, v145, s[14:15]
	v_cmp_gt_f32_e64 s[16:17], s80, v138
	v_cmp_gt_f32_e64 s[18:19], s80, v139
	v_rsq_f32_e32 v132, v132
	v_mul_f32_e32 v141, 0x4b800000, v133
	v_mul_f32_e32 v143, 0x4b800000, v135
	v_cmp_gt_f32_e64 s[0:1], s80, v133
	v_cndmask_b32_e64 v134, v134, v142, s[8:9]
	v_cmp_gt_f32_e64 s[10:11], s80, v135
	v_cndmask_b32_e64 v138, v138, v146, s[16:17]
	v_cndmask_b32_e64 v139, v139, v147, s[18:19]
	v_rsq_f32_e32 v136, v136
	v_rsq_f32_e32 v137, v137
	v_cndmask_b32_e64 v133, v133, v141, s[0:1]
	v_cndmask_b32_e64 v135, v135, v143, s[10:11]
	v_rsq_f32_e32 v134, v134
	v_rsq_f32_e32 v141, v138
	v_rsq_f32_e32 v139, v139
	v_rsq_f32_e32 v133, v133
	v_rsq_f32_e32 v135, v135
	v_mul_f32_e32 v138, 0x45800000, v132
	v_mul_f32_e32 v144, 0x45800000, v136
	v_mul_f32_e32 v145, 0x45800000, v137
	v_cndmask_b32_e32 v148, v132, v138, vcc
	v_mul_f32_e32 v142, 0x45800000, v134
	v_mul_f32_e32 v146, 0x45800000, v141
	v_mul_f32_e32 v147, 0x45800000, v139
	v_cndmask_b32_e64 v138, v136, v144, s[12:13]
	v_cndmask_b32_e64 v136, v137, v145, s[14:15]
	v_pk_mul_f32 v[144:145], v[126:127], v[148:149] op_sel_hi:[1,0]
	v_pk_mul_f32 v[152:153], v[122:123], v[148:149] op_sel_hi:[1,0]
	v_mul_f32_e32 v140, 0x45800000, v133
	v_mul_f32_e32 v143, 0x45800000, v135
	v_cndmask_b32_e64 v142, v134, v142, s[8:9]
	v_cndmask_b32_e64 v134, v141, v146, s[16:17]
	v_cndmask_b32_e64 v132, v139, v147, s[18:19]
	v_pk_mul_f32 v[146:147], v[124:125], v[148:149] op_sel_hi:[1,0]
	v_pk_mul_f32 v[154:155], v[120:121], v[148:149] op_sel_hi:[1,0]
	v_mul_f32_e32 v137, 0xbfb8aa3b, v144
	v_mul_f32_e32 v144, 0xbfb8aa3b, v152
	v_cndmask_b32_e64 v150, v133, v140, s[0:1]
	v_cndmask_b32_e64 v140, v135, v143, s[10:11]
	v_mul_f32_e32 v133, 0xbfb8aa3b, v146
	v_mul_f32_e32 v135, 0xbfb8aa3b, v147
	v_mul_f32_e32 v139, 0xbfb8aa3b, v145
	v_mul_f32_e32 v141, 0xbfb8aa3b, v154
	v_mul_f32_e32 v143, 0xbfb8aa3b, v155
	v_exp_f32_e32 v144, v144
	v_mul_f32_e32 v145, 0xbfb8aa3b, v153
	v_exp_f32_e32 v133, v133
	v_exp_f32_e32 v135, v135
	v_exp_f32_e32 v137, v137
	v_exp_f32_e32 v139, v139
	v_exp_f32_e32 v141, v141
	v_exp_f32_e32 v143, v143
	v_exp_f32_e32 v145, v145
	v_add_f32_e32 v144, 1.0, v144
	v_add_f32_e32 v133, 1.0, v133
	v_add_f32_e32 v135, 1.0, v135
	v_add_f32_e32 v137, 1.0, v137
	v_add_f32_e32 v139, 1.0, v139
	v_add_f32_e32 v141, 1.0, v141
	v_add_f32_e32 v143, 1.0, v143
	v_rcp_f32_e32 v147, v144
	v_add_f32_e32 v144, 1.0, v145
	v_rcp_f32_e32 v133, v133
	v_rcp_f32_e32 v135, v135
	v_rcp_f32_e32 v137, v137
	v_rcp_f32_e32 v139, v139
	v_rcp_f32_e32 v141, v141
	v_rcp_f32_e32 v143, v143
	v_rcp_f32_e32 v149, v144
	v_cvt_pk_bf16_f32 v144, v133, v135
	v_cvt_pk_bf16_f32 v145, v137, v139
	v_cvt_pk_bf16_f32 v146, v141, v143
	v_cvt_pk_bf16_f32 v147, v147, v149
	global_store_dwordx4 v[130:131], v[144:147], off
	v_pk_mul_f32 v[152:153], v[114:115], v[148:149] op_sel_hi:[1,0]
	s_nop 0
	v_pk_mul_f32 v[144:145], v[118:119], v[148:149] op_sel_hi:[1,0]
	v_pk_mul_f32 v[146:147], v[116:117], v[148:149] op_sel_hi:[1,0]
	v_mul_f32_e32 v137, 0xbfb8aa3b, v144
	v_mul_f32_e32 v133, 0xbfb8aa3b, v146
	v_mul_f32_e32 v135, 0xbfb8aa3b, v147
	v_pk_mul_f32 v[146:147], v[112:113], v[148:149] op_sel_hi:[1,0]
	v_mul_f32_e32 v144, 0xbfb8aa3b, v152
	v_mul_f32_e32 v139, 0xbfb8aa3b, v145
	v_mul_f32_e32 v141, 0xbfb8aa3b, v146
	v_mul_f32_e32 v143, 0xbfb8aa3b, v147
	v_exp_f32_e32 v144, v144
	v_mul_f32_e32 v145, 0xbfb8aa3b, v153
	v_exp_f32_e32 v133, v133
	v_exp_f32_e32 v135, v135
	v_exp_f32_e32 v137, v137
	v_exp_f32_e32 v139, v139
	v_exp_f32_e32 v141, v141
	v_exp_f32_e32 v143, v143
	v_exp_f32_e32 v145, v145
	v_add_f32_e32 v144, 1.0, v144
	v_add_f32_e32 v133, 1.0, v133
	v_add_f32_e32 v135, 1.0, v135
	v_add_f32_e32 v137, 1.0, v137
	v_add_f32_e32 v139, 1.0, v139
	v_add_f32_e32 v141, 1.0, v141
	v_add_f32_e32 v143, 1.0, v143
	v_rcp_f32_e32 v147, v144
	v_add_f32_e32 v144, 1.0, v145
	v_rcp_f32_e32 v133, v133
	v_rcp_f32_e32 v135, v135
	v_rcp_f32_e32 v137, v137
	v_rcp_f32_e32 v139, v139
	v_rcp_f32_e32 v141, v141
	v_rcp_f32_e32 v143, v143
	v_rcp_f32_e32 v148, v144
	v_cvt_pk_bf16_f32 v144, v133, v135
	v_cvt_pk_bf16_f32 v145, v137, v139
	v_cvt_pk_bf16_f32 v146, v141, v143
	v_cvt_pk_bf16_f32 v147, v147, v148
	global_store_dwordx4 v[130:131], v[144:147], off offset:256
	v_pk_mul_f32 v[148:149], v[106:107], v[150:151] op_sel_hi:[1,0]
	v_pk_mul_f32 v[152:153], v[98:99], v[150:151] op_sel_hi:[1,0]
	v_pk_mul_f32 v[144:145], v[110:111], v[150:151] op_sel_hi:[1,0]
	v_pk_mul_f32 v[146:147], v[108:109], v[150:151] op_sel_hi:[1,0]
	v_mul_f32_e32 v137, 0xbfb8aa3b, v144
	v_mul_f32_e32 v144, 0xbfb8aa3b, v148
	v_mul_f32_e32 v133, 0xbfb8aa3b, v146
	v_mul_f32_e32 v135, 0xbfb8aa3b, v147
	v_pk_mul_f32 v[146:147], v[104:105], v[150:151] op_sel_hi:[1,0]
	v_mul_f32_e32 v139, 0xbfb8aa3b, v145
	v_exp_f32_e32 v144, v144
	v_mul_f32_e32 v145, 0xbfb8aa3b, v149
	v_mul_f32_e32 v141, 0xbfb8aa3b, v146
; DI unsigned pk_bf16(float lo, float hi) { f32x2 v = {lo, hi}; return __builtin_bit_cast(unsigned, __builtin_convertvector(v, bf16v2)); }
; DI float fast_sigmoid(float x) { return __builtin_amdgcn_rcpf(1.0f + __expf(-x)); }
;     DI void operator()(AccRef acc, const Unit& u, int wr, int wc, int fr, int fq) const {
;     ...
; #pragma unroll
;         for (int ai = 0; ai < 2; ++ai)
; #pragma unroll
;             for (int m = 0; m < 4; ++m)
; #pragma unroll
;                 for (int bj = 0; bj < 2; ++bj) {
;                     const float rs = rsc.r[ai][m];
;                     const f32x4 r0 = acc[ai][bj][m][0] * rs, r1 = acc[ai][bj][m][1] * rs;
;                     u32x4 w;
;                     w.x = pk_bf16(fast_sigmoid(r0[0]), fast_sigmoid(r0[1])); w.y = pk_bf16(fast_sigmoid(r0[2]), fast_sigmoid(r0[3]));
;                     w.z = pk_bf16(fast_sigmoid(r1[0]), fast_sigmoid(r1[1])); w.w = pk_bf16(fast_sigmoid(r1[2]), fast_sigmoid(r1[3]));
;                     *(u32x4*)(Gp + (ai * 128 + m * 16) * 256 + bj * 128) = w;
;                 }
	v_mul_f32_e32 v143, 0xbfb8aa3b, v147
	v_exp_f32_e32 v145, v145
	v_exp_f32_e32 v133, v133
	v_exp_f32_e32 v135, v135
	v_exp_f32_e32 v137, v137
	v_exp_f32_e32 v139, v139
	v_exp_f32_e32 v141, v141
	v_exp_f32_e32 v143, v143
	v_add_f32_e32 v144, 1.0, v144
	v_rcp_f32_e32 v147, v144
	v_add_f32_e32 v144, 1.0, v145
	v_add_f32_e32 v133, 1.0, v133
	v_add_f32_e32 v135, 1.0, v135
	v_add_f32_e32 v137, 1.0, v137
	v_add_f32_e32 v139, 1.0, v139
	v_add_f32_e32 v141, 1.0, v141
	v_add_f32_e32 v143, 1.0, v143
	v_rcp_f32_e32 v148, v144
	v_rcp_f32_e32 v133, v133
	v_rcp_f32_e32 v135, v135
	v_rcp_f32_e32 v137, v137
	v_rcp_f32_e32 v139, v139
	v_rcp_f32_e32 v141, v141
	v_rcp_f32_e32 v143, v143
	v_cvt_pk_bf16_f32 v147, v147, v148
	v_add_co_u32_e32 v148, vcc, s59, v130
	v_cvt_pk_bf16_f32 v144, v133, v135
	v_cvt_pk_bf16_f32 v145, v137, v139
	v_cvt_pk_bf16_f32 v146, v141, v143
	v_addc_co_u32_e32 v149, vcc, 0, v131, vcc
	global_store_dwordx4 v[148:149], v[144:147], off
	s_nop 1
	v_pk_mul_f32 v[144:145], v[102:103], v[150:151] op_sel_hi:[1,0]
	v_pk_mul_f32 v[146:147], v[100:101], v[150:151] op_sel_hi:[1,0]
	v_mul_f32_e32 v137, 0xbfb8aa3b, v144
	v_mul_f32_e32 v133, 0xbfb8aa3b, v146
	v_mul_f32_e32 v135, 0xbfb8aa3b, v147
	v_pk_mul_f32 v[146:147], v[96:97], v[150:151] op_sel_hi:[1,0]
	v_mul_f32_e32 v144, 0xbfb8aa3b, v152
	v_mul_f32_e32 v139, 0xbfb8aa3b, v145
	v_mul_f32_e32 v141, 0xbfb8aa3b, v146
	v_mul_f32_e32 v143, 0xbfb8aa3b, v147
	v_exp_f32_e32 v144, v144
	v_mul_f32_e32 v145, 0xbfb8aa3b, v153
	v_exp_f32_e32 v133, v133
	v_exp_f32_e32 v135, v135
	v_exp_f32_e32 v137, v137
	v_exp_f32_e32 v139, v139
	v_exp_f32_e32 v141, v141
	v_exp_f32_e32 v143, v143
	v_exp_f32_e32 v145, v145
	v_add_f32_e32 v144, 1.0, v144
	v_add_f32_e32 v133, 1.0, v133
	v_add_f32_e32 v135, 1.0, v135
	v_add_f32_e32 v137, 1.0, v137
	v_add_f32_e32 v139, 1.0, v139
	v_add_f32_e32 v141, 1.0, v141
	v_add_f32_e32 v143, 1.0, v143
	v_rcp_f32_e32 v147, v144
	v_add_f32_e32 v144, 1.0, v145
	v_rcp_f32_e32 v133, v133
	v_rcp_f32_e32 v135, v135
	v_rcp_f32_e32 v137, v137
	v_rcp_f32_e32 v139, v139
	v_rcp_f32_e32 v141, v141
	v_rcp_f32_e32 v143, v143
	v_rcp_f32_e32 v150, v144
	v_cvt_pk_bf16_f32 v144, v133, v135
	v_cvt_pk_bf16_f32 v145, v137, v139
	v_cvt_pk_bf16_f32 v146, v141, v143
	v_cvt_pk_bf16_f32 v147, v147, v150
	global_store_dwordx4 v[148:149], v[144:147], off offset:256
	v_pk_mul_f32 v[148:149], v[90:91], v[142:143] op_sel_hi:[1,0]
	s_nop 0
	v_pk_mul_f32 v[144:145], v[94:95], v[142:143] op_sel_hi:[1,0]
	v_pk_mul_f32 v[146:147], v[92:93], v[142:143] op_sel_hi:[1,0]
	v_mul_f32_e32 v137, 0xbfb8aa3b, v144
	v_mul_f32_e32 v144, 0xbfb8aa3b, v148
	v_mul_f32_e32 v133, 0xbfb8aa3b, v146
	v_mul_f32_e32 v135, 0xbfb8aa3b, v147
	v_pk_mul_f32 v[146:147], v[88:89], v[142:143] op_sel_hi:[1,0]
	v_mul_f32_e32 v139, 0xbfb8aa3b, v145
	v_exp_f32_e32 v144, v144
	v_mul_f32_e32 v145, 0xbfb8aa3b, v149
	v_mul_f32_e32 v141, 0xbfb8aa3b, v146
	v_mul_f32_e32 v143, 0xbfb8aa3b, v147
	v_exp_f32_e32 v145, v145
	v_exp_f32_e32 v133, v133
	v_exp_f32_e32 v135, v135
	v_exp_f32_e32 v137, v137
	v_exp_f32_e32 v139, v139
	v_exp_f32_e32 v141, v141
	v_exp_f32_e32 v143, v143
	v_add_f32_e32 v144, 1.0, v144
	v_rcp_f32_e32 v147, v144
	v_add_f32_e32 v144, 1.0, v145
	v_add_f32_e32 v133, 1.0, v133
	v_add_f32_e32 v135, 1.0, v135
	v_add_f32_e32 v137, 1.0, v137
	v_add_f32_e32 v139, 1.0, v139
	v_add_f32_e32 v141, 1.0, v141
	v_add_f32_e32 v143, 1.0, v143
	v_rcp_f32_e32 v148, v144
	v_rcp_f32_e32 v133, v133
	v_rcp_f32_e32 v135, v135
	v_rcp_f32_e32 v137, v137
	v_rcp_f32_e32 v139, v139
	v_rcp_f32_e32 v141, v141
	v_rcp_f32_e32 v143, v143
	v_cvt_pk_bf16_f32 v147, v147, v148
	v_add_co_u32_e32 v148, vcc, s66, v130
	v_cvt_pk_bf16_f32 v144, v133, v135
	v_cvt_pk_bf16_f32 v145, v137, v139
	v_cvt_pk_bf16_f32 v146, v141, v143
	v_addc_co_u32_e32 v149, vcc, 0, v131, vcc
	global_store_dwordx4 v[148:149], v[144:147], off
	v_pk_mul_f32 v[150:151], v[82:83], v[142:143] op_sel_hi:[1,0]
	s_nop 0
	v_pk_mul_f32 v[144:145], v[86:87], v[142:143] op_sel_hi:[1,0]
	v_pk_mul_f32 v[146:147], v[84:85], v[142:143] op_sel_hi:[1,0]
	v_pk_mul_f32 v[142:143], v[80:81], v[142:143] op_sel_hi:[1,0]
	v_mul_f32_e32 v133, 0xbfb8aa3b, v146
	v_mul_f32_e32 v141, 0xbfb8aa3b, v142
	v_mul_f32_e32 v142, 0xbfb8aa3b, v143
	v_exp_f32_e32 v142, v142
	v_mul_f32_e32 v143, 0xbfb8aa3b, v150
	v_mul_f32_e32 v135, 0xbfb8aa3b, v147
	v_mul_f32_e32 v137, 0xbfb8aa3b, v144
	v_mul_f32_e32 v139, 0xbfb8aa3b, v145
	v_exp_f32_e32 v143, v143
	v_mul_f32_e32 v144, 0xbfb8aa3b, v151
	v_exp_f32_e32 v133, v133
	v_exp_f32_e32 v135, v135
	v_exp_f32_e32 v137, v137
	v_exp_f32_e32 v139, v139
	v_exp_f32_e32 v141, v141
	v_exp_f32_e32 v144, v144
	v_add_f32_e32 v142, 1.0, v142
	v_rcp_f32_e32 v145, v142
	v_add_f32_e32 v142, 1.0, v143
	v_add_f32_e32 v133, 1.0, v133
	v_add_f32_e32 v135, 1.0, v135
	v_add_f32_e32 v137, 1.0, v137
	v_add_f32_e32 v139, 1.0, v139
	v_add_f32_e32 v141, 1.0, v141
	v_rcp_f32_e32 v146, v142
	v_add_f32_e32 v142, 1.0, v144
	v_rcp_f32_e32 v133, v133
	v_rcp_f32_e32 v135, v135
	v_rcp_f32_e32 v137, v137
	v_rcp_f32_e32 v139, v139
	v_rcp_f32_e32 v141, v141
	v_rcp_f32_e32 v147, v142
	v_cvt_pk_bf16_f32 v142, v133, v135
	v_cvt_pk_bf16_f32 v143, v137, v139
	v_cvt_pk_bf16_f32 v144, v141, v145
	v_cvt_pk_bf16_f32 v145, v146, v147
	global_store_dwordx4 v[148:149], v[142:145], off offset:256
	v_pk_mul_f32 v[146:147], v[74:75], v[140:141] op_sel_hi:[1,0]
	s_nop 0
	v_pk_mul_f32 v[144:145], v[76:77], v[140:141] op_sel_hi:[1,0]
	v_pk_mul_f32 v[142:143], v[78:79], v[140:141] op_sel_hi:[1,0]
	v_mul_f32_e32 v133, 0xbfb8aa3b, v144
	v_mul_f32_e32 v135, 0xbfb8aa3b, v145
	v_pk_mul_f32 v[144:145], v[72:73], v[140:141] op_sel_hi:[1,0]
	v_mul_f32_e32 v137, 0xbfb8aa3b, v142
; DI unsigned pk_bf16(float lo, float hi) { f32x2 v = {lo, hi}; return __builtin_bit_cast(unsigned, __builtin_convertvector(v, bf16v2)); }
; DI float fast_sigmoid(float x) { return __builtin_amdgcn_rcpf(1.0f + __expf(-x)); }
;     DI void operator()(AccRef acc, const Unit& u, int wr, int wc, int fr, int fq) const {
;     ...
; #pragma unroll
;         for (int ai = 0; ai < 2; ++ai)
; #pragma unroll
;             for (int m = 0; m < 4; ++m)
; #pragma unroll
;                 for (int bj = 0; bj < 2; ++bj) {
;                     const float rs = rsc.r[ai][m];
;                     const f32x4 r0 = acc[ai][bj][m][0] * rs, r1 = acc[ai][bj][m][1] * rs;
;                     u32x4 w;
;                     w.x = pk_bf16(fast_sigmoid(r0[0]), fast_sigmoid(r0[1])); w.y = pk_bf16(fast_sigmoid(r0[2]), fast_sigmoid(r0[3]));
;                     w.z = pk_bf16(fast_sigmoid(r1[0]), fast_sigmoid(r1[1])); w.w = pk_bf16(fast_sigmoid(r1[2]), fast_sigmoid(r1[3]));
;                     *(u32x4*)(Gp + (ai * 128 + m * 16) * 256 + bj * 128) = w;
;                 }
	v_mul_f32_e32 v142, 0xbfb8aa3b, v145
	v_mul_f32_e32 v139, 0xbfb8aa3b, v143
	v_exp_f32_e32 v142, v142
	v_mul_f32_e32 v143, 0xbfb8aa3b, v146
	v_mul_f32_e32 v141, 0xbfb8aa3b, v144
	v_exp_f32_e32 v143, v143
	v_mul_f32_e32 v144, 0xbfb8aa3b, v147
	v_exp_f32_e32 v141, v141
	v_exp_f32_e32 v144, v144
	v_exp_f32_e32 v133, v133
	v_exp_f32_e32 v135, v135
	v_exp_f32_e32 v137, v137
	v_exp_f32_e32 v139, v139
	v_add_f32_e32 v142, 1.0, v142
	v_rcp_f32_e32 v145, v142
	v_add_f32_e32 v142, 1.0, v143
	v_add_f32_e32 v141, 1.0, v141
	v_rcp_f32_e32 v146, v142
	v_add_f32_e32 v142, 1.0, v144
	v_add_f32_e32 v133, 1.0, v133
	v_add_f32_e32 v135, 1.0, v135
	v_add_f32_e32 v137, 1.0, v137
	v_add_f32_e32 v139, 1.0, v139
	v_rcp_f32_e32 v141, v141
	v_rcp_f32_e32 v147, v142
	v_rcp_f32_e32 v133, v133
	v_rcp_f32_e32 v135, v135
	v_rcp_f32_e32 v137, v137
	v_rcp_f32_e32 v139, v139
	v_cvt_pk_bf16_f32 v144, v141, v145
	v_cvt_pk_bf16_f32 v145, v146, v147
	v_add_co_u32_e32 v146, vcc, s67, v130
	v_cvt_pk_bf16_f32 v142, v133, v135
	v_cvt_pk_bf16_f32 v143, v137, v139
	v_addc_co_u32_e32 v147, vcc, 0, v131, vcc
	global_store_dwordx4 v[146:147], v[142:145], off
	v_pk_mul_f32 v[148:149], v[66:67], v[140:141] op_sel_hi:[1,0]
	s_nop 0
	v_pk_mul_f32 v[142:143], v[70:71], v[140:141] op_sel_hi:[1,0]
	v_pk_mul_f32 v[144:145], v[68:69], v[140:141] op_sel_hi:[1,0]
	v_pk_mul_f32 v[140:141], v[64:65], v[140:141] op_sel_hi:[1,0]
	v_mul_f32_e32 v137, 0xbfb8aa3b, v142
	v_mul_f32_e32 v140, 0xbfb8aa3b, v140
	v_exp_f32_e32 v140, v140
	v_mul_f32_e32 v141, 0xbfb8aa3b, v141
	v_exp_f32_e32 v141, v141
	v_mul_f32_e32 v133, 0xbfb8aa3b, v144
	v_add_f32_e32 v140, 1.0, v140
	v_rcp_f32_e32 v142, v140
	v_add_f32_e32 v140, 1.0, v141
	v_mul_f32_e32 v141, 0xbfb8aa3b, v148
	v_mul_f32_e32 v135, 0xbfb8aa3b, v145
	v_mul_f32_e32 v139, 0xbfb8aa3b, v143
	v_exp_f32_e32 v141, v141
	v_mul_f32_e32 v143, 0xbfb8aa3b, v149
	v_exp_f32_e32 v133, v133
	v_exp_f32_e32 v135, v135
	v_exp_f32_e32 v137, v137
	v_exp_f32_e32 v139, v139
	v_exp_f32_e32 v143, v143
	v_rcp_f32_e32 v144, v140
	v_add_f32_e32 v140, 1.0, v141
	v_add_f32_e32 v133, 1.0, v133
	v_add_f32_e32 v135, 1.0, v135
	v_add_f32_e32 v137, 1.0, v137
	v_add_f32_e32 v139, 1.0, v139
	v_rcp_f32_e32 v145, v140
	v_add_f32_e32 v140, 1.0, v143
	v_rcp_f32_e32 v133, v133
	v_rcp_f32_e32 v135, v135
	v_rcp_f32_e32 v137, v137
	v_rcp_f32_e32 v139, v139
	v_rcp_f32_e32 v143, v140
	v_cvt_pk_bf16_f32 v140, v133, v135
	v_cvt_pk_bf16_f32 v142, v142, v144
	v_cvt_pk_bf16_f32 v141, v137, v139
	v_cvt_pk_bf16_f32 v143, v145, v143
	global_store_dwordx4 v[146:147], v[140:143], off offset:256
	v_pk_mul_f32 v[144:145], v[58:59], v[138:139] op_sel_hi:[1,0]
	s_nop 0
	v_pk_mul_f32 v[142:143], v[60:61], v[138:139] op_sel_hi:[1,0]
	v_pk_mul_f32 v[140:141], v[62:63], v[138:139] op_sel_hi:[1,0]
	v_mul_f32_e32 v133, 0xbfb8aa3b, v142
	v_mul_f32_e32 v135, 0xbfb8aa3b, v143
	v_pk_mul_f32 v[142:143], v[56:57], v[138:139] op_sel_hi:[1,0]
	v_mul_f32_e32 v137, 0xbfb8aa3b, v140
	v_mul_f32_e32 v140, 0xbfb8aa3b, v142
	v_mul_f32_e32 v139, 0xbfb8aa3b, v141
	v_exp_f32_e32 v140, v140
	v_mul_f32_e32 v141, 0xbfb8aa3b, v143
	v_exp_f32_e32 v141, v141
	v_mul_f32_e32 v143, 0xbfb8aa3b, v145
	v_add_f32_e32 v140, 1.0, v140
	v_rcp_f32_e32 v142, v140
	v_add_f32_e32 v140, 1.0, v141
	v_mul_f32_e32 v141, 0xbfb8aa3b, v144
	v_exp_f32_e32 v141, v141
	v_exp_f32_e32 v133, v133
	v_exp_f32_e32 v135, v135
	v_exp_f32_e32 v137, v137
	v_exp_f32_e32 v139, v139
	v_exp_f32_e32 v143, v143
	v_rcp_f32_e32 v144, v140
	v_add_f32_e32 v140, 1.0, v141
	v_add_f32_e32 v133, 1.0, v133
	v_add_f32_e32 v135, 1.0, v135
	v_add_f32_e32 v137, 1.0, v137
	v_add_f32_e32 v139, 1.0, v139
	v_rcp_f32_e32 v145, v140
	v_add_f32_e32 v140, 1.0, v143
	v_rcp_f32_e32 v133, v133
	v_rcp_f32_e32 v135, v135
	v_rcp_f32_e32 v137, v137
	v_rcp_f32_e32 v139, v139
	v_rcp_f32_e32 v143, v140
	v_cvt_pk_bf16_f32 v142, v142, v144
	v_add_co_u32_e32 v144, vcc, s62, v130
	v_cvt_pk_bf16_f32 v140, v133, v135
	v_cvt_pk_bf16_f32 v141, v137, v139
	v_cvt_pk_bf16_f32 v143, v145, v143
	v_addc_co_u32_e32 v145, vcc, 0, v131, vcc
	global_store_dwordx4 v[144:145], v[140:143], off
	v_pk_mul_f32 v[146:147], v[50:51], v[138:139] op_sel_hi:[1,0]
	s_nop 0
	v_pk_mul_f32 v[140:141], v[54:55], v[138:139] op_sel_hi:[1,0]
	v_pk_mul_f32 v[142:143], v[52:53], v[138:139] op_sel_hi:[1,0]
	v_pk_mul_f32 v[138:139], v[48:49], v[138:139] op_sel_hi:[1,0]
	v_mul_f32_e32 v137, 0xbfb8aa3b, v140
	v_mul_f32_e32 v138, 0xbfb8aa3b, v138
	v_exp_f32_e32 v138, v138
	v_mul_f32_e32 v139, 0xbfb8aa3b, v139
	v_exp_f32_e32 v139, v139
	v_mul_f32_e32 v140, 0xbfb8aa3b, v141
	v_add_f32_e32 v138, 1.0, v138
	v_rcp_f32_e32 v141, v138
	v_add_f32_e32 v138, 1.0, v139
	v_mul_f32_e32 v139, 0xbfb8aa3b, v146
	v_mul_f32_e32 v133, 0xbfb8aa3b, v142
	v_mul_f32_e32 v135, 0xbfb8aa3b, v143
	v_exp_f32_e32 v139, v139
	v_mul_f32_e32 v142, 0xbfb8aa3b, v147
	v_exp_f32_e32 v133, v133
	v_exp_f32_e32 v135, v135
	v_exp_f32_e32 v137, v137
	v_exp_f32_e32 v140, v140
	v_exp_f32_e32 v142, v142
	v_rcp_f32_e32 v143, v138
	v_add_f32_e32 v138, 1.0, v139
	v_add_f32_e32 v133, 1.0, v133
	v_add_f32_e32 v135, 1.0, v135
	v_add_f32_e32 v137, 1.0, v137
	v_add_f32_e32 v140, 1.0, v140
	v_rcp_f32_e32 v146, v138
	v_add_f32_e32 v138, 1.0, v142
	v_rcp_f32_e32 v133, v133
	v_rcp_f32_e32 v135, v135
	v_rcp_f32_e32 v137, v137
	v_rcp_f32_e32 v140, v140
	v_rcp_f32_e32 v142, v138
	v_cvt_pk_bf16_f32 v138, v133, v135
	v_cvt_pk_bf16_f32 v139, v137, v140
	v_cvt_pk_bf16_f32 v140, v141, v143
	v_cvt_pk_bf16_f32 v141, v146, v142
	global_store_dwordx4 v[144:145], v[138:141], off offset:256
	v_pk_mul_f32 v[142:143], v[42:43], v[136:137] op_sel_hi:[1,0]
	s_nop 0
	v_pk_mul_f32 v[138:139], v[46:47], v[136:137] op_sel_hi:[1,0]
; DI unsigned pk_bf16(float lo, float hi) { f32x2 v = {lo, hi}; return __builtin_bit_cast(unsigned, __builtin_convertvector(v, bf16v2)); }
; DI float fast_sigmoid(float x) { return __builtin_amdgcn_rcpf(1.0f + __expf(-x)); }
;     DI void operator()(AccRef acc, const Unit& u, int wr, int wc, int fr, int fq) const {
;     ...
; #pragma unroll
;         for (int ai = 0; ai < 2; ++ai)
; #pragma unroll
;             for (int m = 0; m < 4; ++m)
; #pragma unroll
;                 for (int bj = 0; bj < 2; ++bj) {
;                     const float rs = rsc.r[ai][m];
;                     const f32x4 r0 = acc[ai][bj][m][0] * rs, r1 = acc[ai][bj][m][1] * rs;
;                     u32x4 w;
;                     w.x = pk_bf16(fast_sigmoid(r0[0]), fast_sigmoid(r0[1])); w.y = pk_bf16(fast_sigmoid(r0[2]), fast_sigmoid(r0[3]));
;                     w.z = pk_bf16(fast_sigmoid(r1[0]), fast_sigmoid(r1[1])); w.w = pk_bf16(fast_sigmoid(r1[2]), fast_sigmoid(r1[3]));
;                     *(u32x4*)(Gp + (ai * 128 + m * 16) * 256 + bj * 128) = w;
;                 }
	v_pk_mul_f32 v[140:141], v[44:45], v[136:137] op_sel_hi:[1,0]
	s_nop 0
	v_mul_f32_e32 v133, 0xbfb8aa3b, v140
	v_mul_f32_e32 v135, 0xbfb8aa3b, v141
	v_pk_mul_f32 v[140:141], v[40:41], v[136:137] op_sel_hi:[1,0]
	v_mul_f32_e32 v137, 0xbfb8aa3b, v138
	v_mul_f32_e32 v138, 0xbfb8aa3b, v139
	v_exp_f32_e32 v138, v138
	v_mul_f32_e32 v139, 0xbfb8aa3b, v140
	v_exp_f32_e32 v139, v139
	v_mul_f32_e32 v140, 0xbfb8aa3b, v141
	v_exp_f32_e32 v140, v140
	v_add_f32_e32 v138, 1.0, v138
	v_rcp_f32_e32 v141, v138
	v_add_f32_e32 v138, 1.0, v139
	v_mul_f32_e32 v139, 0xbfb8aa3b, v142
	v_rcp_f32_e32 v144, v138
	v_add_f32_e32 v138, 1.0, v140
	v_exp_f32_e32 v139, v139
	v_mul_f32_e32 v140, 0xbfb8aa3b, v143
	v_exp_f32_e32 v133, v133
	v_exp_f32_e32 v135, v135
	v_exp_f32_e32 v137, v137
	v_exp_f32_e32 v140, v140
	v_rcp_f32_e32 v142, v138
	v_add_f32_e32 v138, 1.0, v139
	v_add_f32_e32 v133, 1.0, v133
	v_add_f32_e32 v135, 1.0, v135
	v_add_f32_e32 v137, 1.0, v137
	v_rcp_f32_e32 v143, v138
	v_add_f32_e32 v138, 1.0, v140
	v_rcp_f32_e32 v133, v133
	v_rcp_f32_e32 v135, v135
	v_rcp_f32_e32 v137, v137
	v_rcp_f32_e32 v145, v138
	v_cvt_pk_bf16_f32 v140, v144, v142
	v_add_co_u32_e32 v142, vcc, s63, v130
	v_cvt_pk_bf16_f32 v138, v133, v135
	v_cvt_pk_bf16_f32 v139, v137, v141
	v_cvt_pk_bf16_f32 v141, v143, v145
	v_addc_co_u32_e32 v143, vcc, 0, v131, vcc
	global_store_dwordx4 v[142:143], v[138:141], off
	v_pk_mul_f32 v[144:145], v[34:35], v[136:137] op_sel_hi:[1,0]
	s_nop 0
	v_pk_mul_f32 v[138:139], v[38:39], v[136:137] op_sel_hi:[1,0]
	v_pk_mul_f32 v[140:141], v[36:37], v[136:137] op_sel_hi:[1,0]
	v_pk_mul_f32 v[136:137], v[32:33], v[136:137] op_sel_hi:[1,0]
	v_mul_f32_e32 v133, 0xbfb8aa3b, v140
	v_mul_f32_e32 v136, 0xbfb8aa3b, v136
	v_exp_f32_e32 v136, v136
	v_mul_f32_e32 v137, 0xbfb8aa3b, v137
	v_exp_f32_e32 v137, v137
	v_mul_f32_e32 v135, 0xbfb8aa3b, v141
	v_add_f32_e32 v136, 1.0, v136
	v_rcp_f32_e32 v140, v136
	v_add_f32_e32 v136, 1.0, v137
	v_mul_f32_e32 v137, 0xbfb8aa3b, v144
	v_mul_f32_e32 v138, 0xbfb8aa3b, v138
	v_mul_f32_e32 v139, 0xbfb8aa3b, v139
	v_exp_f32_e32 v137, v137
	v_mul_f32_e32 v141, 0xbfb8aa3b, v145
	v_exp_f32_e32 v133, v133
	v_exp_f32_e32 v135, v135
	v_exp_f32_e32 v138, v138
	v_exp_f32_e32 v139, v139
	v_exp_f32_e32 v141, v141
	v_rcp_f32_e32 v144, v136
	v_add_f32_e32 v136, 1.0, v137
	v_add_f32_e32 v133, 1.0, v133
	v_add_f32_e32 v135, 1.0, v135
	v_add_f32_e32 v138, 1.0, v138
	v_add_f32_e32 v139, 1.0, v139
	v_rcp_f32_e32 v145, v136
	v_add_f32_e32 v136, 1.0, v141
	v_rcp_f32_e32 v133, v133
	v_rcp_f32_e32 v135, v135
	v_rcp_f32_e32 v138, v138
	v_rcp_f32_e32 v139, v139
	v_rcp_f32_e32 v141, v136
	v_cvt_pk_bf16_f32 v136, v133, v135
	v_cvt_pk_bf16_f32 v137, v138, v139
	v_cvt_pk_bf16_f32 v138, v140, v144
	v_cvt_pk_bf16_f32 v139, v145, v141
	global_store_dwordx4 v[142:143], v[136:139], off offset:256
	v_pk_mul_f32 v[140:141], v[26:27], v[134:135] op_sel_hi:[1,0]
	s_nop 0
	v_pk_mul_f32 v[136:137], v[30:31], v[134:135] op_sel_hi:[1,0]
	v_pk_mul_f32 v[138:139], v[28:29], v[134:135] op_sel_hi:[1,0]
	v_mul_f32_e32 v136, 0xbfb8aa3b, v136
	v_mul_f32_e32 v135, 0xbfb8aa3b, v139
	v_exp_f32_e32 v135, v135
	v_exp_f32_e32 v136, v136
	v_mul_f32_e32 v137, 0xbfb8aa3b, v137
	v_exp_f32_e32 v137, v137
	v_mul_f32_e32 v133, 0xbfb8aa3b, v138
	v_pk_mul_f32 v[138:139], v[24:25], v[134:135] op_sel_hi:[1,0]
	v_add_f32_e32 v136, 1.0, v136
	v_rcp_f32_e32 v142, v136
	v_add_f32_e32 v136, 1.0, v137
	v_mul_f32_e32 v137, 0xbfb8aa3b, v138
	v_exp_f32_e32 v137, v137
	v_mul_f32_e32 v138, 0xbfb8aa3b, v139
	v_exp_f32_e32 v138, v138
	v_rcp_f32_e32 v139, v136
	v_add_f32_e32 v136, 1.0, v137
	v_mul_f32_e32 v137, 0xbfb8aa3b, v140
	v_rcp_f32_e32 v143, v136
	v_add_f32_e32 v136, 1.0, v138
	v_exp_f32_e32 v137, v137
	v_mul_f32_e32 v138, 0xbfb8aa3b, v141
	v_exp_f32_e32 v133, v133
	v_exp_f32_e32 v138, v138
	v_rcp_f32_e32 v140, v136
	v_add_f32_e32 v136, 1.0, v137
	v_add_f32_e32 v133, 1.0, v133
	v_add_f32_e32 v135, 1.0, v135
	v_rcp_f32_e32 v141, v136
	v_add_f32_e32 v136, 1.0, v138
	v_rcp_f32_e32 v133, v133
	v_rcp_f32_e32 v135, v135
	v_rcp_f32_e32 v144, v136
	v_cvt_pk_bf16_f32 v138, v143, v140
	v_add_co_u32_e32 v140, vcc, s64, v130
	v_cvt_pk_bf16_f32 v136, v133, v135
	v_cvt_pk_bf16_f32 v137, v142, v139
	v_cvt_pk_bf16_f32 v139, v141, v144
	v_addc_co_u32_e32 v141, vcc, 0, v131, vcc
	global_store_dwordx4 v[140:141], v[136:139], off
; DI unsigned pk_bf16(float lo, float hi) { f32x2 v = {lo, hi}; return __builtin_bit_cast(unsigned, __builtin_convertvector(v, bf16v2)); }
; DI float fast_sigmoid(float x) { return __builtin_amdgcn_rcpf(1.0f + __expf(-x)); }
;     DI void operator()(AccRef acc, const Unit& u, int wr, int wc, int fr, int fq) const {
;     ...
; #pragma unroll
;         for (int ai = 0; ai < 2; ++ai)
; #pragma unroll
;             for (int m = 0; m < 4; ++m)
; #pragma unroll
;                 for (int bj = 0; bj < 2; ++bj) {
;                     const float rs = rsc.r[ai][m];
;                     const f32x4 r0 = acc[ai][bj][m][0] * rs, r1 = acc[ai][bj][m][1] * rs;
;                     u32x4 w;
;                     w.x = pk_bf16(fast_sigmoid(r0[0]), fast_sigmoid(r0[1])); w.y = pk_bf16(fast_sigmoid(r0[2]), fast_sigmoid(r0[3]));
;                     w.z = pk_bf16(fast_sigmoid(r1[0]), fast_sigmoid(r1[1])); w.w = pk_bf16(fast_sigmoid(r1[2]), fast_sigmoid(r1[3]));
;                     *(u32x4*)(Gp + (ai * 128 + m * 16) * 256 + bj * 128) = w;
;                 }
	v_pk_mul_f32 v[142:143], v[18:19], v[134:135] op_sel_hi:[1,0]
	s_nop 0
	v_pk_mul_f32 v[138:139], v[20:21], v[134:135] op_sel_hi:[1,0]
	v_pk_mul_f32 v[136:137], v[22:23], v[134:135] op_sel_hi:[1,0]
	v_mul_f32_e32 v135, 0xbfb8aa3b, v139
	v_mul_f32_e32 v133, 0xbfb8aa3b, v138
	v_exp_f32_e32 v138, v135
	v_pk_mul_f32 v[134:135], v[16:17], v[134:135] op_sel_hi:[1,0]
	v_mul_f32_e32 v136, 0xbfb8aa3b, v136
	v_mul_f32_e32 v134, 0xbfb8aa3b, v134
	v_exp_f32_e32 v134, v134
	v_mul_f32_e32 v135, 0xbfb8aa3b, v135
	v_exp_f32_e32 v135, v135
	v_mul_f32_e32 v137, 0xbfb8aa3b, v137
	v_add_f32_e32 v134, 1.0, v134
	v_rcp_f32_e32 v139, v134
	v_add_f32_e32 v134, 1.0, v135
	v_mul_f32_e32 v135, 0xbfb8aa3b, v142
	v_exp_f32_e32 v135, v135
	v_mul_f32_e32 v142, 0xbfb8aa3b, v143
	v_exp_f32_e32 v133, v133
	v_exp_f32_e32 v136, v136
	v_exp_f32_e32 v137, v137
	v_exp_f32_e32 v142, v142
	v_rcp_f32_e32 v143, v134
	v_add_f32_e32 v134, 1.0, v135
	v_add_f32_e32 v133, 1.0, v133
	v_add_f32_e32 v138, 1.0, v138
	v_add_f32_e32 v136, 1.0, v136
	v_add_f32_e32 v137, 1.0, v137
	v_rcp_f32_e32 v144, v134
	v_add_f32_e32 v134, 1.0, v142
	v_rcp_f32_e32 v133, v133
	v_rcp_f32_e32 v138, v138
	v_rcp_f32_e32 v136, v136
	v_rcp_f32_e32 v137, v137
	v_rcp_f32_e32 v142, v134
	v_cvt_pk_bf16_f32 v134, v133, v138
	v_cvt_pk_bf16_f32 v135, v136, v137
	v_cvt_pk_bf16_f32 v136, v139, v143
	v_cvt_pk_bf16_f32 v137, v144, v142
	global_store_dwordx4 v[140:141], v[134:137], off offset:256
	v_pk_mul_f32 v[138:139], v[10:11], v[132:133] op_sel_hi:[1,0]
	s_nop 0
	v_pk_mul_f32 v[134:135], v[14:15], v[132:133] op_sel_hi:[1,0]
	v_pk_mul_f32 v[136:137], v[12:13], v[132:133] op_sel_hi:[1,0]
	v_mul_f32_e32 v134, 0xbfb8aa3b, v134
	v_mul_f32_e32 v133, 0xbfb8aa3b, v136
	v_exp_f32_e32 v133, v133
	v_exp_f32_e32 v134, v134
	v_mul_f32_e32 v135, 0xbfb8aa3b, v135
	v_exp_f32_e32 v135, v135
	v_mul_f32_e32 v136, 0xbfb8aa3b, v137
	v_exp_f32_e32 v140, v136
	v_pk_mul_f32 v[136:137], v[8:9], v[132:133] op_sel_hi:[1,0]
	v_add_f32_e32 v134, 1.0, v134
	v_rcp_f32_e32 v141, v134
	v_add_f32_e32 v134, 1.0, v135
	v_mul_f32_e32 v135, 0xbfb8aa3b, v136
	v_exp_f32_e32 v135, v135
	v_mul_f32_e32 v136, 0xbfb8aa3b, v137
	v_exp_f32_e32 v136, v136
	v_rcp_f32_e32 v137, v134
	v_add_f32_e32 v134, 1.0, v135
	v_mul_f32_e32 v135, 0xbfb8aa3b, v138
	v_rcp_f32_e32 v142, v134
	v_add_f32_e32 v134, 1.0, v136
	v_exp_f32_e32 v135, v135
	v_mul_f32_e32 v136, 0xbfb8aa3b, v139
	v_exp_f32_e32 v136, v136
	v_rcp_f32_e32 v138, v134
	v_add_f32_e32 v134, 1.0, v135
	v_add_f32_e32 v133, 1.0, v133
	v_rcp_f32_e32 v139, v134
	v_add_f32_e32 v134, 1.0, v136
	v_rcp_f32_e32 v133, v133
	v_rcp_f32_e32 v143, v134
	v_add_f32_e32 v140, 1.0, v140
	v_rcp_f32_e32 v140, v140
	v_cvt_pk_bf16_f32 v136, v142, v138
	v_add_co_u32_e32 v138, vcc, s65, v130
	v_cvt_pk_bf16_f32 v135, v141, v137
	v_cvt_pk_bf16_f32 v137, v139, v143
	v_addc_co_u32_e32 v139, vcc, 0, v131, vcc
	v_pk_mul_f32 v[130:131], v[6:7], v[132:133] op_sel_hi:[1,0]
	v_cvt_pk_bf16_f32 v134, v133, v140
	v_mul_f32_e32 v130, 0xbfb8aa3b, v130
	v_exp_f32_e32 v130, v130
	v_mul_f32_e32 v131, 0xbfb8aa3b, v131
	global_store_dwordx4 v[138:139], v[134:137], off
	v_exp_f32_e32 v131, v131
	v_add_f32_e32 v130, 1.0, v130
	v_pk_mul_f32 v[134:135], v[4:5], v[132:133] op_sel_hi:[1,0]
	v_pk_mul_f32 v[136:137], v[2:3], v[132:133] op_sel_hi:[1,0]
	v_mul_f32_e32 v133, 0xbfb8aa3b, v134
	v_exp_f32_e32 v134, v133
	v_mul_f32_e32 v133, 0xbfb8aa3b, v135
	v_exp_f32_e32 v135, v133
	v_pk_mul_f32 v[132:133], v[0:1], v[132:133] op_sel_hi:[1,0]
	v_rcp_f32_e32 v140, v130
	v_add_f32_e32 v130, 1.0, v131
	v_mul_f32_e32 v131, 0xbfb8aa3b, v132
	v_exp_f32_e32 v131, v131
	v_mul_f32_e32 v132, 0xbfb8aa3b, v133
	v_exp_f32_e32 v132, v132
	v_rcp_f32_e32 v133, v130
	v_add_f32_e32 v130, 1.0, v131
	v_mul_f32_e32 v131, 0xbfb8aa3b, v136
	v_rcp_f32_e32 v141, v130
	v_add_f32_e32 v130, 1.0, v132
	v_exp_f32_e32 v131, v131
	v_mul_f32_e32 v132, 0xbfb8aa3b, v137
	v_exp_f32_e32 v132, v132
	v_rcp_f32_e32 v136, v130
	v_add_f32_e32 v130, 1.0, v131
	v_add_f32_e32 v134, 1.0, v134
	v_add_f32_e32 v135, 1.0, v135
	v_rcp_f32_e32 v137, v130
	v_add_f32_e32 v130, 1.0, v132
	v_rcp_f32_e32 v134, v134
	v_rcp_f32_e32 v135, v135
	v_rcp_f32_e32 v142, v130
	v_cvt_pk_bf16_f32 v131, v140, v133
	v_cvt_pk_bf16_f32 v132, v141, v136
	v_cvt_pk_bf16_f32 v130, v134, v135
	v_cvt_pk_bf16_f32 v133, v137, v142
	global_store_dwordx4 v[138:139], v[130:133], off offset:256

; #define PG8_STAGE(bufoff, gbase, voff) do { _Pragma("unroll") for (int _i = 0; _i < 2; ++_i) \
;         __builtin_amdgcn_global_load_lds((const unsigned*)((const char*)(gbase) + (voff)[_i]), (LAS unsigned*)(lds + (bufoff) + ldsw + _i * 8192), 16, 0, 0); } while (0)
; #define PG8_LDA(dst, b, h) do { _Pragma("unroll") for (int m = 0; m < 4; ++m) _Pragma("unroll") for (int k = 0; k < 2; ++k) dst[m][k] = *(const LAS bf16x8*)(lds + PG8_SA(b, h) + aoff + m * 2048 + k * 1024); } while (0)
; #define PG8_LDB(dst, b, h) do { _Pragma("unroll") for (int n = 0; n < 2; ++n) _Pragma("unroll") for (int k = 0; k < 2; ++k) dst[n][k] = *(const LAS bf16x8*)(lds + PG8_SB(b, h) + boff + n * 2048 + k * 1024); } while (0)
; #define PG8_MMA(ai, bj, At, Bt) do { __builtin_amdgcn_s_setprio(1); _Pragma("unroll") for (int m = 0; m < 4; ++m) _Pragma("unroll") for (int n = 0; n < 2; ++n) _Pragma("unroll") for (int k = 0; k < 2; ++k) \
;         acc[ai][bj][m][n] = __builtin_amdgcn_mfma_f32_16x16x32_bf16(Bt[n][k], At[m][k], acc[ai][bj][m][n], 0, 0, 0); __builtin_amdgcn_s_setprio(0); } while (0)
; #define PG8_WAIT_L(n) asm volatile("s_waitcnt lgkmcnt(" #n ")" ::: "memory")
; #define PG8_BAR __builtin_amdgcn_s_barrier()
; #define PG8_SCHED __builtin_amdgcn_sched_barrier(0)
; #define PG8_STAGE(bufoff, gbase, voff) do { _Pragma("unroll") for (int _i = 0; _i < 2; ++_i) \
;         __builtin_amdgcn_global_load_lds((const unsigned*)((const char*)(gbase) + (voff)[_i]), (LAS unsigned*)(lds + (bufoff) + ldsw + _i * 8192), 16, 0, 0); } while (0)
; #define PG8_WAIT_L(n) asm volatile("s_waitcnt lgkmcnt(" #n ")" ::: "memory")
; #define PG8_BAR __builtin_amdgcn_s_barrier()
; #define PG8_SCHED __builtin_amdgcn_sched_barrier(0)
; template <class Epi0, class Epi1>
; DI void gemm_phase_dual(LAS unsigned char* lds, const Gemm g, const Gemm g1, const StaticOrder S, const Epi0 E0, const Epi1 E1) {
;     ...
;             PG8_LDB(B0, 0, 0); PG8_SCHED; PG8_LDA(At, 0, 0); PG8_STAGE(PG8_SA(1, 1), a1 + hstep, voffA);
;             PG8_WAIT_L(8); PG8_BAR; PG8_WAIT_L(0); PG8_MMA(0, 0, At, B0); PG8_BAR; PG8_SCHED;
;             PG8_LDB(B1, 0, 1); PG8_STAGE(PG8_SB(0, 0), b2, voffB);
;             PG8_BAR; PG8_WAIT_L(0); PG8_MMA(0, 1, At, B1); PG8_BAR;
;             PG8_LDA(At, 0, 1); PG8_STAGE(PG8_SA(0, 0), a2, voffA);
;             PG8_BAR; PG8_WAIT_L(0); PG8_MMA(1, 0, At, B0); PG8_BAR; PG8_SCHED;
.LBB0_708:
	ds_read_b128 v[156:159], v179
	ds_read_b128 v[160:163], v179 offset:1024
	ds_read_b128 v[164:167], v179 offset:2048
	ds_read_b128 v[168:171], v179 offset:3072
	s_add_u32 s40, s38, 0xfffc0080
	s_addc_u32 s41, s39, -1
	s_cmp_eq_u32 s69, 12
	s_cselect_b32 s43, s6, s41
	s_cselect_b32 s42, s7, s40
	s_cselect_b32 s41, s17, s68
	s_cselect_b32 s40, s19, s67
	v_lshl_add_u64 v[210:211], s[38:39], 0, v[148:149]
	s_add_i32 m0, s25, 0xc000
	ds_read_b128 v[172:175], v180
	ds_read_b128 v[186:189], v180 offset:2048
	ds_read_b128 v[194:197], v180 offset:4096
	ds_read_b128 v[202:205], v180 offset:6144
	global_load_lds_dwordx4 v[210:211], off
	v_lshl_add_u64 v[210:211], s[38:39], 0, v[150:151]
	s_add_i32 m0, s25, 0xe000
	s_nop 0
	global_load_lds_dwordx4 v[210:211], off
	s_waitcnt lgkmcnt(4)
	s_setprio 1
	s_barrier
	s_waitcnt lgkmcnt(0)
	v_mfma_f32_16x16x32_bf16 v[124:127], v[156:159], v[172:175], v[124:127]
	ds_read_b128 v[182:185], v180 offset:1024
	v_mfma_f32_16x16x32_bf16 v[120:123], v[164:167], v[172:175], v[120:123]
	ds_read_b128 v[190:193], v180 offset:3072
	v_mfma_f32_16x16x32_bf16 v[108:111], v[156:159], v[186:189], v[108:111]
	ds_read_b128 v[198:201], v180 offset:5120
	v_mfma_f32_16x16x32_bf16 v[104:107], v[164:167], v[186:189], v[104:107]
	ds_read_b128 v[206:209], v180 offset:7168
	v_mfma_f32_16x16x32_bf16 v[92:95], v[156:159], v[194:197], v[92:95]
	v_mfma_f32_16x16x32_bf16 v[88:91], v[164:167], v[194:197], v[88:91]
	v_mfma_f32_16x16x32_bf16 v[84:87], v[156:159], v[202:205], v[84:87]
	v_mfma_f32_16x16x32_bf16 v[80:83], v[164:167], v[202:205], v[80:83]
	s_waitcnt lgkmcnt(3)
	v_mfma_f32_16x16x32_bf16 v[124:127], v[160:163], v[182:185], v[124:127]
	v_mfma_f32_16x16x32_bf16 v[120:123], v[168:171], v[182:185], v[120:123]
	s_waitcnt lgkmcnt(2)
	v_mfma_f32_16x16x32_bf16 v[108:111], v[160:163], v[190:193], v[108:111]
	v_mfma_f32_16x16x32_bf16 v[104:107], v[168:171], v[190:193], v[104:107]
	s_waitcnt lgkmcnt(1)
	v_mfma_f32_16x16x32_bf16 v[92:95], v[160:163], v[198:201], v[92:95]
	v_mfma_f32_16x16x32_bf16 v[88:91], v[168:171], v[198:201], v[88:91]
	s_waitcnt lgkmcnt(0)
	s_setprio 2
	s_barrier
	v_mfma_f32_16x16x32_bf16 v[84:87], v[160:163], v[206:209], v[84:87]
	v_mfma_f32_16x16x32_bf16 v[80:83], v[168:171], v[206:209], v[80:83]
	s_setprio 0
	s_add_i32 s76, s52, s44
	v_lshl_add_u64 v[228:229], s[40:41], 0, v[130:131]
	s_mov_b32 m0, s76
	ds_read_b128 v[210:213], v181
	ds_read_b128 v[214:217], v181 offset:1024
	ds_read_b128 v[218:221], v181 offset:2048
	ds_read_b128 v[224:227], v181 offset:3072
	global_load_lds_dwordx4 v[228:229], off
	v_lshl_add_u64 v[230:231], s[40:41], 0, v[134:135]
	s_add_i32 m0, s76, 0x2000
	s_nop 0
	global_load_lds_dwordx4 v[230:231], off
	s_setprio 1
	s_barrier
	s_waitcnt lgkmcnt(0)
	v_mfma_f32_16x16x32_bf16 v[116:119], v[210:213], v[172:175], v[116:119]
	v_mfma_f32_16x16x32_bf16 v[112:115], v[218:221], v[172:175], v[112:115]
	v_mfma_f32_16x16x32_bf16 v[100:103], v[210:213], v[186:189], v[100:103]
	v_mfma_f32_16x16x32_bf16 v[96:99], v[218:221], v[186:189], v[96:99]
	v_mfma_f32_16x16x32_bf16 v[76:79], v[210:213], v[194:197], v[76:79]
	v_mfma_f32_16x16x32_bf16 v[72:75], v[218:221], v[194:197], v[72:75]
	v_mfma_f32_16x16x32_bf16 v[68:71], v[210:213], v[202:205], v[68:71]
	v_mfma_f32_16x16x32_bf16 v[64:67], v[218:221], v[202:205], v[64:67]
	v_mfma_f32_16x16x32_bf16 v[116:119], v[214:217], v[182:185], v[116:119]
	v_mfma_f32_16x16x32_bf16 v[112:115], v[224:227], v[182:185], v[112:115]
	v_mfma_f32_16x16x32_bf16 v[100:103], v[214:217], v[190:193], v[100:103]
	v_mfma_f32_16x16x32_bf16 v[96:99], v[224:227], v[190:193], v[96:99]
	v_mfma_f32_16x16x32_bf16 v[76:79], v[214:217], v[198:201], v[76:79]
	v_mfma_f32_16x16x32_bf16 v[72:75], v[224:227], v[198:201], v[72:75]
	s_setprio 2
	s_barrier
	v_mfma_f32_16x16x32_bf16 v[68:71], v[214:217], v[206:209], v[68:71]
	v_mfma_f32_16x16x32_bf16 v[64:67], v[224:227], v[206:209], v[64:67]
	s_setprio 0
	s_mov_b32 m0, s25
	v_lshl_add_u64 v[232:233], s[42:43], 0, v[128:129]
	ds_read_b128 v[172:175], v180 offset:16384
	ds_read_b128 v[186:189], v180 offset:18432
	ds_read_b128 v[194:197], v180 offset:20480
	ds_read_b128 v[202:205], v180 offset:22528
	global_load_lds_dwordx4 v[232:233], off
	v_lshl_add_u64 v[234:235], s[42:43], 0, v[132:133]
	s_mov_b32 m0, s45
	s_nop 0
	global_load_lds_dwordx4 v[234:235], off
	s_setprio 1
	s_barrier
	s_waitcnt lgkmcnt(0)
	v_mfma_f32_16x16x32_bf16 v[60:63], v[156:159], v[172:175], v[60:63]
	ds_read_b128 v[182:185], v180 offset:17408
	v_mfma_f32_16x16x32_bf16 v[56:59], v[164:167], v[172:175], v[56:59]
	ds_read_b128 v[190:193], v180 offset:19456
	v_mfma_f32_16x16x32_bf16 v[52:55], v[156:159], v[186:189], v[52:55]
	ds_read_b128 v[198:201], v180 offset:21504
	v_mfma_f32_16x16x32_bf16 v[48:51], v[164:167], v[186:189], v[48:51]
	ds_read_b128 v[206:209], v180 offset:23552
	v_mfma_f32_16x16x32_bf16 v[28:31], v[156:159], v[194:197], v[28:31]
	v_mfma_f32_16x16x32_bf16 v[24:27], v[164:167], v[194:197], v[24:27]
	v_mfma_f32_16x16x32_bf16 v[20:23], v[156:159], v[202:205], v[20:23]
	v_mfma_f32_16x16x32_bf16 v[16:19], v[164:167], v[202:205], v[16:19]
	s_waitcnt lgkmcnt(3)
	v_mfma_f32_16x16x32_bf16 v[60:63], v[160:163], v[182:185], v[60:63]
	v_mfma_f32_16x16x32_bf16 v[56:59], v[168:171], v[182:185], v[56:59]
	s_waitcnt lgkmcnt(2)
	v_mfma_f32_16x16x32_bf16 v[52:55], v[160:163], v[190:193], v[52:55]
	v_mfma_f32_16x16x32_bf16 v[48:51], v[168:171], v[190:193], v[48:51]
	s_waitcnt lgkmcnt(1)
	v_mfma_f32_16x16x32_bf16 v[28:31], v[160:163], v[198:201], v[28:31]
	v_mfma_f32_16x16x32_bf16 v[24:27], v[168:171], v[198:201], v[24:27]
	s_waitcnt lgkmcnt(0)
	s_setprio 2
	s_barrier
; #define PG8_STAGE(bufoff, gbase, voff) do { _Pragma("unroll") for (int _i = 0; _i < 2; ++_i) \
;         __builtin_amdgcn_global_load_lds((const unsigned*)((const char*)(gbase) + (voff)[_i]), (LAS unsigned*)(lds + (bufoff) + ldsw + _i * 8192), 16, 0, 0); } while (0)
; #define PG8_LDA(dst, b, h) do { _Pragma("unroll") for (int m = 0; m < 4; ++m) _Pragma("unroll") for (int k = 0; k < 2; ++k) dst[m][k] = *(const LAS bf16x8*)(lds + PG8_SA(b, h) + aoff + m * 2048 + k * 1024); } while (0)
; #define PG8_LDB(dst, b, h) do { _Pragma("unroll") for (int n = 0; n < 2; ++n) _Pragma("unroll") for (int k = 0; k < 2; ++k) dst[n][k] = *(const LAS bf16x8*)(lds + PG8_SB(b, h) + boff + n * 2048 + k * 1024); } while (0)
; #define PG8_MMA(ai, bj, At, Bt) do { __builtin_amdgcn_s_setprio(1); _Pragma("unroll") for (int m = 0; m < 4; ++m) _Pragma("unroll") for (int n = 0; n < 2; ++n) _Pragma("unroll") for (int k = 0; k < 2; ++k) \
;         acc[ai][bj][m][n] = __builtin_amdgcn_mfma_f32_16x16x32_bf16(Bt[n][k], At[m][k], acc[ai][bj][m][n], 0, 0, 0); __builtin_amdgcn_s_setprio(0); } while (0)
; #define PG8_WAIT_V(n) asm volatile("s_waitcnt vmcnt(" #n ")" ::: "memory")
; #define PG8_WAIT_L(n) asm volatile("s_waitcnt lgkmcnt(" #n ")" ::: "memory")
; #define PG8_BAR __builtin_amdgcn_s_barrier()
; #define PG8_SCHED __builtin_amdgcn_sched_barrier(0)
; #define PG8_STAGE(bufoff, gbase, voff) do { _Pragma("unroll") for (int _i = 0; _i < 2; ++_i) \
;         __builtin_amdgcn_global_load_lds((const unsigned*)((const char*)(gbase) + (voff)[_i]), (LAS unsigned*)(lds + (bufoff) + ldsw + _i * 8192), 16, 0, 0); } while (0)
; #define PG8_BAR __builtin_amdgcn_s_barrier()
; template <class Epi0, class Epi1>
; DI void gemm_phase_dual(LAS unsigned char* lds, const Gemm g, const Gemm g1, const StaticOrder S, const Epi0 E0, const Epi1 E1) {
;     ...
;             PG8_BAR; PG8_WAIT_L(0); PG8_MMA(1, 0, At, B0); PG8_BAR; PG8_SCHED;
;             PG8_STAGE(PG8_SB(0, 1), b2 + hstep, voffB);
;             PG8_WAIT_V(6); PG8_BAR; PG8_MMA(1, 1, At, B1); PG8_BAR;
;             PG8_LDB(B0, 1, 0); PG8_SCHED; PG8_LDA(At, 1, 0); PG8_STAGE(PG8_SA(0, 1), a2 + hstep, voffA);
;             PG8_WAIT_L(8); PG8_BAR; PG8_WAIT_L(0); PG8_MMA(0, 0, At, B0); PG8_BAR; PG8_SCHED;
;             PG8_LDB(B1, 1, 1); PG8_STAGE(PG8_SB(1, 0), b3, voffB);
;             PG8_BAR; PG8_WAIT_L(0); PG8_MMA(0, 1, At, B1); PG8_BAR;
	v_mfma_f32_16x16x32_bf16 v[20:23], v[160:163], v[206:209], v[20:23]
	v_mfma_f32_16x16x32_bf16 v[16:19], v[168:171], v[206:209], v[16:19]
	s_setprio 0
	s_add_u32 s76, s40, 0x40000
	s_addc_u32 s77, s41, 0
	s_add_i32 s78, s53, s44
	v_lshl_add_u64 v[156:157], s[76:77], 0, v[130:131]
	s_mov_b32 m0, s78
	s_nop 0
	global_load_lds_dwordx4 v[156:157], off
	v_lshl_add_u64 v[156:157], s[76:77], 0, v[134:135]
	s_add_i32 m0, s78, 0x2000
	s_nop 0
	global_load_lds_dwordx4 v[156:157], off
	s_waitcnt vmcnt(6)
	s_setprio 1
	s_barrier
	v_mfma_f32_16x16x32_bf16 v[44:47], v[210:213], v[172:175], v[44:47]
	v_mfma_f32_16x16x32_bf16 v[40:43], v[218:221], v[172:175], v[40:43]
	v_mfma_f32_16x16x32_bf16 v[36:39], v[210:213], v[186:189], v[36:39]
	v_mfma_f32_16x16x32_bf16 v[32:35], v[218:221], v[186:189], v[32:35]
	v_mfma_f32_16x16x32_bf16 v[12:15], v[210:213], v[194:197], v[12:15]
	v_mfma_f32_16x16x32_bf16 v[8:11], v[218:221], v[194:197], v[8:11]
	v_mfma_f32_16x16x32_bf16 v[4:7], v[210:213], v[202:205], v[4:7]
	v_mfma_f32_16x16x32_bf16 v[0:3], v[218:221], v[202:205], v[0:3]
	v_mfma_f32_16x16x32_bf16 v[44:47], v[214:217], v[182:185], v[44:47]
	v_mfma_f32_16x16x32_bf16 v[40:43], v[224:227], v[182:185], v[40:43]
	v_mfma_f32_16x16x32_bf16 v[36:39], v[214:217], v[190:193], v[36:39]
	v_mfma_f32_16x16x32_bf16 v[32:35], v[224:227], v[190:193], v[32:35]
	v_mfma_f32_16x16x32_bf16 v[12:15], v[214:217], v[198:201], v[12:15]
	v_mfma_f32_16x16x32_bf16 v[8:11], v[224:227], v[198:201], v[8:11]
	s_setprio 2
	s_barrier
	v_mfma_f32_16x16x32_bf16 v[4:7], v[214:217], v[206:209], v[4:7]
	v_mfma_f32_16x16x32_bf16 v[0:3], v[224:227], v[206:209], v[0:3]
	s_setprio 0
	s_add_i32 s76, 0, 0x18000
	v_add_u32_e32 v168, s76, v177
	ds_read_b128 v[156:159], v168
	ds_read_b128 v[160:163], v168 offset:1024
	ds_read_b128 v[164:167], v168 offset:2048
	ds_read_b128 v[168:171], v168 offset:3072
	s_add_u32 s42, s42, 0x40000
	s_addc_u32 s43, s43, 0
	s_mov_b32 m0, s46
	v_lshl_add_u64 v[210:211], s[42:43], 0, v[128:129]
	ds_read_b128 v[172:175], v180 offset:32768
	ds_read_b128 v[186:189], v180 offset:34816
	ds_read_b128 v[194:197], v180 offset:36864
	ds_read_b128 v[202:205], v180 offset:38912
	global_load_lds_dwordx4 v[210:211], off
	v_lshl_add_u64 v[210:211], s[42:43], 0, v[132:133]
	s_mov_b32 m0, s47
	s_nop 0
	global_load_lds_dwordx4 v[210:211], off
	s_waitcnt lgkmcnt(4)
	s_setprio 1
	s_barrier
	s_waitcnt lgkmcnt(0)
	v_mfma_f32_16x16x32_bf16 v[124:127], v[156:159], v[172:175], v[124:127]
	ds_read_b128 v[182:185], v180 offset:33792
	v_mfma_f32_16x16x32_bf16 v[120:123], v[164:167], v[172:175], v[120:123]
	ds_read_b128 v[190:193], v180 offset:35840
	v_mfma_f32_16x16x32_bf16 v[108:111], v[156:159], v[186:189], v[108:111]
	ds_read_b128 v[198:201], v180 offset:37888
	v_mfma_f32_16x16x32_bf16 v[104:107], v[164:167], v[186:189], v[104:107]
	ds_read_b128 v[206:209], v180 offset:39936
	v_mfma_f32_16x16x32_bf16 v[92:95], v[156:159], v[194:197], v[92:95]
	v_mfma_f32_16x16x32_bf16 v[88:91], v[164:167], v[194:197], v[88:91]
	v_mfma_f32_16x16x32_bf16 v[84:87], v[156:159], v[202:205], v[84:87]
	v_mfma_f32_16x16x32_bf16 v[80:83], v[164:167], v[202:205], v[80:83]
	s_waitcnt lgkmcnt(3)
	v_mfma_f32_16x16x32_bf16 v[124:127], v[160:163], v[182:185], v[124:127]
	v_mfma_f32_16x16x32_bf16 v[120:123], v[168:171], v[182:185], v[120:123]
	s_waitcnt lgkmcnt(2)
	v_mfma_f32_16x16x32_bf16 v[108:111], v[160:163], v[190:193], v[108:111]
	v_mfma_f32_16x16x32_bf16 v[104:107], v[168:171], v[190:193], v[104:107]
	s_waitcnt lgkmcnt(1)
	v_mfma_f32_16x16x32_bf16 v[92:95], v[160:163], v[198:201], v[92:95]
	v_mfma_f32_16x16x32_bf16 v[88:91], v[168:171], v[198:201], v[88:91]
	s_waitcnt lgkmcnt(0)
	s_setprio 2
	s_barrier
	v_mfma_f32_16x16x32_bf16 v[84:87], v[160:163], v[206:209], v[84:87]
	v_mfma_f32_16x16x32_bf16 v[80:83], v[168:171], v[206:209], v[80:83]
	s_setprio 0
	s_add_i32 s42, 0, 0x1c000
	s_add_i32 s43, s76, s44
	v_add_u32_e32 v224, s42, v177
	v_lshl_add_u64 v[228:229], v[228:229], 0, s[8:9]
	s_mov_b32 m0, s43
	ds_read_b128 v[210:213], v224
	ds_read_b128 v[214:217], v224 offset:1024
	ds_read_b128 v[218:221], v224 offset:2048
	ds_read_b128 v[224:227], v224 offset:3072
	global_load_lds_dwordx4 v[228:229], off
	v_lshl_add_u64 v[228:229], v[230:231], 0, s[8:9]
	s_add_i32 m0, s43, 0x2000
	s_nop 0
	global_load_lds_dwordx4 v[228:229], off
	s_setprio 1
	s_barrier
	s_waitcnt lgkmcnt(0)
	v_mfma_f32_16x16x32_bf16 v[116:119], v[210:213], v[172:175], v[116:119]
	v_mfma_f32_16x16x32_bf16 v[112:115], v[218:221], v[172:175], v[112:115]
	v_mfma_f32_16x16x32_bf16 v[100:103], v[210:213], v[186:189], v[100:103]
	v_mfma_f32_16x16x32_bf16 v[96:99], v[218:221], v[186:189], v[96:99]
	v_mfma_f32_16x16x32_bf16 v[76:79], v[210:213], v[194:197], v[76:79]
	v_mfma_f32_16x16x32_bf16 v[72:75], v[218:221], v[194:197], v[72:75]
	v_mfma_f32_16x16x32_bf16 v[68:71], v[210:213], v[202:205], v[68:71]
	v_mfma_f32_16x16x32_bf16 v[64:67], v[218:221], v[202:205], v[64:67]
	v_mfma_f32_16x16x32_bf16 v[116:119], v[214:217], v[182:185], v[116:119]
	v_mfma_f32_16x16x32_bf16 v[112:115], v[224:227], v[182:185], v[112:115]
	v_mfma_f32_16x16x32_bf16 v[100:103], v[214:217], v[190:193], v[100:103]
	v_mfma_f32_16x16x32_bf16 v[96:99], v[224:227], v[190:193], v[96:99]
	v_mfma_f32_16x16x32_bf16 v[76:79], v[214:217], v[198:201], v[76:79]
	v_mfma_f32_16x16x32_bf16 v[72:75], v[224:227], v[198:201], v[72:75]
	s_setprio 2
	s_barrier
; #define PG8_STAGE(bufoff, gbase, voff) do { _Pragma("unroll") for (int _i = 0; _i < 2; ++_i) \
;         __builtin_amdgcn_global_load_lds((const unsigned*)((const char*)(gbase) + (voff)[_i]), (LAS unsigned*)(lds + (bufoff) + ldsw + _i * 8192), 16, 0, 0); } while (0)
; #define PG8_LDA(dst, b, h) do { _Pragma("unroll") for (int m = 0; m < 4; ++m) _Pragma("unroll") for (int k = 0; k < 2; ++k) dst[m][k] = *(const LAS bf16x8*)(lds + PG8_SA(b, h) + aoff + m * 2048 + k * 1024); } while (0)
; #define PG8_WAIT_V(n) asm volatile("s_waitcnt vmcnt(" #n ")" ::: "memory")
; #define PG8_WAIT_L(n) asm volatile("s_waitcnt lgkmcnt(" #n ")" ::: "memory")
; #define PG8_BAR __builtin_amdgcn_s_barrier()
; #define PG8_SCHED __builtin_amdgcn_sched_barrier(0)
; #define PG8_WAIT_V(n) asm volatile("s_waitcnt vmcnt(" #n ")" ::: "memory")
; template <class Epi0, class Epi1>
; DI void gemm_phase_dual(LAS unsigned char* lds, const Gemm g, const Gemm g1, const StaticOrder S, const Epi0 E0, const Epi1 E1) {
;     ...
;             PG8_BAR; PG8_WAIT_L(0); PG8_MMA(0, 1, At, B1); PG8_BAR;
;             PG8_LDA(At, 1, 1); PG8_STAGE(PG8_SA(1, 0), a3, voffA);
;             PG8_BAR; PG8_WAIT_L(0); PG8_MMA(1, 0, At, B0); PG8_BAR; PG8_SCHED;
;             PG8_STAGE(PG8_SB(1, 1), b3 + hstep, voffB);
;             PG8_WAIT_V(6); PG8_BAR; PG8_MMA(1, 1, At, B1); PG8_BAR;
;         }
;         if (ui & 1) E1(acc, cur, wr, wc, fr, fq); else E0(acc, cur, wr, wc, fr, fq);
;     DI void operator()(AccRef acc, const Unit& u, int wr, int wc, int fr, int fq) const {
;         const int row0 = u.pm * 256 + wr * 64 + fr, col0 = u.pn * 256 + wc * 32 + 8 * fq;
; #pragma unroll
;         for (int ai = 0; ai < 2; ++ai)
; #pragma unroll
;             for (int mh = 0; mh < 2; ++mh) {
;                 u32x4 gv[2][2], mv[2][2];
; #pragma unroll
;                 for (int mm = 0; mm < 2; ++mm)
; #pragma unroll
;                     for (int bj = 0; bj < 2; ++bj) {
;                         const size_t row = (size_t)(row0 + ai * 128 + (mh * 2 + mm) * 16); const int col = col0 + bj * 128;
;                         gv[mm][bj] = *(const u32x4*)(gab + (size_t)(u.pm * 8 + SECOND * 4 + u.pn) * 65536 + (wr * 64 + fr + ai * 128 + (mh * 2 + mm) * 16) * 256 + wc * 32 + 8 * fq + bj * 128);
;                         if (SECOND) mv[mm][bj] = *(const u32x4*)(mrg + row * 1024 + col);
;                     }
	v_mfma_f32_16x16x32_bf16 v[68:71], v[214:217], v[206:209], v[68:71]
	v_mfma_f32_16x16x32_bf16 v[64:67], v[224:227], v[206:209], v[64:67]
	s_setprio 0
	s_mov_b32 m0, s59
	v_lshl_add_u64 v[228:229], v[232:233], 0, s[8:9]
	ds_read_b128 v[172:175], v180 offset:49152
	ds_read_b128 v[186:189], v180 offset:51200
	ds_read_b128 v[194:197], v180 offset:53248
	ds_read_b128 v[202:205], v180 offset:55296
	global_load_lds_dwordx4 v[228:229], off
	v_lshl_add_u64 v[228:229], v[234:235], 0, s[8:9]
	s_mov_b32 m0, s60
	s_nop 0
	global_load_lds_dwordx4 v[228:229], off
	s_setprio 1
	s_barrier
	s_waitcnt lgkmcnt(0)
	v_mfma_f32_16x16x32_bf16 v[60:63], v[156:159], v[172:175], v[60:63]
	ds_read_b128 v[182:185], v180 offset:50176
	v_mfma_f32_16x16x32_bf16 v[56:59], v[164:167], v[172:175], v[56:59]
	ds_read_b128 v[190:193], v180 offset:52224
	v_mfma_f32_16x16x32_bf16 v[52:55], v[156:159], v[186:189], v[52:55]
	ds_read_b128 v[198:201], v180 offset:54272
	v_mfma_f32_16x16x32_bf16 v[48:51], v[164:167], v[186:189], v[48:51]
	ds_read_b128 v[206:209], v180 offset:56320
	v_mfma_f32_16x16x32_bf16 v[28:31], v[156:159], v[194:197], v[28:31]
	v_mfma_f32_16x16x32_bf16 v[24:27], v[164:167], v[194:197], v[24:27]
	v_mfma_f32_16x16x32_bf16 v[20:23], v[156:159], v[202:205], v[20:23]
	v_mfma_f32_16x16x32_bf16 v[16:19], v[164:167], v[202:205], v[16:19]
	s_waitcnt lgkmcnt(3)
	v_mfma_f32_16x16x32_bf16 v[60:63], v[160:163], v[182:185], v[60:63]
	v_mfma_f32_16x16x32_bf16 v[56:59], v[168:171], v[182:185], v[56:59]
	s_waitcnt lgkmcnt(2)
	v_mfma_f32_16x16x32_bf16 v[52:55], v[160:163], v[190:193], v[52:55]
	v_mfma_f32_16x16x32_bf16 v[48:51], v[168:171], v[190:193], v[48:51]
	s_waitcnt lgkmcnt(1)
	v_mfma_f32_16x16x32_bf16 v[28:31], v[160:163], v[198:201], v[28:31]
	v_mfma_f32_16x16x32_bf16 v[24:27], v[168:171], v[198:201], v[24:27]
	s_waitcnt lgkmcnt(0)
	s_setprio 2
	s_barrier
	v_mfma_f32_16x16x32_bf16 v[20:23], v[160:163], v[206:209], v[20:23]
	v_mfma_f32_16x16x32_bf16 v[16:19], v[168:171], v[206:209], v[16:19]
	s_setprio 0
	s_add_u32 s40, s40, 0x40080
	s_addc_u32 s41, s41, 0
	s_add_i32 s42, s42, s44
	v_lshl_add_u64 v[156:157], s[40:41], 0, v[130:131]
	s_mov_b32 m0, s42
	s_nop 0
	global_load_lds_dwordx4 v[156:157], off
	v_lshl_add_u64 v[156:157], s[40:41], 0, v[134:135]
	s_add_i32 m0, s42, 0x2000
	s_nop 0
	global_load_lds_dwordx4 v[156:157], off
	s_waitcnt vmcnt(6)
	s_setprio 1
	s_barrier
	v_mfma_f32_16x16x32_bf16 v[44:47], v[210:213], v[172:175], v[44:47]
	v_mfma_f32_16x16x32_bf16 v[40:43], v[218:221], v[172:175], v[40:43]
	v_mfma_f32_16x16x32_bf16 v[36:39], v[210:213], v[186:189], v[36:39]
	v_mfma_f32_16x16x32_bf16 v[32:35], v[218:221], v[186:189], v[32:35]
	v_mfma_f32_16x16x32_bf16 v[12:15], v[210:213], v[194:197], v[12:15]
	v_mfma_f32_16x16x32_bf16 v[8:11], v[218:221], v[194:197], v[8:11]
	v_mfma_f32_16x16x32_bf16 v[4:7], v[210:213], v[202:205], v[4:7]
	v_mfma_f32_16x16x32_bf16 v[0:3], v[218:221], v[202:205], v[0:3]
	v_mfma_f32_16x16x32_bf16 v[44:47], v[214:217], v[182:185], v[44:47]
	v_mfma_f32_16x16x32_bf16 v[40:43], v[224:227], v[182:185], v[40:43]
	v_mfma_f32_16x16x32_bf16 v[36:39], v[214:217], v[190:193], v[36:39]
	v_mfma_f32_16x16x32_bf16 v[32:35], v[224:227], v[190:193], v[32:35]
	v_mfma_f32_16x16x32_bf16 v[12:15], v[214:217], v[198:201], v[12:15]
	v_mfma_f32_16x16x32_bf16 v[8:11], v[224:227], v[198:201], v[8:11]
	s_setprio 2
	s_barrier
	v_mfma_f32_16x16x32_bf16 v[4:7], v[214:217], v[206:209], v[4:7]
	v_mfma_f32_16x16x32_bf16 v[0:3], v[224:227], v[206:209], v[0:3]
	s_setprio 0
	s_add_i32 s69, s69, 2
	s_add_u32 s38, s38, 0x100
	s_addc_u32 s39, s39, 0
	s_add_u32 s67, s67, 0x100
	s_addc_u32 s68, s68, 0
	s_cmp_gt_u32 s69, 13
	s_cbranch_scc0 .LBB0_708
	v_lshl_add_u32 v164, s24, 8, v176
	s_lshl_b32 s17, s66, 8
	v_or_b32_e32 v162, s17, v178
	v_or_b32_e32 v160, 16, v164
	s_mov_b64 s[6:7], -1
	s_and_b64 vcc, exec, s[28:29]
	v_ashrrev_i32_e32 v165, 31, v164
	v_ashrrev_i32_e32 v163, 31, v162
	v_ashrrev_i32_e32 v161, 31, v160
	v_or_b32_e32 v158, 32, v164
	v_or_b32_e32 v156, 48, v164
	s_cbranch_vccz .LBB0_711
	s_lshl_b32 s6, s24, 3
	s_add_i32 s6, s66, s6
	s_add_i32 s6, s6, 4
	v_lshlrev_b64 v[168:169], 11, v[160:161]
	s_ashr_i32 s7, s6, 31
	v_lshlrev_b64 v[166:167], 11, v[164:165]
	v_lshlrev_b64 v[170:171], 1, v[162:163]
	v_lshl_add_u64 v[168:169], s[36:37], 0, v[168:169]
	s_lshl_b64 s[6:7], s[6:7], 17
	v_lshl_add_u64 v[166:167], s[36:37], 0, v[166:167]
	v_lshl_add_u64 v[174:175], v[168:169], 0, v[170:171]
	v_lshl_add_u64 v[168:169], v[136:137], 0, s[6:7]
	v_lshl_add_u64 v[166:167], v[166:167], 0, v[170:171]
	v_lshl_add_u64 v[172:173], v[138:139], 1, v[168:169]
	global_load_dwordx4 v[182:185], v[166:167], off
	global_load_dwordx4 v[186:189], v[166:167], off offset:256
	global_load_dwordx4 v[190:193], v[174:175], off
	global_load_dwordx4 v[194:197], v[172:173], off
	global_load_dwordx4 v[198:201], v[172:173], off offset:256
	v_add_co_u32_e32 v206, vcc, s48, v172
	v_ashrrev_i32_e32 v159, 31, v158
	s_nop 0
	v_addc_co_u32_e32 v207, vcc, 0, v173, vcc
	global_load_dwordx4 v[202:205], v[206:207], off
	s_nop 0
	global_load_dwordx4 v[206:209], v[206:207], off offset:256
	s_nop 0
	global_load_dwordx4 v[210:213], v[174:175], off offset:256
	v_ashrrev_i32_e32 v157, 31, v156
	s_mov_b64 s[6:7], 0
	s_waitcnt vmcnt(0)
; DI unsigned pk_bf16(float lo, float hi) { f32x2 v = {lo, hi}; return __builtin_bit_cast(unsigned, __builtin_convertvector(v, bf16v2)); }
; DI float bf_lo(unsigned w) { return __uint_as_float(w << 16); }
; DI float bf_hi(unsigned w) { return __uint_as_float(w & 0xffff0000u); }
;     DI void operator()(AccRef acc, const Unit& u, int wr, int wc, int fr, int fq) const {
;         const int row0 = u.pm * 256 + wr * 64 + fr, col0 = u.pn * 256 + wc * 32 + 8 * fq;
; #pragma unroll
;         for (int ai = 0; ai < 2; ++ai)
; #pragma unroll
;             for (int mh = 0; mh < 2; ++mh) {
;                 u32x4 gv[2][2], mv[2][2];
; #pragma unroll
;                 for (int mm = 0; mm < 2; ++mm)
; #pragma unroll
;                     for (int bj = 0; bj < 2; ++bj) {
;                         const size_t row = (size_t)(row0 + ai * 128 + (mh * 2 + mm) * 16); const int col = col0 + bj * 128;
;                         gv[mm][bj] = *(const u32x4*)(gab + (size_t)(u.pm * 8 + SECOND * 4 + u.pn) * 65536 + (wr * 64 + fr + ai * 128 + (mh * 2 + mm) * 16) * 256 + wc * 32 + 8 * fq + bj * 128);
;                         if (SECOND) mv[mm][bj] = *(const u32x4*)(mrg + row * 1024 + col);
;                     }
; #pragma unroll
;                 for (int mm = 0; mm < 2; ++mm)
; #pragma unroll
;                     for (int bj = 0; bj < 2; ++bj) {
;                         const int m = mh * 2 + mm;
;                         const size_t row = (size_t)(row0 + ai * 128 + m * 16); const int col = col0 + bj * 128;
;                         const u32x4 gt = gv[mm][bj];
;                         const f32x4 r0 = acc[ai][bj][m][0], r1 = acc[ai][bj][m][1];
;                         float v[8] = {bf_lo(gt.x) * r0[0], bf_hi(gt.x) * r0[1], bf_lo(gt.y) * r0[2], bf_hi(gt.y) * r0[3], bf_lo(gt.z) * r1[0], bf_hi(gt.z) * r1[1], bf_lo(gt.w) * r1[2], bf_hi(gt.w) * r1[3]};
;                         if (SECOND) { const u32x4 o = mv[mm][bj]; v[0] += bf_lo(o.x); v[1] += bf_hi(o.x); v[2] += bf_lo(o.y); v[3] += bf_hi(o.y); v[4] += bf_lo(o.z); v[5] += bf_hi(o.z); v[6] += bf_lo(o.w); v[7] += bf_hi(o.w); }
;                         u32x4 w; w.x = pk_bf16(v[0], v[1]); w.y = pk_bf16(v[2], v[3]); w.z = pk_bf16(v[4], v[5]); w.w = pk_bf16(v[6], v[7]);
;                         *(u32x4*)(mrg + row * 1024 + col) = w;
;                     }
	v_lshlrev_b32_e32 v214, 16, v182
	v_and_b32_e32 v215, 0xffff0000, v182
	v_lshlrev_b32_e32 v182, 16, v183
	v_and_b32_e32 v183, 0xffff0000, v183
	v_lshlrev_b32_e32 v216, 16, v184
	v_and_b32_e32 v217, 0xffff0000, v184
	v_lshlrev_b32_e32 v184, 16, v185
	v_and_b32_e32 v185, 0xffff0000, v185
	v_lshlrev_b32_e32 v228, 16, v194
	v_and_b32_e32 v229, 0xffff0000, v194
	v_lshlrev_b32_e32 v194, 16, v195
	v_and_b32_e32 v195, 0xffff0000, v195
	v_lshlrev_b32_e32 v230, 16, v196
	v_and_b32_e32 v231, 0xffff0000, v196
	v_lshlrev_b32_e32 v196, 16, v197
	v_and_b32_e32 v197, 0xffff0000, v197
	v_lshlrev_b32_e32 v218, 16, v186
	v_and_b32_e32 v219, 0xffff0000, v186
	v_lshlrev_b32_e32 v186, 16, v187
	v_and_b32_e32 v187, 0xffff0000, v187
	v_lshlrev_b32_e32 v220, 16, v188
	v_and_b32_e32 v221, 0xffff0000, v188
	v_lshlrev_b32_e32 v188, 16, v189
	v_and_b32_e32 v189, 0xffff0000, v189
	v_lshlrev_b32_e32 v232, 16, v198
	v_and_b32_e32 v233, 0xffff0000, v198
	v_lshlrev_b32_e32 v198, 16, v199
	v_and_b32_e32 v199, 0xffff0000, v199
	v_lshlrev_b32_e32 v234, 16, v200
	v_and_b32_e32 v235, 0xffff0000, v200
	v_lshlrev_b32_e32 v200, 16, v201
	v_and_b32_e32 v201, 0xffff0000, v201
	v_pk_fma_f32 v[214:215], v[124:125], v[228:229], v[214:215]
	v_pk_fma_f32 v[194:195], v[126:127], v[194:195], v[182:183]
	v_pk_fma_f32 v[216:217], v[120:121], v[230:231], v[216:217]
	v_pk_fma_f32 v[196:197], v[122:123], v[196:197], v[184:185]
	v_pk_fma_f32 v[218:219], v[116:117], v[232:233], v[218:219]
	v_pk_fma_f32 v[198:199], v[118:119], v[198:199], v[186:187]
	v_pk_fma_f32 v[220:221], v[112:113], v[234:235], v[220:221]
	v_pk_fma_f32 v[200:201], v[114:115], v[200:201], v[188:189]
	v_cvt_pk_bf16_f32 v182, v214, v215
	v_cvt_pk_bf16_f32 v183, v194, v195
	v_cvt_pk_bf16_f32 v184, v216, v217
	v_cvt_pk_bf16_f32 v185, v196, v197
	v_lshlrev_b32_e32 v224, 16, v190
	v_and_b32_e32 v225, 0xffff0000, v190
	v_lshlrev_b32_e32 v190, 16, v191
	v_and_b32_e32 v191, 0xffff0000, v191
	v_lshlrev_b32_e32 v226, 16, v192
	v_and_b32_e32 v227, 0xffff0000, v192
	v_lshlrev_b32_e32 v228, 16, v202
	v_and_b32_e32 v229, 0xffff0000, v202
	v_lshlrev_b32_e32 v202, 16, v203
	v_and_b32_e32 v203, 0xffff0000, v203
	v_lshlrev_b32_e32 v230, 16, v204
	v_and_b32_e32 v231, 0xffff0000, v204
	v_cvt_pk_bf16_f32 v186, v218, v219
	v_cvt_pk_bf16_f32 v187, v198, v199
	v_cvt_pk_bf16_f32 v188, v220, v221
	v_cvt_pk_bf16_f32 v189, v200, v201
	global_store_dwordx4 v[166:167], v[182:185], off
	global_store_dwordx4 v[166:167], v[186:189], off offset:256
	v_pk_fma_f32 v[194:195], v[108:109], v[228:229], v[224:225]
	v_lshlrev_b32_e32 v182, 16, v205
	v_and_b32_e32 v183, 0xffff0000, v205
	v_lshlrev_b32_e32 v184, 16, v193
	v_and_b32_e32 v185, 0xffff0000, v193
	v_pk_fma_f32 v[190:191], v[110:111], v[202:203], v[190:191]
	v_pk_fma_f32 v[196:197], v[104:105], v[230:231], v[226:227]
	v_pk_fma_f32 v[186:187], v[106:107], v[182:183], v[184:185]
	v_cvt_pk_bf16_f32 v182, v194, v195
	v_cvt_pk_bf16_f32 v183, v190, v191
	v_cvt_pk_bf16_f32 v184, v196, v197
	v_cvt_pk_bf16_f32 v185, v186, v187
	global_store_dwordx4 v[174:175], v[182:185], off
	v_lshlrev_b32_e32 v186, 16, v211
	v_and_b32_e32 v187, 0xffff0000, v211
	v_lshlrev_b32_e32 v182, 16, v206
	v_and_b32_e32 v183, 0xffff0000, v206
	v_lshlrev_b32_e32 v184, 16, v210
	v_and_b32_e32 v185, 0xffff0000, v210
	v_pk_fma_f32 v[182:183], v[100:101], v[182:183], v[184:185]
	v_lshlrev_b32_e32 v184, 16, v207
	v_and_b32_e32 v185, 0xffff0000, v207
	v_pk_fma_f32 v[184:185], v[102:103], v[184:185], v[186:187]
	v_lshlrev_b32_e32 v186, 16, v208
	v_and_b32_e32 v187, 0xffff0000, v208
	v_lshlrev_b32_e32 v188, 16, v212
	v_and_b32_e32 v189, 0xffff0000, v212
	v_pk_fma_f32 v[190:191], v[96:97], v[186:187], v[188:189]
	v_lshlrev_b32_e32 v186, 16, v209
	v_and_b32_e32 v187, 0xffff0000, v209
	v_lshlrev_b32_e32 v188, 16, v213
	v_and_b32_e32 v189, 0xffff0000, v213
	v_cvt_pk_bf16_f32 v182, v182, v183
	v_cvt_pk_bf16_f32 v183, v184, v185
	v_lshlrev_b64 v[184:185], 11, v[158:159]
	v_pk_fma_f32 v[192:193], v[98:99], v[186:187], v[188:189]
	v_lshl_add_u64 v[184:185], s[36:37], 0, v[184:185]
	v_lshl_add_u64 v[210:211], v[184:185], 0, v[170:171]
	v_cvt_pk_bf16_f32 v184, v190, v191
	v_cvt_pk_bf16_f32 v185, v192, v193
	global_load_dwordx4 v[186:189], v[210:211], off
	s_waitcnt vmcnt(0)
	v_lshlrev_b32_e32 v214, 16, v188
	global_store_dwordx4 v[174:175], v[182:185], off offset:256
	v_add_co_u32_e32 v174, vcc, s49, v172
	v_and_b32_e32 v215, 0xffff0000, v188
	s_nop 0
	v_addc_co_u32_e32 v175, vcc, 0, v173, vcc
	global_load_dwordx4 v[182:185], v[174:175], off
	global_load_dwordx4 v[190:193], v[174:175], off offset:256
	global_load_dwordx4 v[194:197], v[210:211], off offset:256
	v_add_co_u32_e32 v202, vcc, s50, v172
	v_lshlrev_b64 v[174:175], 11, v[156:157]
	s_nop 0
	v_addc_co_u32_e32 v203, vcc, 0, v173, vcc
	v_lshl_add_u64 v[198:199], s[36:37], 0, v[174:175]
	global_load_dwordx4 v[172:175], v[202:203], off
	v_lshl_add_u64 v[212:213], v[198:199], 0, v[170:171]
	global_load_dwordx4 v[198:201], v[212:213], off
	s_nop 0
	global_load_dwordx4 v[202:205], v[202:203], off offset:256
	s_nop 0
	global_load_dwordx4 v[206:209], v[212:213], off offset:256
	v_lshlrev_b32_e32 v170, 16, v186
	v_and_b32_e32 v171, 0xffff0000, v186
	v_lshlrev_b32_e32 v186, 16, v187
	v_and_b32_e32 v187, 0xffff0000, v187
	v_lshlrev_b32_e32 v188, 16, v189
	v_and_b32_e32 v189, 0xffff0000, v189
	s_waitcnt vmcnt(0)
; DI unsigned pk_bf16(float lo, float hi) { f32x2 v = {lo, hi}; return __builtin_bit_cast(unsigned, __builtin_convertvector(v, bf16v2)); }
; DI float bf_lo(unsigned w) { return __uint_as_float(w << 16); }
; DI float bf_hi(unsigned w) { return __uint_as_float(w & 0xffff0000u); }
;     DI void operator()(AccRef acc, const Unit& u, int wr, int wc, int fr, int fq) const {
;         const int row0 = u.pm * 256 + wr * 64 + fr, col0 = u.pn * 256 + wc * 32 + 8 * fq;
; #pragma unroll
;         for (int ai = 0; ai < 2; ++ai)
; #pragma unroll
;             for (int mh = 0; mh < 2; ++mh) {
;                 u32x4 gv[2][2], mv[2][2];
; #pragma unroll
;                 for (int mm = 0; mm < 2; ++mm)
; #pragma unroll
;                     for (int bj = 0; bj < 2; ++bj) {
;                         const size_t row = (size_t)(row0 + ai * 128 + (mh * 2 + mm) * 16); const int col = col0 + bj * 128;
;                         gv[mm][bj] = *(const u32x4*)(gab + (size_t)(u.pm * 8 + SECOND * 4 + u.pn) * 65536 + (wr * 64 + fr + ai * 128 + (mh * 2 + mm) * 16) * 256 + wc * 32 + 8 * fq + bj * 128);
;                         if (SECOND) mv[mm][bj] = *(const u32x4*)(mrg + row * 1024 + col);
;                     }
; #pragma unroll
;                 for (int mm = 0; mm < 2; ++mm)
; #pragma unroll
;                     for (int bj = 0; bj < 2; ++bj) {
;                         const int m = mh * 2 + mm;
;                         const size_t row = (size_t)(row0 + ai * 128 + m * 16); const int col = col0 + bj * 128;
;                         const u32x4 gt = gv[mm][bj];
;                         const f32x4 r0 = acc[ai][bj][m][0], r1 = acc[ai][bj][m][1];
;                         float v[8] = {bf_lo(gt.x) * r0[0], bf_hi(gt.x) * r0[1], bf_lo(gt.y) * r0[2], bf_hi(gt.y) * r0[3], bf_lo(gt.z) * r1[0], bf_hi(gt.z) * r1[1], bf_lo(gt.w) * r1[2], bf_hi(gt.w) * r1[3]};
;                         if (SECOND) { const u32x4 o = mv[mm][bj]; v[0] += bf_lo(o.x); v[1] += bf_hi(o.x); v[2] += bf_lo(o.y); v[3] += bf_hi(o.y); v[4] += bf_lo(o.z); v[5] += bf_hi(o.z); v[6] += bf_lo(o.w); v[7] += bf_hi(o.w); }
;                         u32x4 w; w.x = pk_bf16(v[0], v[1]); w.y = pk_bf16(v[2], v[3]); w.z = pk_bf16(v[4], v[5]); w.w = pk_bf16(v[6], v[7]);
;                         *(u32x4*)(mrg + row * 1024 + col) = w;
;                     }
	v_lshlrev_b32_e32 v216, 16, v182
	v_and_b32_e32 v217, 0xffff0000, v182
	v_lshlrev_b32_e32 v182, 16, v183
	v_and_b32_e32 v183, 0xffff0000, v183
	v_lshlrev_b32_e32 v218, 16, v184
	v_and_b32_e32 v219, 0xffff0000, v184
	v_lshlrev_b32_e32 v184, 16, v185
	v_and_b32_e32 v185, 0xffff0000, v185
	v_pk_fma_f32 v[170:171], v[92:93], v[216:217], v[170:171]
	v_pk_fma_f32 v[186:187], v[94:95], v[182:183], v[186:187]
	v_pk_fma_f32 v[214:215], v[88:89], v[218:219], v[214:215]
	v_pk_fma_f32 v[188:189], v[90:91], v[184:185], v[188:189]
	v_cvt_pk_bf16_f32 v182, v170, v171
	v_cvt_pk_bf16_f32 v183, v186, v187
	v_cvt_pk_bf16_f32 v184, v214, v215
	v_cvt_pk_bf16_f32 v185, v188, v189
	global_store_dwordx4 v[210:211], v[182:185], off
	v_lshlrev_b32_e32 v186, 16, v196
	v_and_b32_e32 v187, 0xffff0000, v196
	v_lshlrev_b32_e32 v182, 16, v191
	v_and_b32_e32 v183, 0xffff0000, v191
	v_lshlrev_b32_e32 v184, 16, v195
	v_and_b32_e32 v185, 0xffff0000, v195
	v_pk_fma_f32 v[184:185], v[78:79], v[182:183], v[184:185]
	v_lshlrev_b32_e32 v182, 16, v192
	v_and_b32_e32 v183, 0xffff0000, v192
	v_lshlrev_b32_e32 v220, 16, v190
	v_and_b32_e32 v221, 0xffff0000, v190
	v_lshlrev_b32_e32 v170, 16, v194
	v_and_b32_e32 v171, 0xffff0000, v194
	v_pk_fma_f32 v[186:187], v[72:73], v[182:183], v[186:187]
	v_lshlrev_b32_e32 v182, 16, v193
	v_and_b32_e32 v183, 0xffff0000, v193
	v_lshlrev_b32_e32 v188, 16, v197
	v_and_b32_e32 v189, 0xffff0000, v197
	v_pk_fma_f32 v[170:171], v[76:77], v[220:221], v[170:171]
	v_pk_fma_f32 v[188:189], v[74:75], v[182:183], v[188:189]
	v_cvt_pk_bf16_f32 v182, v170, v171
	v_cvt_pk_bf16_f32 v183, v184, v185
	v_cvt_pk_bf16_f32 v184, v186, v187
	v_cvt_pk_bf16_f32 v185, v188, v189
	global_store_dwordx4 v[210:211], v[182:185], off offset:256
	v_lshlrev_b32_e32 v170, 16, v172
	v_and_b32_e32 v171, 0xffff0000, v172
	v_lshlrev_b32_e32 v182, 16, v198
	v_and_b32_e32 v183, 0xffff0000, v198
	v_pk_fma_f32 v[170:171], v[84:85], v[170:171], v[182:183]
	v_lshlrev_b32_e32 v172, 16, v173
	v_and_b32_e32 v173, 0xffff0000, v173
	v_lshlrev_b32_e32 v182, 16, v199
	v_and_b32_e32 v183, 0xffff0000, v199
	v_pk_fma_f32 v[172:173], v[86:87], v[172:173], v[182:183]
	v_lshlrev_b32_e32 v182, 16, v174
	v_and_b32_e32 v183, 0xffff0000, v174
	v_lshlrev_b32_e32 v184, 16, v200
	v_and_b32_e32 v185, 0xffff0000, v200
	v_pk_fma_f32 v[182:183], v[80:81], v[182:183], v[184:185]
	v_lshlrev_b32_e32 v174, 16, v175
	v_and_b32_e32 v175, 0xffff0000, v175
	v_lshlrev_b32_e32 v184, 16, v201
	v_and_b32_e32 v185, 0xffff0000, v201
	v_pk_fma_f32 v[174:175], v[82:83], v[174:175], v[184:185]
	v_cvt_pk_bf16_f32 v170, v170, v171
	v_cvt_pk_bf16_f32 v171, v172, v173
	v_cvt_pk_bf16_f32 v172, v182, v183
	v_cvt_pk_bf16_f32 v173, v174, v175
	global_store_dwordx4 v[212:213], v[170:173], off
	v_lshlrev_b32_e32 v174, 16, v207
	v_and_b32_e32 v175, 0xffff0000, v207
	v_lshlrev_b32_e32 v170, 16, v202
	v_and_b32_e32 v171, 0xffff0000, v202
	v_lshlrev_b32_e32 v172, 16, v206
	v_and_b32_e32 v173, 0xffff0000, v206
	v_pk_fma_f32 v[170:171], v[68:69], v[170:171], v[172:173]
	v_lshlrev_b32_e32 v172, 16, v203
	v_and_b32_e32 v173, 0xffff0000, v203
	v_pk_fma_f32 v[172:173], v[70:71], v[172:173], v[174:175]
	v_lshlrev_b32_e32 v174, 16, v204
	v_and_b32_e32 v175, 0xffff0000, v204
	v_lshlrev_b32_e32 v182, 16, v208
	v_and_b32_e32 v183, 0xffff0000, v208
	v_pk_fma_f32 v[174:175], v[64:65], v[174:175], v[182:183]
	v_lshlrev_b32_e32 v182, 16, v205
	v_and_b32_e32 v183, 0xffff0000, v205
	v_lshlrev_b32_e32 v184, 16, v209
	v_and_b32_e32 v185, 0xffff0000, v209
	v_pk_fma_f32 v[182:183], v[66:67], v[182:183], v[184:185]
	v_cvt_pk_bf16_f32 v170, v170, v171
	v_cvt_pk_bf16_f32 v171, v172, v173
	v_cvt_pk_bf16_f32 v172, v174, v175
	v_cvt_pk_bf16_f32 v173, v182, v183
	global_store_dwordx4 v[212:213], v[170:173], off offset:256
	v_lshl_add_u64 v[174:175], v[140:141], 1, v[168:169]
	v_add_co_u32_e32 v210, vcc, s61, v166
	global_load_dwordx4 v[170:173], v[174:175], off
	s_nop 0
	v_addc_co_u32_e32 v211, vcc, 0, v167, vcc
	global_load_dwordx4 v[182:185], v[210:211], off
	global_load_dwordx4 v[186:189], v[174:175], off offset:256
	v_lshl_add_u64 v[174:175], v[166:167], 0, s[0:1]
	global_load_dwordx4 v[190:193], v[174:175], off offset:256
	v_lshl_add_u64 v[202:203], v[142:143], 1, v[168:169]
	v_add_co_u32_e32 v212, vcc, s62, v166
	global_load_dwordx4 v[194:197], v[202:203], off
	s_nop 0
	v_addc_co_u32_e32 v213, vcc, 0, v167, vcc
	global_load_dwordx4 v[198:201], v[212:213], off
	s_nop 0
	global_load_dwordx4 v[202:205], v[202:203], off offset:256
	v_lshl_add_u64 v[214:215], v[166:167], 0, s[10:11]
	global_load_dwordx4 v[206:209], v[214:215], off offset:256
	s_waitcnt vmcnt(0)
; DI unsigned pk_bf16(float lo, float hi) { f32x2 v = {lo, hi}; return __builtin_bit_cast(unsigned, __builtin_convertvector(v, bf16v2)); }
; DI float bf_lo(unsigned w) { return __uint_as_float(w << 16); }
; DI float bf_hi(unsigned w) { return __uint_as_float(w & 0xffff0000u); }
;     DI void operator()(AccRef acc, const Unit& u, int wr, int wc, int fr, int fq) const {
;         const int row0 = u.pm * 256 + wr * 64 + fr, col0 = u.pn * 256 + wc * 32 + 8 * fq;
; #pragma unroll
;         for (int ai = 0; ai < 2; ++ai)
; #pragma unroll
;             for (int mh = 0; mh < 2; ++mh) {
;                 u32x4 gv[2][2], mv[2][2];
; #pragma unroll
;                 for (int mm = 0; mm < 2; ++mm)
; #pragma unroll
;                     for (int bj = 0; bj < 2; ++bj) {
;                         const size_t row = (size_t)(row0 + ai * 128 + (mh * 2 + mm) * 16); const int col = col0 + bj * 128;
;                         gv[mm][bj] = *(const u32x4*)(gab + (size_t)(u.pm * 8 + SECOND * 4 + u.pn) * 65536 + (wr * 64 + fr + ai * 128 + (mh * 2 + mm) * 16) * 256 + wc * 32 + 8 * fq + bj * 128);
;                         if (SECOND) mv[mm][bj] = *(const u32x4*)(mrg + row * 1024 + col);
;                     }
; #pragma unroll
;                 for (int mm = 0; mm < 2; ++mm)
; #pragma unroll
;                     for (int bj = 0; bj < 2; ++bj) {
;                         const int m = mh * 2 + mm;
;                         const size_t row = (size_t)(row0 + ai * 128 + m * 16); const int col = col0 + bj * 128;
;                         const u32x4 gt = gv[mm][bj];
;                         const f32x4 r0 = acc[ai][bj][m][0], r1 = acc[ai][bj][m][1];
;                         float v[8] = {bf_lo(gt.x) * r0[0], bf_hi(gt.x) * r0[1], bf_lo(gt.y) * r0[2], bf_hi(gt.y) * r0[3], bf_lo(gt.z) * r1[0], bf_hi(gt.z) * r1[1], bf_lo(gt.w) * r1[2], bf_hi(gt.w) * r1[3]};
;                         if (SECOND) { const u32x4 o = mv[mm][bj]; v[0] += bf_lo(o.x); v[1] += bf_hi(o.x); v[2] += bf_lo(o.y); v[3] += bf_hi(o.y); v[4] += bf_lo(o.z); v[5] += bf_hi(o.z); v[6] += bf_lo(o.w); v[7] += bf_hi(o.w); }
;                         u32x4 w; w.x = pk_bf16(v[0], v[1]); w.y = pk_bf16(v[2], v[3]); w.z = pk_bf16(v[4], v[5]); w.w = pk_bf16(v[6], v[7]);
;                         *(u32x4*)(mrg + row * 1024 + col) = w;
;                     }
	v_lshlrev_b32_e32 v216, 16, v170
	v_and_b32_e32 v217, 0xffff0000, v170
	v_lshlrev_b32_e32 v218, 16, v182
	v_and_b32_e32 v219, 0xffff0000, v182
	v_lshlrev_b32_e32 v170, 16, v171
	v_and_b32_e32 v171, 0xffff0000, v171
	v_lshlrev_b32_e32 v182, 16, v183
	v_and_b32_e32 v183, 0xffff0000, v183
	v_pk_fma_f32 v[216:217], v[60:61], v[216:217], v[218:219]
	v_pk_fma_f32 v[182:183], v[62:63], v[170:171], v[182:183]
	v_lshlrev_b32_e32 v170, 16, v172
	v_and_b32_e32 v171, 0xffff0000, v172
	v_lshlrev_b32_e32 v218, 16, v184
	v_and_b32_e32 v219, 0xffff0000, v184
	v_pk_fma_f32 v[218:219], v[56:57], v[170:171], v[218:219]
	v_lshlrev_b32_e32 v170, 16, v173
	v_and_b32_e32 v171, 0xffff0000, v173
	v_lshlrev_b32_e32 v172, 16, v185
	v_and_b32_e32 v173, 0xffff0000, v185
	v_pk_fma_f32 v[184:185], v[58:59], v[170:171], v[172:173]
	v_cvt_pk_bf16_f32 v170, v216, v217
	v_cvt_pk_bf16_f32 v171, v182, v183
	v_cvt_pk_bf16_f32 v172, v218, v219
	v_cvt_pk_bf16_f32 v173, v184, v185
	global_store_dwordx4 v[210:211], v[170:173], off
	v_lshlrev_b32_e32 v182, 16, v191
	v_and_b32_e32 v183, 0xffff0000, v191
	v_lshlrev_b32_e32 v170, 16, v186
	v_and_b32_e32 v171, 0xffff0000, v186
	v_lshlrev_b32_e32 v172, 16, v190
	v_and_b32_e32 v173, 0xffff0000, v190
	v_pk_fma_f32 v[170:171], v[44:45], v[170:171], v[172:173]
	v_lshlrev_b32_e32 v172, 16, v187
	v_and_b32_e32 v173, 0xffff0000, v187
	v_pk_fma_f32 v[172:173], v[46:47], v[172:173], v[182:183]
	v_lshlrev_b32_e32 v182, 16, v188
	v_and_b32_e32 v183, 0xffff0000, v188
	v_lshlrev_b32_e32 v184, 16, v192
	v_and_b32_e32 v185, 0xffff0000, v192
	v_pk_fma_f32 v[182:183], v[40:41], v[182:183], v[184:185]
	v_lshlrev_b32_e32 v184, 16, v189
	v_and_b32_e32 v185, 0xffff0000, v189
	v_lshlrev_b32_e32 v186, 16, v193
	v_and_b32_e32 v187, 0xffff0000, v193
	v_pk_fma_f32 v[184:185], v[42:43], v[184:185], v[186:187]
	v_cvt_pk_bf16_f32 v170, v170, v171
	v_cvt_pk_bf16_f32 v171, v172, v173
	v_cvt_pk_bf16_f32 v172, v182, v183
	v_cvt_pk_bf16_f32 v173, v184, v185
	global_store_dwordx4 v[174:175], v[170:173], off offset:256
	v_lshlrev_b32_e32 v174, 16, v199
	v_and_b32_e32 v175, 0xffff0000, v199
	v_lshlrev_b32_e32 v170, 16, v194
	v_and_b32_e32 v171, 0xffff0000, v194
	v_lshlrev_b32_e32 v172, 16, v198
	v_and_b32_e32 v173, 0xffff0000, v198
	v_pk_fma_f32 v[170:171], v[52:53], v[170:171], v[172:173]
	v_lshlrev_b32_e32 v172, 16, v195
	v_and_b32_e32 v173, 0xffff0000, v195
	v_pk_fma_f32 v[172:173], v[54:55], v[172:173], v[174:175]
	v_lshlrev_b32_e32 v174, 16, v196
	v_and_b32_e32 v175, 0xffff0000, v196
	v_lshlrev_b32_e32 v182, 16, v200
	v_and_b32_e32 v183, 0xffff0000, v200
	v_pk_fma_f32 v[174:175], v[48:49], v[174:175], v[182:183]
	v_lshlrev_b32_e32 v182, 16, v197
	v_and_b32_e32 v183, 0xffff0000, v197
	v_lshlrev_b32_e32 v184, 16, v201
	v_and_b32_e32 v185, 0xffff0000, v201
	v_pk_fma_f32 v[182:183], v[50:51], v[182:183], v[184:185]
	v_cvt_pk_bf16_f32 v170, v170, v171
	v_cvt_pk_bf16_f32 v171, v172, v173
	v_cvt_pk_bf16_f32 v172, v174, v175
	v_cvt_pk_bf16_f32 v173, v182, v183
	global_store_dwordx4 v[212:213], v[170:173], off
	v_lshlrev_b32_e32 v174, 16, v207
	v_and_b32_e32 v175, 0xffff0000, v207
	v_lshlrev_b32_e32 v170, 16, v202
	v_and_b32_e32 v171, 0xffff0000, v202
	v_lshlrev_b32_e32 v172, 16, v206
	v_and_b32_e32 v173, 0xffff0000, v206
	v_pk_fma_f32 v[170:171], v[36:37], v[170:171], v[172:173]
	v_lshlrev_b32_e32 v172, 16, v203
	v_and_b32_e32 v173, 0xffff0000, v203
	v_pk_fma_f32 v[172:173], v[38:39], v[172:173], v[174:175]
	v_lshlrev_b32_e32 v174, 16, v204
	v_and_b32_e32 v175, 0xffff0000, v204
	v_lshlrev_b32_e32 v182, 16, v208
	v_and_b32_e32 v183, 0xffff0000, v208
	v_pk_fma_f32 v[174:175], v[32:33], v[174:175], v[182:183]
	v_lshlrev_b32_e32 v182, 16, v205
	v_and_b32_e32 v183, 0xffff0000, v205
	v_lshlrev_b32_e32 v184, 16, v209
	v_and_b32_e32 v185, 0xffff0000, v209
	v_pk_fma_f32 v[182:183], v[34:35], v[182:183], v[184:185]
	v_cvt_pk_bf16_f32 v170, v170, v171
	v_cvt_pk_bf16_f32 v171, v172, v173
	v_cvt_pk_bf16_f32 v172, v174, v175
	v_cvt_pk_bf16_f32 v173, v182, v183
	global_store_dwordx4 v[214:215], v[170:173], off offset:256
	v_lshl_add_u64 v[174:175], v[144:145], 1, v[168:169]
	v_add_co_u32_e32 v206, vcc, s63, v166
	global_load_dwordx4 v[170:173], v[174:175], off
	s_nop 0
	v_addc_co_u32_e32 v207, vcc, 0, v167, vcc
	global_load_dwordx4 v[182:185], v[206:207], off
	global_load_dwordx4 v[186:189], v[174:175], off offset:256
	v_lshl_add_u64 v[174:175], v[166:167], 0, s[12:13]
	global_load_dwordx4 v[190:193], v[174:175], off offset:256
	v_lshl_add_u64 v[168:169], v[146:147], 1, v[168:169]
	v_add_co_u32_e32 v208, vcc, s64, v166
	global_load_dwordx4 v[194:197], v[168:169], off
	s_nop 0
	v_addc_co_u32_e32 v209, vcc, 0, v167, vcc
	global_load_dwordx4 v[198:201], v[208:209], off
	global_load_dwordx4 v[202:205], v[168:169], off offset:256
	v_lshl_add_u64 v[210:211], v[166:167], 0, s[14:15]
	global_load_dwordx4 v[166:169], v[210:211], off offset:256
	s_waitcnt vmcnt(0)
; DI unsigned pk_bf16(float lo, float hi) { f32x2 v = {lo, hi}; return __builtin_bit_cast(unsigned, __builtin_convertvector(v, bf16v2)); }
; DI float bf_lo(unsigned w) { return __uint_as_float(w << 16); }
; DI float bf_hi(unsigned w) { return __uint_as_float(w & 0xffff0000u); }
;     DI void operator()(AccRef acc, const Unit& u, int wr, int wc, int fr, int fq) const {
;     ...
;                 for (int mm = 0; mm < 2; ++mm)
; #pragma unroll
;                     for (int bj = 0; bj < 2; ++bj) {
;                         const int m = mh * 2 + mm;
;                         const size_t row = (size_t)(row0 + ai * 128 + m * 16); const int col = col0 + bj * 128;
;                         const u32x4 gt = gv[mm][bj];
;                         const f32x4 r0 = acc[ai][bj][m][0], r1 = acc[ai][bj][m][1];
;                         float v[8] = {bf_lo(gt.x) * r0[0], bf_hi(gt.x) * r0[1], bf_lo(gt.y) * r0[2], bf_hi(gt.y) * r0[3], bf_lo(gt.z) * r1[0], bf_hi(gt.z) * r1[1], bf_lo(gt.w) * r1[2], bf_hi(gt.w) * r1[3]};
;                         if (SECOND) { const u32x4 o = mv[mm][bj]; v[0] += bf_lo(o.x); v[1] += bf_hi(o.x); v[2] += bf_lo(o.y); v[3] += bf_hi(o.y); v[4] += bf_lo(o.z); v[5] += bf_hi(o.z); v[6] += bf_lo(o.w); v[7] += bf_hi(o.w); }
;                         u32x4 w; w.x = pk_bf16(v[0], v[1]); w.y = pk_bf16(v[2], v[3]); w.z = pk_bf16(v[4], v[5]); w.w = pk_bf16(v[6], v[7]);
;                         *(u32x4*)(mrg + row * 1024 + col) = w;
;                     }
	v_lshlrev_b32_e32 v212, 16, v170
	v_and_b32_e32 v213, 0xffff0000, v170
	v_lshlrev_b32_e32 v214, 16, v182
	v_and_b32_e32 v215, 0xffff0000, v182
	v_lshlrev_b32_e32 v170, 16, v171
	v_and_b32_e32 v171, 0xffff0000, v171
	v_lshlrev_b32_e32 v182, 16, v183
	v_and_b32_e32 v183, 0xffff0000, v183
	v_pk_fma_f32 v[212:213], v[28:29], v[212:213], v[214:215]
	v_pk_fma_f32 v[182:183], v[30:31], v[170:171], v[182:183]
	v_lshlrev_b32_e32 v170, 16, v172
	v_and_b32_e32 v171, 0xffff0000, v172
	v_lshlrev_b32_e32 v214, 16, v184
	v_and_b32_e32 v215, 0xffff0000, v184
	v_pk_fma_f32 v[214:215], v[24:25], v[170:171], v[214:215]
	v_lshlrev_b32_e32 v170, 16, v173
	v_and_b32_e32 v171, 0xffff0000, v173
	v_lshlrev_b32_e32 v172, 16, v185
	v_and_b32_e32 v173, 0xffff0000, v185
	v_pk_fma_f32 v[184:185], v[26:27], v[170:171], v[172:173]
	v_cvt_pk_bf16_f32 v170, v212, v213
	v_cvt_pk_bf16_f32 v171, v182, v183
	v_cvt_pk_bf16_f32 v172, v214, v215
	v_cvt_pk_bf16_f32 v173, v184, v185
	global_store_dwordx4 v[206:207], v[170:173], off
	v_lshlrev_b32_e32 v182, 16, v191
	v_and_b32_e32 v183, 0xffff0000, v191
	v_lshlrev_b32_e32 v170, 16, v186
	v_and_b32_e32 v171, 0xffff0000, v186
	v_lshlrev_b32_e32 v172, 16, v190
	v_and_b32_e32 v173, 0xffff0000, v190
	v_pk_fma_f32 v[170:171], v[12:13], v[170:171], v[172:173]
	v_lshlrev_b32_e32 v172, 16, v187
	v_and_b32_e32 v173, 0xffff0000, v187
	v_pk_fma_f32 v[172:173], v[14:15], v[172:173], v[182:183]
	v_lshlrev_b32_e32 v182, 16, v188
	v_and_b32_e32 v183, 0xffff0000, v188
	v_lshlrev_b32_e32 v184, 16, v192
	v_and_b32_e32 v185, 0xffff0000, v192
	v_pk_fma_f32 v[182:183], v[8:9], v[182:183], v[184:185]
	v_lshlrev_b32_e32 v184, 16, v189
	v_and_b32_e32 v185, 0xffff0000, v189
	v_lshlrev_b32_e32 v186, 16, v193
	v_and_b32_e32 v187, 0xffff0000, v193
	v_pk_fma_f32 v[184:185], v[10:11], v[184:185], v[186:187]
	v_cvt_pk_bf16_f32 v170, v170, v171
	v_cvt_pk_bf16_f32 v171, v172, v173
	v_cvt_pk_bf16_f32 v172, v182, v183
	v_cvt_pk_bf16_f32 v173, v184, v185
	global_store_dwordx4 v[174:175], v[170:173], off offset:256
	v_lshlrev_b32_e32 v174, 16, v199
	v_and_b32_e32 v175, 0xffff0000, v199
	v_lshlrev_b32_e32 v170, 16, v194
	v_and_b32_e32 v171, 0xffff0000, v194
	v_lshlrev_b32_e32 v172, 16, v198
	v_and_b32_e32 v173, 0xffff0000, v198
	v_pk_fma_f32 v[170:171], v[20:21], v[170:171], v[172:173]
	v_lshlrev_b32_e32 v172, 16, v195
	v_and_b32_e32 v173, 0xffff0000, v195
	v_pk_fma_f32 v[172:173], v[22:23], v[172:173], v[174:175]
	v_lshlrev_b32_e32 v174, 16, v196
	v_and_b32_e32 v175, 0xffff0000, v196
	v_lshlrev_b32_e32 v182, 16, v200
	v_and_b32_e32 v183, 0xffff0000, v200
	v_pk_fma_f32 v[174:175], v[16:17], v[174:175], v[182:183]
	v_lshlrev_b32_e32 v182, 16, v197
	v_and_b32_e32 v183, 0xffff0000, v197
	v_lshlrev_b32_e32 v184, 16, v201
	v_and_b32_e32 v185, 0xffff0000, v201
	v_pk_fma_f32 v[182:183], v[18:19], v[182:183], v[184:185]
	v_cvt_pk_bf16_f32 v170, v170, v171
	v_cvt_pk_bf16_f32 v171, v172, v173
	v_cvt_pk_bf16_f32 v172, v174, v175
	v_cvt_pk_bf16_f32 v173, v182, v183
	global_store_dwordx4 v[208:209], v[170:173], off
	v_lshlrev_b32_e32 v174, 16, v168
	v_and_b32_e32 v175, 0xffff0000, v168
	v_lshlrev_b32_e32 v170, 16, v202
	v_and_b32_e32 v171, 0xffff0000, v202
	v_lshlrev_b32_e32 v172, 16, v166
	v_and_b32_e32 v173, 0xffff0000, v166
	v_pk_fma_f32 v[170:171], v[4:5], v[170:171], v[172:173]
	v_lshlrev_b32_e32 v172, 16, v203
	v_and_b32_e32 v173, 0xffff0000, v203
	v_lshlrev_b32_e32 v166, 16, v167
	v_and_b32_e32 v167, 0xffff0000, v167
	v_pk_fma_f32 v[172:173], v[6:7], v[172:173], v[166:167]
	v_lshlrev_b32_e32 v166, 16, v204
	v_and_b32_e32 v167, 0xffff0000, v204
	v_pk_fma_f32 v[174:175], v[0:1], v[166:167], v[174:175]
	v_lshlrev_b32_e32 v166, 16, v205
	v_and_b32_e32 v167, 0xffff0000, v205
	v_lshlrev_b32_e32 v168, 16, v169
	v_and_b32_e32 v169, 0xffff0000, v169
	v_pk_fma_f32 v[182:183], v[2:3], v[166:167], v[168:169]
	v_cvt_pk_bf16_f32 v166, v170, v171
	v_cvt_pk_bf16_f32 v167, v172, v173
	v_cvt_pk_bf16_f32 v168, v174, v175
	v_cvt_pk_bf16_f32 v169, v182, v183
	global_store_dwordx4 v[210:211], v[166:169], off offset:256

; #define PG8_STAGE(bufoff, gbase, voff) do { _Pragma("unroll") for (int _i = 0; _i < 2; ++_i) \
;         __builtin_amdgcn_global_load_lds((const unsigned*)((const char*)(gbase) + (voff)[_i]), (LAS unsigned*)(lds + (bufoff) + ldsw + _i * 8192), 16, 0, 0); } while (0)
; #define PG8_LDA(dst, b, h) do { _Pragma("unroll") for (int m = 0; m < 4; ++m) _Pragma("unroll") for (int k = 0; k < 2; ++k) dst[m][k] = *(const LAS bf16x8*)(lds + PG8_SA(b, h) + aoff + m * 2048 + k * 1024); } while (0)
; #define PG8_LDB(dst, b, h) do { _Pragma("unroll") for (int n = 0; n < 2; ++n) _Pragma("unroll") for (int k = 0; k < 2; ++k) dst[n][k] = *(const LAS bf16x8*)(lds + PG8_SB(b, h) + boff + n * 2048 + k * 1024); } while (0)
; #define PG8_MMA(ai, bj, At, Bt) do { __builtin_amdgcn_s_setprio(1); _Pragma("unroll") for (int m = 0; m < 4; ++m) _Pragma("unroll") for (int n = 0; n < 2; ++n) _Pragma("unroll") for (int k = 0; k < 2; ++k) \
;         acc[ai][bj][m][n] = __builtin_amdgcn_mfma_f32_16x16x32_bf16(Bt[n][k], At[m][k], acc[ai][bj][m][n], 0, 0, 0); __builtin_amdgcn_s_setprio(0); } while (0)
; #define PG8_WAIT_L(n) asm volatile("s_waitcnt lgkmcnt(" #n ")" ::: "memory")
; #define PG8_BAR __builtin_amdgcn_s_barrier()
; #define PG8_SCHED __builtin_amdgcn_sched_barrier(0)
; #define PG8_STAGE(bufoff, gbase, voff) do { _Pragma("unroll") for (int _i = 0; _i < 2; ++_i) \
;         __builtin_amdgcn_global_load_lds((const unsigned*)((const char*)(gbase) + (voff)[_i]), (LAS unsigned*)(lds + (bufoff) + ldsw + _i * 8192), 16, 0, 0); } while (0)
; #define PG8_LDA(dst, b, h) do { _Pragma("unroll") for (int m = 0; m < 4; ++m) _Pragma("unroll") for (int k = 0; k < 2; ++k) dst[m][k] = *(const LAS bf16x8*)(lds + PG8_SA(b, h) + aoff + m * 2048 + k * 1024); } while (0)
; template <class Epi>
; DI void gemm_phase(LAS unsigned char* lds, const Gemm g, const StaticOrder S, const Epi E) {
;     ...
;             PG8_LDB(B0, 0, 0); PG8_SCHED; PG8_LDA(At, 0, 0); PG8_STAGE(PG8_SA(1, 1), a1 + hstep, voffA);
;             PG8_WAIT_L(8); PG8_BAR; PG8_WAIT_L(0); PG8_MMA(0, 0, At, B0); PG8_BAR; PG8_SCHED;
;             PG8_LDB(B1, 0, 1); PG8_STAGE(PG8_SB(0, 0), b2, voffB);
;             PG8_BAR; PG8_WAIT_L(0); PG8_MMA(0, 1, At, B1); PG8_BAR;
;             PG8_LDA(At, 0, 1); PG8_STAGE(PG8_SA(0, 0), a2, voffA);
;             PG8_BAR; PG8_WAIT_L(0); PG8_MMA(1, 0, At, B0); PG8_BAR; PG8_SCHED;
.LBB0_786:
	ds_read_b128 v[128:131], v187
	ds_read_b128 v[132:135], v187 offset:1024
	ds_read_b128 v[136:139], v187 offset:2048
	ds_read_b128 v[140:143], v187 offset:3072
	s_add_u32 s28, s24, 0xfffc0080
	s_addc_u32 s29, s25, -1
	s_cmp_eq_u32 s52, 12
	s_cselect_b32 s39, s6, s29
	s_cselect_b32 s38, s7, s28
	s_cselect_b32 s29, s11, s51
	s_cselect_b32 s28, s13, s50
	v_lshl_add_u64 v[200:201], s[24:25], 0, v[160:161]
	s_add_i32 m0, s19, 0xc000
	ds_read_b128 v[144:147], v188
	ds_read_b128 v[168:171], v188 offset:2048
	ds_read_b128 v[176:179], v188 offset:4096
	ds_read_b128 v[192:195], v188 offset:6144
	global_load_lds_dwordx4 v[200:201], off
	v_lshl_add_u64 v[200:201], s[24:25], 0, v[162:163]
	s_add_i32 m0, s19, 0xe000
	s_nop 0
	global_load_lds_dwordx4 v[200:201], off
	s_waitcnt lgkmcnt(4)
	s_setprio 1
	s_barrier
	s_waitcnt lgkmcnt(0)
	v_mfma_f32_16x16x32_bf16 v[124:127], v[128:131], v[144:147], v[124:127]
	ds_read_b128 v[148:151], v188 offset:1024
	v_mfma_f32_16x16x32_bf16 v[120:123], v[136:139], v[144:147], v[120:123]
	ds_read_b128 v[172:175], v188 offset:3072
	v_mfma_f32_16x16x32_bf16 v[108:111], v[128:131], v[168:171], v[108:111]
	ds_read_b128 v[180:183], v188 offset:5120
	v_mfma_f32_16x16x32_bf16 v[104:107], v[136:139], v[168:171], v[104:107]
	ds_read_b128 v[196:199], v188 offset:7168
	v_mfma_f32_16x16x32_bf16 v[92:95], v[128:131], v[176:179], v[92:95]
	v_mfma_f32_16x16x32_bf16 v[88:91], v[136:139], v[176:179], v[88:91]
	v_mfma_f32_16x16x32_bf16 v[76:79], v[128:131], v[192:195], v[76:79]
	v_mfma_f32_16x16x32_bf16 v[72:75], v[136:139], v[192:195], v[72:75]
	s_waitcnt lgkmcnt(3)
	v_mfma_f32_16x16x32_bf16 v[124:127], v[132:135], v[148:151], v[124:127]
	v_mfma_f32_16x16x32_bf16 v[120:123], v[140:143], v[148:151], v[120:123]
	s_waitcnt lgkmcnt(2)
	v_mfma_f32_16x16x32_bf16 v[108:111], v[132:135], v[172:175], v[108:111]
	v_mfma_f32_16x16x32_bf16 v[104:107], v[140:143], v[172:175], v[104:107]
	s_waitcnt lgkmcnt(1)
	v_mfma_f32_16x16x32_bf16 v[92:95], v[132:135], v[180:183], v[92:95]
	v_mfma_f32_16x16x32_bf16 v[88:91], v[140:143], v[180:183], v[88:91]
	s_waitcnt lgkmcnt(0)
	s_setprio 2
	s_barrier
	v_mfma_f32_16x16x32_bf16 v[76:79], v[132:135], v[196:199], v[76:79]
	v_mfma_f32_16x16x32_bf16 v[72:75], v[140:143], v[196:199], v[72:75]
	s_setprio 0
	s_add_i32 s53, s48, s40
	v_lshl_add_u64 v[216:217], s[28:29], 0, v[154:155]
	s_mov_b32 m0, s53
	ds_read_b128 v[200:203], v189
	ds_read_b128 v[204:207], v189 offset:1024
	ds_read_b128 v[208:211], v189 offset:2048
	ds_read_b128 v[212:215], v189 offset:3072
	global_load_lds_dwordx4 v[216:217], off
	v_lshl_add_u64 v[218:219], s[28:29], 0, v[158:159]
	s_add_i32 m0, s53, 0x2000
	s_nop 0
	global_load_lds_dwordx4 v[218:219], off
	s_setprio 1
	s_barrier
	s_waitcnt lgkmcnt(0)
	v_mfma_f32_16x16x32_bf16 v[116:119], v[200:203], v[144:147], v[116:119]
	v_mfma_f32_16x16x32_bf16 v[112:115], v[208:211], v[144:147], v[112:115]
	v_mfma_f32_16x16x32_bf16 v[100:103], v[200:203], v[168:171], v[100:103]
	v_mfma_f32_16x16x32_bf16 v[96:99], v[208:211], v[168:171], v[96:99]
	v_mfma_f32_16x16x32_bf16 v[84:87], v[200:203], v[176:179], v[84:87]
	v_mfma_f32_16x16x32_bf16 v[80:83], v[208:211], v[176:179], v[80:83]
	v_mfma_f32_16x16x32_bf16 v[68:71], v[200:203], v[192:195], v[68:71]
	v_mfma_f32_16x16x32_bf16 v[64:67], v[208:211], v[192:195], v[64:67]
	v_mfma_f32_16x16x32_bf16 v[116:119], v[204:207], v[148:151], v[116:119]
	v_mfma_f32_16x16x32_bf16 v[112:115], v[212:215], v[148:151], v[112:115]
	v_mfma_f32_16x16x32_bf16 v[100:103], v[204:207], v[172:175], v[100:103]
	v_mfma_f32_16x16x32_bf16 v[96:99], v[212:215], v[172:175], v[96:99]
	v_mfma_f32_16x16x32_bf16 v[84:87], v[204:207], v[180:183], v[84:87]
	v_mfma_f32_16x16x32_bf16 v[80:83], v[212:215], v[180:183], v[80:83]
	s_setprio 2
	s_barrier
	v_mfma_f32_16x16x32_bf16 v[68:71], v[204:207], v[196:199], v[68:71]
	v_mfma_f32_16x16x32_bf16 v[64:67], v[212:215], v[196:199], v[64:67]
	s_setprio 0
	s_mov_b32 m0, s19
	v_lshl_add_u64 v[220:221], s[38:39], 0, v[152:153]
	ds_read_b128 v[144:147], v188 offset:16384
	ds_read_b128 v[168:171], v188 offset:18432
	ds_read_b128 v[176:179], v188 offset:20480
	ds_read_b128 v[192:195], v188 offset:22528
	global_load_lds_dwordx4 v[220:221], off
	v_lshl_add_u64 v[224:225], s[38:39], 0, v[156:157]
	s_mov_b32 m0, s23
	s_nop 0
	global_load_lds_dwordx4 v[224:225], off
	s_setprio 1
	s_barrier
	s_waitcnt lgkmcnt(0)
	v_mfma_f32_16x16x32_bf16 v[60:63], v[128:131], v[144:147], v[60:63]
	ds_read_b128 v[148:151], v188 offset:17408
	v_mfma_f32_16x16x32_bf16 v[56:59], v[136:139], v[144:147], v[56:59]
	ds_read_b128 v[172:175], v188 offset:19456
	v_mfma_f32_16x16x32_bf16 v[44:47], v[128:131], v[168:171], v[44:47]
	ds_read_b128 v[180:183], v188 offset:21504
	v_mfma_f32_16x16x32_bf16 v[40:43], v[136:139], v[168:171], v[40:43]
	ds_read_b128 v[196:199], v188 offset:23552
	v_mfma_f32_16x16x32_bf16 v[28:31], v[128:131], v[176:179], v[28:31]
	v_mfma_f32_16x16x32_bf16 v[24:27], v[136:139], v[176:179], v[24:27]
	v_mfma_f32_16x16x32_bf16 v[12:15], v[128:131], v[192:195], v[12:15]
	v_mfma_f32_16x16x32_bf16 v[8:11], v[136:139], v[192:195], v[8:11]
	s_waitcnt lgkmcnt(3)
	v_mfma_f32_16x16x32_bf16 v[60:63], v[132:135], v[148:151], v[60:63]
	v_mfma_f32_16x16x32_bf16 v[56:59], v[140:143], v[148:151], v[56:59]
	s_waitcnt lgkmcnt(2)
	v_mfma_f32_16x16x32_bf16 v[44:47], v[132:135], v[172:175], v[44:47]
	v_mfma_f32_16x16x32_bf16 v[40:43], v[140:143], v[172:175], v[40:43]
	s_waitcnt lgkmcnt(1)
	v_mfma_f32_16x16x32_bf16 v[28:31], v[132:135], v[180:183], v[28:31]
	v_mfma_f32_16x16x32_bf16 v[24:27], v[140:143], v[180:183], v[24:27]
	s_waitcnt lgkmcnt(0)
	s_setprio 2
	s_barrier
; #define PG8_STAGE(bufoff, gbase, voff) do { _Pragma("unroll") for (int _i = 0; _i < 2; ++_i) \
;         __builtin_amdgcn_global_load_lds((const unsigned*)((const char*)(gbase) + (voff)[_i]), (LAS unsigned*)(lds + (bufoff) + ldsw + _i * 8192), 16, 0, 0); } while (0)
; #define PG8_LDA(dst, b, h) do { _Pragma("unroll") for (int m = 0; m < 4; ++m) _Pragma("unroll") for (int k = 0; k < 2; ++k) dst[m][k] = *(const LAS bf16x8*)(lds + PG8_SA(b, h) + aoff + m * 2048 + k * 1024); } while (0)
; #define PG8_LDB(dst, b, h) do { _Pragma("unroll") for (int n = 0; n < 2; ++n) _Pragma("unroll") for (int k = 0; k < 2; ++k) dst[n][k] = *(const LAS bf16x8*)(lds + PG8_SB(b, h) + boff + n * 2048 + k * 1024); } while (0)
; #define PG8_MMA(ai, bj, At, Bt) do { __builtin_amdgcn_s_setprio(1); _Pragma("unroll") for (int m = 0; m < 4; ++m) _Pragma("unroll") for (int n = 0; n < 2; ++n) _Pragma("unroll") for (int k = 0; k < 2; ++k) \
;         acc[ai][bj][m][n] = __builtin_amdgcn_mfma_f32_16x16x32_bf16(Bt[n][k], At[m][k], acc[ai][bj][m][n], 0, 0, 0); __builtin_amdgcn_s_setprio(0); } while (0)
; #define PG8_WAIT_V(n) asm volatile("s_waitcnt vmcnt(" #n ")" ::: "memory")
; #define PG8_WAIT_L(n) asm volatile("s_waitcnt lgkmcnt(" #n ")" ::: "memory")
; #define PG8_BAR __builtin_amdgcn_s_barrier()
; #define PG8_SCHED __builtin_amdgcn_sched_barrier(0)
; #define PG8_STAGE(bufoff, gbase, voff) do { _Pragma("unroll") for (int _i = 0; _i < 2; ++_i) \
;         __builtin_amdgcn_global_load_lds((const unsigned*)((const char*)(gbase) + (voff)[_i]), (LAS unsigned*)(lds + (bufoff) + ldsw + _i * 8192), 16, 0, 0); } while (0)
; #define PG8_WAIT_V(n) asm volatile("s_waitcnt vmcnt(" #n ")" ::: "memory")
; template <class Epi>
; DI void gemm_phase(LAS unsigned char* lds, const Gemm g, const StaticOrder S, const Epi E) {
;     ...
;             PG8_BAR; PG8_WAIT_L(0); PG8_MMA(1, 0, At, B0); PG8_BAR; PG8_SCHED;
;             PG8_STAGE(PG8_SB(0, 1), b2 + hstep, voffB);
;             PG8_WAIT_V(6); PG8_BAR; PG8_MMA(1, 1, At, B1); PG8_BAR;
;             PG8_LDB(B0, 1, 0); PG8_SCHED; PG8_LDA(At, 1, 0); PG8_STAGE(PG8_SA(0, 1), a2 + hstep, voffA);
;             PG8_WAIT_L(8); PG8_BAR; PG8_WAIT_L(0); PG8_MMA(0, 0, At, B0); PG8_BAR; PG8_SCHED;
;             PG8_LDB(B1, 1, 1); PG8_STAGE(PG8_SB(1, 0), b3, voffB);
;             PG8_BAR; PG8_WAIT_L(0); PG8_MMA(0, 1, At, B1); PG8_BAR;
	v_mfma_f32_16x16x32_bf16 v[12:15], v[132:135], v[196:199], v[12:15]
	v_mfma_f32_16x16x32_bf16 v[8:11], v[140:143], v[196:199], v[8:11]
	s_setprio 0
	s_add_u32 s58, s28, 0x40000
	s_addc_u32 s59, s29, 0
	s_add_i32 s53, s49, s40
	v_lshl_add_u64 v[128:129], s[58:59], 0, v[154:155]
	s_mov_b32 m0, s53
	s_nop 0
	global_load_lds_dwordx4 v[128:129], off
	v_lshl_add_u64 v[128:129], s[58:59], 0, v[158:159]
	s_add_i32 m0, s53, 0x2000
	s_nop 0
	global_load_lds_dwordx4 v[128:129], off
	s_waitcnt vmcnt(6)
	s_setprio 1
	s_barrier
	v_mfma_f32_16x16x32_bf16 v[52:55], v[200:203], v[144:147], v[52:55]
	v_mfma_f32_16x16x32_bf16 v[48:51], v[208:211], v[144:147], v[48:51]
	v_mfma_f32_16x16x32_bf16 v[36:39], v[200:203], v[168:171], v[36:39]
	v_mfma_f32_16x16x32_bf16 v[32:35], v[208:211], v[168:171], v[32:35]
	v_mfma_f32_16x16x32_bf16 v[20:23], v[200:203], v[176:179], v[20:23]
	v_mfma_f32_16x16x32_bf16 v[16:19], v[208:211], v[176:179], v[16:19]
	v_mfma_f32_16x16x32_bf16 v[4:7], v[200:203], v[192:195], v[4:7]
	v_mfma_f32_16x16x32_bf16 v[0:3], v[208:211], v[192:195], v[0:3]
	v_mfma_f32_16x16x32_bf16 v[52:55], v[204:207], v[148:151], v[52:55]
	v_mfma_f32_16x16x32_bf16 v[48:51], v[212:215], v[148:151], v[48:51]
	v_mfma_f32_16x16x32_bf16 v[36:39], v[204:207], v[172:175], v[36:39]
	v_mfma_f32_16x16x32_bf16 v[32:35], v[212:215], v[172:175], v[32:35]
	v_mfma_f32_16x16x32_bf16 v[20:23], v[204:207], v[180:183], v[20:23]
	v_mfma_f32_16x16x32_bf16 v[16:19], v[212:215], v[180:183], v[16:19]
	s_setprio 2
	s_barrier
	v_mfma_f32_16x16x32_bf16 v[4:7], v[204:207], v[196:199], v[4:7]
	v_mfma_f32_16x16x32_bf16 v[0:3], v[212:215], v[196:199], v[0:3]
	s_setprio 0
	s_add_i32 s53, 0, 0x18000
	v_add_u32_e32 v140, s53, v185
	ds_read_b128 v[128:131], v140
	ds_read_b128 v[132:135], v140 offset:1024
	ds_read_b128 v[136:139], v140 offset:2048
	ds_read_b128 v[140:143], v140 offset:3072
	s_add_u32 s38, s38, 0x40000
	s_addc_u32 s39, s39, 0
	s_mov_b32 m0, s41
	v_lshl_add_u64 v[200:201], s[38:39], 0, v[152:153]
	ds_read_b128 v[144:147], v188 offset:32768
	ds_read_b128 v[168:171], v188 offset:34816
	ds_read_b128 v[176:179], v188 offset:36864
	ds_read_b128 v[192:195], v188 offset:38912
	global_load_lds_dwordx4 v[200:201], off
	v_lshl_add_u64 v[200:201], s[38:39], 0, v[156:157]
	s_mov_b32 m0, s42
	s_nop 0
	global_load_lds_dwordx4 v[200:201], off
	s_waitcnt lgkmcnt(4)
	s_setprio 1
	s_barrier
	s_waitcnt lgkmcnt(0)
	v_mfma_f32_16x16x32_bf16 v[124:127], v[128:131], v[144:147], v[124:127]
	ds_read_b128 v[148:151], v188 offset:33792
	v_mfma_f32_16x16x32_bf16 v[120:123], v[136:139], v[144:147], v[120:123]
	ds_read_b128 v[172:175], v188 offset:35840
	v_mfma_f32_16x16x32_bf16 v[108:111], v[128:131], v[168:171], v[108:111]
	ds_read_b128 v[180:183], v188 offset:37888
	v_mfma_f32_16x16x32_bf16 v[104:107], v[136:139], v[168:171], v[104:107]
	ds_read_b128 v[196:199], v188 offset:39936
	v_mfma_f32_16x16x32_bf16 v[92:95], v[128:131], v[176:179], v[92:95]
	v_mfma_f32_16x16x32_bf16 v[88:91], v[136:139], v[176:179], v[88:91]
	v_mfma_f32_16x16x32_bf16 v[76:79], v[128:131], v[192:195], v[76:79]
	v_mfma_f32_16x16x32_bf16 v[72:75], v[136:139], v[192:195], v[72:75]
	s_waitcnt lgkmcnt(3)
	v_mfma_f32_16x16x32_bf16 v[124:127], v[132:135], v[148:151], v[124:127]
	v_mfma_f32_16x16x32_bf16 v[120:123], v[140:143], v[148:151], v[120:123]
	s_waitcnt lgkmcnt(2)
	v_mfma_f32_16x16x32_bf16 v[108:111], v[132:135], v[172:175], v[108:111]
	v_mfma_f32_16x16x32_bf16 v[104:107], v[140:143], v[172:175], v[104:107]
	s_waitcnt lgkmcnt(1)
	v_mfma_f32_16x16x32_bf16 v[92:95], v[132:135], v[180:183], v[92:95]
	v_mfma_f32_16x16x32_bf16 v[88:91], v[140:143], v[180:183], v[88:91]
	s_waitcnt lgkmcnt(0)
	s_setprio 2
	s_barrier
	v_mfma_f32_16x16x32_bf16 v[76:79], v[132:135], v[196:199], v[76:79]
	v_mfma_f32_16x16x32_bf16 v[72:75], v[140:143], v[196:199], v[72:75]
	s_setprio 0
	s_add_i32 s38, 0, 0x1c000
	s_add_i32 s39, s53, s40
	v_add_u32_e32 v191, s38, v185
	v_lshl_add_u64 v[216:217], v[216:217], 0, s[8:9]
	s_mov_b32 m0, s39
	ds_read_b128 v[200:203], v191
	ds_read_b128 v[204:207], v191 offset:1024
	ds_read_b128 v[208:211], v191 offset:2048
	ds_read_b128 v[212:215], v191 offset:3072
	global_load_lds_dwordx4 v[216:217], off
	v_lshl_add_u64 v[216:217], v[218:219], 0, s[8:9]
	s_add_i32 m0, s39, 0x2000
	s_nop 0
	global_load_lds_dwordx4 v[216:217], off
	s_setprio 1
	s_barrier
	s_waitcnt lgkmcnt(0)
	v_mfma_f32_16x16x32_bf16 v[116:119], v[200:203], v[144:147], v[116:119]
	v_mfma_f32_16x16x32_bf16 v[112:115], v[208:211], v[144:147], v[112:115]
	v_mfma_f32_16x16x32_bf16 v[100:103], v[200:203], v[168:171], v[100:103]
	v_mfma_f32_16x16x32_bf16 v[96:99], v[208:211], v[168:171], v[96:99]
	v_mfma_f32_16x16x32_bf16 v[84:87], v[200:203], v[176:179], v[84:87]
	v_mfma_f32_16x16x32_bf16 v[80:83], v[208:211], v[176:179], v[80:83]
	v_mfma_f32_16x16x32_bf16 v[68:71], v[200:203], v[192:195], v[68:71]
	v_mfma_f32_16x16x32_bf16 v[64:67], v[208:211], v[192:195], v[64:67]
	v_mfma_f32_16x16x32_bf16 v[116:119], v[204:207], v[148:151], v[116:119]
	v_mfma_f32_16x16x32_bf16 v[112:115], v[212:215], v[148:151], v[112:115]
	v_mfma_f32_16x16x32_bf16 v[100:103], v[204:207], v[172:175], v[100:103]
	v_mfma_f32_16x16x32_bf16 v[96:99], v[212:215], v[172:175], v[96:99]
	v_mfma_f32_16x16x32_bf16 v[84:87], v[204:207], v[180:183], v[84:87]
	v_mfma_f32_16x16x32_bf16 v[80:83], v[212:215], v[180:183], v[80:83]
	s_setprio 2
	s_barrier
; #define PG8_STAGE(bufoff, gbase, voff) do { _Pragma("unroll") for (int _i = 0; _i < 2; ++_i) \
;         __builtin_amdgcn_global_load_lds((const unsigned*)((const char*)(gbase) + (voff)[_i]), (LAS unsigned*)(lds + (bufoff) + ldsw + _i * 8192), 16, 0, 0); } while (0)
; #define PG8_LDA(dst, b, h) do { _Pragma("unroll") for (int m = 0; m < 4; ++m) _Pragma("unroll") for (int k = 0; k < 2; ++k) dst[m][k] = *(const LAS bf16x8*)(lds + PG8_SA(b, h) + aoff + m * 2048 + k * 1024); } while (0)
; #define PG8_MMA(ai, bj, At, Bt) do { __builtin_amdgcn_s_setprio(1); _Pragma("unroll") for (int m = 0; m < 4; ++m) _Pragma("unroll") for (int n = 0; n < 2; ++n) _Pragma("unroll") for (int k = 0; k < 2; ++k) \
;         acc[ai][bj][m][n] = __builtin_amdgcn_mfma_f32_16x16x32_bf16(Bt[n][k], At[m][k], acc[ai][bj][m][n], 0, 0, 0); __builtin_amdgcn_s_setprio(0); } while (0)
; #define PG8_WAIT_V(n) asm volatile("s_waitcnt vmcnt(" #n ")" ::: "memory")
; #define PG8_WAIT_L(n) asm volatile("s_waitcnt lgkmcnt(" #n ")" ::: "memory")
; #define PG8_BAR __builtin_amdgcn_s_barrier()
; #define PG8_SCHED __builtin_amdgcn_sched_barrier(0)
; #define PG8_STAGE(bufoff, gbase, voff) do { _Pragma("unroll") for (int _i = 0; _i < 2; ++_i) \
;         __builtin_amdgcn_global_load_lds((const unsigned*)((const char*)(gbase) + (voff)[_i]), (LAS unsigned*)(lds + (bufoff) + ldsw + _i * 8192), 16, 0, 0); } while (0)
; #define PG8_LDA(dst, b, h) do { _Pragma("unroll") for (int m = 0; m < 4; ++m) _Pragma("unroll") for (int k = 0; k < 2; ++k) dst[m][k] = *(const LAS bf16x8*)(lds + PG8_SA(b, h) + aoff + m * 2048 + k * 1024); } while (0)
; #define PG8_WAIT_V(n) asm volatile("s_waitcnt vmcnt(" #n ")" ::: "memory")
; #define PG8_WAIT_L(n) asm volatile("s_waitcnt lgkmcnt(" #n ")" ::: "memory")
; #define PG8_BAR __builtin_amdgcn_s_barrier()
; #define PG8_SCHED __builtin_amdgcn_sched_barrier(0)
; template <class Epi>
; DI void gemm_phase(LAS unsigned char* lds, const Gemm g, const StaticOrder S, const Epi E) {
;     ...
;             PG8_BAR; PG8_WAIT_L(0); PG8_MMA(0, 1, At, B1); PG8_BAR;
;             PG8_LDA(At, 1, 1); PG8_STAGE(PG8_SA(1, 0), a3, voffA);
;             PG8_BAR; PG8_WAIT_L(0); PG8_MMA(1, 0, At, B0); PG8_BAR; PG8_SCHED;
;             PG8_STAGE(PG8_SB(1, 1), b3 + hstep, voffB);
;             PG8_WAIT_V(6); PG8_BAR; PG8_MMA(1, 1, At, B1); PG8_BAR;
	v_mfma_f32_16x16x32_bf16 v[68:71], v[204:207], v[196:199], v[68:71]
	v_mfma_f32_16x16x32_bf16 v[64:67], v[212:215], v[196:199], v[64:67]
	s_setprio 0
	s_mov_b32 m0, s44
	v_lshl_add_u64 v[216:217], v[220:221], 0, s[8:9]
	ds_read_b128 v[144:147], v188 offset:49152
	ds_read_b128 v[168:171], v188 offset:51200
	ds_read_b128 v[176:179], v188 offset:53248
	ds_read_b128 v[192:195], v188 offset:55296
	global_load_lds_dwordx4 v[216:217], off
	v_lshl_add_u64 v[216:217], v[224:225], 0, s[8:9]
	s_mov_b32 m0, s45
	s_nop 0
	global_load_lds_dwordx4 v[216:217], off
	s_setprio 1
	s_barrier
	s_waitcnt lgkmcnt(0)
	v_mfma_f32_16x16x32_bf16 v[60:63], v[128:131], v[144:147], v[60:63]
	ds_read_b128 v[148:151], v188 offset:50176
	v_mfma_f32_16x16x32_bf16 v[56:59], v[136:139], v[144:147], v[56:59]
	ds_read_b128 v[172:175], v188 offset:52224
	v_mfma_f32_16x16x32_bf16 v[44:47], v[128:131], v[168:171], v[44:47]
	ds_read_b128 v[180:183], v188 offset:54272
	v_mfma_f32_16x16x32_bf16 v[40:43], v[136:139], v[168:171], v[40:43]
	ds_read_b128 v[196:199], v188 offset:56320
	v_mfma_f32_16x16x32_bf16 v[28:31], v[128:131], v[176:179], v[28:31]
	v_mfma_f32_16x16x32_bf16 v[24:27], v[136:139], v[176:179], v[24:27]
	v_mfma_f32_16x16x32_bf16 v[12:15], v[128:131], v[192:195], v[12:15]
	v_mfma_f32_16x16x32_bf16 v[8:11], v[136:139], v[192:195], v[8:11]
	s_waitcnt lgkmcnt(3)
	v_mfma_f32_16x16x32_bf16 v[60:63], v[132:135], v[148:151], v[60:63]
	v_mfma_f32_16x16x32_bf16 v[56:59], v[140:143], v[148:151], v[56:59]
	s_waitcnt lgkmcnt(2)
	v_mfma_f32_16x16x32_bf16 v[44:47], v[132:135], v[172:175], v[44:47]
	v_mfma_f32_16x16x32_bf16 v[40:43], v[140:143], v[172:175], v[40:43]
	s_waitcnt lgkmcnt(1)
	v_mfma_f32_16x16x32_bf16 v[28:31], v[132:135], v[180:183], v[28:31]
	v_mfma_f32_16x16x32_bf16 v[24:27], v[140:143], v[180:183], v[24:27]
	s_waitcnt lgkmcnt(0)
	s_setprio 2
	s_barrier
	v_mfma_f32_16x16x32_bf16 v[12:15], v[132:135], v[196:199], v[12:15]
	v_mfma_f32_16x16x32_bf16 v[8:11], v[140:143], v[196:199], v[8:11]
	s_setprio 0
	s_add_u32 s28, s28, 0x40080
	s_addc_u32 s29, s29, 0
	s_add_i32 s38, s38, s40
	v_lshl_add_u64 v[128:129], s[28:29], 0, v[154:155]
	s_mov_b32 m0, s38
	s_nop 0
	global_load_lds_dwordx4 v[128:129], off
	v_lshl_add_u64 v[128:129], s[28:29], 0, v[158:159]
	s_add_i32 m0, s38, 0x2000
	s_nop 0
	global_load_lds_dwordx4 v[128:129], off
	s_waitcnt vmcnt(6)
	s_setprio 1
	s_barrier
	v_mfma_f32_16x16x32_bf16 v[52:55], v[200:203], v[144:147], v[52:55]
	v_mfma_f32_16x16x32_bf16 v[48:51], v[208:211], v[144:147], v[48:51]
	v_mfma_f32_16x16x32_bf16 v[36:39], v[200:203], v[168:171], v[36:39]
	v_mfma_f32_16x16x32_bf16 v[32:35], v[208:211], v[168:171], v[32:35]
	v_mfma_f32_16x16x32_bf16 v[20:23], v[200:203], v[176:179], v[20:23]
	v_mfma_f32_16x16x32_bf16 v[16:19], v[208:211], v[176:179], v[16:19]
	v_mfma_f32_16x16x32_bf16 v[4:7], v[200:203], v[192:195], v[4:7]
	v_mfma_f32_16x16x32_bf16 v[0:3], v[208:211], v[192:195], v[0:3]
	v_mfma_f32_16x16x32_bf16 v[52:55], v[204:207], v[148:151], v[52:55]
	v_mfma_f32_16x16x32_bf16 v[48:51], v[212:215], v[148:151], v[48:51]
	v_mfma_f32_16x16x32_bf16 v[36:39], v[204:207], v[172:175], v[36:39]
	v_mfma_f32_16x16x32_bf16 v[32:35], v[212:215], v[172:175], v[32:35]
	v_mfma_f32_16x16x32_bf16 v[20:23], v[204:207], v[180:183], v[20:23]
	v_mfma_f32_16x16x32_bf16 v[16:19], v[212:215], v[180:183], v[16:19]
	s_setprio 2
	s_barrier
	v_mfma_f32_16x16x32_bf16 v[4:7], v[204:207], v[196:199], v[4:7]
	v_mfma_f32_16x16x32_bf16 v[0:3], v[212:215], v[196:199], v[0:3]
	s_setprio 0
	s_add_i32 s52, s52, 2
	s_add_u32 s24, s24, 0x100
	s_addc_u32 s25, s25, 0
	s_add_u32 s50, s50, 0x100
	s_addc_u32 s51, s51, 0
	s_cmp_gt_u32 s52, 13
	s_cbranch_scc0 .LBB0_786
; DI unsigned pk_bf16(float lo, float hi) { f32x2 v = {lo, hi}; return __builtin_bit_cast(unsigned, __builtin_convertvector(v, bf16v2)); }
; DI f32x4 bf_lo4(u32x4 w) { f32x4 r; r[0] = bf_lo(w.x); r[1] = bf_hi(w.x); r[2] = bf_lo(w.y); r[3] = bf_hi(w.y); return r; }
; DI f32x4 bf_hi4(u32x4 w) { f32x4 r; r[0] = bf_lo(w.z); r[1] = bf_hi(w.z); r[2] = bf_lo(w.w); r[3] = bf_hi(w.w); return r; }
;     DI void operator()(AccRef acc, const Unit& u, int wr, int wc, int fr, int fq) const {
;         const float scale = HALFSTEP ? 0.5f : 1.0f;
;         const int row0 = u.pm * 256 + wr * 64 + fr, col0 = u.pn * 256 + wc * 32 + 8 * fq;
; #pragma unroll
;         for (int ai = 0; ai < 2; ++ai) {
;             f32x4 bv[4][2][2];
; #pragma unroll
;             for (int m = 0; m < 4; ++m)
; #pragma unroll
;                 for (int bj = 0; bj < 2; ++bj) {
;                     const size_t o = (size_t)(row0 + ai * 128 + m * 16) * DM + col0 + bj * 128;
;                     if (BASEF32) { bv[m][bj][0] = *(const f32x4*)(basef + o); bv[m][bj][1] = *(const f32x4*)(basef + o + 4); }
;                     else { const u32x4 h = *(const u32x4*)(xnb + o); bv[m][bj][0] = bf_lo4(h); bv[m][bj][1] = bf_hi4(h); }
;                 }
; #pragma unroll
;             for (int m = 0; m < 4; ++m) {
;                 const int row = row0 + ai * 128 + m * 16;
;                 float q = 0.f;
; #pragma unroll
;                 for (int bj = 0; bj < 2; ++bj) {
;                     const size_t o = (size_t)row * DM + col0 + bj * 128;
;                     const f32x4 r0 = bv[m][bj][0] + scale * acc[ai][bj][m][0], r1 = bv[m][bj][1] + scale * acc[ai][bj][m][1];
;                     u32x4 w; w.x = pk_bf16(r0[0], r0[1]); w.y = pk_bf16(r0[2], r0[3]); w.z = pk_bf16(r1[0], r1[1]); w.w = pk_bf16(r1[2], r1[3]);
;                     *(u32x4*)(xnb + o) = w;
;                     if (STATS) q += r0[0] * r0[0] + r0[1] * r0[1] + r0[2] * r0[2] + r0[3] * r0[3] + r1[0] * r1[0] + r1[1] * r1[1] + r1[2] * r1[2] + r1[3] * r1[3];
;                 }
;                 if (STATS) { q += __shfl_xor(q, 16); q += __shfl_xor(q, 32); if (fq == 0) atomicAdd(ss + row, q); }
	v_lshl_add_u32 v170, s18, 8, v184
	v_lshl_or_b32 v128, s22, 8, v186
	v_ashrrev_i32_e32 v129, 31, v128
	v_ashrrev_i32_e32 v171, 31, v170
	v_lshl_add_u64 v[168:169], v[128:129], 1, s[56:57]
	v_lshlrev_b64 v[128:129], 11, v[170:171]
	v_lshl_add_u64 v[202:203], v[168:169], 0, v[128:129]
	global_load_dwordx4 v[194:197], v[202:203], off
	global_load_dwordx4 v[198:201], v[202:203], off offset:256
	v_or_b32_e32 v180, 16, v170
	v_or_b32_e32 v176, 32, v170
	v_or_b32_e32 v172, 48, v170
	v_ashrrev_i32_e32 v181, 31, v180
	v_ashrrev_i32_e32 v177, 31, v176
	v_ashrrev_i32_e32 v173, 31, v172
	v_lshlrev_b64 v[128:129], 11, v[180:181]
	v_lshlrev_b64 v[130:131], 11, v[176:177]
	v_lshlrev_b64 v[132:133], 11, v[172:173]
	v_lshl_add_u64 v[182:183], v[168:169], 0, v[128:129]
	v_lshl_add_u64 v[178:179], v[168:169], 0, v[130:131]
	v_lshl_add_u64 v[174:175], v[168:169], 0, v[132:133]
	global_load_dwordx4 v[148:151], v[182:183], off
	global_load_dwordx4 v[144:147], v[182:183], off offset:256
	global_load_dwordx4 v[140:143], v[178:179], off
	global_load_dwordx4 v[136:139], v[178:179], off offset:256
	global_load_dwordx4 v[132:135], v[174:175], off
	global_load_dwordx4 v[128:131], v[174:175], off offset:256
	v_and_b32_e32 v192, 64, v190
	v_xor_b32_e32 v191, 16, v190
	v_add_u32_e32 v192, 64, v192
	v_cmp_lt_i32_e32 vcc, v191, v192
	v_xor_b32_e32 v193, 32, v190
	s_waitcnt vmcnt(0)
	v_lshlrev_b32_e32 v204, 16, v194
	v_and_b32_e32 v205, 0xffff0000, v194
	v_lshlrev_b32_e32 v208, 16, v198
	v_and_b32_e32 v209, 0xffff0000, v198
	v_lshlrev_b32_e32 v194, 16, v195
	v_and_b32_e32 v195, 0xffff0000, v195
	v_lshlrev_b32_e32 v210, 16, v200
	v_and_b32_e32 v211, 0xffff0000, v200
	v_lshlrev_b32_e32 v200, 16, v201
	v_and_b32_e32 v201, 0xffff0000, v201
	v_pk_add_f32 v[124:125], v[124:125], v[204:205]
	v_pk_add_f32 v[116:117], v[116:117], v[208:209]
	v_lshlrev_b32_e32 v198, 16, v199
	v_and_b32_e32 v199, 0xffff0000, v199
	v_pk_add_f32 v[126:127], v[126:127], v[194:195]
	v_pk_add_f32 v[194:195], v[114:115], v[200:201]
	v_mul_f32_e32 v114, v125, v125
	v_mul_f32_e32 v115, v117, v117
	v_pk_add_f32 v[118:119], v[118:119], v[198:199]
	v_fmac_f32_e32 v114, v124, v124
	v_fmac_f32_e32 v115, v116, v116
	v_lshlrev_b32_e32 v206, 16, v196
	v_and_b32_e32 v207, 0xffff0000, v196
	v_lshlrev_b32_e32 v196, 16, v197
	v_and_b32_e32 v197, 0xffff0000, v197
	v_fmac_f32_e32 v114, v126, v126
	v_fmac_f32_e32 v115, v118, v118
	v_pk_add_f32 v[122:123], v[122:123], v[196:197]
	v_pk_add_f32 v[120:121], v[120:121], v[206:207]
	v_pk_add_f32 v[196:197], v[112:113], v[210:211]
	v_fmac_f32_e32 v114, v127, v127
	v_fmac_f32_e32 v115, v119, v119
	v_fmac_f32_e32 v114, v120, v120
	v_fmac_f32_e32 v115, v196, v196
	v_fmac_f32_e32 v114, v121, v121
	v_fmac_f32_e32 v115, v197, v197
	v_fmac_f32_e32 v114, v122, v122
	v_fmac_f32_e32 v115, v194, v194
	v_cndmask_b32_e32 v191, v190, v191, vcc
	v_fmac_f32_e32 v114, v123, v123
	v_fmac_f32_e32 v115, v195, v195
	v_cmp_lt_i32_e32 vcc, v193, v192
	v_lshlrev_b32_e32 v192, 2, v191
	v_cvt_pk_bf16_f32 v112, v124, v125
	v_add_f32_e32 v124, v114, v115
	ds_bpermute_b32 v125, v192, v124
	v_cndmask_b32_e32 v193, v190, v193, vcc
	v_cvt_pk_bf16_f32 v113, v126, v127
	v_cvt_pk_bf16_f32 v114, v120, v121
	v_cvt_pk_bf16_f32 v115, v122, v123
	v_lshlrev_b32_e32 v191, 2, v193
	global_store_dwordx4 v[202:203], v[112:115], off
	s_waitcnt lgkmcnt(0)
	s_nop 0
	v_add_f32_e32 v112, v124, v125
	ds_bpermute_b32 v113, v191, v112
	v_cvt_pk_bf16_f32 v114, v116, v117
	v_cvt_pk_bf16_f32 v115, v118, v119
	v_cvt_pk_bf16_f32 v116, v196, v197
	v_cvt_pk_bf16_f32 v117, v194, v195
	global_store_dwordx4 v[202:203], v[114:117], off offset:256
	s_and_saveexec_b64 s[6:7], s[0:1]
	s_cbranch_execz .LBB0_789
	s_waitcnt lgkmcnt(0)
	v_add_f32_e32 v114, v112, v113
	v_lshl_add_u64 v[112:113], v[170:171], 2, s[20:21]
	global_atomic_add_f32 v[112:113], v114, off

; #define PG8_STAGE(bufoff, gbase, voff) do { _Pragma("unroll") for (int _i = 0; _i < 2; ++_i) \
;         __builtin_amdgcn_global_load_lds((const unsigned*)((const char*)(gbase) + (voff)[_i]), (LAS unsigned*)(lds + (bufoff) + ldsw + _i * 8192), 16, 0, 0); } while (0)
; #define PG8_LDA(dst, b, h) do { _Pragma("unroll") for (int m = 0; m < 4; ++m) _Pragma("unroll") for (int k = 0; k < 2; ++k) dst[m][k] = *(const LAS bf16x8*)(lds + PG8_SA(b, h) + aoff + m * 2048 + k * 1024); } while (0)
; #define PG8_LDB(dst, b, h) do { _Pragma("unroll") for (int n = 0; n < 2; ++n) _Pragma("unroll") for (int k = 0; k < 2; ++k) dst[n][k] = *(const LAS bf16x8*)(lds + PG8_SB(b, h) + boff + n * 2048 + k * 1024); } while (0)
; #define PG8_MMA(ai, bj, At, Bt) do { __builtin_amdgcn_s_setprio(1); _Pragma("unroll") for (int m = 0; m < 4; ++m) _Pragma("unroll") for (int n = 0; n < 2; ++n) _Pragma("unroll") for (int k = 0; k < 2; ++k) \
;         acc[ai][bj][m][n] = __builtin_amdgcn_mfma_f32_16x16x32_bf16(Bt[n][k], At[m][k], acc[ai][bj][m][n], 0, 0, 0); __builtin_amdgcn_s_setprio(0); } while (0)
; template <class Epi>
; DI void gemm_phase(LAS unsigned char* lds, const Gemm g, const StaticOrder S, const Epi E) {
;     ...
;         for (int t = 0; t < nt; t += 2) {
;             const bool last = (t == nt - 2);
;             const char* a1 = cA + (size_t)(t + 1) * kstep;
;             const char* a2 = last ? nA : cA + (size_t)(t + 2) * kstep; const char* b2 = last ? nB : cB + (size_t)(t + 2) * kstep;
;             const char* a3 = a2 + kstep; const char* b3 = b2 + kstep;
;             PG8_LDB(B0, 0, 0); PG8_SCHED; PG8_LDA(At, 0, 0); PG8_STAGE(PG8_SA(1, 1), a1 + hstep, voffA);
;             PG8_WAIT_L(8); PG8_BAR; PG8_WAIT_L(0); PG8_MMA(0, 0, At, B0); PG8_BAR; PG8_SCHED;
;             PG8_LDB(B1, 0, 1); PG8_STAGE(PG8_SB(0, 0), b2, voffB);
;             PG8_BAR; PG8_WAIT_L(0); PG8_MMA(0, 1, At, B1); PG8_BAR;
;             PG8_LDA(At, 0, 1); PG8_STAGE(PG8_SA(0, 0), a2, voffA);
;             PG8_BAR; PG8_WAIT_L(0); PG8_MMA(1, 0, At, B0); PG8_BAR; PG8_SCHED;
;             PG8_STAGE(PG8_SB(0, 1), b2 + hstep, voffB);
;             PG8_WAIT_V(6); PG8_BAR; PG8_MMA(1, 1, At, B1); PG8_BAR;
;             PG8_LDB(B0, 1, 0); PG8_SCHED; PG8_LDA(At, 1, 0); PG8_STAGE(PG8_SA(0, 1), a2 + hstep, voffA);
;             PG8_WAIT_L(8); PG8_BAR; PG8_WAIT_L(0); PG8_MMA(0, 0, At, B0); PG8_BAR; PG8_SCHED;
.LBB0_865:
	ds_read_b128 v[144:147], v155
	ds_read_b128 v[160:163], v155 offset:1024
	ds_read_b128 v[164:167], v155 offset:2048
	ds_read_b128 v[168:171], v155 offset:3072
	s_add_u32 s10, s8, 0xfffc0080
	s_addc_u32 s11, s9, -1
	s_cmp_eq_u32 s25, 12
	s_cselect_b32 s13, s14, s11
	s_cselect_b32 s12, s15, s10
	s_cselect_b32 s11, s16, s19
	s_cselect_b32 s10, s17, s18
	v_lshl_add_u64 v[204:205], s[8:9], 0, v[136:137]
	s_add_i32 m0, s40, 0xc000
	ds_read_b128 v[172:175], v157
	ds_read_b128 v[180:183], v157 offset:2048
	ds_read_b128 v[188:191], v157 offset:4096
	ds_read_b128 v[196:199], v157 offset:6144
	global_load_lds_dwordx4 v[204:205], off
	v_lshl_add_u64 v[204:205], s[8:9], 0, v[138:139]
	s_add_i32 m0, s40, 0xe000
	s_nop 0
	global_load_lds_dwordx4 v[204:205], off
	s_waitcnt lgkmcnt(4)
	s_setprio 1
	s_barrier
	s_waitcnt lgkmcnt(0)
	v_mfma_f32_16x16x32_bf16 v[124:127], v[144:147], v[172:175], v[124:127]
	ds_read_b128 v[176:179], v157 offset:1024
	v_mfma_f32_16x16x32_bf16 v[120:123], v[164:167], v[172:175], v[120:123]
	ds_read_b128 v[184:187], v157 offset:3072
	v_mfma_f32_16x16x32_bf16 v[108:111], v[144:147], v[180:183], v[108:111]
	ds_read_b128 v[192:195], v157 offset:5120
	v_mfma_f32_16x16x32_bf16 v[104:107], v[164:167], v[180:183], v[104:107]
	ds_read_b128 v[200:203], v157 offset:7168
	v_mfma_f32_16x16x32_bf16 v[92:95], v[144:147], v[188:191], v[92:95]
	v_mfma_f32_16x16x32_bf16 v[88:91], v[164:167], v[188:191], v[88:91]
	v_mfma_f32_16x16x32_bf16 v[76:79], v[144:147], v[196:199], v[76:79]
	v_mfma_f32_16x16x32_bf16 v[72:75], v[164:167], v[196:199], v[72:75]
	s_waitcnt lgkmcnt(3)
	v_mfma_f32_16x16x32_bf16 v[124:127], v[160:163], v[176:179], v[124:127]
	v_mfma_f32_16x16x32_bf16 v[120:123], v[168:171], v[176:179], v[120:123]
	s_waitcnt lgkmcnt(2)
	v_mfma_f32_16x16x32_bf16 v[108:111], v[160:163], v[184:187], v[108:111]
	v_mfma_f32_16x16x32_bf16 v[104:107], v[168:171], v[184:187], v[104:107]
	s_waitcnt lgkmcnt(1)
	v_mfma_f32_16x16x32_bf16 v[92:95], v[160:163], v[192:195], v[92:95]
	v_mfma_f32_16x16x32_bf16 v[88:91], v[168:171], v[192:195], v[88:91]
	s_waitcnt lgkmcnt(0)
	s_setprio 2
	s_barrier
	v_mfma_f32_16x16x32_bf16 v[76:79], v[160:163], v[200:203], v[76:79]
	v_mfma_f32_16x16x32_bf16 v[72:75], v[168:171], v[200:203], v[72:75]
	s_setprio 0
	s_add_i32 s29, s49, s34
	v_lshl_add_u64 v[220:221], s[10:11], 0, v[132:133]
	s_mov_b32 m0, s29
	ds_read_b128 v[204:207], v158
	ds_read_b128 v[208:211], v158 offset:1024
	ds_read_b128 v[212:215], v158 offset:2048
	ds_read_b128 v[216:219], v158 offset:3072
	global_load_lds_dwordx4 v[220:221], off
	v_lshl_add_u64 v[224:225], s[10:11], 0, v[128:129]
	s_add_i32 m0, s29, 0x2000
	s_nop 0
	global_load_lds_dwordx4 v[224:225], off
	s_setprio 1
	s_barrier
	s_waitcnt lgkmcnt(0)
	v_mfma_f32_16x16x32_bf16 v[116:119], v[204:207], v[172:175], v[116:119]
	v_mfma_f32_16x16x32_bf16 v[112:115], v[212:215], v[172:175], v[112:115]
	v_mfma_f32_16x16x32_bf16 v[100:103], v[204:207], v[180:183], v[100:103]
	v_mfma_f32_16x16x32_bf16 v[96:99], v[212:215], v[180:183], v[96:99]
	v_mfma_f32_16x16x32_bf16 v[84:87], v[204:207], v[188:191], v[84:87]
	v_mfma_f32_16x16x32_bf16 v[80:83], v[212:215], v[188:191], v[80:83]
	v_mfma_f32_16x16x32_bf16 v[68:71], v[204:207], v[196:199], v[68:71]
	v_mfma_f32_16x16x32_bf16 v[64:67], v[212:215], v[196:199], v[64:67]
	v_mfma_f32_16x16x32_bf16 v[116:119], v[208:211], v[176:179], v[116:119]
	v_mfma_f32_16x16x32_bf16 v[112:115], v[216:219], v[176:179], v[112:115]
	v_mfma_f32_16x16x32_bf16 v[100:103], v[208:211], v[184:187], v[100:103]
	v_mfma_f32_16x16x32_bf16 v[96:99], v[216:219], v[184:187], v[96:99]
	v_mfma_f32_16x16x32_bf16 v[84:87], v[208:211], v[192:195], v[84:87]
	v_mfma_f32_16x16x32_bf16 v[80:83], v[216:219], v[192:195], v[80:83]
	s_setprio 2
	s_barrier
	v_mfma_f32_16x16x32_bf16 v[68:71], v[208:211], v[200:203], v[68:71]
	v_mfma_f32_16x16x32_bf16 v[64:67], v[216:219], v[200:203], v[64:67]
	s_setprio 0
	s_mov_b32 m0, s40
	v_lshl_add_u64 v[226:227], s[12:13], 0, v[134:135]
	ds_read_b128 v[172:175], v157 offset:16384
	ds_read_b128 v[180:183], v157 offset:18432
	ds_read_b128 v[188:191], v157 offset:20480
	ds_read_b128 v[196:199], v157 offset:22528
	global_load_lds_dwordx4 v[226:227], off
	v_lshl_add_u64 v[228:229], s[12:13], 0, v[130:131]
	s_mov_b32 m0, s41
	s_nop 0
	global_load_lds_dwordx4 v[228:229], off
	s_setprio 1
	s_barrier
	s_waitcnt lgkmcnt(0)
	v_mfma_f32_16x16x32_bf16 v[60:63], v[144:147], v[172:175], v[60:63]
	ds_read_b128 v[176:179], v157 offset:17408
	v_mfma_f32_16x16x32_bf16 v[56:59], v[164:167], v[172:175], v[56:59]
	ds_read_b128 v[184:187], v157 offset:19456
	v_mfma_f32_16x16x32_bf16 v[44:47], v[144:147], v[180:183], v[44:47]
	ds_read_b128 v[192:195], v157 offset:21504
	v_mfma_f32_16x16x32_bf16 v[40:43], v[164:167], v[180:183], v[40:43]
	ds_read_b128 v[200:203], v157 offset:23552
	v_mfma_f32_16x16x32_bf16 v[28:31], v[144:147], v[188:191], v[28:31]
	v_mfma_f32_16x16x32_bf16 v[24:27], v[164:167], v[188:191], v[24:27]
	v_mfma_f32_16x16x32_bf16 v[12:15], v[144:147], v[196:199], v[12:15]
	v_mfma_f32_16x16x32_bf16 v[8:11], v[164:167], v[196:199], v[8:11]
	s_waitcnt lgkmcnt(3)
	v_mfma_f32_16x16x32_bf16 v[60:63], v[160:163], v[176:179], v[60:63]
	v_mfma_f32_16x16x32_bf16 v[56:59], v[168:171], v[176:179], v[56:59]
	s_waitcnt lgkmcnt(2)
	v_mfma_f32_16x16x32_bf16 v[44:47], v[160:163], v[184:187], v[44:47]
	v_mfma_f32_16x16x32_bf16 v[40:43], v[168:171], v[184:187], v[40:43]
	s_waitcnt lgkmcnt(1)
	v_mfma_f32_16x16x32_bf16 v[28:31], v[160:163], v[192:195], v[28:31]
	v_mfma_f32_16x16x32_bf16 v[24:27], v[168:171], v[192:195], v[24:27]
	s_waitcnt lgkmcnt(0)
	s_setprio 2
	s_barrier
; #define PG8_STAGE(bufoff, gbase, voff) do { _Pragma("unroll") for (int _i = 0; _i < 2; ++_i) \
;         __builtin_amdgcn_global_load_lds((const unsigned*)((const char*)(gbase) + (voff)[_i]), (LAS unsigned*)(lds + (bufoff) + ldsw + _i * 8192), 16, 0, 0); } while (0)
; #define PG8_LDA(dst, b, h) do { _Pragma("unroll") for (int m = 0; m < 4; ++m) _Pragma("unroll") for (int k = 0; k < 2; ++k) dst[m][k] = *(const LAS bf16x8*)(lds + PG8_SA(b, h) + aoff + m * 2048 + k * 1024); } while (0)
; #define PG8_LDB(dst, b, h) do { _Pragma("unroll") for (int n = 0; n < 2; ++n) _Pragma("unroll") for (int k = 0; k < 2; ++k) dst[n][k] = *(const LAS bf16x8*)(lds + PG8_SB(b, h) + boff + n * 2048 + k * 1024); } while (0)
; #define PG8_MMA(ai, bj, At, Bt) do { __builtin_amdgcn_s_setprio(1); _Pragma("unroll") for (int m = 0; m < 4; ++m) _Pragma("unroll") for (int n = 0; n < 2; ++n) _Pragma("unroll") for (int k = 0; k < 2; ++k) \
;         acc[ai][bj][m][n] = __builtin_amdgcn_mfma_f32_16x16x32_bf16(Bt[n][k], At[m][k], acc[ai][bj][m][n], 0, 0, 0); __builtin_amdgcn_s_setprio(0); } while (0)
; #define PG8_WAIT_V(n) asm volatile("s_waitcnt vmcnt(" #n ")" ::: "memory")
; #define PG8_WAIT_L(n) asm volatile("s_waitcnt lgkmcnt(" #n ")" ::: "memory")
; #define PG8_BAR __builtin_amdgcn_s_barrier()
; #define PG8_SCHED __builtin_amdgcn_sched_barrier(0)
; #define PG8_WAIT_V(n) asm volatile("s_waitcnt vmcnt(" #n ")" ::: "memory")
; #define PG8_WAIT_L(n) asm volatile("s_waitcnt lgkmcnt(" #n ")" ::: "memory")
; template <class Epi>
; DI void gemm_phase(LAS unsigned char* lds, const Gemm g, const StaticOrder S, const Epi E) {
;     ...
;             PG8_STAGE(PG8_SB(0, 1), b2 + hstep, voffB);
;             PG8_WAIT_V(6); PG8_BAR; PG8_MMA(1, 1, At, B1); PG8_BAR;
;             PG8_LDB(B0, 1, 0); PG8_SCHED; PG8_LDA(At, 1, 0); PG8_STAGE(PG8_SA(0, 1), a2 + hstep, voffA);
;             PG8_WAIT_L(8); PG8_BAR; PG8_WAIT_L(0); PG8_MMA(0, 0, At, B0); PG8_BAR; PG8_SCHED;
;             PG8_LDB(B1, 1, 1); PG8_STAGE(PG8_SB(1, 0), b3, voffB);
;             PG8_BAR; PG8_WAIT_L(0); PG8_MMA(0, 1, At, B1); PG8_BAR;
;             PG8_LDA(At, 1, 1); PG8_STAGE(PG8_SA(1, 0), a3, voffA);
;             PG8_BAR; PG8_WAIT_L(0); PG8_MMA(1, 0, At, B0); PG8_BAR; PG8_SCHED;
;             PG8_STAGE(PG8_SB(1, 1), b3 + hstep, voffB);
;             PG8_WAIT_V(6); PG8_BAR; PG8_MMA(1, 1, At, B1); PG8_BAR;
	v_mfma_f32_16x16x32_bf16 v[12:15], v[160:163], v[200:203], v[12:15]
	v_mfma_f32_16x16x32_bf16 v[8:11], v[168:171], v[200:203], v[8:11]
	s_setprio 0
	s_add_u32 s58, s10, 0x40000
	s_addc_u32 s59, s11, 0
	s_add_i32 s29, s50, s34
	v_lshl_add_u64 v[144:145], s[58:59], 0, v[132:133]
	s_mov_b32 m0, s29
	s_nop 0
	global_load_lds_dwordx4 v[144:145], off
	v_lshl_add_u64 v[144:145], s[58:59], 0, v[128:129]
	s_add_i32 m0, s29, 0x2000
	s_nop 0
	global_load_lds_dwordx4 v[144:145], off
	s_waitcnt vmcnt(6)
	s_setprio 1
	s_barrier
	v_mfma_f32_16x16x32_bf16 v[52:55], v[204:207], v[172:175], v[52:55]
	v_mfma_f32_16x16x32_bf16 v[48:51], v[212:215], v[172:175], v[48:51]
	v_mfma_f32_16x16x32_bf16 v[36:39], v[204:207], v[180:183], v[36:39]
	v_mfma_f32_16x16x32_bf16 v[32:35], v[212:215], v[180:183], v[32:35]
	v_mfma_f32_16x16x32_bf16 v[20:23], v[204:207], v[188:191], v[20:23]
	v_mfma_f32_16x16x32_bf16 v[16:19], v[212:215], v[188:191], v[16:19]
	v_mfma_f32_16x16x32_bf16 v[4:7], v[204:207], v[196:199], v[4:7]
	v_mfma_f32_16x16x32_bf16 v[0:3], v[212:215], v[196:199], v[0:3]
	v_mfma_f32_16x16x32_bf16 v[52:55], v[208:211], v[176:179], v[52:55]
	v_mfma_f32_16x16x32_bf16 v[48:51], v[216:219], v[176:179], v[48:51]
	v_mfma_f32_16x16x32_bf16 v[36:39], v[208:211], v[184:187], v[36:39]
	v_mfma_f32_16x16x32_bf16 v[32:35], v[216:219], v[184:187], v[32:35]
	v_mfma_f32_16x16x32_bf16 v[20:23], v[208:211], v[192:195], v[20:23]
	v_mfma_f32_16x16x32_bf16 v[16:19], v[216:219], v[192:195], v[16:19]
	s_setprio 2
	s_barrier
	v_mfma_f32_16x16x32_bf16 v[4:7], v[208:211], v[200:203], v[4:7]
	v_mfma_f32_16x16x32_bf16 v[0:3], v[216:219], v[200:203], v[0:3]
	s_setprio 0
	s_add_i32 s29, 0, 0x18000
	v_add_u32_e32 v148, s29, v151
	ds_read_b128 v[144:147], v148
	ds_read_b128 v[160:163], v148 offset:1024
	ds_read_b128 v[164:167], v148 offset:2048
	ds_read_b128 v[168:171], v148 offset:3072
	s_add_u32 s12, s12, 0x40000
	s_addc_u32 s13, s13, 0
	s_mov_b32 m0, s42
	v_lshl_add_u64 v[204:205], s[12:13], 0, v[134:135]
	ds_read_b128 v[172:175], v157 offset:32768
	ds_read_b128 v[180:183], v157 offset:34816
	ds_read_b128 v[188:191], v157 offset:36864
	ds_read_b128 v[196:199], v157 offset:38912
	global_load_lds_dwordx4 v[204:205], off
	v_lshl_add_u64 v[204:205], s[12:13], 0, v[130:131]
	s_mov_b32 m0, s43
	s_nop 0
	global_load_lds_dwordx4 v[204:205], off
	s_waitcnt lgkmcnt(4)
	s_setprio 1
	s_barrier
	s_waitcnt lgkmcnt(0)
	v_mfma_f32_16x16x32_bf16 v[124:127], v[144:147], v[172:175], v[124:127]
	ds_read_b128 v[176:179], v157 offset:33792
	v_mfma_f32_16x16x32_bf16 v[120:123], v[164:167], v[172:175], v[120:123]
	ds_read_b128 v[184:187], v157 offset:35840
	v_mfma_f32_16x16x32_bf16 v[108:111], v[144:147], v[180:183], v[108:111]
	ds_read_b128 v[192:195], v157 offset:37888
	v_mfma_f32_16x16x32_bf16 v[104:107], v[164:167], v[180:183], v[104:107]
	ds_read_b128 v[200:203], v157 offset:39936
	v_mfma_f32_16x16x32_bf16 v[92:95], v[144:147], v[188:191], v[92:95]
	v_mfma_f32_16x16x32_bf16 v[88:91], v[164:167], v[188:191], v[88:91]
	v_mfma_f32_16x16x32_bf16 v[76:79], v[144:147], v[196:199], v[76:79]
	v_mfma_f32_16x16x32_bf16 v[72:75], v[164:167], v[196:199], v[72:75]
	s_waitcnt lgkmcnt(3)
	v_mfma_f32_16x16x32_bf16 v[124:127], v[160:163], v[176:179], v[124:127]
	v_mfma_f32_16x16x32_bf16 v[120:123], v[168:171], v[176:179], v[120:123]
	s_waitcnt lgkmcnt(2)
	v_mfma_f32_16x16x32_bf16 v[108:111], v[160:163], v[184:187], v[108:111]
	v_mfma_f32_16x16x32_bf16 v[104:107], v[168:171], v[184:187], v[104:107]
	s_waitcnt lgkmcnt(1)
	v_mfma_f32_16x16x32_bf16 v[92:95], v[160:163], v[192:195], v[92:95]
	v_mfma_f32_16x16x32_bf16 v[88:91], v[168:171], v[192:195], v[88:91]
	s_waitcnt lgkmcnt(0)
	s_setprio 2
	s_barrier
	v_mfma_f32_16x16x32_bf16 v[76:79], v[160:163], v[200:203], v[76:79]
	v_mfma_f32_16x16x32_bf16 v[72:75], v[168:171], v[200:203], v[72:75]
	s_setprio 0
	s_add_i32 s12, 0, 0x1c000
	s_add_i32 s13, s29, s34
	v_add_u32_e32 v148, s12, v151
	v_lshl_add_u64 v[220:221], v[220:221], 0, s[22:23]
	s_mov_b32 m0, s13
	ds_read_b128 v[204:207], v148
	ds_read_b128 v[208:211], v148 offset:1024
	ds_read_b128 v[212:215], v148 offset:2048
	ds_read_b128 v[216:219], v148 offset:3072
	global_load_lds_dwordx4 v[220:221], off
	v_lshl_add_u64 v[220:221], v[224:225], 0, s[22:23]
	s_add_i32 m0, s13, 0x2000
	s_nop 0
	global_load_lds_dwordx4 v[220:221], off
	s_setprio 1
	s_barrier
	s_waitcnt lgkmcnt(0)
	v_mfma_f32_16x16x32_bf16 v[116:119], v[204:207], v[172:175], v[116:119]
	v_mfma_f32_16x16x32_bf16 v[112:115], v[212:215], v[172:175], v[112:115]
	v_mfma_f32_16x16x32_bf16 v[100:103], v[204:207], v[180:183], v[100:103]
	v_mfma_f32_16x16x32_bf16 v[96:99], v[212:215], v[180:183], v[96:99]
	v_mfma_f32_16x16x32_bf16 v[84:87], v[204:207], v[188:191], v[84:87]
	v_mfma_f32_16x16x32_bf16 v[80:83], v[212:215], v[188:191], v[80:83]
	v_mfma_f32_16x16x32_bf16 v[68:71], v[204:207], v[196:199], v[68:71]
	v_mfma_f32_16x16x32_bf16 v[64:67], v[212:215], v[196:199], v[64:67]
	v_mfma_f32_16x16x32_bf16 v[116:119], v[208:211], v[176:179], v[116:119]
	v_mfma_f32_16x16x32_bf16 v[112:115], v[216:219], v[176:179], v[112:115]
	v_mfma_f32_16x16x32_bf16 v[100:103], v[208:211], v[184:187], v[100:103]
	v_mfma_f32_16x16x32_bf16 v[96:99], v[216:219], v[184:187], v[96:99]
	v_mfma_f32_16x16x32_bf16 v[84:87], v[208:211], v[192:195], v[84:87]
	v_mfma_f32_16x16x32_bf16 v[80:83], v[216:219], v[192:195], v[80:83]
	s_setprio 2
	s_barrier
; #define PG8_STAGE(bufoff, gbase, voff) do { _Pragma("unroll") for (int _i = 0; _i < 2; ++_i) \
;         __builtin_amdgcn_global_load_lds((const unsigned*)((const char*)(gbase) + (voff)[_i]), (LAS unsigned*)(lds + (bufoff) + ldsw + _i * 8192), 16, 0, 0); } while (0)
; #define PG8_LDA(dst, b, h) do { _Pragma("unroll") for (int m = 0; m < 4; ++m) _Pragma("unroll") for (int k = 0; k < 2; ++k) dst[m][k] = *(const LAS bf16x8*)(lds + PG8_SA(b, h) + aoff + m * 2048 + k * 1024); } while (0)
; #define PG8_LDB(dst, b, h) do { _Pragma("unroll") for (int n = 0; n < 2; ++n) _Pragma("unroll") for (int k = 0; k < 2; ++k) dst[n][k] = *(const LAS bf16x8*)(lds + PG8_SB(b, h) + boff + n * 2048 + k * 1024); } while (0)
; #define PG8_MMA(ai, bj, At, Bt) do { __builtin_amdgcn_s_setprio(1); _Pragma("unroll") for (int m = 0; m < 4; ++m) _Pragma("unroll") for (int n = 0; n < 2; ++n) _Pragma("unroll") for (int k = 0; k < 2; ++k) \
;         acc[ai][bj][m][n] = __builtin_amdgcn_mfma_f32_16x16x32_bf16(Bt[n][k], At[m][k], acc[ai][bj][m][n], 0, 0, 0); __builtin_amdgcn_s_setprio(0); } while (0)
; #define PG8_WAIT_V(n) asm volatile("s_waitcnt vmcnt(" #n ")" ::: "memory")
; #define PG8_WAIT_L(n) asm volatile("s_waitcnt lgkmcnt(" #n ")" ::: "memory")
; #define PG8_BAR __builtin_amdgcn_s_barrier()
; #define PG8_SCHED __builtin_amdgcn_sched_barrier(0)
; #define PG8_WAIT_V(n) asm volatile("s_waitcnt vmcnt(" #n ")" ::: "memory")
; #define PG8_WAIT_L(n) asm volatile("s_waitcnt lgkmcnt(" #n ")" ::: "memory")
; DI RowScales load_rowscales(const float* ss, int row0) {
;     RowScales t;
; #pragma unroll
;     for (int ai = 0; ai < 2; ++ai)
; #pragma unroll
;         for (int m = 0; m < 4; ++m) t.r[ai][m] = ss[row0 + ai * 128 + m * 16];
; template <class Epi>
; DI void gemm_phase(LAS unsigned char* lds, const Gemm g, const StaticOrder S, const Epi E) {
;     ...
;             PG8_WAIT_L(8); PG8_BAR; PG8_WAIT_L(0); PG8_MMA(0, 0, At, B0); PG8_BAR; PG8_SCHED;
;             PG8_LDB(B1, 1, 1); PG8_STAGE(PG8_SB(1, 0), b3, voffB);
;             PG8_BAR; PG8_WAIT_L(0); PG8_MMA(0, 1, At, B1); PG8_BAR;
;             PG8_LDA(At, 1, 1); PG8_STAGE(PG8_SA(1, 0), a3, voffA);
;             PG8_BAR; PG8_WAIT_L(0); PG8_MMA(1, 0, At, B0); PG8_BAR; PG8_SCHED;
;             PG8_STAGE(PG8_SB(1, 1), b3 + hstep, voffB);
;             PG8_WAIT_V(6); PG8_BAR; PG8_MMA(1, 1, At, B1); PG8_BAR;
	v_mfma_f32_16x16x32_bf16 v[68:71], v[208:211], v[200:203], v[68:71]
	v_mfma_f32_16x16x32_bf16 v[64:67], v[216:219], v[200:203], v[64:67]
	s_setprio 0
	s_mov_b32 m0, s45
	v_lshl_add_u64 v[220:221], v[226:227], 0, s[22:23]
	ds_read_b128 v[172:175], v157 offset:49152
	ds_read_b128 v[180:183], v157 offset:51200
	ds_read_b128 v[188:191], v157 offset:53248
	ds_read_b128 v[196:199], v157 offset:55296
	global_load_lds_dwordx4 v[220:221], off
	v_lshl_add_u64 v[220:221], v[228:229], 0, s[22:23]
	s_mov_b32 m0, s46
	s_nop 0
	global_load_lds_dwordx4 v[220:221], off
	s_setprio 1
	s_barrier
	s_waitcnt lgkmcnt(0)
	v_mfma_f32_16x16x32_bf16 v[60:63], v[144:147], v[172:175], v[60:63]
	ds_read_b128 v[176:179], v157 offset:50176
	v_mfma_f32_16x16x32_bf16 v[56:59], v[164:167], v[172:175], v[56:59]
	ds_read_b128 v[184:187], v157 offset:52224
	v_mfma_f32_16x16x32_bf16 v[44:47], v[144:147], v[180:183], v[44:47]
	ds_read_b128 v[192:195], v157 offset:54272
	v_mfma_f32_16x16x32_bf16 v[40:43], v[164:167], v[180:183], v[40:43]
	ds_read_b128 v[200:203], v157 offset:56320
	v_mfma_f32_16x16x32_bf16 v[28:31], v[144:147], v[188:191], v[28:31]
	v_mfma_f32_16x16x32_bf16 v[24:27], v[164:167], v[188:191], v[24:27]
	v_mfma_f32_16x16x32_bf16 v[12:15], v[144:147], v[196:199], v[12:15]
	v_mfma_f32_16x16x32_bf16 v[8:11], v[164:167], v[196:199], v[8:11]
	s_waitcnt lgkmcnt(3)
	v_mfma_f32_16x16x32_bf16 v[60:63], v[160:163], v[176:179], v[60:63]
	v_mfma_f32_16x16x32_bf16 v[56:59], v[168:171], v[176:179], v[56:59]
	s_waitcnt lgkmcnt(2)
	v_mfma_f32_16x16x32_bf16 v[44:47], v[160:163], v[184:187], v[44:47]
	v_mfma_f32_16x16x32_bf16 v[40:43], v[168:171], v[184:187], v[40:43]
	s_waitcnt lgkmcnt(1)
	v_mfma_f32_16x16x32_bf16 v[28:31], v[160:163], v[192:195], v[28:31]
	v_mfma_f32_16x16x32_bf16 v[24:27], v[168:171], v[192:195], v[24:27]
	s_waitcnt lgkmcnt(0)
	s_setprio 2
	s_barrier
	v_mfma_f32_16x16x32_bf16 v[12:15], v[160:163], v[200:203], v[12:15]
	v_mfma_f32_16x16x32_bf16 v[8:11], v[168:171], v[200:203], v[8:11]
	s_setprio 0
	s_add_u32 s10, s10, 0x40080
	s_addc_u32 s11, s11, 0
	s_add_i32 s12, s12, s34
	v_lshl_add_u64 v[144:145], s[10:11], 0, v[132:133]
	s_mov_b32 m0, s12
	s_nop 0
	global_load_lds_dwordx4 v[144:145], off
	v_lshl_add_u64 v[144:145], s[10:11], 0, v[128:129]
	s_add_i32 m0, s12, 0x2000
	s_nop 0
	global_load_lds_dwordx4 v[144:145], off
	s_waitcnt vmcnt(6)
	s_setprio 1
	s_barrier
	v_mfma_f32_16x16x32_bf16 v[52:55], v[204:207], v[172:175], v[52:55]
	v_mfma_f32_16x16x32_bf16 v[48:51], v[212:215], v[172:175], v[48:51]
	v_mfma_f32_16x16x32_bf16 v[36:39], v[204:207], v[180:183], v[36:39]
	v_mfma_f32_16x16x32_bf16 v[32:35], v[212:215], v[180:183], v[32:35]
	v_mfma_f32_16x16x32_bf16 v[20:23], v[204:207], v[188:191], v[20:23]
	v_mfma_f32_16x16x32_bf16 v[16:19], v[212:215], v[188:191], v[16:19]
	v_mfma_f32_16x16x32_bf16 v[4:7], v[204:207], v[196:199], v[4:7]
	v_mfma_f32_16x16x32_bf16 v[0:3], v[212:215], v[196:199], v[0:3]
	v_mfma_f32_16x16x32_bf16 v[52:55], v[208:211], v[176:179], v[52:55]
	v_mfma_f32_16x16x32_bf16 v[48:51], v[216:219], v[176:179], v[48:51]
	v_mfma_f32_16x16x32_bf16 v[36:39], v[208:211], v[184:187], v[36:39]
	v_mfma_f32_16x16x32_bf16 v[32:35], v[216:219], v[184:187], v[32:35]
	v_mfma_f32_16x16x32_bf16 v[20:23], v[208:211], v[192:195], v[20:23]
	v_mfma_f32_16x16x32_bf16 v[16:19], v[216:219], v[192:195], v[16:19]
	s_setprio 2
	s_barrier
	v_mfma_f32_16x16x32_bf16 v[4:7], v[208:211], v[200:203], v[4:7]
	v_mfma_f32_16x16x32_bf16 v[0:3], v[216:219], v[200:203], v[0:3]
	s_setprio 0
	s_add_i32 s25, s25, 2
	s_add_u32 s8, s8, 0x100
	s_addc_u32 s9, s9, 0
	s_add_u32 s18, s18, 0x100
	s_addc_u32 s19, s19, 0
	s_cmp_gt_u32 s25, 13
	s_cbranch_scc0 .LBB0_865
	v_lshl_add_u32 v146, s4, 8, v149
	v_ashrrev_i32_e32 v147, 31, v146
	v_lshl_add_u64 v[144:145], v[146:147], 2, s[20:21]
	global_load_dword v147, v[144:145], off
	global_load_dword v148, v[144:145], off offset:64
	global_load_dword v150, v[144:145], off offset:128
	global_load_dword v152, v[144:145], off offset:192
	global_load_dword v154, v[144:145], off offset:512
	global_load_dword v156, v[144:145], off offset:576
	global_load_dword v160, v[144:145], off offset:640
	global_load_dword v161, v[144:145], off offset:704
	v_lshl_or_b32 v144, s5, 7, v153
	v_ashrrev_i32_e32 v145, 31, v144
	v_lshl_add_u64 v[144:145], v[144:145], 1, s[54:55]
	s_waitcnt vmcnt(0)
; DI unsigned pk_bf16(float lo, float hi) { f32x2 v = {lo, hi}; return __builtin_bit_cast(unsigned, __builtin_convertvector(v, bf16v2)); }
; DI float fast_silu(float x) { return x * fast_sigmoid(x); }
; DI RowScales load_rowscales(const float* ss, int row0) {
;     ...
;         for (int m = 0; m < 4; ++m) t.r[ai][m] = ss[row0 + ai * 128 + m * 16];
; #pragma unroll
;     for (int ai = 0; ai < 2; ++ai)
; #pragma unroll
;         for (int m = 0; m < 4; ++m) t.r[ai][m] = rsqrtf(t.r[ai][m] * (1.0f / 1024.0f) + 1e-6f);
;     DI void operator()(AccRef acc, const Unit& u, int wr, int wc, int fr, int fq) const {
;     ...
; #pragma unroll
;         for (int ai = 0; ai < 2; ++ai)
; #pragma unroll
;             for (int m = 0; m < 4; ++m) {
;                 const int row = row0 + ai * 128 + m * 16;
;                 const float r = RS ? rsc.r[ai][m] : 1.0f;
;                 const f32x4 a0 = acc[ai][0][m][0] * r, a1 = acc[ai][0][m][1] * r, b0 = acc[ai][1][m][0] * r, b1 = acc[ai][1][m][1] * r;
;                 u32x4 w;
;                 w.x = pk_bf16(fast_silu(a0[0]) * b0[0], fast_silu(a0[1]) * b0[1]); w.y = pk_bf16(fast_silu(a0[2]) * b0[2], fast_silu(a0[3]) * b0[3]);
;                 w.z = pk_bf16(fast_silu(a1[0]) * b1[0], fast_silu(a1[1]) * b1[1]); w.w = pk_bf16(fast_silu(a1[2]) * b1[2], fast_silu(a1[3]) * b1[3]);
;                 *(u32x4*)(G + (size_t)row * DFF + col) = w;
	v_fmamk_f32 v147, v147, 0x3a800000, v159
	v_mul_f32_e32 v162, 0x4b800000, v147
	v_cmp_gt_f32_e32 vcc, s51, v147
	v_fmamk_f32 v152, v152, 0x3a800000, v159
	v_fmamk_f32 v154, v154, 0x3a800000, v159
	v_cndmask_b32_e32 v147, v147, v162, vcc
	v_mul_f32_e32 v165, 0x4b800000, v152
	v_fmamk_f32 v161, v161, 0x3a800000, v159
	v_mul_f32_e32 v166, 0x4b800000, v154
	v_mul_f32_e32 v169, 0x4b800000, v161
	v_cmp_gt_f32_e64 s[10:11], s51, v152
	v_cmp_gt_f32_e64 s[12:13], s51, v154
	v_cmp_gt_f32_e64 s[18:19], s51, v161
	v_rsq_f32_e32 v147, v147
	v_fmamk_f32 v156, v156, 0x3a800000, v159
	v_cndmask_b32_e64 v152, v152, v165, s[10:11]
	v_cndmask_b32_e64 v154, v154, v166, s[12:13]
	v_cndmask_b32_e64 v161, v161, v169, s[18:19]
	v_fmamk_f32 v148, v148, 0x3a800000, v159
	v_fmamk_f32 v160, v160, 0x3a800000, v159
	v_mul_f32_e32 v167, 0x4b800000, v156
	v_cmp_gt_f32_e64 s[14:15], s51, v156
	v_rsq_f32_e32 v152, v152
	v_rsq_f32_e32 v154, v154
	v_rsq_f32_e32 v161, v161
	v_mul_f32_e32 v163, 0x4b800000, v148
	v_mul_f32_e32 v168, 0x4b800000, v160
	v_cmp_gt_f32_e64 s[4:5], s51, v148
	v_cndmask_b32_e64 v156, v156, v167, s[14:15]
	v_cmp_gt_f32_e64 s[16:17], s51, v160
	v_fmamk_f32 v150, v150, 0x3a800000, v159
	v_cndmask_b32_e64 v148, v148, v163, s[4:5]
	v_cndmask_b32_e64 v160, v160, v168, s[16:17]
	v_rsq_f32_e32 v163, v156
	v_mul_f32_e32 v156, 0x45800000, v147
	v_mul_f32_e32 v164, 0x4b800000, v150
	v_cmp_gt_f32_e64 s[8:9], s51, v150
	v_rsq_f32_e32 v165, v160
	v_cndmask_b32_e32 v160, v147, v156, vcc
	v_cndmask_b32_e64 v150, v150, v164, s[8:9]
	v_rsq_f32_e32 v148, v148
	v_mul_f32_e32 v166, 0x45800000, v152
	v_mul_f32_e32 v167, 0x45800000, v154
	v_pk_mul_f32 v[126:127], v[126:127], v[160:161] op_sel_hi:[1,0]
	v_pk_mul_f32 v[124:125], v[124:125], v[160:161] op_sel_hi:[1,0]
	v_rsq_f32_e32 v150, v150
	v_cndmask_b32_e64 v156, v152, v166, s[10:11]
	v_cndmask_b32_e64 v154, v154, v167, s[12:13]
	v_pk_mul_f32 v[122:123], v[122:123], v[160:161] op_sel_hi:[1,0]
	v_pk_mul_f32 v[120:121], v[120:121], v[160:161] op_sel_hi:[1,0]
	v_pk_mul_f32 v[118:119], v[118:119], v[160:161] op_sel_hi:[1,0]
	v_pk_mul_f32 v[116:117], v[116:117], v[160:161] op_sel_hi:[1,0]
	v_pk_mul_f32 v[166:167], v[114:115], v[160:161] op_sel_hi:[1,0]
	v_pk_mul_f32 v[114:115], v[112:113], v[160:161] op_sel_hi:[1,0]
	v_mul_f32_e32 v112, 0xbfb8aa3b, v124
	v_mul_f32_e32 v113, 0xbfb8aa3b, v125
	v_mul_f32_e32 v147, 0xbfb8aa3b, v126
	v_mul_f32_e32 v160, 0xbfb8aa3b, v127
	v_exp_f32_e32 v112, v112
	v_exp_f32_e32 v113, v113
	v_exp_f32_e32 v147, v147
	v_exp_f32_e32 v160, v160
	v_mul_f32_e32 v162, 0x45800000, v148
	v_mul_f32_e32 v170, 0x45800000, v161
	v_mul_f32_e32 v164, 0x45800000, v150
	v_mul_f32_e32 v169, 0x45800000, v165
	v_cndmask_b32_e64 v162, v148, v162, s[4:5]
	v_cndmask_b32_e64 v148, v161, v170, s[18:19]
	v_mul_f32_e32 v161, 0xbfb8aa3b, v120
	v_cndmask_b32_e64 v164, v150, v164, s[8:9]
	v_cndmask_b32_e64 v150, v165, v169, s[16:17]
	v_exp_f32_e32 v165, v161
	v_add_f32_e32 v112, 1.0, v112
	v_add_f32_e32 v113, 1.0, v113
	v_add_f32_e32 v147, 1.0, v147
	v_add_f32_e32 v161, 1.0, v160
	v_rcp_f32_e32 v112, v112
	v_rcp_f32_e32 v113, v113
	v_rcp_f32_e32 v160, v147
	v_rcp_f32_e32 v161, v161
	v_mul_f32_e32 v168, 0x45800000, v163
	v_pk_mul_f32 v[112:113], v[124:125], v[112:113]
	v_cndmask_b32_e64 v152, v163, v168, s[14:15]
	v_pk_mul_f32 v[124:125], v[126:127], v[160:161]
	v_mul_f32_e32 v163, 0xbfb8aa3b, v121
	v_pk_mul_f32 v[112:113], v[116:117], v[112:113]
	v_pk_mul_f32 v[116:117], v[118:119], v[124:125]
	v_exp_f32_e32 v163, v163
	v_cvt_pk_bf16_f32 v112, v112, v113
	v_cvt_pk_bf16_f32 v113, v116, v117
	v_mul_f32_e32 v117, 0xbfb8aa3b, v122
	v_mul_f32_e32 v118, 0xbfb8aa3b, v123
	v_exp_f32_e32 v117, v117
	v_exp_f32_e32 v118, v118
	v_add_f32_e32 v116, 1.0, v163
	v_add_f32_e32 v147, 1.0, v165
	v_rcp_f32_e32 v169, v116
	v_add_f32_e32 v116, 1.0, v117
	v_add_f32_e32 v117, 1.0, v118
	v_rcp_f32_e32 v168, v147
	v_rcp_f32_e32 v116, v116
	v_rcp_f32_e32 v117, v117
	v_pk_mul_f32 v[108:109], v[108:109], v[162:163] op_sel_hi:[1,0]
	v_pk_mul_f32 v[118:119], v[120:121], v[168:169]
	v_pk_mul_f32 v[110:111], v[110:111], v[162:163] op_sel_hi:[1,0]
	v_pk_mul_f32 v[116:117], v[122:123], v[116:117]
	v_pk_mul_f32 v[114:115], v[114:115], v[118:119]
	v_pk_mul_f32 v[116:117], v[166:167], v[116:117]
	v_cvt_pk_bf16_f32 v114, v114, v115
	v_cvt_pk_bf16_f32 v115, v116, v117
	v_mad_i64_i32 v[116:117], s[4:5], v146, s52, v[144:145]
	global_store_dwordx4 v[116:117], v[112:115], off
	v_pk_mul_f32 v[100:101], v[100:101], v[162:163] op_sel_hi:[1,0]
	v_pk_mul_f32 v[104:105], v[104:105], v[162:163] op_sel_hi:[1,0]
	v_pk_mul_f32 v[112:113], v[98:99], v[162:163] op_sel_hi:[1,0]
	v_mul_f32_e32 v98, 0xbfb8aa3b, v108
	v_exp_f32_e32 v114, v98
	v_mul_f32_e32 v98, 0xbfb8aa3b, v109
	v_exp_f32_e32 v115, v98
	v_pk_mul_f32 v[98:99], v[96:97], v[162:163] op_sel_hi:[1,0]
	v_add_f32_e32 v96, 1.0, v114
	v_mul_f32_e32 v114, 0xbfb8aa3b, v110
	v_add_f32_e32 v97, 1.0, v115
	v_mul_f32_e32 v115, 0xbfb8aa3b, v111
	v_exp_f32_e32 v114, v114
	v_exp_f32_e32 v115, v115
	v_rcp_f32_e32 v96, v96
	v_rcp_f32_e32 v97, v97
	v_add_f32_e32 v114, 1.0, v114
	v_add_f32_e32 v115, 1.0, v115
	v_rcp_f32_e32 v114, v114
	v_rcp_f32_e32 v115, v115
	v_pk_mul_f32 v[96:97], v[108:109], v[96:97]
	v_pk_mul_f32 v[102:103], v[102:103], v[162:163] op_sel_hi:[1,0]
	v_pk_mul_f32 v[96:97], v[100:101], v[96:97]
	v_pk_mul_f32 v[100:101], v[110:111], v[114:115]
	v_cvt_pk_bf16_f32 v96, v96, v97
	v_mul_f32_e32 v97, 0xbfb8aa3b, v104
	v_pk_mul_f32 v[100:101], v[102:103], v[100:101]
	v_exp_f32_e32 v102, v97
	v_mul_f32_e32 v97, 0xbfb8aa3b, v105
	v_exp_f32_e32 v103, v97
	v_pk_mul_f32 v[106:107], v[106:107], v[162:163] op_sel_hi:[1,0]
; DI unsigned pk_bf16(float lo, float hi) { f32x2 v = {lo, hi}; return __builtin_bit_cast(unsigned, __builtin_convertvector(v, bf16v2)); }
; DI float fast_silu(float x) { return x * fast_sigmoid(x); }
;     DI void operator()(AccRef acc, const Unit& u, int wr, int wc, int fr, int fq) const {
;     ...
; #pragma unroll
;         for (int ai = 0; ai < 2; ++ai)
; #pragma unroll
;             for (int m = 0; m < 4; ++m) {
;                 const int row = row0 + ai * 128 + m * 16;
;                 const float r = RS ? rsc.r[ai][m] : 1.0f;
;                 const f32x4 a0 = acc[ai][0][m][0] * r, a1 = acc[ai][0][m][1] * r, b0 = acc[ai][1][m][0] * r, b1 = acc[ai][1][m][1] * r;
;                 u32x4 w;
;                 w.x = pk_bf16(fast_silu(a0[0]) * b0[0], fast_silu(a0[1]) * b0[1]); w.y = pk_bf16(fast_silu(a0[2]) * b0[2], fast_silu(a0[3]) * b0[3]);
;                 w.z = pk_bf16(fast_silu(a1[0]) * b1[0], fast_silu(a1[1]) * b1[1]); w.w = pk_bf16(fast_silu(a1[2]) * b1[2], fast_silu(a1[3]) * b1[3]);
;                 *(u32x4*)(G + (size_t)row * DFF + col) = w;
	v_cvt_pk_bf16_f32 v97, v100, v101
	v_add_f32_e32 v100, 1.0, v102
	v_add_f32_e32 v101, 1.0, v103
	v_mul_f32_e32 v102, 0xbfb8aa3b, v106
	v_mul_f32_e32 v103, 0xbfb8aa3b, v107
	v_exp_f32_e32 v102, v102
	v_exp_f32_e32 v103, v103
	v_rcp_f32_e32 v100, v100
	v_rcp_f32_e32 v101, v101
	v_add_f32_e32 v102, 1.0, v102
	v_add_f32_e32 v103, 1.0, v103
	v_rcp_f32_e32 v102, v102
	v_rcp_f32_e32 v103, v103
	v_pk_mul_f32 v[100:101], v[104:105], v[100:101]
	v_or_b32_e32 v116, 16, v146
	v_pk_mul_f32 v[98:99], v[98:99], v[100:101]
	v_pk_mul_f32 v[100:101], v[106:107], v[102:103]
	v_cvt_pk_bf16_f32 v98, v98, v99
	v_pk_mul_f32 v[100:101], v[112:113], v[100:101]
	v_pk_mul_f32 v[92:93], v[92:93], v[164:165] op_sel_hi:[1,0]
	v_cvt_pk_bf16_f32 v99, v100, v101
	v_mad_i64_i32 v[100:101], s[4:5], v116, s52, v[144:145]
	global_store_dwordx4 v[100:101], v[96:99], off
	v_pk_mul_f32 v[94:95], v[94:95], v[164:165] op_sel_hi:[1,0]
	v_pk_mul_f32 v[84:85], v[84:85], v[164:165] op_sel_hi:[1,0]
	v_pk_mul_f32 v[96:97], v[82:83], v[164:165] op_sel_hi:[1,0]
	v_mul_f32_e32 v82, 0xbfb8aa3b, v92
	v_exp_f32_e32 v98, v82
	v_mul_f32_e32 v82, 0xbfb8aa3b, v93
	v_exp_f32_e32 v99, v82
	v_pk_mul_f32 v[82:83], v[80:81], v[164:165] op_sel_hi:[1,0]
	v_add_f32_e32 v80, 1.0, v98
	v_mul_f32_e32 v98, 0xbfb8aa3b, v94
	v_add_f32_e32 v81, 1.0, v99
	v_mul_f32_e32 v99, 0xbfb8aa3b, v95
	v_exp_f32_e32 v98, v98
	v_exp_f32_e32 v99, v99
	v_rcp_f32_e32 v80, v80
	v_rcp_f32_e32 v81, v81
	v_add_f32_e32 v98, 1.0, v98
	v_add_f32_e32 v99, 1.0, v99
	v_rcp_f32_e32 v98, v98
	v_rcp_f32_e32 v99, v99
	v_pk_mul_f32 v[80:81], v[92:93], v[80:81]
	v_pk_mul_f32 v[88:89], v[88:89], v[164:165] op_sel_hi:[1,0]
	v_pk_mul_f32 v[80:81], v[84:85], v[80:81]
	v_pk_mul_f32 v[86:87], v[86:87], v[164:165] op_sel_hi:[1,0]
	v_cvt_pk_bf16_f32 v80, v80, v81
	v_pk_mul_f32 v[84:85], v[94:95], v[98:99]
	v_mul_f32_e32 v81, 0xbfb8aa3b, v88
	v_pk_mul_f32 v[84:85], v[86:87], v[84:85]
	v_exp_f32_e32 v86, v81
	v_mul_f32_e32 v81, 0xbfb8aa3b, v89
	v_exp_f32_e32 v87, v81
	v_pk_mul_f32 v[90:91], v[90:91], v[164:165] op_sel_hi:[1,0]
	v_cvt_pk_bf16_f32 v81, v84, v85
	v_add_f32_e32 v84, 1.0, v86
	v_add_f32_e32 v85, 1.0, v87
	v_mul_f32_e32 v86, 0xbfb8aa3b, v90
	v_mul_f32_e32 v87, 0xbfb8aa3b, v91
	v_exp_f32_e32 v86, v86
	v_exp_f32_e32 v87, v87
	v_rcp_f32_e32 v84, v84
	v_rcp_f32_e32 v85, v85
	v_add_f32_e32 v86, 1.0, v86
	v_add_f32_e32 v87, 1.0, v87
	v_rcp_f32_e32 v86, v86
	v_rcp_f32_e32 v87, v87
	v_pk_mul_f32 v[84:85], v[88:89], v[84:85]
	v_or_b32_e32 v100, 32, v146
	v_pk_mul_f32 v[82:83], v[82:83], v[84:85]
	v_pk_mul_f32 v[84:85], v[90:91], v[86:87]
	v_cvt_pk_bf16_f32 v82, v82, v83
	v_pk_mul_f32 v[84:85], v[96:97], v[84:85]
	v_pk_mul_f32 v[76:77], v[76:77], v[156:157] op_sel_hi:[1,0]
	v_cvt_pk_bf16_f32 v83, v84, v85
	v_mad_i64_i32 v[84:85], s[4:5], v100, s52, v[144:145]
	global_store_dwordx4 v[84:85], v[80:83], off
	v_pk_mul_f32 v[78:79], v[78:79], v[156:157] op_sel_hi:[1,0]
	v_pk_mul_f32 v[68:69], v[68:69], v[156:157] op_sel_hi:[1,0]
	v_pk_mul_f32 v[80:81], v[66:67], v[156:157] op_sel_hi:[1,0]
	v_mul_f32_e32 v66, 0xbfb8aa3b, v76
	v_exp_f32_e32 v82, v66
	v_mul_f32_e32 v66, 0xbfb8aa3b, v77
	v_exp_f32_e32 v83, v66
	v_pk_mul_f32 v[66:67], v[64:65], v[156:157] op_sel_hi:[1,0]
	v_add_f32_e32 v64, 1.0, v82
	v_mul_f32_e32 v82, 0xbfb8aa3b, v78
	v_add_f32_e32 v65, 1.0, v83
	v_mul_f32_e32 v83, 0xbfb8aa3b, v79
	v_exp_f32_e32 v82, v82
	v_exp_f32_e32 v83, v83
	v_rcp_f32_e32 v64, v64
	v_rcp_f32_e32 v65, v65
	v_add_f32_e32 v82, 1.0, v82
	v_add_f32_e32 v83, 1.0, v83
	v_rcp_f32_e32 v82, v82
	v_rcp_f32_e32 v83, v83
	v_pk_mul_f32 v[64:65], v[76:77], v[64:65]
	v_pk_mul_f32 v[72:73], v[72:73], v[156:157] op_sel_hi:[1,0]
	v_pk_mul_f32 v[64:65], v[68:69], v[64:65]
	v_pk_mul_f32 v[70:71], v[70:71], v[156:157] op_sel_hi:[1,0]
	v_cvt_pk_bf16_f32 v64, v64, v65
	v_pk_mul_f32 v[68:69], v[78:79], v[82:83]
	v_mul_f32_e32 v65, 0xbfb8aa3b, v72
	v_pk_mul_f32 v[68:69], v[70:71], v[68:69]
	v_exp_f32_e32 v70, v65
	v_mul_f32_e32 v65, 0xbfb8aa3b, v73
	v_exp_f32_e32 v71, v65
	v_pk_mul_f32 v[74:75], v[74:75], v[156:157] op_sel_hi:[1,0]
	v_cvt_pk_bf16_f32 v65, v68, v69
	v_add_f32_e32 v68, 1.0, v70
	v_add_f32_e32 v69, 1.0, v71
	v_mul_f32_e32 v70, 0xbfb8aa3b, v74
	v_mul_f32_e32 v71, 0xbfb8aa3b, v75
	v_exp_f32_e32 v70, v70
	v_exp_f32_e32 v71, v71
	v_rcp_f32_e32 v68, v68
	v_rcp_f32_e32 v69, v69
	v_add_f32_e32 v70, 1.0, v70
	v_add_f32_e32 v71, 1.0, v71
	v_rcp_f32_e32 v70, v70
	v_rcp_f32_e32 v71, v71
	v_pk_mul_f32 v[68:69], v[72:73], v[68:69]
	v_or_b32_e32 v84, 48, v146
	v_pk_mul_f32 v[66:67], v[66:67], v[68:69]
	v_pk_mul_f32 v[68:69], v[74:75], v[70:71]
	v_cvt_pk_bf16_f32 v66, v66, v67
	v_pk_mul_f32 v[68:69], v[80:81], v[68:69]
	v_pk_mul_f32 v[60:61], v[60:61], v[154:155] op_sel_hi:[1,0]
	v_cvt_pk_bf16_f32 v67, v68, v69
	v_mad_i64_i32 v[68:69], s[4:5], v84, s52, v[144:145]
	global_store_dwordx4 v[68:69], v[64:67], off
	v_pk_mul_f32 v[62:63], v[62:63], v[154:155] op_sel_hi:[1,0]
	v_pk_mul_f32 v[52:53], v[52:53], v[154:155] op_sel_hi:[1,0]
	v_pk_mul_f32 v[64:65], v[50:51], v[154:155] op_sel_hi:[1,0]
	v_mul_f32_e32 v50, 0xbfb8aa3b, v60
	v_exp_f32_e32 v66, v50
	v_mul_f32_e32 v50, 0xbfb8aa3b, v61
	v_exp_f32_e32 v67, v50
	v_pk_mul_f32 v[50:51], v[48:49], v[154:155] op_sel_hi:[1,0]
	v_add_f32_e32 v48, 1.0, v66
	v_mul_f32_e32 v66, 0xbfb8aa3b, v62
	v_add_f32_e32 v49, 1.0, v67
	v_mul_f32_e32 v67, 0xbfb8aa3b, v63
	v_exp_f32_e32 v66, v66
	v_exp_f32_e32 v67, v67
	v_rcp_f32_e32 v48, v48
	v_rcp_f32_e32 v49, v49
	v_add_f32_e32 v66, 1.0, v66
	v_add_f32_e32 v67, 1.0, v67
	v_rcp_f32_e32 v66, v66
	v_rcp_f32_e32 v67, v67
	v_pk_mul_f32 v[48:49], v[60:61], v[48:49]
	v_pk_mul_f32 v[56:57], v[56:57], v[154:155] op_sel_hi:[1,0]
; DI unsigned pk_bf16(float lo, float hi) { f32x2 v = {lo, hi}; return __builtin_bit_cast(unsigned, __builtin_convertvector(v, bf16v2)); }
; DI float fast_silu(float x) { return x * fast_sigmoid(x); }
;     DI void operator()(AccRef acc, const Unit& u, int wr, int wc, int fr, int fq) const {
;     ...
; #pragma unroll
;         for (int ai = 0; ai < 2; ++ai)
; #pragma unroll
;             for (int m = 0; m < 4; ++m) {
;                 const int row = row0 + ai * 128 + m * 16;
;                 const float r = RS ? rsc.r[ai][m] : 1.0f;
;                 const f32x4 a0 = acc[ai][0][m][0] * r, a1 = acc[ai][0][m][1] * r, b0 = acc[ai][1][m][0] * r, b1 = acc[ai][1][m][1] * r;
;                 u32x4 w;
;                 w.x = pk_bf16(fast_silu(a0[0]) * b0[0], fast_silu(a0[1]) * b0[1]); w.y = pk_bf16(fast_silu(a0[2]) * b0[2], fast_silu(a0[3]) * b0[3]);
;                 w.z = pk_bf16(fast_silu(a1[0]) * b1[0], fast_silu(a1[1]) * b1[1]); w.w = pk_bf16(fast_silu(a1[2]) * b1[2], fast_silu(a1[3]) * b1[3]);
;                 *(u32x4*)(G + (size_t)row * DFF + col) = w;
	v_pk_mul_f32 v[48:49], v[52:53], v[48:49]
	v_pk_mul_f32 v[54:55], v[54:55], v[154:155] op_sel_hi:[1,0]
	v_cvt_pk_bf16_f32 v48, v48, v49
	v_pk_mul_f32 v[52:53], v[62:63], v[66:67]
	v_mul_f32_e32 v49, 0xbfb8aa3b, v56
	v_pk_mul_f32 v[52:53], v[54:55], v[52:53]
	v_exp_f32_e32 v54, v49
	v_mul_f32_e32 v49, 0xbfb8aa3b, v57
	v_exp_f32_e32 v55, v49
	v_pk_mul_f32 v[58:59], v[58:59], v[154:155] op_sel_hi:[1,0]
	v_cvt_pk_bf16_f32 v49, v52, v53
	v_add_f32_e32 v52, 1.0, v54
	v_add_f32_e32 v53, 1.0, v55
	v_mul_f32_e32 v54, 0xbfb8aa3b, v58
	v_mul_f32_e32 v55, 0xbfb8aa3b, v59
	v_exp_f32_e32 v54, v54
	v_exp_f32_e32 v55, v55
	v_rcp_f32_e32 v52, v52
	v_rcp_f32_e32 v53, v53
	v_add_f32_e32 v54, 1.0, v54
	v_add_f32_e32 v55, 1.0, v55
	v_rcp_f32_e32 v54, v54
	v_rcp_f32_e32 v55, v55
	v_pk_mul_f32 v[52:53], v[56:57], v[52:53]
	v_add_u32_e32 v68, 0x80, v146
	v_pk_mul_f32 v[50:51], v[50:51], v[52:53]
	v_pk_mul_f32 v[52:53], v[58:59], v[54:55]
	v_cvt_pk_bf16_f32 v50, v50, v51
	v_pk_mul_f32 v[52:53], v[64:65], v[52:53]
	v_pk_mul_f32 v[44:45], v[44:45], v[152:153] op_sel_hi:[1,0]
	v_cvt_pk_bf16_f32 v51, v52, v53
	v_mad_i64_i32 v[52:53], s[4:5], v68, s52, v[144:145]
	global_store_dwordx4 v[52:53], v[48:51], off
	v_pk_mul_f32 v[46:47], v[46:47], v[152:153] op_sel_hi:[1,0]
	v_pk_mul_f32 v[36:37], v[36:37], v[152:153] op_sel_hi:[1,0]
	v_pk_mul_f32 v[48:49], v[34:35], v[152:153] op_sel_hi:[1,0]
	v_mul_f32_e32 v34, 0xbfb8aa3b, v44
	v_exp_f32_e32 v50, v34
	v_mul_f32_e32 v34, 0xbfb8aa3b, v45
	v_exp_f32_e32 v51, v34
	v_pk_mul_f32 v[34:35], v[32:33], v[152:153] op_sel_hi:[1,0]
	v_add_f32_e32 v32, 1.0, v50
	v_mul_f32_e32 v50, 0xbfb8aa3b, v46
	v_add_f32_e32 v33, 1.0, v51
	v_mul_f32_e32 v51, 0xbfb8aa3b, v47
	v_exp_f32_e32 v50, v50
	v_exp_f32_e32 v51, v51
	v_rcp_f32_e32 v32, v32
	v_rcp_f32_e32 v33, v33
	v_add_f32_e32 v50, 1.0, v50
	v_add_f32_e32 v51, 1.0, v51
	v_rcp_f32_e32 v50, v50
	v_rcp_f32_e32 v51, v51
	v_pk_mul_f32 v[32:33], v[44:45], v[32:33]
	v_pk_mul_f32 v[40:41], v[40:41], v[152:153] op_sel_hi:[1,0]
	v_pk_mul_f32 v[32:33], v[36:37], v[32:33]
	v_pk_mul_f32 v[38:39], v[38:39], v[152:153] op_sel_hi:[1,0]
	v_cvt_pk_bf16_f32 v32, v32, v33
	v_pk_mul_f32 v[36:37], v[46:47], v[50:51]
	v_mul_f32_e32 v33, 0xbfb8aa3b, v40
	v_pk_mul_f32 v[36:37], v[38:39], v[36:37]
	v_exp_f32_e32 v38, v33
	v_mul_f32_e32 v33, 0xbfb8aa3b, v41
	v_exp_f32_e32 v39, v33
	v_pk_mul_f32 v[42:43], v[42:43], v[152:153] op_sel_hi:[1,0]
	v_cvt_pk_bf16_f32 v33, v36, v37
	v_add_f32_e32 v36, 1.0, v38
	v_add_f32_e32 v37, 1.0, v39
	v_mul_f32_e32 v38, 0xbfb8aa3b, v42
	v_mul_f32_e32 v39, 0xbfb8aa3b, v43
	v_exp_f32_e32 v38, v38
	v_exp_f32_e32 v39, v39
	v_rcp_f32_e32 v36, v36
	v_rcp_f32_e32 v37, v37
	v_add_f32_e32 v38, 1.0, v38
	v_add_f32_e32 v39, 1.0, v39
	v_rcp_f32_e32 v38, v38
	v_rcp_f32_e32 v39, v39
	v_pk_mul_f32 v[36:37], v[40:41], v[36:37]
	v_add_u32_e32 v52, 0x90, v146
	v_pk_mul_f32 v[34:35], v[34:35], v[36:37]
	v_pk_mul_f32 v[36:37], v[42:43], v[38:39]
	v_cvt_pk_bf16_f32 v34, v34, v35
	v_pk_mul_f32 v[36:37], v[48:49], v[36:37]
	v_pk_mul_f32 v[28:29], v[28:29], v[150:151] op_sel_hi:[1,0]
	v_cvt_pk_bf16_f32 v35, v36, v37
	v_mad_i64_i32 v[36:37], s[4:5], v52, s52, v[144:145]
	global_store_dwordx4 v[36:37], v[32:35], off
	v_pk_mul_f32 v[30:31], v[30:31], v[150:151] op_sel_hi:[1,0]
	v_pk_mul_f32 v[20:21], v[20:21], v[150:151] op_sel_hi:[1,0]
	v_pk_mul_f32 v[32:33], v[18:19], v[150:151] op_sel_hi:[1,0]
	v_mul_f32_e32 v18, 0xbfb8aa3b, v28
	v_exp_f32_e32 v34, v18
	v_mul_f32_e32 v18, 0xbfb8aa3b, v29
	v_exp_f32_e32 v35, v18
	v_pk_mul_f32 v[18:19], v[16:17], v[150:151] op_sel_hi:[1,0]
	v_add_f32_e32 v16, 1.0, v34
	v_mul_f32_e32 v34, 0xbfb8aa3b, v30
; DI unsigned pk_bf16(float lo, float hi) { f32x2 v = {lo, hi}; return __builtin_bit_cast(unsigned, __builtin_convertvector(v, bf16v2)); }
; DI float fast_silu(float x) { return x * fast_sigmoid(x); }
; #define PG8_WAIT_V(n) asm volatile("s_waitcnt vmcnt(" #n ")" ::: "memory")
; #define PG8_BAR __builtin_amdgcn_s_barrier()
; #define PG8_WAIT_V(n) asm volatile("s_waitcnt vmcnt(" #n ")" ::: "memory")
; #define PG8_BAR __builtin_amdgcn_s_barrier()
; template <class Epi>
; DI void gemm_phase(LAS unsigned char* lds, const Gemm g, const StaticOrder S, const Epi E) {
;     ...
;         if (!has_next) break;
; #pragma unroll
;         for (int a = 0; a < 2; ++a)
; #pragma unroll
;             for (int b = 0; b < 2; ++b)
; #pragma unroll
;                 for (int m = 0; m < 4; ++m)
; #pragma unroll
;                     for (int n = 0; n < 2; ++n) acc[a][b][m][n] = (f32x4){0.f, 0.f, 0.f, 0.f};
;         cur = nxt; cA = nA; cB = nB; ++ui;
;     }
;     PG8_WAIT_V(0);
;     if (wr == 0) PG8_BAR;
;     PG8_BAR;
;     DI void operator()(AccRef acc, const Unit& u, int wr, int wc, int fr, int fq) const {
;     ...
; #pragma unroll
;         for (int ai = 0; ai < 2; ++ai)
; #pragma unroll
;             for (int m = 0; m < 4; ++m) {
;                 const int row = row0 + ai * 128 + m * 16;
;                 const float r = RS ? rsc.r[ai][m] : 1.0f;
;                 const f32x4 a0 = acc[ai][0][m][0] * r, a1 = acc[ai][0][m][1] * r, b0 = acc[ai][1][m][0] * r, b1 = acc[ai][1][m][1] * r;
;                 u32x4 w;
;                 w.x = pk_bf16(fast_silu(a0[0]) * b0[0], fast_silu(a0[1]) * b0[1]); w.y = pk_bf16(fast_silu(a0[2]) * b0[2], fast_silu(a0[3]) * b0[3]);
;                 w.z = pk_bf16(fast_silu(a1[0]) * b1[0], fast_silu(a1[1]) * b1[1]); w.w = pk_bf16(fast_silu(a1[2]) * b1[2], fast_silu(a1[3]) * b1[3]);
;                 *(u32x4*)(G + (size_t)row * DFF + col) = w;
	v_add_f32_e32 v17, 1.0, v35
	v_mul_f32_e32 v35, 0xbfb8aa3b, v31
	v_exp_f32_e32 v34, v34
	v_exp_f32_e32 v35, v35
	v_rcp_f32_e32 v16, v16
	v_rcp_f32_e32 v17, v17
	v_add_f32_e32 v34, 1.0, v34
	v_add_f32_e32 v35, 1.0, v35
	v_rcp_f32_e32 v34, v34
	v_rcp_f32_e32 v35, v35
	v_pk_mul_f32 v[16:17], v[28:29], v[16:17]
	v_pk_mul_f32 v[24:25], v[24:25], v[150:151] op_sel_hi:[1,0]
	v_pk_mul_f32 v[16:17], v[20:21], v[16:17]
	v_pk_mul_f32 v[22:23], v[22:23], v[150:151] op_sel_hi:[1,0]
	v_cvt_pk_bf16_f32 v16, v16, v17
	v_pk_mul_f32 v[20:21], v[30:31], v[34:35]
	v_mul_f32_e32 v17, 0xbfb8aa3b, v24
	v_pk_mul_f32 v[20:21], v[22:23], v[20:21]
	v_exp_f32_e32 v22, v17
	v_mul_f32_e32 v17, 0xbfb8aa3b, v25
	v_exp_f32_e32 v23, v17
	v_pk_mul_f32 v[26:27], v[26:27], v[150:151] op_sel_hi:[1,0]
	v_cvt_pk_bf16_f32 v17, v20, v21
	v_add_f32_e32 v20, 1.0, v22
	v_add_f32_e32 v21, 1.0, v23
	v_mul_f32_e32 v22, 0xbfb8aa3b, v26
	v_mul_f32_e32 v23, 0xbfb8aa3b, v27
	v_exp_f32_e32 v22, v22
	v_exp_f32_e32 v23, v23
	v_rcp_f32_e32 v20, v20
	v_rcp_f32_e32 v21, v21
	v_add_f32_e32 v22, 1.0, v22
	v_add_f32_e32 v23, 1.0, v23
	v_rcp_f32_e32 v22, v22
	v_rcp_f32_e32 v23, v23
	v_pk_mul_f32 v[20:21], v[24:25], v[20:21]
	v_add_u32_e32 v36, 0xa0, v146
	v_pk_mul_f32 v[18:19], v[18:19], v[20:21]
	v_pk_mul_f32 v[20:21], v[26:27], v[22:23]
	v_cvt_pk_bf16_f32 v18, v18, v19
	v_pk_mul_f32 v[20:21], v[32:33], v[20:21]
	v_pk_mul_f32 v[12:13], v[12:13], v[148:149] op_sel_hi:[1,0]
	v_cvt_pk_bf16_f32 v19, v20, v21
	v_mad_i64_i32 v[20:21], s[4:5], v36, s52, v[144:145]
	global_store_dwordx4 v[20:21], v[16:19], off
	v_pk_mul_f32 v[14:15], v[14:15], v[148:149] op_sel_hi:[1,0]
	v_pk_mul_f32 v[4:5], v[4:5], v[148:149] op_sel_hi:[1,0]
	v_pk_mul_f32 v[16:17], v[2:3], v[148:149] op_sel_hi:[1,0]
	v_mul_f32_e32 v2, 0xbfb8aa3b, v12
	v_exp_f32_e32 v18, v2
	v_mul_f32_e32 v2, 0xbfb8aa3b, v13
	v_exp_f32_e32 v19, v2
	v_pk_mul_f32 v[2:3], v[0:1], v[148:149] op_sel_hi:[1,0]
	v_add_f32_e32 v0, 1.0, v18
	v_mul_f32_e32 v18, 0xbfb8aa3b, v14
	v_add_f32_e32 v1, 1.0, v19
	v_mul_f32_e32 v19, 0xbfb8aa3b, v15
	v_exp_f32_e32 v18, v18
	v_exp_f32_e32 v19, v19
	v_rcp_f32_e32 v0, v0
	v_rcp_f32_e32 v1, v1
	v_add_f32_e32 v18, 1.0, v18
	v_add_f32_e32 v19, 1.0, v19
	v_rcp_f32_e32 v18, v18
	v_rcp_f32_e32 v19, v19
	v_pk_mul_f32 v[0:1], v[12:13], v[0:1]
	v_pk_mul_f32 v[8:9], v[8:9], v[148:149] op_sel_hi:[1,0]
	v_pk_mul_f32 v[0:1], v[4:5], v[0:1]
	v_pk_mul_f32 v[6:7], v[6:7], v[148:149] op_sel_hi:[1,0]
	v_cvt_pk_bf16_f32 v0, v0, v1
	v_pk_mul_f32 v[4:5], v[14:15], v[18:19]
	v_mul_f32_e32 v1, 0xbfb8aa3b, v8
	v_pk_mul_f32 v[4:5], v[6:7], v[4:5]
	v_exp_f32_e32 v6, v1
	v_mul_f32_e32 v1, 0xbfb8aa3b, v9
	v_exp_f32_e32 v7, v1
	v_pk_mul_f32 v[10:11], v[10:11], v[148:149] op_sel_hi:[1,0]
	v_cvt_pk_bf16_f32 v1, v4, v5
	v_add_f32_e32 v4, 1.0, v6
	v_add_f32_e32 v5, 1.0, v7
	v_mul_f32_e32 v6, 0xbfb8aa3b, v10
	v_mul_f32_e32 v7, 0xbfb8aa3b, v11
	v_exp_f32_e32 v6, v6
	v_exp_f32_e32 v7, v7
	v_rcp_f32_e32 v4, v4
	v_rcp_f32_e32 v5, v5
	v_add_f32_e32 v6, 1.0, v6
	v_add_f32_e32 v7, 1.0, v7
	v_rcp_f32_e32 v6, v6
	v_rcp_f32_e32 v7, v7
	v_pk_mul_f32 v[4:5], v[8:9], v[4:5]
	v_add_u32_e32 v20, 0xb0, v146
	v_pk_mul_f32 v[2:3], v[2:3], v[4:5]
	v_pk_mul_f32 v[4:5], v[10:11], v[6:7]
	v_cvt_pk_bf16_f32 v2, v2, v3
	v_pk_mul_f32 v[4:5], v[16:17], v[4:5]
	s_and_b64 vcc, exec, s[0:1]
	v_cvt_pk_bf16_f32 v3, v4, v5
	v_mad_i64_i32 v[4:5], s[4:5], v20, s52, v[144:145]
	s_mov_b32 s5, s24
	s_mov_b32 s4, s28
	s_mov_b64 s[10:11], s[38:39]
	s_mov_b64 s[8:9], s[36:37]
	global_store_dwordx4 v[4:5], v[0:3], off
	s_cbranch_vccz .LBB0_862
	s_waitcnt vmcnt(0)
	s_cmpk_gt_u32 s6, 0xff
	s_cbranch_scc1 .LBB0_869
	s_barrier

; #define PG8_STAGE(bufoff, gbase, voff) do { _Pragma("unroll") for (int _i = 0; _i < 2; ++_i) \
;         __builtin_amdgcn_global_load_lds((const unsigned*)((const char*)(gbase) + (voff)[_i]), (LAS unsigned*)(lds + (bufoff) + ldsw + _i * 8192), 16, 0, 0); } while (0)
; #define PG8_LDA(dst, b, h) do { _Pragma("unroll") for (int m = 0; m < 4; ++m) _Pragma("unroll") for (int k = 0; k < 2; ++k) dst[m][k] = *(const LAS bf16x8*)(lds + PG8_SA(b, h) + aoff + m * 2048 + k * 1024); } while (0)
; #define PG8_LDB(dst, b, h) do { _Pragma("unroll") for (int n = 0; n < 2; ++n) _Pragma("unroll") for (int k = 0; k < 2; ++k) dst[n][k] = *(const LAS bf16x8*)(lds + PG8_SB(b, h) + boff + n * 2048 + k * 1024); } while (0)
; #define PG8_MMA(ai, bj, At, Bt) do { __builtin_amdgcn_s_setprio(1); _Pragma("unroll") for (int m = 0; m < 4; ++m) _Pragma("unroll") for (int n = 0; n < 2; ++n) _Pragma("unroll") for (int k = 0; k < 2; ++k) \
;         acc[ai][bj][m][n] = __builtin_amdgcn_mfma_f32_16x16x32_bf16(Bt[n][k], At[m][k], acc[ai][bj][m][n], 0, 0, 0); __builtin_amdgcn_s_setprio(0); } while (0)
; template <class Epi>
; DI void gemm_phase(LAS unsigned char* lds, const Gemm g, const StaticOrder S, const Epi E) {
;     ...
;         for (int t = 0; t < nt; t += 2) {
;             const bool last = (t == nt - 2);
;             const char* a1 = cA + (size_t)(t + 1) * kstep;
;             const char* a2 = last ? nA : cA + (size_t)(t + 2) * kstep; const char* b2 = last ? nB : cB + (size_t)(t + 2) * kstep;
;             const char* a3 = a2 + kstep; const char* b3 = b2 + kstep;
;             PG8_LDB(B0, 0, 0); PG8_SCHED; PG8_LDA(At, 0, 0); PG8_STAGE(PG8_SA(1, 1), a1 + hstep, voffA);
;             PG8_WAIT_L(8); PG8_BAR; PG8_WAIT_L(0); PG8_MMA(0, 0, At, B0); PG8_BAR; PG8_SCHED;
;             PG8_LDB(B1, 0, 1); PG8_STAGE(PG8_SB(0, 0), b2, voffB);
;             PG8_BAR; PG8_WAIT_L(0); PG8_MMA(0, 1, At, B1); PG8_BAR;
;             PG8_LDA(At, 0, 1); PG8_STAGE(PG8_SA(0, 0), a2, voffA);
;             PG8_BAR; PG8_WAIT_L(0); PG8_MMA(1, 0, At, B0); PG8_BAR; PG8_SCHED;
;             PG8_STAGE(PG8_SB(0, 1), b2 + hstep, voffB);
;             PG8_WAIT_V(6); PG8_BAR; PG8_MMA(1, 1, At, B1); PG8_BAR;
;             PG8_LDB(B0, 1, 0); PG8_SCHED; PG8_LDA(At, 1, 0); PG8_STAGE(PG8_SA(0, 1), a2 + hstep, voffA);
;             PG8_WAIT_L(8); PG8_BAR; PG8_WAIT_L(0); PG8_MMA(0, 0, At, B0); PG8_BAR; PG8_SCHED;
.LBB0_941:
	ds_read_b128 v[144:147], v199
	ds_read_b128 v[148:151], v199 offset:1024
	ds_read_b128 v[152:155], v199 offset:2048
	ds_read_b128 v[156:159], v199 offset:3072
	s_add_u32 s22, s20, 0x100
	s_addc_u32 s23, s21, 0
	s_cmp_eq_u32 s58, 40
	s_cselect_b32 s27, s9, s23
	s_cselect_b32 s26, s8, s22
	s_cselect_b32 s25, s5, s53
	s_cselect_b32 s24, s4, s52
	v_lshl_add_u64 v[192:193], s[20:21], 0, v[136:137]
	s_add_i32 m0, s33, 0xc000
	ds_read_b128 v[160:163], v200
	ds_read_b128 v[168:171], v200 offset:2048
	ds_read_b128 v[176:179], v200 offset:4096
	ds_read_b128 v[184:187], v200 offset:6144
	global_load_lds_dwordx4 v[192:193], off
	v_lshl_add_u64 v[192:193], s[20:21], 0, v[138:139]
	s_add_i32 m0, s33, 0xe000
	s_nop 0
	global_load_lds_dwordx4 v[192:193], off
	s_waitcnt lgkmcnt(4)
	s_setprio 1
	s_barrier
	s_waitcnt lgkmcnt(0)
	v_mfma_f32_16x16x32_bf16 v[124:127], v[144:147], v[160:163], v[124:127]
	ds_read_b128 v[164:167], v200 offset:1024
	v_mfma_f32_16x16x32_bf16 v[120:123], v[152:155], v[160:163], v[120:123]
	ds_read_b128 v[172:175], v200 offset:3072
	v_mfma_f32_16x16x32_bf16 v[108:111], v[144:147], v[168:171], v[108:111]
	ds_read_b128 v[180:183], v200 offset:5120
	v_mfma_f32_16x16x32_bf16 v[104:107], v[152:155], v[168:171], v[104:107]
	ds_read_b128 v[188:191], v200 offset:7168
	v_mfma_f32_16x16x32_bf16 v[92:95], v[144:147], v[176:179], v[92:95]
	v_mfma_f32_16x16x32_bf16 v[88:91], v[152:155], v[176:179], v[88:91]
	v_mfma_f32_16x16x32_bf16 v[84:87], v[144:147], v[184:187], v[84:87]
	v_mfma_f32_16x16x32_bf16 v[76:79], v[152:155], v[184:187], v[76:79]
	s_waitcnt lgkmcnt(3)
	v_mfma_f32_16x16x32_bf16 v[124:127], v[148:151], v[164:167], v[124:127]
	v_mfma_f32_16x16x32_bf16 v[120:123], v[156:159], v[164:167], v[120:123]
	s_waitcnt lgkmcnt(2)
	v_mfma_f32_16x16x32_bf16 v[108:111], v[148:151], v[172:175], v[108:111]
	v_mfma_f32_16x16x32_bf16 v[104:107], v[156:159], v[172:175], v[104:107]
	s_waitcnt lgkmcnt(1)
	v_mfma_f32_16x16x32_bf16 v[92:95], v[148:151], v[180:183], v[92:95]
	v_mfma_f32_16x16x32_bf16 v[88:91], v[156:159], v[180:183], v[88:91]
	s_waitcnt lgkmcnt(0)
	s_setprio 2
	s_barrier
	v_mfma_f32_16x16x32_bf16 v[84:87], v[148:151], v[188:191], v[84:87]
	v_mfma_f32_16x16x32_bf16 v[76:79], v[156:159], v[188:191], v[76:79]
	s_setprio 0
	s_add_i32 s20, s42, s29
	v_lshl_add_u64 v[214:215], s[24:25], 0, v[130:131]
	s_mov_b32 m0, s20
	ds_read_b128 v[192:195], v201
	ds_read_b128 v[202:205], v201 offset:1024
	ds_read_b128 v[206:209], v201 offset:2048
	ds_read_b128 v[210:213], v201 offset:3072
	global_load_lds_dwordx4 v[214:215], off
	v_lshl_add_u64 v[216:217], s[24:25], 0, v[134:135]
	s_add_i32 m0, s20, 0x2000
	s_nop 0
	global_load_lds_dwordx4 v[216:217], off
	s_setprio 1
	s_barrier
	s_waitcnt lgkmcnt(0)
	v_mfma_f32_16x16x32_bf16 v[116:119], v[192:195], v[160:163], v[116:119]
	v_mfma_f32_16x16x32_bf16 v[112:115], v[206:209], v[160:163], v[112:115]
	v_mfma_f32_16x16x32_bf16 v[100:103], v[192:195], v[168:171], v[100:103]
	v_mfma_f32_16x16x32_bf16 v[96:99], v[206:209], v[168:171], v[96:99]
	v_mfma_f32_16x16x32_bf16 v[80:83], v[192:195], v[176:179], v[80:83]
	v_mfma_f32_16x16x32_bf16 v[72:75], v[206:209], v[176:179], v[72:75]
	v_mfma_f32_16x16x32_bf16 v[68:71], v[192:195], v[184:187], v[68:71]
	v_mfma_f32_16x16x32_bf16 v[64:67], v[206:209], v[184:187], v[64:67]
	v_mfma_f32_16x16x32_bf16 v[116:119], v[202:205], v[164:167], v[116:119]
	v_mfma_f32_16x16x32_bf16 v[112:115], v[210:213], v[164:167], v[112:115]
	v_mfma_f32_16x16x32_bf16 v[100:103], v[202:205], v[172:175], v[100:103]
	v_mfma_f32_16x16x32_bf16 v[96:99], v[210:213], v[172:175], v[96:99]
	v_mfma_f32_16x16x32_bf16 v[80:83], v[202:205], v[180:183], v[80:83]
	v_mfma_f32_16x16x32_bf16 v[72:75], v[210:213], v[180:183], v[72:75]
	s_setprio 2
	s_barrier
	v_mfma_f32_16x16x32_bf16 v[68:71], v[202:205], v[188:191], v[68:71]
	v_mfma_f32_16x16x32_bf16 v[64:67], v[210:213], v[188:191], v[64:67]
	s_setprio 0
	s_mov_b32 m0, s33
	v_lshl_add_u64 v[218:219], s[26:27], 0, v[128:129]
	ds_read_b128 v[160:163], v200 offset:16384
	ds_read_b128 v[168:171], v200 offset:18432
	ds_read_b128 v[176:179], v200 offset:20480
	ds_read_b128 v[184:187], v200 offset:22528
	global_load_lds_dwordx4 v[218:219], off
	v_lshl_add_u64 v[220:221], s[26:27], 0, v[132:133]
	s_mov_b32 m0, s34
	s_nop 0
	global_load_lds_dwordx4 v[220:221], off
	s_setprio 1
	s_barrier
	s_waitcnt lgkmcnt(0)
	v_mfma_f32_16x16x32_bf16 v[60:63], v[144:147], v[160:163], v[60:63]
	ds_read_b128 v[164:167], v200 offset:17408
	v_mfma_f32_16x16x32_bf16 v[56:59], v[152:155], v[160:163], v[56:59]
	ds_read_b128 v[172:175], v200 offset:19456
	v_mfma_f32_16x16x32_bf16 v[48:51], v[144:147], v[168:171], v[48:51]
	ds_read_b128 v[180:183], v200 offset:21504
	v_mfma_f32_16x16x32_bf16 v[40:43], v[152:155], v[168:171], v[40:43]
	ds_read_b128 v[188:191], v200 offset:23552
	v_mfma_f32_16x16x32_bf16 v[32:35], v[144:147], v[176:179], v[32:35]
	v_mfma_f32_16x16x32_bf16 v[24:27], v[152:155], v[176:179], v[24:27]
	v_mfma_f32_16x16x32_bf16 v[16:19], v[144:147], v[184:187], v[16:19]
	v_mfma_f32_16x16x32_bf16 v[8:11], v[152:155], v[184:187], v[8:11]
	s_waitcnt lgkmcnt(3)
	v_mfma_f32_16x16x32_bf16 v[60:63], v[148:151], v[164:167], v[60:63]
	v_mfma_f32_16x16x32_bf16 v[56:59], v[156:159], v[164:167], v[56:59]
	s_waitcnt lgkmcnt(2)
	v_mfma_f32_16x16x32_bf16 v[48:51], v[148:151], v[172:175], v[48:51]
	v_mfma_f32_16x16x32_bf16 v[40:43], v[156:159], v[172:175], v[40:43]
	s_waitcnt lgkmcnt(1)
	v_mfma_f32_16x16x32_bf16 v[32:35], v[148:151], v[180:183], v[32:35]
	v_mfma_f32_16x16x32_bf16 v[24:27], v[156:159], v[180:183], v[24:27]
	s_waitcnt lgkmcnt(0)
	s_setprio 2
	s_barrier
; #define PG8_STAGE(bufoff, gbase, voff) do { _Pragma("unroll") for (int _i = 0; _i < 2; ++_i) \
;         __builtin_amdgcn_global_load_lds((const unsigned*)((const char*)(gbase) + (voff)[_i]), (LAS unsigned*)(lds + (bufoff) + ldsw + _i * 8192), 16, 0, 0); } while (0)
; #define PG8_LDA(dst, b, h) do { _Pragma("unroll") for (int m = 0; m < 4; ++m) _Pragma("unroll") for (int k = 0; k < 2; ++k) dst[m][k] = *(const LAS bf16x8*)(lds + PG8_SA(b, h) + aoff + m * 2048 + k * 1024); } while (0)
; #define PG8_LDB(dst, b, h) do { _Pragma("unroll") for (int n = 0; n < 2; ++n) _Pragma("unroll") for (int k = 0; k < 2; ++k) dst[n][k] = *(const LAS bf16x8*)(lds + PG8_SB(b, h) + boff + n * 2048 + k * 1024); } while (0)
; #define PG8_MMA(ai, bj, At, Bt) do { __builtin_amdgcn_s_setprio(1); _Pragma("unroll") for (int m = 0; m < 4; ++m) _Pragma("unroll") for (int n = 0; n < 2; ++n) _Pragma("unroll") for (int k = 0; k < 2; ++k) \
;         acc[ai][bj][m][n] = __builtin_amdgcn_mfma_f32_16x16x32_bf16(Bt[n][k], At[m][k], acc[ai][bj][m][n], 0, 0, 0); __builtin_amdgcn_s_setprio(0); } while (0)
; #define PG8_WAIT_V(n) asm volatile("s_waitcnt vmcnt(" #n ")" ::: "memory")
; #define PG8_WAIT_L(n) asm volatile("s_waitcnt lgkmcnt(" #n ")" ::: "memory")
; #define PG8_BAR __builtin_amdgcn_s_barrier()
; #define PG8_SCHED __builtin_amdgcn_sched_barrier(0)
; #define PG8_WAIT_V(n) asm volatile("s_waitcnt vmcnt(" #n ")" ::: "memory")
; #define PG8_WAIT_L(n) asm volatile("s_waitcnt lgkmcnt(" #n ")" ::: "memory")
; template <class Epi>
; DI void gemm_phase(LAS unsigned char* lds, const Gemm g, const StaticOrder S, const Epi E) {
;     ...
;             PG8_STAGE(PG8_SB(0, 1), b2 + hstep, voffB);
;             PG8_WAIT_V(6); PG8_BAR; PG8_MMA(1, 1, At, B1); PG8_BAR;
;             PG8_LDB(B0, 1, 0); PG8_SCHED; PG8_LDA(At, 1, 0); PG8_STAGE(PG8_SA(0, 1), a2 + hstep, voffA);
;             PG8_WAIT_L(8); PG8_BAR; PG8_WAIT_L(0); PG8_MMA(0, 0, At, B0); PG8_BAR; PG8_SCHED;
;             PG8_LDB(B1, 1, 1); PG8_STAGE(PG8_SB(1, 0), b3, voffB);
;             PG8_BAR; PG8_WAIT_L(0); PG8_MMA(0, 1, At, B1); PG8_BAR;
;             PG8_LDA(At, 1, 1); PG8_STAGE(PG8_SA(1, 0), a3, voffA);
;             PG8_BAR; PG8_WAIT_L(0); PG8_MMA(1, 0, At, B0); PG8_BAR; PG8_SCHED;
;             PG8_STAGE(PG8_SB(1, 1), b3 + hstep, voffB);
;             PG8_WAIT_V(6); PG8_BAR; PG8_MMA(1, 1, At, B1); PG8_BAR;
	v_mfma_f32_16x16x32_bf16 v[16:19], v[148:151], v[188:191], v[16:19]
	v_mfma_f32_16x16x32_bf16 v[8:11], v[156:159], v[188:191], v[8:11]
	s_setprio 0
	s_add_u32 s20, s24, 0xb0000
	s_addc_u32 s21, s25, 0
	s_add_i32 s59, s43, s29
	v_lshl_add_u64 v[144:145], s[20:21], 0, v[130:131]
	s_mov_b32 m0, s59
	s_nop 0
	global_load_lds_dwordx4 v[144:145], off
	v_lshl_add_u64 v[144:145], s[20:21], 0, v[134:135]
	s_add_i32 m0, s59, 0x2000
	s_nop 0
	global_load_lds_dwordx4 v[144:145], off
	s_waitcnt vmcnt(6)
	s_setprio 1
	s_barrier
	v_mfma_f32_16x16x32_bf16 v[52:55], v[192:195], v[160:163], v[52:55]
	v_mfma_f32_16x16x32_bf16 v[44:47], v[206:209], v[160:163], v[44:47]
	v_mfma_f32_16x16x32_bf16 v[36:39], v[192:195], v[168:171], v[36:39]
	v_mfma_f32_16x16x32_bf16 v[28:31], v[206:209], v[168:171], v[28:31]
	v_mfma_f32_16x16x32_bf16 v[20:23], v[192:195], v[176:179], v[20:23]
	v_mfma_f32_16x16x32_bf16 v[12:15], v[206:209], v[176:179], v[12:15]
	v_mfma_f32_16x16x32_bf16 v[4:7], v[192:195], v[184:187], v[4:7]
	v_mfma_f32_16x16x32_bf16 v[0:3], v[206:209], v[184:187], v[0:3]
	v_mfma_f32_16x16x32_bf16 v[52:55], v[202:205], v[164:167], v[52:55]
	v_mfma_f32_16x16x32_bf16 v[44:47], v[210:213], v[164:167], v[44:47]
	v_mfma_f32_16x16x32_bf16 v[36:39], v[202:205], v[172:175], v[36:39]
	v_mfma_f32_16x16x32_bf16 v[28:31], v[210:213], v[172:175], v[28:31]
	v_mfma_f32_16x16x32_bf16 v[20:23], v[202:205], v[180:183], v[20:23]
	v_mfma_f32_16x16x32_bf16 v[12:15], v[210:213], v[180:183], v[12:15]
	s_setprio 2
	s_barrier
	v_mfma_f32_16x16x32_bf16 v[4:7], v[202:205], v[188:191], v[4:7]
	v_mfma_f32_16x16x32_bf16 v[0:3], v[210:213], v[188:191], v[0:3]
	s_setprio 0
	s_add_i32 s59, 0, 0x18000
	v_add_u32_e32 v156, s59, v197
	ds_read_b128 v[144:147], v156
	ds_read_b128 v[148:151], v156 offset:1024
	ds_read_b128 v[152:155], v156 offset:2048
	ds_read_b128 v[156:159], v156 offset:3072
	s_add_u32 s20, s26, 0xb0000
	s_addc_u32 s21, s27, 0
	s_mov_b32 m0, s35
	v_lshl_add_u64 v[192:193], s[20:21], 0, v[128:129]
	ds_read_b128 v[160:163], v200 offset:32768
	ds_read_b128 v[168:171], v200 offset:34816
	ds_read_b128 v[176:179], v200 offset:36864
	ds_read_b128 v[184:187], v200 offset:38912
	global_load_lds_dwordx4 v[192:193], off
	v_lshl_add_u64 v[192:193], s[20:21], 0, v[132:133]
	s_mov_b32 m0, s36
	s_nop 0
	global_load_lds_dwordx4 v[192:193], off
	s_waitcnt lgkmcnt(4)
	s_setprio 1
	s_barrier
	s_waitcnt lgkmcnt(0)
	v_mfma_f32_16x16x32_bf16 v[124:127], v[144:147], v[160:163], v[124:127]
	ds_read_b128 v[164:167], v200 offset:33792
	v_mfma_f32_16x16x32_bf16 v[120:123], v[152:155], v[160:163], v[120:123]
	ds_read_b128 v[172:175], v200 offset:35840
	v_mfma_f32_16x16x32_bf16 v[108:111], v[144:147], v[168:171], v[108:111]
	ds_read_b128 v[180:183], v200 offset:37888
	v_mfma_f32_16x16x32_bf16 v[104:107], v[152:155], v[168:171], v[104:107]
	ds_read_b128 v[188:191], v200 offset:39936
	v_mfma_f32_16x16x32_bf16 v[92:95], v[144:147], v[176:179], v[92:95]
	v_mfma_f32_16x16x32_bf16 v[88:91], v[152:155], v[176:179], v[88:91]
	v_mfma_f32_16x16x32_bf16 v[84:87], v[144:147], v[184:187], v[84:87]
	v_mfma_f32_16x16x32_bf16 v[76:79], v[152:155], v[184:187], v[76:79]
	s_waitcnt lgkmcnt(3)
	v_mfma_f32_16x16x32_bf16 v[124:127], v[148:151], v[164:167], v[124:127]
	v_mfma_f32_16x16x32_bf16 v[120:123], v[156:159], v[164:167], v[120:123]
	s_waitcnt lgkmcnt(2)
	v_mfma_f32_16x16x32_bf16 v[108:111], v[148:151], v[172:175], v[108:111]
	v_mfma_f32_16x16x32_bf16 v[104:107], v[156:159], v[172:175], v[104:107]
	s_waitcnt lgkmcnt(1)
	v_mfma_f32_16x16x32_bf16 v[92:95], v[148:151], v[180:183], v[92:95]
	v_mfma_f32_16x16x32_bf16 v[88:91], v[156:159], v[180:183], v[88:91]
	s_waitcnt lgkmcnt(0)
	s_setprio 2
	s_barrier
	v_mfma_f32_16x16x32_bf16 v[84:87], v[148:151], v[188:191], v[84:87]
	v_mfma_f32_16x16x32_bf16 v[76:79], v[156:159], v[188:191], v[76:79]
	s_setprio 0
	s_add_i32 s26, 0, 0x1c000
	s_add_i32 s20, s59, s29
	v_add_u32_e32 v210, s26, v197
	v_lshl_add_u64 v[214:215], v[214:215], 0, s[10:11]
	s_mov_b32 m0, s20
	ds_read_b128 v[192:195], v210
	ds_read_b128 v[202:205], v210 offset:1024
	ds_read_b128 v[206:209], v210 offset:2048
	ds_read_b128 v[210:213], v210 offset:3072
	global_load_lds_dwordx4 v[214:215], off
	v_lshl_add_u64 v[214:215], v[216:217], 0, s[10:11]
	s_add_i32 m0, s20, 0x2000
	s_nop 0
	global_load_lds_dwordx4 v[214:215], off
	s_setprio 1
	s_barrier
	s_waitcnt lgkmcnt(0)
	v_mfma_f32_16x16x32_bf16 v[116:119], v[192:195], v[160:163], v[116:119]
	v_mfma_f32_16x16x32_bf16 v[112:115], v[206:209], v[160:163], v[112:115]
	v_mfma_f32_16x16x32_bf16 v[100:103], v[192:195], v[168:171], v[100:103]
	v_mfma_f32_16x16x32_bf16 v[96:99], v[206:209], v[168:171], v[96:99]
	v_mfma_f32_16x16x32_bf16 v[80:83], v[192:195], v[176:179], v[80:83]
	v_mfma_f32_16x16x32_bf16 v[72:75], v[206:209], v[176:179], v[72:75]
	v_mfma_f32_16x16x32_bf16 v[68:71], v[192:195], v[184:187], v[68:71]
	v_mfma_f32_16x16x32_bf16 v[64:67], v[206:209], v[184:187], v[64:67]
	v_mfma_f32_16x16x32_bf16 v[116:119], v[202:205], v[164:167], v[116:119]
	v_mfma_f32_16x16x32_bf16 v[112:115], v[210:213], v[164:167], v[112:115]
	v_mfma_f32_16x16x32_bf16 v[100:103], v[202:205], v[172:175], v[100:103]
	v_mfma_f32_16x16x32_bf16 v[96:99], v[210:213], v[172:175], v[96:99]
	v_mfma_f32_16x16x32_bf16 v[80:83], v[202:205], v[180:183], v[80:83]
	v_mfma_f32_16x16x32_bf16 v[72:75], v[210:213], v[180:183], v[72:75]
	s_setprio 2
	s_barrier
; DI f32x4 bf_lo4(u32x4 w) { f32x4 r; r[0] = bf_lo(w.x); r[1] = bf_hi(w.x); r[2] = bf_lo(w.y); r[3] = bf_hi(w.y); return r; }
; DI f32x4 bf_hi4(u32x4 w) { f32x4 r; r[0] = bf_lo(w.z); r[1] = bf_hi(w.z); r[2] = bf_lo(w.w); r[3] = bf_hi(w.w); return r; }
; #define PG8_STAGE(bufoff, gbase, voff) do { _Pragma("unroll") for (int _i = 0; _i < 2; ++_i) \
;         __builtin_amdgcn_global_load_lds((const unsigned*)((const char*)(gbase) + (voff)[_i]), (LAS unsigned*)(lds + (bufoff) + ldsw + _i * 8192), 16, 0, 0); } while (0)
; #define PG8_LDA(dst, b, h) do { _Pragma("unroll") for (int m = 0; m < 4; ++m) _Pragma("unroll") for (int k = 0; k < 2; ++k) dst[m][k] = *(const LAS bf16x8*)(lds + PG8_SA(b, h) + aoff + m * 2048 + k * 1024); } while (0)
; #define PG8_LDB(dst, b, h) do { _Pragma("unroll") for (int n = 0; n < 2; ++n) _Pragma("unroll") for (int k = 0; k < 2; ++k) dst[n][k] = *(const LAS bf16x8*)(lds + PG8_SB(b, h) + boff + n * 2048 + k * 1024); } while (0)
; #define PG8_WAIT_V(n) asm volatile("s_waitcnt vmcnt(" #n ")" ::: "memory")
; template <class Epi>
; DI void gemm_phase(LAS unsigned char* lds, const Gemm g, const StaticOrder S, const Epi E) {
;     ...
;             PG8_WAIT_L(8); PG8_BAR; PG8_WAIT_L(0); PG8_MMA(0, 0, At, B0); PG8_BAR; PG8_SCHED;
;             PG8_LDB(B1, 1, 1); PG8_STAGE(PG8_SB(1, 0), b3, voffB);
;             PG8_BAR; PG8_WAIT_L(0); PG8_MMA(0, 1, At, B1); PG8_BAR;
;             PG8_LDA(At, 1, 1); PG8_STAGE(PG8_SA(1, 0), a3, voffA);
;             PG8_BAR; PG8_WAIT_L(0); PG8_MMA(1, 0, At, B0); PG8_BAR; PG8_SCHED;
;             PG8_STAGE(PG8_SB(1, 1), b3 + hstep, voffB);
;             PG8_WAIT_V(6); PG8_BAR; PG8_MMA(1, 1, At, B1); PG8_BAR;
;     DI void operator()(AccRef acc, const Unit& u, int wr, int wc, int fr, int fq) const {
;     ...
; #pragma unroll
;         for (int ai = 0; ai < 2; ++ai) {
;             f32x4 bv[4][2][2];
; #pragma unroll
;             for (int m = 0; m < 4; ++m)
; #pragma unroll
;                 for (int bj = 0; bj < 2; ++bj) {
;                     const size_t o = (size_t)(row0 + ai * 128 + m * 16) * DM + col0 + bj * 128;
;                     if (BASEF32) { bv[m][bj][0] = *(const f32x4*)(basef + o); bv[m][bj][1] = *(const f32x4*)(basef + o + 4); }
;                     else { const u32x4 h = *(const u32x4*)(xnb + o); bv[m][bj][0] = bf_lo4(h); bv[m][bj][1] = bf_hi4(h); }
;                 }
	v_mfma_f32_16x16x32_bf16 v[68:71], v[202:205], v[188:191], v[68:71]
	v_mfma_f32_16x16x32_bf16 v[64:67], v[210:213], v[188:191], v[64:67]
	s_setprio 0
	s_mov_b32 m0, s38
	v_lshl_add_u64 v[214:215], v[218:219], 0, s[10:11]
	ds_read_b128 v[160:163], v200 offset:49152
	ds_read_b128 v[168:171], v200 offset:51200
	ds_read_b128 v[176:179], v200 offset:53248
	ds_read_b128 v[184:187], v200 offset:55296
	global_load_lds_dwordx4 v[214:215], off
	v_lshl_add_u64 v[214:215], v[220:221], 0, s[10:11]
	s_mov_b32 m0, s39
	s_nop 0
	global_load_lds_dwordx4 v[214:215], off
	s_setprio 1
	s_barrier
	s_waitcnt lgkmcnt(0)
	v_mfma_f32_16x16x32_bf16 v[60:63], v[144:147], v[160:163], v[60:63]
	ds_read_b128 v[164:167], v200 offset:50176
	v_mfma_f32_16x16x32_bf16 v[56:59], v[152:155], v[160:163], v[56:59]
	ds_read_b128 v[172:175], v200 offset:52224
	v_mfma_f32_16x16x32_bf16 v[48:51], v[144:147], v[168:171], v[48:51]
	ds_read_b128 v[180:183], v200 offset:54272
	v_mfma_f32_16x16x32_bf16 v[40:43], v[152:155], v[168:171], v[40:43]
	ds_read_b128 v[188:191], v200 offset:56320
	v_mfma_f32_16x16x32_bf16 v[32:35], v[144:147], v[176:179], v[32:35]
	v_mfma_f32_16x16x32_bf16 v[24:27], v[152:155], v[176:179], v[24:27]
	v_mfma_f32_16x16x32_bf16 v[16:19], v[144:147], v[184:187], v[16:19]
	v_mfma_f32_16x16x32_bf16 v[8:11], v[152:155], v[184:187], v[8:11]
	s_waitcnt lgkmcnt(3)
	v_mfma_f32_16x16x32_bf16 v[60:63], v[148:151], v[164:167], v[60:63]
	v_mfma_f32_16x16x32_bf16 v[56:59], v[156:159], v[164:167], v[56:59]
	s_waitcnt lgkmcnt(2)
	v_mfma_f32_16x16x32_bf16 v[48:51], v[148:151], v[172:175], v[48:51]
	v_mfma_f32_16x16x32_bf16 v[40:43], v[156:159], v[172:175], v[40:43]
	s_waitcnt lgkmcnt(1)
	v_mfma_f32_16x16x32_bf16 v[32:35], v[148:151], v[180:183], v[32:35]
	v_mfma_f32_16x16x32_bf16 v[24:27], v[156:159], v[180:183], v[24:27]
	s_waitcnt lgkmcnt(0)
	s_setprio 2
	s_barrier
	v_mfma_f32_16x16x32_bf16 v[16:19], v[148:151], v[188:191], v[16:19]
	v_mfma_f32_16x16x32_bf16 v[8:11], v[156:159], v[188:191], v[8:11]
	s_setprio 0
	s_add_u32 s20, s24, 0xb0080
	s_addc_u32 s21, s25, 0
	s_add_i32 s24, s26, s29
	v_lshl_add_u64 v[144:145], s[20:21], 0, v[130:131]
	s_mov_b32 m0, s24
	s_nop 0
	global_load_lds_dwordx4 v[144:145], off
	v_lshl_add_u64 v[144:145], s[20:21], 0, v[134:135]
	s_add_i32 m0, s24, 0x2000
	s_nop 0
	global_load_lds_dwordx4 v[144:145], off
	s_waitcnt vmcnt(6)
	s_setprio 1
	s_barrier
	v_mfma_f32_16x16x32_bf16 v[52:55], v[192:195], v[160:163], v[52:55]
	v_mfma_f32_16x16x32_bf16 v[44:47], v[206:209], v[160:163], v[44:47]
	v_mfma_f32_16x16x32_bf16 v[36:39], v[192:195], v[168:171], v[36:39]
	v_mfma_f32_16x16x32_bf16 v[28:31], v[206:209], v[168:171], v[28:31]
	v_mfma_f32_16x16x32_bf16 v[20:23], v[192:195], v[176:179], v[20:23]
	v_mfma_f32_16x16x32_bf16 v[12:15], v[206:209], v[176:179], v[12:15]
	v_mfma_f32_16x16x32_bf16 v[4:7], v[192:195], v[184:187], v[4:7]
	v_mfma_f32_16x16x32_bf16 v[0:3], v[206:209], v[184:187], v[0:3]
	v_mfma_f32_16x16x32_bf16 v[52:55], v[202:205], v[164:167], v[52:55]
	v_mfma_f32_16x16x32_bf16 v[44:47], v[210:213], v[164:167], v[44:47]
	v_mfma_f32_16x16x32_bf16 v[36:39], v[202:205], v[172:175], v[36:39]
	v_mfma_f32_16x16x32_bf16 v[28:31], v[210:213], v[172:175], v[28:31]
	v_mfma_f32_16x16x32_bf16 v[20:23], v[202:205], v[180:183], v[20:23]
	v_mfma_f32_16x16x32_bf16 v[12:15], v[210:213], v[180:183], v[12:15]
	s_setprio 2
	s_barrier
	v_mfma_f32_16x16x32_bf16 v[4:7], v[202:205], v[188:191], v[4:7]
	v_mfma_f32_16x16x32_bf16 v[0:3], v[210:213], v[188:191], v[0:3]
	s_setprio 0
	s_add_i32 s58, s58, 2
	s_add_u32 s52, s52, 0x100
	s_addc_u32 s53, s53, 0
	s_cmp_gt_u32 s58, 41
	s_mov_b64 s[20:21], s[22:23]
	s_cbranch_scc0 .LBB0_941
	v_lshl_add_u32 v148, s50, 8, v196
	v_lshl_or_b32 v144, s51, 8, v198
	v_or_b32_e32 v146, 16, v148
	v_ashrrev_i32_e32 v145, 31, v144
	v_ashrrev_i32_e32 v147, 31, v146
	v_lshl_add_u64 v[176:177], v[144:145], 1, s[56:57]
	v_ashrrev_i32_e32 v149, 31, v148
	v_lshlrev_b64 v[146:147], 11, v[146:147]
	v_lshlrev_b64 v[144:145], 11, v[148:149]
	v_lshl_add_u64 v[150:151], v[176:177], 0, v[146:147]
	v_or_b32_e32 v146, 32, v148
	v_or_b32_e32 v148, 48, v148
	v_ashrrev_i32_e32 v147, 31, v146
	v_ashrrev_i32_e32 v149, 31, v148
	v_lshl_add_u64 v[144:145], v[176:177], 0, v[144:145]
	v_lshlrev_b64 v[146:147], 11, v[146:147]
	v_lshlrev_b64 v[148:149], 11, v[148:149]
	global_load_dwordx4 v[152:155], v[144:145], off
	global_load_dwordx4 v[156:159], v[144:145], off offset:256
	v_lshl_add_u64 v[146:147], v[176:177], 0, v[146:147]
	v_lshl_add_u64 v[148:149], v[176:177], 0, v[148:149]
	global_load_dwordx4 v[160:163], v[150:151], off
	global_load_dwordx4 v[164:167], v[150:151], off offset:256
	global_load_dwordx4 v[168:171], v[146:147], off
	global_load_dwordx4 v[172:175], v[146:147], off offset:256
	global_load_dwordx4 v[202:205], v[148:149], off
	global_load_dwordx4 v[206:209], v[148:149], off offset:256
	s_mov_b32 s51, s48
	s_mov_b32 s50, s49
	s_mov_b64 s[22:23], s[4:5]
	s_mov_b64 s[20:21], s[8:9]
	s_waitcnt vmcnt(0)
; DI unsigned pk_bf16(float lo, float hi) { f32x2 v = {lo, hi}; return __builtin_bit_cast(unsigned, __builtin_convertvector(v, bf16v2)); }
; DI f32x4 bf_lo4(u32x4 w) { f32x4 r; r[0] = bf_lo(w.x); r[1] = bf_hi(w.x); r[2] = bf_lo(w.y); r[3] = bf_hi(w.y); return r; }
; DI f32x4 bf_hi4(u32x4 w) { f32x4 r; r[0] = bf_lo(w.z); r[1] = bf_hi(w.z); r[2] = bf_lo(w.w); r[3] = bf_hi(w.w); return r; }
;     DI void operator()(AccRef acc, const Unit& u, int wr, int wc, int fr, int fq) const {
;     ...
; #pragma unroll
;         for (int ai = 0; ai < 2; ++ai) {
;             f32x4 bv[4][2][2];
; #pragma unroll
;             for (int m = 0; m < 4; ++m)
; #pragma unroll
;                 for (int bj = 0; bj < 2; ++bj) {
;                     const size_t o = (size_t)(row0 + ai * 128 + m * 16) * DM + col0 + bj * 128;
;                     if (BASEF32) { bv[m][bj][0] = *(const f32x4*)(basef + o); bv[m][bj][1] = *(const f32x4*)(basef + o + 4); }
;                     else { const u32x4 h = *(const u32x4*)(xnb + o); bv[m][bj][0] = bf_lo4(h); bv[m][bj][1] = bf_hi4(h); }
;                 }
; #pragma unroll
;             for (int m = 0; m < 4; ++m) {
;                 const int row = row0 + ai * 128 + m * 16;
;                 float q = 0.f;
; #pragma unroll
;                 for (int bj = 0; bj < 2; ++bj) {
;                     const size_t o = (size_t)row * DM + col0 + bj * 128;
;                     const f32x4 r0 = bv[m][bj][0] + scale * acc[ai][bj][m][0], r1 = bv[m][bj][1] + scale * acc[ai][bj][m][1];
;                     u32x4 w; w.x = pk_bf16(r0[0], r0[1]); w.y = pk_bf16(r0[2], r0[3]); w.z = pk_bf16(r1[0], r1[1]); w.w = pk_bf16(r1[2], r1[3]);
;                     *(u32x4*)(xnb + o) = w;
;                     if (STATS) q += r0[0] * r0[0] + r0[1] * r0[1] + r0[2] * r0[2] + r0[3] * r0[3] + r1[0] * r1[0] + r1[1] * r1[1] + r1[2] * r1[2] + r1[3] * r1[3];
;                 }
	v_lshlrev_b32_e32 v214, 16, v154
	v_and_b32_e32 v215, 0xffff0000, v154
	v_lshlrev_b32_e32 v216, 16, v155
	v_and_b32_e32 v217, 0xffff0000, v155
	v_lshlrev_b32_e32 v210, 16, v152
	v_and_b32_e32 v211, 0xffff0000, v152
	v_lshlrev_b32_e32 v212, 16, v153
	v_and_b32_e32 v213, 0xffff0000, v153
	v_lshlrev_b32_e32 v194, 16, v162
	v_and_b32_e32 v195, 0xffff0000, v162
	v_lshlrev_b32_e32 v230, 16, v163
	v_and_b32_e32 v231, 0xffff0000, v163
	v_lshlrev_b32_e32 v154, 16, v202
	v_and_b32_e32 v155, 0xffff0000, v202
	v_lshlrev_b32_e32 v162, 16, v203
	v_and_b32_e32 v163, 0xffff0000, v203
	v_pk_fma_f32 v[202:203], v[122:123], 0.5, v[216:217] op_sel_hi:[1,0,1]
	v_pk_fma_f32 v[122:123], v[120:121], 0.5, v[214:215] op_sel_hi:[1,0,1]
	v_lshlrev_b32_e32 v218, 16, v156
	v_and_b32_e32 v219, 0xffff0000, v156
	v_lshlrev_b32_e32 v220, 16, v157
	v_and_b32_e32 v221, 0xffff0000, v157
	v_pk_fma_f32 v[126:127], v[126:127], 0.5, v[212:213] op_sel_hi:[1,0,1]
	v_pk_fma_f32 v[124:125], v[124:125], 0.5, v[210:211] op_sel_hi:[1,0,1]
	v_cvt_pk_bf16_f32 v122, v122, v123
	v_cvt_pk_bf16_f32 v123, v202, v203
	v_add_co_u32_e32 v202, vcc, s44, v144
	v_lshlrev_b32_e32 v224, 16, v158
	v_and_b32_e32 v225, 0xffff0000, v158
	v_lshlrev_b32_e32 v226, 16, v159
	v_and_b32_e32 v227, 0xffff0000, v159
	v_cvt_pk_bf16_f32 v120, v124, v125
	v_cvt_pk_bf16_f32 v121, v126, v127
	v_pk_fma_f32 v[118:119], v[118:119], 0.5, v[220:221] op_sel_hi:[1,0,1]
	v_pk_fma_f32 v[116:117], v[116:117], 0.5, v[218:219] op_sel_hi:[1,0,1]
	v_addc_co_u32_e32 v203, vcc, 0, v145, vcc
	v_lshlrev_b32_e32 v192, 16, v160
	v_and_b32_e32 v193, 0xffff0000, v160
	global_store_dwordx4 v[144:145], v[120:123], off
	v_pk_fma_f32 v[108:109], v[108:109], 0.5, v[192:193] op_sel_hi:[1,0,1]
	v_lshl_add_u64 v[192:193], v[144:145], 0, s[12:13]
	v_pk_fma_f32 v[120:121], v[114:115], 0.5, v[226:227] op_sel_hi:[1,0,1]
	v_pk_fma_f32 v[114:115], v[112:113], 0.5, v[224:225] op_sel_hi:[1,0,1]
	v_cvt_pk_bf16_f32 v112, v116, v117
	v_cvt_pk_bf16_f32 v113, v118, v119
	global_load_dwordx4 v[116:119], v[202:203], off
	v_cvt_pk_bf16_f32 v114, v114, v115
	v_cvt_pk_bf16_f32 v115, v120, v121
	v_lshlrev_b32_e32 v228, 16, v161
	v_and_b32_e32 v229, 0xffff0000, v161
	global_store_dwordx4 v[144:145], v[112:115], off offset:256
	v_pk_fma_f32 v[120:121], v[106:107], 0.5, v[230:231] op_sel_hi:[1,0,1]
	v_pk_fma_f32 v[110:111], v[110:111], 0.5, v[228:229] op_sel_hi:[1,0,1]
	v_pk_fma_f32 v[112:113], v[104:105], 0.5, v[194:195] op_sel_hi:[1,0,1]
	global_load_dwordx4 v[104:107], v[192:193], off offset:256
	v_add_co_u32_e32 v194, vcc, s45, v144
	v_lshlrev_b32_e32 v184, 16, v164
	s_nop 0
	v_addc_co_u32_e32 v195, vcc, 0, v145, vcc
	v_and_b32_e32 v185, 0xffff0000, v164
	v_lshlrev_b32_e32 v188, 16, v165
	v_and_b32_e32 v189, 0xffff0000, v165
	v_lshlrev_b32_e32 v186, 16, v166
	v_and_b32_e32 v187, 0xffff0000, v166
	v_lshlrev_b32_e32 v190, 16, v167
	v_and_b32_e32 v191, 0xffff0000, v167
	v_cvt_pk_bf16_f32 v108, v108, v109
	v_cvt_pk_bf16_f32 v109, v110, v111
	v_cvt_pk_bf16_f32 v110, v112, v113
	global_load_dwordx4 v[112:115], v[194:195], off
	v_cvt_pk_bf16_f32 v111, v120, v121
	global_store_dwordx4 v[150:151], v[108:111], off
	v_pk_fma_f32 v[124:125], v[98:99], 0.5, v[190:191] op_sel_hi:[1,0,1]
	v_pk_fma_f32 v[96:97], v[96:97], 0.5, v[186:187] op_sel_hi:[1,0,1]
	v_pk_fma_f32 v[110:111], v[102:103], 0.5, v[188:189] op_sel_hi:[1,0,1]
	v_pk_fma_f32 v[108:109], v[100:101], 0.5, v[184:185] op_sel_hi:[1,0,1]
	v_lshl_add_u64 v[98:99], v[144:145], 0, s[14:15]
	global_load_dwordx4 v[100:103], v[98:99], off offset:256
	v_cvt_pk_bf16_f32 v108, v108, v109
	v_cvt_pk_bf16_f32 v109, v110, v111
	v_cvt_pk_bf16_f32 v110, v96, v97
	v_add_co_u32_e32 v96, vcc, s46, v144
	v_lshlrev_b32_e32 v176, 16, v168
	s_nop 0
	v_addc_co_u32_e32 v97, vcc, 0, v145, vcc
	v_and_b32_e32 v177, 0xffff0000, v168
	v_lshlrev_b32_e32 v180, 16, v169
	v_and_b32_e32 v181, 0xffff0000, v169
	v_lshlrev_b32_e32 v178, 16, v170
	v_and_b32_e32 v179, 0xffff0000, v170
	v_lshlrev_b32_e32 v182, 16, v171
	v_and_b32_e32 v183, 0xffff0000, v171
	global_load_dwordx4 v[120:123], v[96:97], off
	v_cvt_pk_bf16_f32 v111, v124, v125
	global_store_dwordx4 v[150:151], v[108:111], off offset:256
	v_pk_fma_f32 v[150:151], v[90:91], 0.5, v[182:183] op_sel_hi:[1,0,1]
	v_pk_fma_f32 v[88:89], v[88:89], 0.5, v[178:179] op_sel_hi:[1,0,1]
	v_pk_fma_f32 v[110:111], v[94:95], 0.5, v[180:181] op_sel_hi:[1,0,1]
	v_pk_fma_f32 v[108:109], v[92:93], 0.5, v[176:177] op_sel_hi:[1,0,1]
	v_lshl_add_u64 v[90:91], v[144:145], 0, s[16:17]
	global_load_dwordx4 v[92:95], v[90:91], off offset:256
	v_cvt_pk_bf16_f32 v108, v108, v109
	v_cvt_pk_bf16_f32 v109, v110, v111
	v_cvt_pk_bf16_f32 v110, v88, v89
	v_add_co_u32_e32 v88, vcc, s47, v144
	v_lshlrev_b32_e32 v170, 16, v174
	s_nop 0
	v_addc_co_u32_e32 v89, vcc, 0, v145, vcc
	v_and_b32_e32 v171, 0xffff0000, v174
	global_load_dwordx4 v[124:127], v[88:89], off
	v_lshlrev_b32_e32 v168, 16, v172
	v_and_b32_e32 v169, 0xffff0000, v172
	v_lshlrev_b32_e32 v172, 16, v173
	v_and_b32_e32 v173, 0xffff0000, v173
	v_cvt_pk_bf16_f32 v111, v150, v151
	v_pk_fma_f32 v[150:151], v[72:73], 0.5, v[170:171] op_sel_hi:[1,0,1]
	v_lshl_add_u64 v[72:73], v[144:145], 0, s[18:19]
	global_store_dwordx4 v[146:147], v[108:111], off
	v_lshlrev_b32_e32 v174, 16, v175
	v_and_b32_e32 v175, 0xffff0000, v175
	v_pk_fma_f32 v[110:111], v[82:83], 0.5, v[172:173] op_sel_hi:[1,0,1]
	v_pk_fma_f32 v[108:109], v[80:81], 0.5, v[168:169] op_sel_hi:[1,0,1]
	global_load_dwordx4 v[80:83], v[72:73], off offset:256
	v_lshlrev_b32_e32 v160, 16, v204
	v_and_b32_e32 v161, 0xffff0000, v204
	v_lshlrev_b32_e32 v166, 16, v205
	v_and_b32_e32 v167, 0xffff0000, v205
	v_pk_fma_f32 v[74:75], v[74:75], 0.5, v[174:175] op_sel_hi:[1,0,1]
	v_cvt_pk_bf16_f32 v108, v108, v109
	v_cvt_pk_bf16_f32 v109, v110, v111
	v_cvt_pk_bf16_f32 v111, v74, v75
	v_pk_fma_f32 v[86:87], v[86:87], 0.5, v[162:163] op_sel_hi:[1,0,1]
	v_pk_fma_f32 v[74:75], v[84:85], 0.5, v[154:155] op_sel_hi:[1,0,1]
	v_pk_fma_f32 v[78:79], v[78:79], 0.5, v[166:167] op_sel_hi:[1,0,1]
	v_pk_fma_f32 v[76:77], v[76:77], 0.5, v[160:161] op_sel_hi:[1,0,1]
	v_lshlrev_b32_e32 v152, 16, v206
	v_and_b32_e32 v153, 0xffff0000, v206
	v_lshlrev_b32_e32 v158, 16, v207
	v_and_b32_e32 v159, 0xffff0000, v207
	v_lshlrev_b32_e32 v156, 16, v208
	v_and_b32_e32 v157, 0xffff0000, v208
	v_lshlrev_b32_e32 v164, 16, v209
	v_and_b32_e32 v165, 0xffff0000, v209
	v_cvt_pk_bf16_f32 v74, v74, v75
	v_cvt_pk_bf16_f32 v75, v86, v87
	v_cvt_pk_bf16_f32 v76, v76, v77
	v_cvt_pk_bf16_f32 v77, v78, v79
	global_store_dwordx4 v[148:149], v[74:77], off
	v_pk_fma_f32 v[70:71], v[70:71], 0.5, v[158:159] op_sel_hi:[1,0,1]
	v_pk_fma_f32 v[68:69], v[68:69], 0.5, v[152:153] op_sel_hi:[1,0,1]
	v_pk_fma_f32 v[74:75], v[66:67], 0.5, v[164:165] op_sel_hi:[1,0,1]
	v_pk_fma_f32 v[66:67], v[64:65], 0.5, v[156:157] op_sel_hi:[1,0,1]
	v_cvt_pk_bf16_f32 v64, v68, v69
	v_cvt_pk_bf16_f32 v65, v70, v71
	v_cvt_pk_bf16_f32 v66, v66, v67
	v_cvt_pk_bf16_f32 v67, v74, v75
	global_store_dwordx4 v[148:149], v[64:67], off offset:256
	s_waitcnt vmcnt(0)
; DI unsigned pk_bf16(float lo, float hi) { f32x2 v = {lo, hi}; return __builtin_bit_cast(unsigned, __builtin_convertvector(v, bf16v2)); }
; #define PG8_WAIT_V(n) asm volatile("s_waitcnt vmcnt(" #n ")" ::: "memory")
; #define PG8_BAR __builtin_amdgcn_s_barrier()
; #define PG8_WAIT_V(n) asm volatile("s_waitcnt vmcnt(" #n ")" ::: "memory")
; #define PG8_BAR __builtin_amdgcn_s_barrier()
; template <class Epi>
; DI void gemm_phase(LAS unsigned char* lds, const Gemm g, const StaticOrder S, const Epi E) {
;     ...
;         if (!has_next) break;
; #pragma unroll
;         for (int a = 0; a < 2; ++a)
; #pragma unroll
;             for (int b = 0; b < 2; ++b)
; #pragma unroll
;                 for (int m = 0; m < 4; ++m)
; #pragma unroll
;                     for (int n = 0; n < 2; ++n) acc[a][b][m][n] = (f32x4){0.f, 0.f, 0.f, 0.f};
;         cur = nxt; cA = nA; cB = nB; ++ui;
;     }
;     PG8_WAIT_V(0);
;     if (wr == 0) PG8_BAR;
;     PG8_BAR;
;     DI void operator()(AccRef acc, const Unit& u, int wr, int wc, int fr, int fq) const {
;     ...
; #pragma unroll
;             for (int m = 0; m < 4; ++m) {
;                 const int row = row0 + ai * 128 + m * 16;
;                 float q = 0.f;
; #pragma unroll
;                 for (int bj = 0; bj < 2; ++bj) {
;                     const size_t o = (size_t)row * DM + col0 + bj * 128;
;                     const f32x4 r0 = bv[m][bj][0] + scale * acc[ai][bj][m][0], r1 = bv[m][bj][1] + scale * acc[ai][bj][m][1];
;                     u32x4 w; w.x = pk_bf16(r0[0], r0[1]); w.y = pk_bf16(r0[2], r0[3]); w.z = pk_bf16(r1[0], r1[1]); w.w = pk_bf16(r1[2], r1[3]);
;                     *(u32x4*)(xnb + o) = w;
;                     if (STATS) q += r0[0] * r0[0] + r0[1] * r0[1] + r0[2] * r0[2] + r0[3] * r0[3] + r1[0] * r1[0] + r1[1] * r1[1] + r1[2] * r1[2] + r1[3] * r1[3];
;                 }
	v_lshlrev_b32_e32 v68, 16, v118
	v_and_b32_e32 v69, 0xffff0000, v118
	v_lshlrev_b32_e32 v64, 16, v116
	v_and_b32_e32 v65, 0xffff0000, v116
	v_lshlrev_b32_e32 v66, 16, v117
	v_and_b32_e32 v67, 0xffff0000, v117
	v_lshlrev_b32_e32 v70, 16, v119
	v_and_b32_e32 v71, 0xffff0000, v119
	v_pk_fma_f32 v[62:63], v[62:63], 0.5, v[66:67] op_sel_hi:[1,0,1]
	v_pk_fma_f32 v[60:61], v[60:61], 0.5, v[64:65] op_sel_hi:[1,0,1]
	v_pk_fma_f32 v[64:65], v[58:59], 0.5, v[70:71] op_sel_hi:[1,0,1]
	v_pk_fma_f32 v[58:59], v[56:57], 0.5, v[68:69] op_sel_hi:[1,0,1]
	v_lshlrev_b32_e32 v74, 16, v104
	v_and_b32_e32 v75, 0xffff0000, v104
	v_lshlrev_b32_e32 v76, 16, v105
	v_and_b32_e32 v77, 0xffff0000, v105
	v_lshlrev_b32_e32 v78, 16, v106
	v_and_b32_e32 v79, 0xffff0000, v106
	v_lshlrev_b32_e32 v84, 16, v107
	v_and_b32_e32 v85, 0xffff0000, v107
	v_cvt_pk_bf16_f32 v56, v60, v61
	v_cvt_pk_bf16_f32 v57, v62, v63
	v_cvt_pk_bf16_f32 v58, v58, v59
	v_cvt_pk_bf16_f32 v59, v64, v65
	v_cvt_pk_bf16_f32 v110, v150, v151
	global_store_dwordx4 v[202:203], v[56:59], off
	v_pk_fma_f32 v[54:55], v[54:55], 0.5, v[76:77] op_sel_hi:[1,0,1]
	v_pk_fma_f32 v[52:53], v[52:53], 0.5, v[74:75] op_sel_hi:[1,0,1]
	v_pk_fma_f32 v[56:57], v[46:47], 0.5, v[84:85] op_sel_hi:[1,0,1]
	v_pk_fma_f32 v[46:47], v[44:45], 0.5, v[78:79] op_sel_hi:[1,0,1]
	global_store_dwordx4 v[146:147], v[108:111], off offset:256
	v_lshlrev_b32_e32 v86, 16, v112
	v_and_b32_e32 v87, 0xffff0000, v112
	v_lshlrev_b32_e32 v104, 16, v113
	v_and_b32_e32 v105, 0xffff0000, v113
	v_lshlrev_b32_e32 v106, 16, v114
	v_and_b32_e32 v107, 0xffff0000, v114
	v_lshlrev_b32_e32 v108, 16, v115
	v_and_b32_e32 v109, 0xffff0000, v115
	v_cvt_pk_bf16_f32 v44, v52, v53
	v_cvt_pk_bf16_f32 v45, v54, v55
	v_cvt_pk_bf16_f32 v46, v46, v47
	v_cvt_pk_bf16_f32 v47, v56, v57
	global_store_dwordx4 v[192:193], v[44:47], off offset:256
	v_lshlrev_b32_e32 v110, 16, v100
	v_and_b32_e32 v111, 0xffff0000, v100
	v_pk_fma_f32 v[44:45], v[50:51], 0.5, v[104:105] op_sel_hi:[1,0,1]
	v_pk_fma_f32 v[46:47], v[48:49], 0.5, v[86:87] op_sel_hi:[1,0,1]
	v_pk_fma_f32 v[48:49], v[42:43], 0.5, v[108:109] op_sel_hi:[1,0,1]
	v_pk_fma_f32 v[42:43], v[40:41], 0.5, v[106:107] op_sel_hi:[1,0,1]
	v_lshlrev_b32_e32 v100, 16, v101
	v_and_b32_e32 v101, 0xffff0000, v101
	v_lshlrev_b32_e32 v112, 16, v102
	v_and_b32_e32 v113, 0xffff0000, v102
	v_lshlrev_b32_e32 v102, 16, v103
	v_and_b32_e32 v103, 0xffff0000, v103
	v_cvt_pk_bf16_f32 v40, v46, v47
	v_cvt_pk_bf16_f32 v41, v44, v45
	v_cvt_pk_bf16_f32 v42, v42, v43
	v_cvt_pk_bf16_f32 v43, v48, v49
	global_store_dwordx4 v[194:195], v[40:43], off
	v_pk_fma_f32 v[38:39], v[38:39], 0.5, v[100:101] op_sel_hi:[1,0,1]
	v_pk_fma_f32 v[36:37], v[36:37], 0.5, v[110:111] op_sel_hi:[1,0,1]
	v_pk_fma_f32 v[40:41], v[30:31], 0.5, v[102:103] op_sel_hi:[1,0,1]
	v_pk_fma_f32 v[30:31], v[28:29], 0.5, v[112:113] op_sel_hi:[1,0,1]
	v_lshlrev_b32_e32 v114, 16, v120
	v_and_b32_e32 v115, 0xffff0000, v120
	v_lshlrev_b32_e32 v116, 16, v121
	v_and_b32_e32 v117, 0xffff0000, v121
	v_lshlrev_b32_e32 v118, 16, v122
	v_and_b32_e32 v119, 0xffff0000, v122
	v_lshlrev_b32_e32 v120, 16, v123
	v_and_b32_e32 v121, 0xffff0000, v123
	v_cvt_pk_bf16_f32 v28, v36, v37
	v_cvt_pk_bf16_f32 v29, v38, v39
	v_cvt_pk_bf16_f32 v30, v30, v31
	v_cvt_pk_bf16_f32 v31, v40, v41
	global_store_dwordx4 v[98:99], v[28:31], off offset:256
	v_lshlrev_b32_e32 v122, 16, v92
	v_and_b32_e32 v123, 0xffff0000, v92
	v_pk_fma_f32 v[28:29], v[34:35], 0.5, v[116:117] op_sel_hi:[1,0,1]
	v_pk_fma_f32 v[30:31], v[32:33], 0.5, v[114:115] op_sel_hi:[1,0,1]
	v_pk_fma_f32 v[32:33], v[26:27], 0.5, v[120:121] op_sel_hi:[1,0,1]
	v_pk_fma_f32 v[26:27], v[24:25], 0.5, v[118:119] op_sel_hi:[1,0,1]
	v_lshlrev_b32_e32 v92, 16, v93
	v_and_b32_e32 v93, 0xffff0000, v93
	v_lshlrev_b32_e32 v144, 16, v94
	v_and_b32_e32 v145, 0xffff0000, v94
	v_lshlrev_b32_e32 v94, 16, v95
	v_and_b32_e32 v95, 0xffff0000, v95
	v_cvt_pk_bf16_f32 v24, v30, v31
	v_cvt_pk_bf16_f32 v25, v28, v29
	v_cvt_pk_bf16_f32 v26, v26, v27
	v_cvt_pk_bf16_f32 v27, v32, v33
	global_store_dwordx4 v[96:97], v[24:27], off
	v_pk_fma_f32 v[22:23], v[22:23], 0.5, v[92:93] op_sel_hi:[1,0,1]
	v_pk_fma_f32 v[20:21], v[20:21], 0.5, v[122:123] op_sel_hi:[1,0,1]
	v_pk_fma_f32 v[24:25], v[14:15], 0.5, v[94:95] op_sel_hi:[1,0,1]
	v_pk_fma_f32 v[14:15], v[12:13], 0.5, v[144:145] op_sel_hi:[1,0,1]
	v_lshlrev_b32_e32 v146, 16, v124
	v_and_b32_e32 v147, 0xffff0000, v124
	v_lshlrev_b32_e32 v124, 16, v125
	v_and_b32_e32 v125, 0xffff0000, v125
	v_lshlrev_b32_e32 v148, 16, v126
	v_and_b32_e32 v149, 0xffff0000, v126
	v_lshlrev_b32_e32 v126, 16, v127
	v_and_b32_e32 v127, 0xffff0000, v127
	v_cvt_pk_bf16_f32 v12, v20, v21
	v_cvt_pk_bf16_f32 v13, v22, v23
	v_cvt_pk_bf16_f32 v14, v14, v15
	v_cvt_pk_bf16_f32 v15, v24, v25
	global_store_dwordx4 v[90:91], v[12:15], off offset:256
	v_lshlrev_b32_e32 v150, 16, v80
	v_and_b32_e32 v151, 0xffff0000, v80
	v_pk_fma_f32 v[12:13], v[18:19], 0.5, v[124:125] op_sel_hi:[1,0,1]
	v_pk_fma_f32 v[14:15], v[16:17], 0.5, v[146:147] op_sel_hi:[1,0,1]
	v_pk_fma_f32 v[16:17], v[10:11], 0.5, v[126:127] op_sel_hi:[1,0,1]
	v_pk_fma_f32 v[10:11], v[8:9], 0.5, v[148:149] op_sel_hi:[1,0,1]
	v_lshlrev_b32_e32 v80, 16, v81
	v_and_b32_e32 v81, 0xffff0000, v81
	v_lshlrev_b32_e32 v152, 16, v82
	v_and_b32_e32 v153, 0xffff0000, v82
	v_lshlrev_b32_e32 v82, 16, v83
	v_and_b32_e32 v83, 0xffff0000, v83
	v_cvt_pk_bf16_f32 v8, v14, v15
	v_cvt_pk_bf16_f32 v9, v12, v13
	v_cvt_pk_bf16_f32 v10, v10, v11
	v_cvt_pk_bf16_f32 v11, v16, v17
	global_store_dwordx4 v[88:89], v[8:11], off
	v_pk_fma_f32 v[6:7], v[6:7], 0.5, v[80:81] op_sel_hi:[1,0,1]
	v_pk_fma_f32 v[4:5], v[4:5], 0.5, v[150:151] op_sel_hi:[1,0,1]
	v_pk_fma_f32 v[8:9], v[2:3], 0.5, v[82:83] op_sel_hi:[1,0,1]
	v_pk_fma_f32 v[2:3], v[0:1], 0.5, v[152:153] op_sel_hi:[1,0,1]
	v_cvt_pk_bf16_f32 v0, v4, v5
	v_cvt_pk_bf16_f32 v1, v6, v7
	v_cvt_pk_bf16_f32 v2, v2, v3
	v_cvt_pk_bf16_f32 v3, v8, v9
	s_and_b64 vcc, exec, s[0:1]
	global_store_dwordx4 v[72:73], v[0:3], off offset:256
	s_cbranch_vccz .LBB0_930
	s_waitcnt vmcnt(0)
	s_cmpk_gt_u32 s6, 0xff
	s_cbranch_scc1 .LBB0_945
	s_barrier
